# prep/post table-load rings one rank deeper (prep D 6->7 of 8 slots, post D 10->11 of 12 slots)
# speedup vs baseline: 1.0064x; 1.0030x over previous
.Lgprep_batch:
	s_mov_b32 s6, s13
	s_min_u32 s6, s6, 0x27ff
	s_mul_i32 s7, s6, 0x2f00
	s_add_u32 s7, s7, 0x2400
	s_add_u32 s8, s74, s7
	s_addc_u32 s9, s75, 0
	global_load_dword v20, v233, s[8:9] offset:2048 sc1
	global_load_dword v25, v233, s[8:9] offset:2304 sc1
	s_add_u32 s6, s13, 1
	s_min_u32 s6, s6, 0x27ff
	s_mul_i32 s7, s6, 0x2f00
	s_add_u32 s7, s7, 0x2400
	s_add_u32 s8, s74, s7
	s_addc_u32 s9, s75, 0
	global_load_dword v21, v233, s[8:9] offset:2048 sc1
	global_load_dword v26, v233, s[8:9] offset:2304 sc1
	s_add_u32 s6, s13, 2
	s_min_u32 s6, s6, 0x27ff
	s_mul_i32 s7, s6, 0x2f00
	s_add_u32 s7, s7, 0x2400
	s_add_u32 s8, s74, s7
	s_addc_u32 s9, s75, 0
	global_load_dword v22, v233, s[8:9] offset:2048 sc1
	global_load_dword v27, v233, s[8:9] offset:2304 sc1
	s_add_u32 s6, s13, 3
	s_min_u32 s6, s6, 0x27ff
	s_mul_i32 s7, s6, 0x2f00
	s_add_u32 s7, s7, 0x2400
	s_add_u32 s8, s74, s7
	s_addc_u32 s9, s75, 0
	global_load_dword v23, v233, s[8:9] offset:2048 sc1
	global_load_dword v28, v233, s[8:9] offset:2304 sc1
	s_add_u32 s6, s13, 4
	s_min_u32 s6, s6, 0x27ff
	s_mul_i32 s7, s6, 0x2f00
	s_add_u32 s7, s7, 0x2400
	s_add_u32 s8, s74, s7
	s_addc_u32 s9, s75, 0
	global_load_dword v24, v233, s[8:9] offset:2048 sc1
	global_load_dword v29, v233, s[8:9] offset:2304 sc1
	s_mov_b32 s6, s13
	s_min_u32 s6, s6, 0x27ff
	s_mul_i32 s7, s6, 0x2f00
	s_add_u32 s7, s7, 0x2400
	s_add_u32 s8, s74, s7
	s_addc_u32 s9, s75, 0
	global_load_dwordx4 v[0:3], v232, s[8:9] sc1
	s_add_u32 s6, s13, 1
	s_min_u32 s6, s6, 0x27ff
	s_mul_i32 s7, s6, 0x2f00
	s_add_u32 s7, s7, 0x2400
	s_add_u32 s8, s74, s7
	s_addc_u32 s9, s75, 0
	global_load_dwordx4 v[4:7], v232, s[8:9] sc1
	s_add_u32 s6, s13, 2
	s_min_u32 s6, s6, 0x27ff
	s_mul_i32 s7, s6, 0x2f00
	s_add_u32 s7, s7, 0x2400
	s_add_u32 s8, s74, s7
	s_addc_u32 s9, s75, 0
	global_load_dwordx4 v[8:11], v232, s[8:9] sc1
	s_add_u32 s6, s13, 3
	s_min_u32 s6, s6, 0x27ff
	s_mul_i32 s7, s6, 0x2f00
	s_add_u32 s7, s7, 0x2400
	s_add_u32 s8, s74, s7
	s_addc_u32 s9, s75, 0
	global_load_dwordx4 v[12:15], v232, s[8:9] sc1
	s_add_u32 s6, s13, 4
	s_min_u32 s6, s6, 0x27ff
	s_mul_i32 s7, s6, 0x2f00
	s_add_u32 s7, s7, 0x2400
	s_add_u32 s8, s74, s7
	s_addc_u32 s9, s75, 0
	global_load_dwordx4 v[16:19], v232, s[8:9] sc1
	s_add_u32 s2, s16, 0x0
	s_addc_u32 s3, s17, 0
	s_add_u32 s40, s18, 0x0
	s_addc_u32 s41, s19, 0
	global_load_dwordx4 v[168:171], v232, s[2:3]
	global_load_dwordx4 v[172:175], v232, s[40:41]
	global_load_dwordx4 v[176:179], v232, s[2:3] offset:1024
	global_load_dwordx4 v[180:183], v232, s[40:41] offset:1024
	global_load_dwordx4 v[184:187], v232, s[2:3] offset:2048
	global_load_dwordx4 v[188:191], v232, s[40:41] offset:2048
	global_load_dwordx4 v[192:195], v232, s[2:3] offset:3072
	global_load_dwordx4 v[196:199], v232, s[40:41] offset:3072
	s_add_u32 s2, s2, 0x1000
	s_addc_u32 s3, s3, 0
	s_add_u32 s40, s40, 0x1000
	s_addc_u32 s41, s41, 0
	global_load_dwordx4 v[200:203], v232, s[2:3]
	global_load_dwordx4 v[204:207], v232, s[40:41]
	global_load_dwordx4 v[208:211], v232, s[2:3] offset:1024
	global_load_dwordx4 v[212:215], v232, s[40:41] offset:1024
	global_load_dwordx4 v[216:219], v232, s[2:3] offset:2048
	global_load_dwordx4 v[220:223], v232, s[40:41] offset:2048
	s_waitcnt vmcnt(19)
	v_add_f32_e64 v92, |v20|, |v20|
	v_mul_f32_e32 v93, 0x3fb8aa3b, v92
	v_rndne_f32_e32 v94, v93
	s_mov_b32 s4, 0x3fb8aa3b
	v_sub_f32_e32 v95, v93, v94
	v_fma_f32 v93, v92, s4, -v93
	v_fmac_f32_e32 v93, 0x32a5705f, v92
	v_add_f32_e32 v93, v95, v93
	v_cvt_i32_f32_e32 v94, v94
	v_exp_f32_e32 v93, v93
	s_mov_b32 s4, 0xc2ce8ed0
	v_cmp_ngt_f32_e32 vcc, s4, v92
	s_mov_b32 s4, 0x42b17218
	v_ldexp_f32 v93, v93, v94
	s_nop 0
	v_cndmask_b32_e32 v93, 0, v93, vcc
	v_cmp_nlt_f32_e32 vcc, s4, v92
	s_nop 1
	v_cndmask_b32_e32 v92, v134, v93, vcc
	v_add_f32_e32 v92, 1.0, v92
	v_rcp_f32_e32 v92, v92
	s_nop 0
	v_fma_f32 v96, v92, -2.0, 1.0
	v_mul_f32_e32 v98, v20, v20
	v_fmamk_f32 v97, v98, 0xbbbac73d, v131
	v_fmaak_f32 v97, v98, v97, 0xbd5c1c4e
	v_fmaak_f32 v97, v98, v97, 0x3e088382
	v_fmaak_f32 v97, v98, v97, 0xbeaaaa99
	v_mul_f32_e64 v97, |v20|, v97
	v_fma_f32 v97, v98, v97, |v20|
	s_mov_b32 s4, 0x3f200000
	v_cmp_nlt_f32_e64 vcc, |v20|, s4
	s_nop 1
	v_cndmask_b32_e32 v97, v97, v96, vcc
	s_brev_b32 s4, -2
	v_bfi_b32 v20, s4, v97, v20
	v_add_f32_e64 v92, |v21|, |v21|
	v_mul_f32_e32 v93, 0x3fb8aa3b, v92
	v_rndne_f32_e32 v94, v93
	s_mov_b32 s4, 0x3fb8aa3b
	v_sub_f32_e32 v95, v93, v94
	v_fma_f32 v93, v92, s4, -v93
	v_fmac_f32_e32 v93, 0x32a5705f, v92
	v_add_f32_e32 v93, v95, v93
	v_cvt_i32_f32_e32 v94, v94
	v_exp_f32_e32 v93, v93
	s_mov_b32 s4, 0xc2ce8ed0
	v_cmp_ngt_f32_e32 vcc, s4, v92
	s_mov_b32 s4, 0x42b17218
	v_ldexp_f32 v93, v93, v94
	s_nop 0
	v_cndmask_b32_e32 v93, 0, v93, vcc
	v_cmp_nlt_f32_e32 vcc, s4, v92
	s_nop 1
	v_cndmask_b32_e32 v92, v134, v93, vcc
	v_add_f32_e32 v92, 1.0, v92
	v_rcp_f32_e32 v92, v92
	s_nop 0
	v_fma_f32 v96, v92, -2.0, 1.0
	v_mul_f32_e32 v98, v21, v21
	v_fmamk_f32 v97, v98, 0xbbbac73d, v131
	v_fmaak_f32 v97, v98, v97, 0xbd5c1c4e
	v_fmaak_f32 v97, v98, v97, 0x3e088382
	v_fmaak_f32 v97, v98, v97, 0xbeaaaa99
	v_mul_f32_e64 v97, |v21|, v97
	v_fma_f32 v97, v98, v97, |v21|
	s_mov_b32 s4, 0x3f200000
	v_cmp_nlt_f32_e64 vcc, |v21|, s4
	s_nop 1
	v_cndmask_b32_e32 v97, v97, v96, vcc
	s_brev_b32 s4, -2
	v_bfi_b32 v21, s4, v97, v21
	v_add_f32_e64 v92, |v22|, |v22|
	v_mul_f32_e32 v93, 0x3fb8aa3b, v92
	v_rndne_f32_e32 v94, v93
	s_mov_b32 s4, 0x3fb8aa3b
	v_sub_f32_e32 v95, v93, v94
	v_fma_f32 v93, v92, s4, -v93
	v_fmac_f32_e32 v93, 0x32a5705f, v92
	v_add_f32_e32 v93, v95, v93
	v_cvt_i32_f32_e32 v94, v94
	v_exp_f32_e32 v93, v93
	s_mov_b32 s4, 0xc2ce8ed0
	v_cmp_ngt_f32_e32 vcc, s4, v92
	s_mov_b32 s4, 0x42b17218
	v_ldexp_f32 v93, v93, v94
	s_nop 0
	v_cndmask_b32_e32 v93, 0, v93, vcc
	v_cmp_nlt_f32_e32 vcc, s4, v92
	s_nop 1
	v_cndmask_b32_e32 v92, v134, v93, vcc
	v_add_f32_e32 v92, 1.0, v92
	v_rcp_f32_e32 v92, v92
	s_nop 0
	v_fma_f32 v96, v92, -2.0, 1.0
	v_mul_f32_e32 v98, v22, v22
	v_fmamk_f32 v97, v98, 0xbbbac73d, v131
	v_fmaak_f32 v97, v98, v97, 0xbd5c1c4e
	v_fmaak_f32 v97, v98, v97, 0x3e088382
	v_fmaak_f32 v97, v98, v97, 0xbeaaaa99
	v_mul_f32_e64 v97, |v22|, v97
	v_fma_f32 v97, v98, v97, |v22|
	s_mov_b32 s4, 0x3f200000
	v_cmp_nlt_f32_e64 vcc, |v22|, s4
	s_nop 1
	v_cndmask_b32_e32 v97, v97, v96, vcc
	s_brev_b32 s4, -2
	v_bfi_b32 v22, s4, v97, v22
	v_add_f32_e64 v92, |v23|, |v23|
	v_mul_f32_e32 v93, 0x3fb8aa3b, v92
	v_rndne_f32_e32 v94, v93
	s_mov_b32 s4, 0x3fb8aa3b
	v_sub_f32_e32 v95, v93, v94
	v_fma_f32 v93, v92, s4, -v93
	v_fmac_f32_e32 v93, 0x32a5705f, v92
	v_add_f32_e32 v93, v95, v93
	v_cvt_i32_f32_e32 v94, v94
	v_exp_f32_e32 v93, v93
	s_mov_b32 s4, 0xc2ce8ed0
	v_cmp_ngt_f32_e32 vcc, s4, v92
	s_mov_b32 s4, 0x42b17218
	v_ldexp_f32 v93, v93, v94
	s_nop 0
	v_cndmask_b32_e32 v93, 0, v93, vcc
	v_cmp_nlt_f32_e32 vcc, s4, v92
	s_nop 1
	v_cndmask_b32_e32 v92, v134, v93, vcc
	v_add_f32_e32 v92, 1.0, v92
	v_rcp_f32_e32 v92, v92
	s_nop 0
	v_fma_f32 v96, v92, -2.0, 1.0
	v_mul_f32_e32 v98, v23, v23
	v_fmamk_f32 v97, v98, 0xbbbac73d, v131
	v_fmaak_f32 v97, v98, v97, 0xbd5c1c4e
	v_fmaak_f32 v97, v98, v97, 0x3e088382
	v_fmaak_f32 v97, v98, v97, 0xbeaaaa99
	v_mul_f32_e64 v97, |v23|, v97
	v_fma_f32 v97, v98, v97, |v23|
	s_mov_b32 s4, 0x3f200000
	v_cmp_nlt_f32_e64 vcc, |v23|, s4
	s_nop 1
	v_cndmask_b32_e32 v97, v97, v96, vcc
	s_brev_b32 s4, -2
	v_bfi_b32 v23, s4, v97, v23
	v_add_f32_e64 v92, |v24|, |v24|
	v_mul_f32_e32 v93, 0x3fb8aa3b, v92
	v_rndne_f32_e32 v94, v93
	s_mov_b32 s4, 0x3fb8aa3b
	v_sub_f32_e32 v95, v93, v94
	v_fma_f32 v93, v92, s4, -v93
	v_fmac_f32_e32 v93, 0x32a5705f, v92
	v_add_f32_e32 v93, v95, v93
	v_cvt_i32_f32_e32 v94, v94
	v_exp_f32_e32 v93, v93
	s_mov_b32 s4, 0xc2ce8ed0
	v_cmp_ngt_f32_e32 vcc, s4, v92
	s_mov_b32 s4, 0x42b17218
	v_ldexp_f32 v93, v93, v94
	s_nop 0
	v_cndmask_b32_e32 v93, 0, v93, vcc
	v_cmp_nlt_f32_e32 vcc, s4, v92
	s_nop 1
	v_cndmask_b32_e32 v92, v134, v93, vcc
	v_add_f32_e32 v92, 1.0, v92
	v_rcp_f32_e32 v92, v92
	s_nop 0
	v_fma_f32 v96, v92, -2.0, 1.0
	v_mul_f32_e32 v98, v24, v24
	v_fmamk_f32 v97, v98, 0xbbbac73d, v131
	v_fmaak_f32 v97, v98, v97, 0xbd5c1c4e
	v_fmaak_f32 v97, v98, v97, 0x3e088382
	v_fmaak_f32 v97, v98, v97, 0xbeaaaa99
	v_mul_f32_e64 v97, |v24|, v97
	v_fma_f32 v97, v98, v97, |v24|
	s_mov_b32 s4, 0x3f200000
	v_cmp_nlt_f32_e64 vcc, |v24|, s4
	s_nop 1
	v_cndmask_b32_e32 v97, v97, v96, vcc
	s_brev_b32 s4, -2
	v_bfi_b32 v24, s4, v97, v24
	s_waitcnt vmcnt(14)
	v_mul_f32_e32 v0, v30, v0
	v_mul_f32_e32 v1, v31, v1
	v_mul_f32_e32 v2, v32, v2
	v_mul_f32_e32 v3, v33, v3
	v_mul_f32_e32 v92, v0, v0
	v_mul_f32_e32 v93, v2, v2
	v_fmac_f32_e32 v92, v1, v1
	v_fmac_f32_e32 v93, v3, v3
	v_add_f32_e32 v92, v92, v93
	s_nop 1
	v_add_f32_dpp v92, v92, v92 quad_perm:[1,0,3,2] row_mask:0xf bank_mask:0xf bound_ctrl:1
	s_nop 1
	v_add_f32_dpp v92, v92, v92 quad_perm:[2,3,0,1] row_mask:0xf bank_mask:0xf bound_ctrl:1
	s_nop 1
	v_add_f32_dpp v92, v92, v92 row_half_mirror row_mask:0xf bank_mask:0xf bound_ctrl:1
	s_nop 1
	v_add_f32_dpp v92, v92, v92 row_mirror row_mask:0xf bank_mask:0xf bound_ctrl:1
	v_add_f32_e32 v92, 0x358637bd, v92
	v_rsq_f32_e32 v92, v92
	s_nop 0
	v_mul_f32_e32 v0, v0, v92
	v_mul_f32_e32 v1, v1, v92
	v_mul_f32_e32 v2, v2, v92
	v_mul_f32_e32 v3, v3, v92
	v_mul_f32_e32 v4, v30, v4
	v_mul_f32_e32 v5, v31, v5
	v_mul_f32_e32 v6, v32, v6
	v_mul_f32_e32 v7, v33, v7
	v_mul_f32_e32 v92, v4, v4
	v_mul_f32_e32 v93, v6, v6
	v_fmac_f32_e32 v92, v5, v5
	v_fmac_f32_e32 v93, v7, v7
	v_add_f32_e32 v92, v92, v93
	s_nop 1
	v_add_f32_dpp v92, v92, v92 quad_perm:[1,0,3,2] row_mask:0xf bank_mask:0xf bound_ctrl:1
	s_nop 1
	v_add_f32_dpp v92, v92, v92 quad_perm:[2,3,0,1] row_mask:0xf bank_mask:0xf bound_ctrl:1
	s_nop 1
	v_add_f32_dpp v92, v92, v92 row_half_mirror row_mask:0xf bank_mask:0xf bound_ctrl:1
	s_nop 1
	v_add_f32_dpp v92, v92, v92 row_mirror row_mask:0xf bank_mask:0xf bound_ctrl:1
	v_add_f32_e32 v92, 0x358637bd, v92
	v_rsq_f32_e32 v92, v92
	s_nop 0
	v_mul_f32_e32 v4, v4, v92
	v_mul_f32_e32 v5, v5, v92
	v_mul_f32_e32 v6, v6, v92
	v_mul_f32_e32 v7, v7, v92
	v_mul_f32_e32 v8, v30, v8
	v_mul_f32_e32 v9, v31, v9
	v_mul_f32_e32 v10, v32, v10
	v_mul_f32_e32 v11, v33, v11
	v_mul_f32_e32 v92, v8, v8
	v_mul_f32_e32 v93, v10, v10
	v_fmac_f32_e32 v92, v9, v9
	v_fmac_f32_e32 v93, v11, v11
	v_add_f32_e32 v92, v92, v93
	s_nop 1
	v_add_f32_dpp v92, v92, v92 quad_perm:[1,0,3,2] row_mask:0xf bank_mask:0xf bound_ctrl:1
	s_nop 1
	v_add_f32_dpp v92, v92, v92 quad_perm:[2,3,0,1] row_mask:0xf bank_mask:0xf bound_ctrl:1
	s_nop 1
	v_add_f32_dpp v92, v92, v92 row_half_mirror row_mask:0xf bank_mask:0xf bound_ctrl:1
	s_nop 1
	v_add_f32_dpp v92, v92, v92 row_mirror row_mask:0xf bank_mask:0xf bound_ctrl:1
	v_add_f32_e32 v92, 0x358637bd, v92
	v_rsq_f32_e32 v92, v92
	s_nop 0
	v_mul_f32_e32 v8, v8, v92
	v_mul_f32_e32 v9, v9, v92
	v_mul_f32_e32 v10, v10, v92
	v_mul_f32_e32 v11, v11, v92
	v_mul_f32_e32 v12, v30, v12
	v_mul_f32_e32 v13, v31, v13
	v_mul_f32_e32 v14, v32, v14
	v_mul_f32_e32 v15, v33, v15
	v_mul_f32_e32 v92, v12, v12
	v_mul_f32_e32 v93, v14, v14
	v_fmac_f32_e32 v92, v13, v13
	v_fmac_f32_e32 v93, v15, v15
	v_add_f32_e32 v92, v92, v93
	s_nop 1
	v_add_f32_dpp v92, v92, v92 quad_perm:[1,0,3,2] row_mask:0xf bank_mask:0xf bound_ctrl:1
	s_nop 1
	v_add_f32_dpp v92, v92, v92 quad_perm:[2,3,0,1] row_mask:0xf bank_mask:0xf bound_ctrl:1
	s_nop 1
	v_add_f32_dpp v92, v92, v92 row_half_mirror row_mask:0xf bank_mask:0xf bound_ctrl:1
	s_nop 1
	v_add_f32_dpp v92, v92, v92 row_mirror row_mask:0xf bank_mask:0xf bound_ctrl:1
	v_add_f32_e32 v92, 0x358637bd, v92
	v_rsq_f32_e32 v92, v92
	s_nop 0
	v_mul_f32_e32 v12, v12, v92
	v_mul_f32_e32 v13, v13, v92
	v_mul_f32_e32 v14, v14, v92
	v_mul_f32_e32 v15, v15, v92
	v_mul_f32_e32 v16, v30, v16
	v_mul_f32_e32 v17, v31, v17
	v_mul_f32_e32 v18, v32, v18
	v_mul_f32_e32 v19, v33, v19
	v_mul_f32_e32 v92, v16, v16
	v_mul_f32_e32 v93, v18, v18
	v_fmac_f32_e32 v92, v17, v17
	v_fmac_f32_e32 v93, v19, v19
	v_add_f32_e32 v92, v92, v93
	s_nop 1
	v_add_f32_dpp v92, v92, v92 quad_perm:[1,0,3,2] row_mask:0xf bank_mask:0xf bound_ctrl:1
	s_nop 1
	v_add_f32_dpp v92, v92, v92 quad_perm:[2,3,0,1] row_mask:0xf bank_mask:0xf bound_ctrl:1
	s_nop 1
	v_add_f32_dpp v92, v92, v92 row_half_mirror row_mask:0xf bank_mask:0xf bound_ctrl:1
	s_nop 1
	v_add_f32_dpp v92, v92, v92 row_mirror row_mask:0xf bank_mask:0xf bound_ctrl:1
	v_add_f32_e32 v92, 0x358637bd, v92
	v_rsq_f32_e32 v92, v92
	s_nop 0
	v_mul_f32_e32 v16, v16, v92
	v_mul_f32_e32 v17, v17, v92
	v_mul_f32_e32 v18, v18, v92
	v_mul_f32_e32 v19, v19, v92
	v_mov_b32_e32 v52, v34
	v_mov_b32_e32 v56, v42
	v_mov_b32_e32 v53, v35
	v_mov_b32_e32 v57, v43
	v_mov_b32_e32 v54, v36
	v_mov_b32_e32 v58, v44
	v_mov_b32_e32 v55, v37
	v_mov_b32_e32 v59, v45
	v_mov_b32_e32 v60, v34
	v_mov_b32_e32 v64, v42
	v_mov_b32_e32 v61, v35
	v_mov_b32_e32 v65, v43
	v_mov_b32_e32 v62, v36
	v_mov_b32_e32 v66, v44
	v_mov_b32_e32 v63, v37
	v_mov_b32_e32 v67, v45
	v_mov_b32_e32 v68, v34
	v_mov_b32_e32 v72, v42
	v_mov_b32_e32 v69, v35
	v_mov_b32_e32 v73, v43
	v_mov_b32_e32 v70, v36
	v_mov_b32_e32 v74, v44
	v_mov_b32_e32 v71, v37
	v_mov_b32_e32 v75, v45
	v_mov_b32_e32 v76, v34
	v_mov_b32_e32 v80, v42
	v_mov_b32_e32 v77, v35
	v_mov_b32_e32 v81, v43
	v_mov_b32_e32 v78, v36
	v_mov_b32_e32 v82, v44
	v_mov_b32_e32 v79, v37
	v_mov_b32_e32 v83, v45
	v_mov_b32_e32 v84, v34
	v_mov_b32_e32 v88, v42
	v_mov_b32_e32 v85, v35
	v_mov_b32_e32 v89, v43
	v_mov_b32_e32 v86, v36
	v_mov_b32_e32 v90, v44
	v_mov_b32_e32 v87, v37
	v_mov_b32_e32 v91, v45
	global_load_dwordx4 v[224:227], v232, s[2:3] offset:3072
	global_load_dwordx4 v[228:231], v232, s[40:41] offset:3072
	s_add_u32 s2, s2, 0x1000
	s_addc_u32 s3, s3, 0
	s_add_u32 s40, s40, 0x1000
	s_addc_u32 s41, s41, 0
	s_waitcnt vmcnt(14)
	v_readlane_b32 s48, v20, 0
	v_readlane_b32 s58, v25, 0
	v_readlane_b32 s50, v21, 0
	v_readlane_b32 s60, v26, 0
	v_readlane_b32 s52, v22, 0
	v_readlane_b32 s62, v27, 0
	v_readlane_b32 s54, v23, 0
	v_readlane_b32 s64, v28, 0
	v_readlane_b32 s56, v24, 0
	v_readlane_b32 s66, v29, 0
	v_pk_fma_f32 v[52:53], v[168:169], s[48:49], v[52:53] op_sel_hi:[1,0,1]
	v_pk_fma_f32 v[54:55], v[170:171], s[48:49], v[54:55] op_sel_hi:[1,0,1]
	v_pk_fma_f32 v[56:57], v[172:173], s[58:59], v[56:57] op_sel_hi:[1,0,1]
	v_pk_fma_f32 v[58:59], v[174:175], s[58:59], v[58:59] op_sel_hi:[1,0,1]
	v_pk_fma_f32 v[60:61], v[168:169], s[50:51], v[60:61] op_sel_hi:[1,0,1]
	v_pk_fma_f32 v[62:63], v[170:171], s[50:51], v[62:63] op_sel_hi:[1,0,1]
	v_pk_fma_f32 v[64:65], v[172:173], s[60:61], v[64:65] op_sel_hi:[1,0,1]
	v_pk_fma_f32 v[66:67], v[174:175], s[60:61], v[66:67] op_sel_hi:[1,0,1]
	v_pk_fma_f32 v[68:69], v[168:169], s[52:53], v[68:69] op_sel_hi:[1,0,1]
	v_pk_fma_f32 v[70:71], v[170:171], s[52:53], v[70:71] op_sel_hi:[1,0,1]
	v_pk_fma_f32 v[72:73], v[172:173], s[62:63], v[72:73] op_sel_hi:[1,0,1]
	v_pk_fma_f32 v[74:75], v[174:175], s[62:63], v[74:75] op_sel_hi:[1,0,1]
	v_pk_fma_f32 v[76:77], v[168:169], s[54:55], v[76:77] op_sel_hi:[1,0,1]
	v_pk_fma_f32 v[78:79], v[170:171], s[54:55], v[78:79] op_sel_hi:[1,0,1]
	v_pk_fma_f32 v[80:81], v[172:173], s[64:65], v[80:81] op_sel_hi:[1,0,1]
	v_pk_fma_f32 v[82:83], v[174:175], s[64:65], v[82:83] op_sel_hi:[1,0,1]
	v_pk_fma_f32 v[84:85], v[168:169], s[56:57], v[84:85] op_sel_hi:[1,0,1]
	v_pk_fma_f32 v[86:87], v[170:171], s[56:57], v[86:87] op_sel_hi:[1,0,1]
	v_pk_fma_f32 v[88:89], v[172:173], s[66:67], v[88:89] op_sel_hi:[1,0,1]
	v_pk_fma_f32 v[90:91], v[174:175], s[66:67], v[90:91] op_sel_hi:[1,0,1]
	global_load_dwordx4 v[168:171], v232, s[2:3]
	global_load_dwordx4 v[172:175], v232, s[40:41]
	s_waitcnt vmcnt(14)
	v_readlane_b32 s48, v20, 1
	v_readlane_b32 s58, v25, 1
	v_readlane_b32 s50, v21, 1
	v_readlane_b32 s60, v26, 1
	v_readlane_b32 s52, v22, 1
	v_readlane_b32 s62, v27, 1
	v_readlane_b32 s54, v23, 1
	v_readlane_b32 s64, v28, 1
	v_readlane_b32 s56, v24, 1
	v_readlane_b32 s66, v29, 1
	v_pk_fma_f32 v[52:53], v[176:177], s[48:49], v[52:53] op_sel_hi:[1,0,1]
	v_pk_fma_f32 v[54:55], v[178:179], s[48:49], v[54:55] op_sel_hi:[1,0,1]
	v_pk_fma_f32 v[56:57], v[180:181], s[58:59], v[56:57] op_sel_hi:[1,0,1]
	v_pk_fma_f32 v[58:59], v[182:183], s[58:59], v[58:59] op_sel_hi:[1,0,1]
	v_pk_fma_f32 v[60:61], v[176:177], s[50:51], v[60:61] op_sel_hi:[1,0,1]
	v_pk_fma_f32 v[62:63], v[178:179], s[50:51], v[62:63] op_sel_hi:[1,0,1]
	v_pk_fma_f32 v[64:65], v[180:181], s[60:61], v[64:65] op_sel_hi:[1,0,1]
	v_pk_fma_f32 v[66:67], v[182:183], s[60:61], v[66:67] op_sel_hi:[1,0,1]
	v_pk_fma_f32 v[68:69], v[176:177], s[52:53], v[68:69] op_sel_hi:[1,0,1]
	v_pk_fma_f32 v[70:71], v[178:179], s[52:53], v[70:71] op_sel_hi:[1,0,1]
	v_pk_fma_f32 v[72:73], v[180:181], s[62:63], v[72:73] op_sel_hi:[1,0,1]
	v_pk_fma_f32 v[74:75], v[182:183], s[62:63], v[74:75] op_sel_hi:[1,0,1]
	v_pk_fma_f32 v[76:77], v[176:177], s[54:55], v[76:77] op_sel_hi:[1,0,1]
	v_pk_fma_f32 v[78:79], v[178:179], s[54:55], v[78:79] op_sel_hi:[1,0,1]
	v_pk_fma_f32 v[80:81], v[180:181], s[64:65], v[80:81] op_sel_hi:[1,0,1]
	v_pk_fma_f32 v[82:83], v[182:183], s[64:65], v[82:83] op_sel_hi:[1,0,1]
	v_pk_fma_f32 v[84:85], v[176:177], s[56:57], v[84:85] op_sel_hi:[1,0,1]
	v_pk_fma_f32 v[86:87], v[178:179], s[56:57], v[86:87] op_sel_hi:[1,0,1]
	v_pk_fma_f32 v[88:89], v[180:181], s[66:67], v[88:89] op_sel_hi:[1,0,1]
	v_pk_fma_f32 v[90:91], v[182:183], s[66:67], v[90:91] op_sel_hi:[1,0,1]
	global_load_dwordx4 v[176:179], v232, s[2:3] offset:1024
	global_load_dwordx4 v[180:183], v232, s[40:41] offset:1024
	s_waitcnt vmcnt(14)
	v_readlane_b32 s48, v20, 2
	v_readlane_b32 s58, v25, 2
	v_readlane_b32 s50, v21, 2
	v_readlane_b32 s60, v26, 2
	v_readlane_b32 s52, v22, 2
	v_readlane_b32 s62, v27, 2
	v_readlane_b32 s54, v23, 2
	v_readlane_b32 s64, v28, 2
	v_readlane_b32 s56, v24, 2
	v_readlane_b32 s66, v29, 2
	v_pk_fma_f32 v[52:53], v[184:185], s[48:49], v[52:53] op_sel_hi:[1,0,1]
	v_pk_fma_f32 v[54:55], v[186:187], s[48:49], v[54:55] op_sel_hi:[1,0,1]
	v_pk_fma_f32 v[56:57], v[188:189], s[58:59], v[56:57] op_sel_hi:[1,0,1]
	v_pk_fma_f32 v[58:59], v[190:191], s[58:59], v[58:59] op_sel_hi:[1,0,1]
	v_pk_fma_f32 v[60:61], v[184:185], s[50:51], v[60:61] op_sel_hi:[1,0,1]
	v_pk_fma_f32 v[62:63], v[186:187], s[50:51], v[62:63] op_sel_hi:[1,0,1]
	v_pk_fma_f32 v[64:65], v[188:189], s[60:61], v[64:65] op_sel_hi:[1,0,1]
	v_pk_fma_f32 v[66:67], v[190:191], s[60:61], v[66:67] op_sel_hi:[1,0,1]
	v_pk_fma_f32 v[68:69], v[184:185], s[52:53], v[68:69] op_sel_hi:[1,0,1]
	v_pk_fma_f32 v[70:71], v[186:187], s[52:53], v[70:71] op_sel_hi:[1,0,1]
	v_pk_fma_f32 v[72:73], v[188:189], s[62:63], v[72:73] op_sel_hi:[1,0,1]
	v_pk_fma_f32 v[74:75], v[190:191], s[62:63], v[74:75] op_sel_hi:[1,0,1]
	v_pk_fma_f32 v[76:77], v[184:185], s[54:55], v[76:77] op_sel_hi:[1,0,1]
	v_pk_fma_f32 v[78:79], v[186:187], s[54:55], v[78:79] op_sel_hi:[1,0,1]
	v_pk_fma_f32 v[80:81], v[188:189], s[64:65], v[80:81] op_sel_hi:[1,0,1]
	v_pk_fma_f32 v[82:83], v[190:191], s[64:65], v[82:83] op_sel_hi:[1,0,1]
	v_pk_fma_f32 v[84:85], v[184:185], s[56:57], v[84:85] op_sel_hi:[1,0,1]
	v_pk_fma_f32 v[86:87], v[186:187], s[56:57], v[86:87] op_sel_hi:[1,0,1]
	v_pk_fma_f32 v[88:89], v[188:189], s[66:67], v[88:89] op_sel_hi:[1,0,1]
	v_pk_fma_f32 v[90:91], v[190:191], s[66:67], v[90:91] op_sel_hi:[1,0,1]
	global_load_dwordx4 v[184:187], v232, s[2:3] offset:2048
	global_load_dwordx4 v[188:191], v232, s[40:41] offset:2048
	s_waitcnt vmcnt(14)
	v_readlane_b32 s48, v20, 3
	v_readlane_b32 s58, v25, 3
	v_readlane_b32 s50, v21, 3
	v_readlane_b32 s60, v26, 3
	v_readlane_b32 s52, v22, 3
	v_readlane_b32 s62, v27, 3
	v_readlane_b32 s54, v23, 3
	v_readlane_b32 s64, v28, 3
	v_readlane_b32 s56, v24, 3
	v_readlane_b32 s66, v29, 3
	v_pk_fma_f32 v[52:53], v[192:193], s[48:49], v[52:53] op_sel_hi:[1,0,1]
	v_pk_fma_f32 v[54:55], v[194:195], s[48:49], v[54:55] op_sel_hi:[1,0,1]
	v_pk_fma_f32 v[56:57], v[196:197], s[58:59], v[56:57] op_sel_hi:[1,0,1]
	v_pk_fma_f32 v[58:59], v[198:199], s[58:59], v[58:59] op_sel_hi:[1,0,1]
	v_pk_fma_f32 v[60:61], v[192:193], s[50:51], v[60:61] op_sel_hi:[1,0,1]
	v_pk_fma_f32 v[62:63], v[194:195], s[50:51], v[62:63] op_sel_hi:[1,0,1]
	v_pk_fma_f32 v[64:65], v[196:197], s[60:61], v[64:65] op_sel_hi:[1,0,1]
	v_pk_fma_f32 v[66:67], v[198:199], s[60:61], v[66:67] op_sel_hi:[1,0,1]
	v_pk_fma_f32 v[68:69], v[192:193], s[52:53], v[68:69] op_sel_hi:[1,0,1]
	v_pk_fma_f32 v[70:71], v[194:195], s[52:53], v[70:71] op_sel_hi:[1,0,1]
	v_pk_fma_f32 v[72:73], v[196:197], s[62:63], v[72:73] op_sel_hi:[1,0,1]
	v_pk_fma_f32 v[74:75], v[198:199], s[62:63], v[74:75] op_sel_hi:[1,0,1]
	v_pk_fma_f32 v[76:77], v[192:193], s[54:55], v[76:77] op_sel_hi:[1,0,1]
	v_pk_fma_f32 v[78:79], v[194:195], s[54:55], v[78:79] op_sel_hi:[1,0,1]
	v_pk_fma_f32 v[80:81], v[196:197], s[64:65], v[80:81] op_sel_hi:[1,0,1]
	v_pk_fma_f32 v[82:83], v[198:199], s[64:65], v[82:83] op_sel_hi:[1,0,1]
	v_pk_fma_f32 v[84:85], v[192:193], s[56:57], v[84:85] op_sel_hi:[1,0,1]
	v_pk_fma_f32 v[86:87], v[194:195], s[56:57], v[86:87] op_sel_hi:[1,0,1]
	v_pk_fma_f32 v[88:89], v[196:197], s[66:67], v[88:89] op_sel_hi:[1,0,1]
	v_pk_fma_f32 v[90:91], v[198:199], s[66:67], v[90:91] op_sel_hi:[1,0,1]
	global_load_dwordx4 v[192:195], v232, s[2:3] offset:3072
	global_load_dwordx4 v[196:199], v232, s[40:41] offset:3072
	s_add_u32 s2, s2, 0x1000
	s_addc_u32 s3, s3, 0
	s_add_u32 s40, s40, 0x1000
	s_addc_u32 s41, s41, 0
	s_waitcnt vmcnt(14)
	v_readlane_b32 s48, v20, 4
	v_readlane_b32 s58, v25, 4
	v_readlane_b32 s50, v21, 4
	v_readlane_b32 s60, v26, 4
	v_readlane_b32 s52, v22, 4
	v_readlane_b32 s62, v27, 4
	v_readlane_b32 s54, v23, 4
	v_readlane_b32 s64, v28, 4
	v_readlane_b32 s56, v24, 4
	v_readlane_b32 s66, v29, 4
	v_pk_fma_f32 v[52:53], v[200:201], s[48:49], v[52:53] op_sel_hi:[1,0,1]
	v_pk_fma_f32 v[54:55], v[202:203], s[48:49], v[54:55] op_sel_hi:[1,0,1]
	v_pk_fma_f32 v[56:57], v[204:205], s[58:59], v[56:57] op_sel_hi:[1,0,1]
	v_pk_fma_f32 v[58:59], v[206:207], s[58:59], v[58:59] op_sel_hi:[1,0,1]
	v_pk_fma_f32 v[60:61], v[200:201], s[50:51], v[60:61] op_sel_hi:[1,0,1]
	v_pk_fma_f32 v[62:63], v[202:203], s[50:51], v[62:63] op_sel_hi:[1,0,1]
	v_pk_fma_f32 v[64:65], v[204:205], s[60:61], v[64:65] op_sel_hi:[1,0,1]
	v_pk_fma_f32 v[66:67], v[206:207], s[60:61], v[66:67] op_sel_hi:[1,0,1]
	v_pk_fma_f32 v[68:69], v[200:201], s[52:53], v[68:69] op_sel_hi:[1,0,1]
	v_pk_fma_f32 v[70:71], v[202:203], s[52:53], v[70:71] op_sel_hi:[1,0,1]
	v_pk_fma_f32 v[72:73], v[204:205], s[62:63], v[72:73] op_sel_hi:[1,0,1]
	v_pk_fma_f32 v[74:75], v[206:207], s[62:63], v[74:75] op_sel_hi:[1,0,1]
	v_pk_fma_f32 v[76:77], v[200:201], s[54:55], v[76:77] op_sel_hi:[1,0,1]
	v_pk_fma_f32 v[78:79], v[202:203], s[54:55], v[78:79] op_sel_hi:[1,0,1]
	v_pk_fma_f32 v[80:81], v[204:205], s[64:65], v[80:81] op_sel_hi:[1,0,1]
	v_pk_fma_f32 v[82:83], v[206:207], s[64:65], v[82:83] op_sel_hi:[1,0,1]
	v_pk_fma_f32 v[84:85], v[200:201], s[56:57], v[84:85] op_sel_hi:[1,0,1]
	v_pk_fma_f32 v[86:87], v[202:203], s[56:57], v[86:87] op_sel_hi:[1,0,1]
	v_pk_fma_f32 v[88:89], v[204:205], s[66:67], v[88:89] op_sel_hi:[1,0,1]
	v_pk_fma_f32 v[90:91], v[206:207], s[66:67], v[90:91] op_sel_hi:[1,0,1]
	global_load_dwordx4 v[200:203], v232, s[2:3]
	global_load_dwordx4 v[204:207], v232, s[40:41]
	s_waitcnt vmcnt(14)
	v_readlane_b32 s48, v20, 5
	v_readlane_b32 s58, v25, 5
	v_readlane_b32 s50, v21, 5
	v_readlane_b32 s60, v26, 5
	v_readlane_b32 s52, v22, 5
	v_readlane_b32 s62, v27, 5
	v_readlane_b32 s54, v23, 5
	v_readlane_b32 s64, v28, 5
	v_readlane_b32 s56, v24, 5
	v_readlane_b32 s66, v29, 5
	v_pk_fma_f32 v[52:53], v[208:209], s[48:49], v[52:53] op_sel_hi:[1,0,1]
	v_pk_fma_f32 v[54:55], v[210:211], s[48:49], v[54:55] op_sel_hi:[1,0,1]
	v_pk_fma_f32 v[56:57], v[212:213], s[58:59], v[56:57] op_sel_hi:[1,0,1]
	v_pk_fma_f32 v[58:59], v[214:215], s[58:59], v[58:59] op_sel_hi:[1,0,1]
	v_pk_fma_f32 v[60:61], v[208:209], s[50:51], v[60:61] op_sel_hi:[1,0,1]
	v_pk_fma_f32 v[62:63], v[210:211], s[50:51], v[62:63] op_sel_hi:[1,0,1]
	v_pk_fma_f32 v[64:65], v[212:213], s[60:61], v[64:65] op_sel_hi:[1,0,1]
	v_pk_fma_f32 v[66:67], v[214:215], s[60:61], v[66:67] op_sel_hi:[1,0,1]
	v_pk_fma_f32 v[68:69], v[208:209], s[52:53], v[68:69] op_sel_hi:[1,0,1]
	v_pk_fma_f32 v[70:71], v[210:211], s[52:53], v[70:71] op_sel_hi:[1,0,1]
	v_pk_fma_f32 v[72:73], v[212:213], s[62:63], v[72:73] op_sel_hi:[1,0,1]
	v_pk_fma_f32 v[74:75], v[214:215], s[62:63], v[74:75] op_sel_hi:[1,0,1]
	v_pk_fma_f32 v[76:77], v[208:209], s[54:55], v[76:77] op_sel_hi:[1,0,1]
	v_pk_fma_f32 v[78:79], v[210:211], s[54:55], v[78:79] op_sel_hi:[1,0,1]
	v_pk_fma_f32 v[80:81], v[212:213], s[64:65], v[80:81] op_sel_hi:[1,0,1]
	v_pk_fma_f32 v[82:83], v[214:215], s[64:65], v[82:83] op_sel_hi:[1,0,1]
	v_pk_fma_f32 v[84:85], v[208:209], s[56:57], v[84:85] op_sel_hi:[1,0,1]
	v_pk_fma_f32 v[86:87], v[210:211], s[56:57], v[86:87] op_sel_hi:[1,0,1]
	v_pk_fma_f32 v[88:89], v[212:213], s[66:67], v[88:89] op_sel_hi:[1,0,1]
	v_pk_fma_f32 v[90:91], v[214:215], s[66:67], v[90:91] op_sel_hi:[1,0,1]
	global_load_dwordx4 v[208:211], v232, s[2:3] offset:1024
	global_load_dwordx4 v[212:215], v232, s[40:41] offset:1024
	s_waitcnt vmcnt(14)
	v_readlane_b32 s48, v20, 6
	v_readlane_b32 s58, v25, 6
	v_readlane_b32 s50, v21, 6
	v_readlane_b32 s60, v26, 6
	v_readlane_b32 s52, v22, 6
	v_readlane_b32 s62, v27, 6
	v_readlane_b32 s54, v23, 6
	v_readlane_b32 s64, v28, 6
	v_readlane_b32 s56, v24, 6
	v_readlane_b32 s66, v29, 6
	v_pk_fma_f32 v[52:53], v[216:217], s[48:49], v[52:53] op_sel_hi:[1,0,1]
	v_pk_fma_f32 v[54:55], v[218:219], s[48:49], v[54:55] op_sel_hi:[1,0,1]
	v_pk_fma_f32 v[56:57], v[220:221], s[58:59], v[56:57] op_sel_hi:[1,0,1]
	v_pk_fma_f32 v[58:59], v[222:223], s[58:59], v[58:59] op_sel_hi:[1,0,1]
	v_pk_fma_f32 v[60:61], v[216:217], s[50:51], v[60:61] op_sel_hi:[1,0,1]
	v_pk_fma_f32 v[62:63], v[218:219], s[50:51], v[62:63] op_sel_hi:[1,0,1]
	v_pk_fma_f32 v[64:65], v[220:221], s[60:61], v[64:65] op_sel_hi:[1,0,1]
	v_pk_fma_f32 v[66:67], v[222:223], s[60:61], v[66:67] op_sel_hi:[1,0,1]
	v_pk_fma_f32 v[68:69], v[216:217], s[52:53], v[68:69] op_sel_hi:[1,0,1]
	v_pk_fma_f32 v[70:71], v[218:219], s[52:53], v[70:71] op_sel_hi:[1,0,1]
	v_pk_fma_f32 v[72:73], v[220:221], s[62:63], v[72:73] op_sel_hi:[1,0,1]
	v_pk_fma_f32 v[74:75], v[222:223], s[62:63], v[74:75] op_sel_hi:[1,0,1]
	v_pk_fma_f32 v[76:77], v[216:217], s[54:55], v[76:77] op_sel_hi:[1,0,1]
	v_pk_fma_f32 v[78:79], v[218:219], s[54:55], v[78:79] op_sel_hi:[1,0,1]
	v_pk_fma_f32 v[80:81], v[220:221], s[64:65], v[80:81] op_sel_hi:[1,0,1]
	v_pk_fma_f32 v[82:83], v[222:223], s[64:65], v[82:83] op_sel_hi:[1,0,1]
	v_pk_fma_f32 v[84:85], v[216:217], s[56:57], v[84:85] op_sel_hi:[1,0,1]
	v_pk_fma_f32 v[86:87], v[218:219], s[56:57], v[86:87] op_sel_hi:[1,0,1]
	v_pk_fma_f32 v[88:89], v[220:221], s[66:67], v[88:89] op_sel_hi:[1,0,1]
	v_pk_fma_f32 v[90:91], v[222:223], s[66:67], v[90:91] op_sel_hi:[1,0,1]
	global_load_dwordx4 v[216:219], v232, s[2:3] offset:2048
	global_load_dwordx4 v[220:223], v232, s[40:41] offset:2048
	s_waitcnt vmcnt(14)
	v_readlane_b32 s48, v20, 7
	v_readlane_b32 s58, v25, 7
	v_readlane_b32 s50, v21, 7
	v_readlane_b32 s60, v26, 7
	v_readlane_b32 s52, v22, 7
	v_readlane_b32 s62, v27, 7
	v_readlane_b32 s54, v23, 7
	v_readlane_b32 s64, v28, 7
	v_readlane_b32 s56, v24, 7
	v_readlane_b32 s66, v29, 7
	v_pk_fma_f32 v[52:53], v[224:225], s[48:49], v[52:53] op_sel_hi:[1,0,1]
	v_pk_fma_f32 v[54:55], v[226:227], s[48:49], v[54:55] op_sel_hi:[1,0,1]
	v_pk_fma_f32 v[56:57], v[228:229], s[58:59], v[56:57] op_sel_hi:[1,0,1]
	v_pk_fma_f32 v[58:59], v[230:231], s[58:59], v[58:59] op_sel_hi:[1,0,1]
	v_pk_fma_f32 v[60:61], v[224:225], s[50:51], v[60:61] op_sel_hi:[1,0,1]
	v_pk_fma_f32 v[62:63], v[226:227], s[50:51], v[62:63] op_sel_hi:[1,0,1]
	v_pk_fma_f32 v[64:65], v[228:229], s[60:61], v[64:65] op_sel_hi:[1,0,1]
	v_pk_fma_f32 v[66:67], v[230:231], s[60:61], v[66:67] op_sel_hi:[1,0,1]
	v_pk_fma_f32 v[68:69], v[224:225], s[52:53], v[68:69] op_sel_hi:[1,0,1]
	v_pk_fma_f32 v[70:71], v[226:227], s[52:53], v[70:71] op_sel_hi:[1,0,1]
	v_pk_fma_f32 v[72:73], v[228:229], s[62:63], v[72:73] op_sel_hi:[1,0,1]
	v_pk_fma_f32 v[74:75], v[230:231], s[62:63], v[74:75] op_sel_hi:[1,0,1]
	v_pk_fma_f32 v[76:77], v[224:225], s[54:55], v[76:77] op_sel_hi:[1,0,1]
	v_pk_fma_f32 v[78:79], v[226:227], s[54:55], v[78:79] op_sel_hi:[1,0,1]
	v_pk_fma_f32 v[80:81], v[228:229], s[64:65], v[80:81] op_sel_hi:[1,0,1]
	v_pk_fma_f32 v[82:83], v[230:231], s[64:65], v[82:83] op_sel_hi:[1,0,1]
	v_pk_fma_f32 v[84:85], v[224:225], s[56:57], v[84:85] op_sel_hi:[1,0,1]
	v_pk_fma_f32 v[86:87], v[226:227], s[56:57], v[86:87] op_sel_hi:[1,0,1]
	v_pk_fma_f32 v[88:89], v[228:229], s[66:67], v[88:89] op_sel_hi:[1,0,1]
	v_pk_fma_f32 v[90:91], v[230:231], s[66:67], v[90:91] op_sel_hi:[1,0,1]
	global_load_dwordx4 v[224:227], v232, s[2:3] offset:3072
	global_load_dwordx4 v[228:231], v232, s[40:41] offset:3072
	s_add_u32 s2, s2, 0x1000
	s_addc_u32 s3, s3, 0
	s_add_u32 s40, s40, 0x1000
	s_addc_u32 s41, s41, 0
	s_waitcnt vmcnt(14)
	v_readlane_b32 s48, v20, 8
	v_readlane_b32 s58, v25, 8
	v_readlane_b32 s50, v21, 8
	v_readlane_b32 s60, v26, 8
	v_readlane_b32 s52, v22, 8
	v_readlane_b32 s62, v27, 8
	v_readlane_b32 s54, v23, 8
	v_readlane_b32 s64, v28, 8
	v_readlane_b32 s56, v24, 8
	v_readlane_b32 s66, v29, 8
	v_pk_fma_f32 v[52:53], v[168:169], s[48:49], v[52:53] op_sel_hi:[1,0,1]
	v_pk_fma_f32 v[54:55], v[170:171], s[48:49], v[54:55] op_sel_hi:[1,0,1]
	v_pk_fma_f32 v[56:57], v[172:173], s[58:59], v[56:57] op_sel_hi:[1,0,1]
	v_pk_fma_f32 v[58:59], v[174:175], s[58:59], v[58:59] op_sel_hi:[1,0,1]
	v_pk_fma_f32 v[60:61], v[168:169], s[50:51], v[60:61] op_sel_hi:[1,0,1]
	v_pk_fma_f32 v[62:63], v[170:171], s[50:51], v[62:63] op_sel_hi:[1,0,1]
	v_pk_fma_f32 v[64:65], v[172:173], s[60:61], v[64:65] op_sel_hi:[1,0,1]
	v_pk_fma_f32 v[66:67], v[174:175], s[60:61], v[66:67] op_sel_hi:[1,0,1]
	v_pk_fma_f32 v[68:69], v[168:169], s[52:53], v[68:69] op_sel_hi:[1,0,1]
	v_pk_fma_f32 v[70:71], v[170:171], s[52:53], v[70:71] op_sel_hi:[1,0,1]
	v_pk_fma_f32 v[72:73], v[172:173], s[62:63], v[72:73] op_sel_hi:[1,0,1]
	v_pk_fma_f32 v[74:75], v[174:175], s[62:63], v[74:75] op_sel_hi:[1,0,1]
	v_pk_fma_f32 v[76:77], v[168:169], s[54:55], v[76:77] op_sel_hi:[1,0,1]
	v_pk_fma_f32 v[78:79], v[170:171], s[54:55], v[78:79] op_sel_hi:[1,0,1]
	v_pk_fma_f32 v[80:81], v[172:173], s[64:65], v[80:81] op_sel_hi:[1,0,1]
	v_pk_fma_f32 v[82:83], v[174:175], s[64:65], v[82:83] op_sel_hi:[1,0,1]
	v_pk_fma_f32 v[84:85], v[168:169], s[56:57], v[84:85] op_sel_hi:[1,0,1]
	v_pk_fma_f32 v[86:87], v[170:171], s[56:57], v[86:87] op_sel_hi:[1,0,1]
	v_pk_fma_f32 v[88:89], v[172:173], s[66:67], v[88:89] op_sel_hi:[1,0,1]
	v_pk_fma_f32 v[90:91], v[174:175], s[66:67], v[90:91] op_sel_hi:[1,0,1]
	global_load_dwordx4 v[168:171], v232, s[2:3]
	global_load_dwordx4 v[172:175], v232, s[40:41]
	s_waitcnt vmcnt(14)
	v_readlane_b32 s48, v20, 9
	v_readlane_b32 s58, v25, 9
	v_readlane_b32 s50, v21, 9
	v_readlane_b32 s60, v26, 9
	v_readlane_b32 s52, v22, 9
	v_readlane_b32 s62, v27, 9
	v_readlane_b32 s54, v23, 9
	v_readlane_b32 s64, v28, 9
	v_readlane_b32 s56, v24, 9
	v_readlane_b32 s66, v29, 9
	v_pk_fma_f32 v[52:53], v[176:177], s[48:49], v[52:53] op_sel_hi:[1,0,1]
	v_pk_fma_f32 v[54:55], v[178:179], s[48:49], v[54:55] op_sel_hi:[1,0,1]
	v_pk_fma_f32 v[56:57], v[180:181], s[58:59], v[56:57] op_sel_hi:[1,0,1]
	v_pk_fma_f32 v[58:59], v[182:183], s[58:59], v[58:59] op_sel_hi:[1,0,1]
	v_pk_fma_f32 v[60:61], v[176:177], s[50:51], v[60:61] op_sel_hi:[1,0,1]
	v_pk_fma_f32 v[62:63], v[178:179], s[50:51], v[62:63] op_sel_hi:[1,0,1]
	v_pk_fma_f32 v[64:65], v[180:181], s[60:61], v[64:65] op_sel_hi:[1,0,1]
	v_pk_fma_f32 v[66:67], v[182:183], s[60:61], v[66:67] op_sel_hi:[1,0,1]
	v_pk_fma_f32 v[68:69], v[176:177], s[52:53], v[68:69] op_sel_hi:[1,0,1]
	v_pk_fma_f32 v[70:71], v[178:179], s[52:53], v[70:71] op_sel_hi:[1,0,1]
	v_pk_fma_f32 v[72:73], v[180:181], s[62:63], v[72:73] op_sel_hi:[1,0,1]
	v_pk_fma_f32 v[74:75], v[182:183], s[62:63], v[74:75] op_sel_hi:[1,0,1]
	v_pk_fma_f32 v[76:77], v[176:177], s[54:55], v[76:77] op_sel_hi:[1,0,1]
	v_pk_fma_f32 v[78:79], v[178:179], s[54:55], v[78:79] op_sel_hi:[1,0,1]
	v_pk_fma_f32 v[80:81], v[180:181], s[64:65], v[80:81] op_sel_hi:[1,0,1]
	v_pk_fma_f32 v[82:83], v[182:183], s[64:65], v[82:83] op_sel_hi:[1,0,1]
	v_pk_fma_f32 v[84:85], v[176:177], s[56:57], v[84:85] op_sel_hi:[1,0,1]
	v_pk_fma_f32 v[86:87], v[178:179], s[56:57], v[86:87] op_sel_hi:[1,0,1]
	v_pk_fma_f32 v[88:89], v[180:181], s[66:67], v[88:89] op_sel_hi:[1,0,1]
	v_pk_fma_f32 v[90:91], v[182:183], s[66:67], v[90:91] op_sel_hi:[1,0,1]
	global_load_dwordx4 v[176:179], v232, s[2:3] offset:1024
	global_load_dwordx4 v[180:183], v232, s[40:41] offset:1024
	s_waitcnt vmcnt(14)
	v_readlane_b32 s48, v20, 10
	v_readlane_b32 s58, v25, 10
	v_readlane_b32 s50, v21, 10
	v_readlane_b32 s60, v26, 10
	v_readlane_b32 s52, v22, 10
	v_readlane_b32 s62, v27, 10
	v_readlane_b32 s54, v23, 10
	v_readlane_b32 s64, v28, 10
	v_readlane_b32 s56, v24, 10
	v_readlane_b32 s66, v29, 10
	v_pk_fma_f32 v[52:53], v[184:185], s[48:49], v[52:53] op_sel_hi:[1,0,1]
	v_pk_fma_f32 v[54:55], v[186:187], s[48:49], v[54:55] op_sel_hi:[1,0,1]
	v_pk_fma_f32 v[56:57], v[188:189], s[58:59], v[56:57] op_sel_hi:[1,0,1]
	v_pk_fma_f32 v[58:59], v[190:191], s[58:59], v[58:59] op_sel_hi:[1,0,1]
	v_pk_fma_f32 v[60:61], v[184:185], s[50:51], v[60:61] op_sel_hi:[1,0,1]
	v_pk_fma_f32 v[62:63], v[186:187], s[50:51], v[62:63] op_sel_hi:[1,0,1]
	v_pk_fma_f32 v[64:65], v[188:189], s[60:61], v[64:65] op_sel_hi:[1,0,1]
	v_pk_fma_f32 v[66:67], v[190:191], s[60:61], v[66:67] op_sel_hi:[1,0,1]
	v_pk_fma_f32 v[68:69], v[184:185], s[52:53], v[68:69] op_sel_hi:[1,0,1]
	v_pk_fma_f32 v[70:71], v[186:187], s[52:53], v[70:71] op_sel_hi:[1,0,1]
	v_pk_fma_f32 v[72:73], v[188:189], s[62:63], v[72:73] op_sel_hi:[1,0,1]
	v_pk_fma_f32 v[74:75], v[190:191], s[62:63], v[74:75] op_sel_hi:[1,0,1]
	v_pk_fma_f32 v[76:77], v[184:185], s[54:55], v[76:77] op_sel_hi:[1,0,1]
	v_pk_fma_f32 v[78:79], v[186:187], s[54:55], v[78:79] op_sel_hi:[1,0,1]
	v_pk_fma_f32 v[80:81], v[188:189], s[64:65], v[80:81] op_sel_hi:[1,0,1]
	v_pk_fma_f32 v[82:83], v[190:191], s[64:65], v[82:83] op_sel_hi:[1,0,1]
	v_pk_fma_f32 v[84:85], v[184:185], s[56:57], v[84:85] op_sel_hi:[1,0,1]
	v_pk_fma_f32 v[86:87], v[186:187], s[56:57], v[86:87] op_sel_hi:[1,0,1]
	v_pk_fma_f32 v[88:89], v[188:189], s[66:67], v[88:89] op_sel_hi:[1,0,1]
	v_pk_fma_f32 v[90:91], v[190:191], s[66:67], v[90:91] op_sel_hi:[1,0,1]
	global_load_dwordx4 v[184:187], v232, s[2:3] offset:2048
	global_load_dwordx4 v[188:191], v232, s[40:41] offset:2048
	s_waitcnt vmcnt(14)
	v_readlane_b32 s48, v20, 11
	v_readlane_b32 s58, v25, 11
	v_readlane_b32 s50, v21, 11
	v_readlane_b32 s60, v26, 11
	v_readlane_b32 s52, v22, 11
	v_readlane_b32 s62, v27, 11
	v_readlane_b32 s54, v23, 11
	v_readlane_b32 s64, v28, 11
	v_readlane_b32 s56, v24, 11
	v_readlane_b32 s66, v29, 11
	v_pk_fma_f32 v[52:53], v[192:193], s[48:49], v[52:53] op_sel_hi:[1,0,1]
	v_pk_fma_f32 v[54:55], v[194:195], s[48:49], v[54:55] op_sel_hi:[1,0,1]
	v_pk_fma_f32 v[56:57], v[196:197], s[58:59], v[56:57] op_sel_hi:[1,0,1]
	v_pk_fma_f32 v[58:59], v[198:199], s[58:59], v[58:59] op_sel_hi:[1,0,1]
	v_pk_fma_f32 v[60:61], v[192:193], s[50:51], v[60:61] op_sel_hi:[1,0,1]
	v_pk_fma_f32 v[62:63], v[194:195], s[50:51], v[62:63] op_sel_hi:[1,0,1]
	v_pk_fma_f32 v[64:65], v[196:197], s[60:61], v[64:65] op_sel_hi:[1,0,1]
	v_pk_fma_f32 v[66:67], v[198:199], s[60:61], v[66:67] op_sel_hi:[1,0,1]
	v_pk_fma_f32 v[68:69], v[192:193], s[52:53], v[68:69] op_sel_hi:[1,0,1]
	v_pk_fma_f32 v[70:71], v[194:195], s[52:53], v[70:71] op_sel_hi:[1,0,1]
	v_pk_fma_f32 v[72:73], v[196:197], s[62:63], v[72:73] op_sel_hi:[1,0,1]
	v_pk_fma_f32 v[74:75], v[198:199], s[62:63], v[74:75] op_sel_hi:[1,0,1]
	v_pk_fma_f32 v[76:77], v[192:193], s[54:55], v[76:77] op_sel_hi:[1,0,1]
	v_pk_fma_f32 v[78:79], v[194:195], s[54:55], v[78:79] op_sel_hi:[1,0,1]
	v_pk_fma_f32 v[80:81], v[196:197], s[64:65], v[80:81] op_sel_hi:[1,0,1]
	v_pk_fma_f32 v[82:83], v[198:199], s[64:65], v[82:83] op_sel_hi:[1,0,1]
	v_pk_fma_f32 v[84:85], v[192:193], s[56:57], v[84:85] op_sel_hi:[1,0,1]
	v_pk_fma_f32 v[86:87], v[194:195], s[56:57], v[86:87] op_sel_hi:[1,0,1]
	v_pk_fma_f32 v[88:89], v[196:197], s[66:67], v[88:89] op_sel_hi:[1,0,1]
	v_pk_fma_f32 v[90:91], v[198:199], s[66:67], v[90:91] op_sel_hi:[1,0,1]
	global_load_dwordx4 v[192:195], v232, s[2:3] offset:3072
	global_load_dwordx4 v[196:199], v232, s[40:41] offset:3072
	s_add_u32 s2, s2, 0x1000
	s_addc_u32 s3, s3, 0
	s_add_u32 s40, s40, 0x1000
	s_addc_u32 s41, s41, 0
	s_waitcnt vmcnt(14)
	v_readlane_b32 s48, v20, 12
	v_readlane_b32 s58, v25, 12
	v_readlane_b32 s50, v21, 12
	v_readlane_b32 s60, v26, 12
	v_readlane_b32 s52, v22, 12
	v_readlane_b32 s62, v27, 12
	v_readlane_b32 s54, v23, 12
	v_readlane_b32 s64, v28, 12
	v_readlane_b32 s56, v24, 12
	v_readlane_b32 s66, v29, 12
	v_pk_fma_f32 v[52:53], v[200:201], s[48:49], v[52:53] op_sel_hi:[1,0,1]
	v_pk_fma_f32 v[54:55], v[202:203], s[48:49], v[54:55] op_sel_hi:[1,0,1]
	v_pk_fma_f32 v[56:57], v[204:205], s[58:59], v[56:57] op_sel_hi:[1,0,1]
	v_pk_fma_f32 v[58:59], v[206:207], s[58:59], v[58:59] op_sel_hi:[1,0,1]
	v_pk_fma_f32 v[60:61], v[200:201], s[50:51], v[60:61] op_sel_hi:[1,0,1]
	v_pk_fma_f32 v[62:63], v[202:203], s[50:51], v[62:63] op_sel_hi:[1,0,1]
	v_pk_fma_f32 v[64:65], v[204:205], s[60:61], v[64:65] op_sel_hi:[1,0,1]
	v_pk_fma_f32 v[66:67], v[206:207], s[60:61], v[66:67] op_sel_hi:[1,0,1]
	v_pk_fma_f32 v[68:69], v[200:201], s[52:53], v[68:69] op_sel_hi:[1,0,1]
	v_pk_fma_f32 v[70:71], v[202:203], s[52:53], v[70:71] op_sel_hi:[1,0,1]
	v_pk_fma_f32 v[72:73], v[204:205], s[62:63], v[72:73] op_sel_hi:[1,0,1]
	v_pk_fma_f32 v[74:75], v[206:207], s[62:63], v[74:75] op_sel_hi:[1,0,1]
	v_pk_fma_f32 v[76:77], v[200:201], s[54:55], v[76:77] op_sel_hi:[1,0,1]
	v_pk_fma_f32 v[78:79], v[202:203], s[54:55], v[78:79] op_sel_hi:[1,0,1]
	v_pk_fma_f32 v[80:81], v[204:205], s[64:65], v[80:81] op_sel_hi:[1,0,1]
	v_pk_fma_f32 v[82:83], v[206:207], s[64:65], v[82:83] op_sel_hi:[1,0,1]
	v_pk_fma_f32 v[84:85], v[200:201], s[56:57], v[84:85] op_sel_hi:[1,0,1]
	v_pk_fma_f32 v[86:87], v[202:203], s[56:57], v[86:87] op_sel_hi:[1,0,1]
	v_pk_fma_f32 v[88:89], v[204:205], s[66:67], v[88:89] op_sel_hi:[1,0,1]
	v_pk_fma_f32 v[90:91], v[206:207], s[66:67], v[90:91] op_sel_hi:[1,0,1]
	global_load_dwordx4 v[200:203], v232, s[2:3]
	global_load_dwordx4 v[204:207], v232, s[40:41]
	s_waitcnt vmcnt(14)
	v_readlane_b32 s48, v20, 13
	v_readlane_b32 s58, v25, 13
	v_readlane_b32 s50, v21, 13
	v_readlane_b32 s60, v26, 13
	v_readlane_b32 s52, v22, 13
	v_readlane_b32 s62, v27, 13
	v_readlane_b32 s54, v23, 13
	v_readlane_b32 s64, v28, 13
	v_readlane_b32 s56, v24, 13
	v_readlane_b32 s66, v29, 13
	v_pk_fma_f32 v[52:53], v[208:209], s[48:49], v[52:53] op_sel_hi:[1,0,1]
	v_pk_fma_f32 v[54:55], v[210:211], s[48:49], v[54:55] op_sel_hi:[1,0,1]
	v_pk_fma_f32 v[56:57], v[212:213], s[58:59], v[56:57] op_sel_hi:[1,0,1]
	v_pk_fma_f32 v[58:59], v[214:215], s[58:59], v[58:59] op_sel_hi:[1,0,1]
	v_pk_fma_f32 v[60:61], v[208:209], s[50:51], v[60:61] op_sel_hi:[1,0,1]
	v_pk_fma_f32 v[62:63], v[210:211], s[50:51], v[62:63] op_sel_hi:[1,0,1]
	v_pk_fma_f32 v[64:65], v[212:213], s[60:61], v[64:65] op_sel_hi:[1,0,1]
	v_pk_fma_f32 v[66:67], v[214:215], s[60:61], v[66:67] op_sel_hi:[1,0,1]
	v_pk_fma_f32 v[68:69], v[208:209], s[52:53], v[68:69] op_sel_hi:[1,0,1]
	v_pk_fma_f32 v[70:71], v[210:211], s[52:53], v[70:71] op_sel_hi:[1,0,1]
	v_pk_fma_f32 v[72:73], v[212:213], s[62:63], v[72:73] op_sel_hi:[1,0,1]
	v_pk_fma_f32 v[74:75], v[214:215], s[62:63], v[74:75] op_sel_hi:[1,0,1]
	v_pk_fma_f32 v[76:77], v[208:209], s[54:55], v[76:77] op_sel_hi:[1,0,1]
	v_pk_fma_f32 v[78:79], v[210:211], s[54:55], v[78:79] op_sel_hi:[1,0,1]
	v_pk_fma_f32 v[80:81], v[212:213], s[64:65], v[80:81] op_sel_hi:[1,0,1]
	v_pk_fma_f32 v[82:83], v[214:215], s[64:65], v[82:83] op_sel_hi:[1,0,1]
	v_pk_fma_f32 v[84:85], v[208:209], s[56:57], v[84:85] op_sel_hi:[1,0,1]
	v_pk_fma_f32 v[86:87], v[210:211], s[56:57], v[86:87] op_sel_hi:[1,0,1]
	v_pk_fma_f32 v[88:89], v[212:213], s[66:67], v[88:89] op_sel_hi:[1,0,1]
	v_pk_fma_f32 v[90:91], v[214:215], s[66:67], v[90:91] op_sel_hi:[1,0,1]
	global_load_dwordx4 v[208:211], v232, s[2:3] offset:1024
	global_load_dwordx4 v[212:215], v232, s[40:41] offset:1024
	s_waitcnt vmcnt(14)
	v_readlane_b32 s48, v20, 14
	v_readlane_b32 s58, v25, 14
	v_readlane_b32 s50, v21, 14
	v_readlane_b32 s60, v26, 14
	v_readlane_b32 s52, v22, 14
	v_readlane_b32 s62, v27, 14
	v_readlane_b32 s54, v23, 14
	v_readlane_b32 s64, v28, 14
	v_readlane_b32 s56, v24, 14
	v_readlane_b32 s66, v29, 14
	v_pk_fma_f32 v[52:53], v[216:217], s[48:49], v[52:53] op_sel_hi:[1,0,1]
	v_pk_fma_f32 v[54:55], v[218:219], s[48:49], v[54:55] op_sel_hi:[1,0,1]
	v_pk_fma_f32 v[56:57], v[220:221], s[58:59], v[56:57] op_sel_hi:[1,0,1]
	v_pk_fma_f32 v[58:59], v[222:223], s[58:59], v[58:59] op_sel_hi:[1,0,1]
	v_pk_fma_f32 v[60:61], v[216:217], s[50:51], v[60:61] op_sel_hi:[1,0,1]
	v_pk_fma_f32 v[62:63], v[218:219], s[50:51], v[62:63] op_sel_hi:[1,0,1]
	v_pk_fma_f32 v[64:65], v[220:221], s[60:61], v[64:65] op_sel_hi:[1,0,1]
	v_pk_fma_f32 v[66:67], v[222:223], s[60:61], v[66:67] op_sel_hi:[1,0,1]
	v_pk_fma_f32 v[68:69], v[216:217], s[52:53], v[68:69] op_sel_hi:[1,0,1]
	v_pk_fma_f32 v[70:71], v[218:219], s[52:53], v[70:71] op_sel_hi:[1,0,1]
	v_pk_fma_f32 v[72:73], v[220:221], s[62:63], v[72:73] op_sel_hi:[1,0,1]
	v_pk_fma_f32 v[74:75], v[222:223], s[62:63], v[74:75] op_sel_hi:[1,0,1]
	v_pk_fma_f32 v[76:77], v[216:217], s[54:55], v[76:77] op_sel_hi:[1,0,1]
	v_pk_fma_f32 v[78:79], v[218:219], s[54:55], v[78:79] op_sel_hi:[1,0,1]
	v_pk_fma_f32 v[80:81], v[220:221], s[64:65], v[80:81] op_sel_hi:[1,0,1]
	v_pk_fma_f32 v[82:83], v[222:223], s[64:65], v[82:83] op_sel_hi:[1,0,1]
	v_pk_fma_f32 v[84:85], v[216:217], s[56:57], v[84:85] op_sel_hi:[1,0,1]
	v_pk_fma_f32 v[86:87], v[218:219], s[56:57], v[86:87] op_sel_hi:[1,0,1]
	v_pk_fma_f32 v[88:89], v[220:221], s[66:67], v[88:89] op_sel_hi:[1,0,1]
	v_pk_fma_f32 v[90:91], v[222:223], s[66:67], v[90:91] op_sel_hi:[1,0,1]
	global_load_dwordx4 v[216:219], v232, s[2:3] offset:2048
	global_load_dwordx4 v[220:223], v232, s[40:41] offset:2048
	s_waitcnt vmcnt(14)
	v_readlane_b32 s48, v20, 15
	v_readlane_b32 s58, v25, 15
	v_readlane_b32 s50, v21, 15
	v_readlane_b32 s60, v26, 15
	v_readlane_b32 s52, v22, 15
	v_readlane_b32 s62, v27, 15
	v_readlane_b32 s54, v23, 15
	v_readlane_b32 s64, v28, 15
	v_readlane_b32 s56, v24, 15
	v_readlane_b32 s66, v29, 15
	v_pk_fma_f32 v[52:53], v[224:225], s[48:49], v[52:53] op_sel_hi:[1,0,1]
	v_pk_fma_f32 v[54:55], v[226:227], s[48:49], v[54:55] op_sel_hi:[1,0,1]
	v_pk_fma_f32 v[56:57], v[228:229], s[58:59], v[56:57] op_sel_hi:[1,0,1]
	v_pk_fma_f32 v[58:59], v[230:231], s[58:59], v[58:59] op_sel_hi:[1,0,1]
	v_pk_fma_f32 v[60:61], v[224:225], s[50:51], v[60:61] op_sel_hi:[1,0,1]
	v_pk_fma_f32 v[62:63], v[226:227], s[50:51], v[62:63] op_sel_hi:[1,0,1]
	v_pk_fma_f32 v[64:65], v[228:229], s[60:61], v[64:65] op_sel_hi:[1,0,1]
	v_pk_fma_f32 v[66:67], v[230:231], s[60:61], v[66:67] op_sel_hi:[1,0,1]
	v_pk_fma_f32 v[68:69], v[224:225], s[52:53], v[68:69] op_sel_hi:[1,0,1]
	v_pk_fma_f32 v[70:71], v[226:227], s[52:53], v[70:71] op_sel_hi:[1,0,1]
	v_pk_fma_f32 v[72:73], v[228:229], s[62:63], v[72:73] op_sel_hi:[1,0,1]
	v_pk_fma_f32 v[74:75], v[230:231], s[62:63], v[74:75] op_sel_hi:[1,0,1]
	v_pk_fma_f32 v[76:77], v[224:225], s[54:55], v[76:77] op_sel_hi:[1,0,1]
	v_pk_fma_f32 v[78:79], v[226:227], s[54:55], v[78:79] op_sel_hi:[1,0,1]
	v_pk_fma_f32 v[80:81], v[228:229], s[64:65], v[80:81] op_sel_hi:[1,0,1]
	v_pk_fma_f32 v[82:83], v[230:231], s[64:65], v[82:83] op_sel_hi:[1,0,1]
	v_pk_fma_f32 v[84:85], v[224:225], s[56:57], v[84:85] op_sel_hi:[1,0,1]
	v_pk_fma_f32 v[86:87], v[226:227], s[56:57], v[86:87] op_sel_hi:[1,0,1]
	v_pk_fma_f32 v[88:89], v[228:229], s[66:67], v[88:89] op_sel_hi:[1,0,1]
	v_pk_fma_f32 v[90:91], v[230:231], s[66:67], v[90:91] op_sel_hi:[1,0,1]
	global_load_dwordx4 v[224:227], v232, s[2:3] offset:3072
	global_load_dwordx4 v[228:231], v232, s[40:41] offset:3072
	s_add_u32 s2, s2, 0x1000
	s_addc_u32 s3, s3, 0
	s_add_u32 s40, s40, 0x1000
	s_addc_u32 s41, s41, 0
	s_waitcnt vmcnt(14)
	v_readlane_b32 s48, v20, 16
	v_readlane_b32 s58, v25, 16
	v_readlane_b32 s50, v21, 16
	v_readlane_b32 s60, v26, 16
	v_readlane_b32 s52, v22, 16
	v_readlane_b32 s62, v27, 16
	v_readlane_b32 s54, v23, 16
	v_readlane_b32 s64, v28, 16
	v_readlane_b32 s56, v24, 16
	v_readlane_b32 s66, v29, 16
	v_pk_fma_f32 v[52:53], v[168:169], s[48:49], v[52:53] op_sel_hi:[1,0,1]
	v_pk_fma_f32 v[54:55], v[170:171], s[48:49], v[54:55] op_sel_hi:[1,0,1]
	v_pk_fma_f32 v[56:57], v[172:173], s[58:59], v[56:57] op_sel_hi:[1,0,1]
	v_pk_fma_f32 v[58:59], v[174:175], s[58:59], v[58:59] op_sel_hi:[1,0,1]
	v_pk_fma_f32 v[60:61], v[168:169], s[50:51], v[60:61] op_sel_hi:[1,0,1]
	v_pk_fma_f32 v[62:63], v[170:171], s[50:51], v[62:63] op_sel_hi:[1,0,1]
	v_pk_fma_f32 v[64:65], v[172:173], s[60:61], v[64:65] op_sel_hi:[1,0,1]
	v_pk_fma_f32 v[66:67], v[174:175], s[60:61], v[66:67] op_sel_hi:[1,0,1]
	v_pk_fma_f32 v[68:69], v[168:169], s[52:53], v[68:69] op_sel_hi:[1,0,1]
	v_pk_fma_f32 v[70:71], v[170:171], s[52:53], v[70:71] op_sel_hi:[1,0,1]
	v_pk_fma_f32 v[72:73], v[172:173], s[62:63], v[72:73] op_sel_hi:[1,0,1]
	v_pk_fma_f32 v[74:75], v[174:175], s[62:63], v[74:75] op_sel_hi:[1,0,1]
	v_pk_fma_f32 v[76:77], v[168:169], s[54:55], v[76:77] op_sel_hi:[1,0,1]
	v_pk_fma_f32 v[78:79], v[170:171], s[54:55], v[78:79] op_sel_hi:[1,0,1]
	v_pk_fma_f32 v[80:81], v[172:173], s[64:65], v[80:81] op_sel_hi:[1,0,1]
	v_pk_fma_f32 v[82:83], v[174:175], s[64:65], v[82:83] op_sel_hi:[1,0,1]
	v_pk_fma_f32 v[84:85], v[168:169], s[56:57], v[84:85] op_sel_hi:[1,0,1]
	v_pk_fma_f32 v[86:87], v[170:171], s[56:57], v[86:87] op_sel_hi:[1,0,1]
	v_pk_fma_f32 v[88:89], v[172:173], s[66:67], v[88:89] op_sel_hi:[1,0,1]
	v_pk_fma_f32 v[90:91], v[174:175], s[66:67], v[90:91] op_sel_hi:[1,0,1]
	global_load_dwordx4 v[168:171], v232, s[2:3]
	global_load_dwordx4 v[172:175], v232, s[40:41]
	s_waitcnt vmcnt(14)
	v_readlane_b32 s48, v20, 17
	v_readlane_b32 s58, v25, 17
	v_readlane_b32 s50, v21, 17
	v_readlane_b32 s60, v26, 17
	v_readlane_b32 s52, v22, 17
	v_readlane_b32 s62, v27, 17
	v_readlane_b32 s54, v23, 17
	v_readlane_b32 s64, v28, 17
	v_readlane_b32 s56, v24, 17
	v_readlane_b32 s66, v29, 17
	v_pk_fma_f32 v[52:53], v[176:177], s[48:49], v[52:53] op_sel_hi:[1,0,1]
	v_pk_fma_f32 v[54:55], v[178:179], s[48:49], v[54:55] op_sel_hi:[1,0,1]
	v_pk_fma_f32 v[56:57], v[180:181], s[58:59], v[56:57] op_sel_hi:[1,0,1]
	v_pk_fma_f32 v[58:59], v[182:183], s[58:59], v[58:59] op_sel_hi:[1,0,1]
	v_pk_fma_f32 v[60:61], v[176:177], s[50:51], v[60:61] op_sel_hi:[1,0,1]
	v_pk_fma_f32 v[62:63], v[178:179], s[50:51], v[62:63] op_sel_hi:[1,0,1]
	v_pk_fma_f32 v[64:65], v[180:181], s[60:61], v[64:65] op_sel_hi:[1,0,1]
	v_pk_fma_f32 v[66:67], v[182:183], s[60:61], v[66:67] op_sel_hi:[1,0,1]
	v_pk_fma_f32 v[68:69], v[176:177], s[52:53], v[68:69] op_sel_hi:[1,0,1]
	v_pk_fma_f32 v[70:71], v[178:179], s[52:53], v[70:71] op_sel_hi:[1,0,1]
	v_pk_fma_f32 v[72:73], v[180:181], s[62:63], v[72:73] op_sel_hi:[1,0,1]
	v_pk_fma_f32 v[74:75], v[182:183], s[62:63], v[74:75] op_sel_hi:[1,0,1]
	v_pk_fma_f32 v[76:77], v[176:177], s[54:55], v[76:77] op_sel_hi:[1,0,1]
	v_pk_fma_f32 v[78:79], v[178:179], s[54:55], v[78:79] op_sel_hi:[1,0,1]
	v_pk_fma_f32 v[80:81], v[180:181], s[64:65], v[80:81] op_sel_hi:[1,0,1]
	v_pk_fma_f32 v[82:83], v[182:183], s[64:65], v[82:83] op_sel_hi:[1,0,1]
	v_pk_fma_f32 v[84:85], v[176:177], s[56:57], v[84:85] op_sel_hi:[1,0,1]
	v_pk_fma_f32 v[86:87], v[178:179], s[56:57], v[86:87] op_sel_hi:[1,0,1]
	v_pk_fma_f32 v[88:89], v[180:181], s[66:67], v[88:89] op_sel_hi:[1,0,1]
	v_pk_fma_f32 v[90:91], v[182:183], s[66:67], v[90:91] op_sel_hi:[1,0,1]
	global_load_dwordx4 v[176:179], v232, s[2:3] offset:1024
	global_load_dwordx4 v[180:183], v232, s[40:41] offset:1024
	s_waitcnt vmcnt(14)
	v_readlane_b32 s48, v20, 18
	v_readlane_b32 s58, v25, 18
	v_readlane_b32 s50, v21, 18
	v_readlane_b32 s60, v26, 18
	v_readlane_b32 s52, v22, 18
	v_readlane_b32 s62, v27, 18
	v_readlane_b32 s54, v23, 18
	v_readlane_b32 s64, v28, 18
	v_readlane_b32 s56, v24, 18
	v_readlane_b32 s66, v29, 18
	v_pk_fma_f32 v[52:53], v[184:185], s[48:49], v[52:53] op_sel_hi:[1,0,1]
	v_pk_fma_f32 v[54:55], v[186:187], s[48:49], v[54:55] op_sel_hi:[1,0,1]
	v_pk_fma_f32 v[56:57], v[188:189], s[58:59], v[56:57] op_sel_hi:[1,0,1]
	v_pk_fma_f32 v[58:59], v[190:191], s[58:59], v[58:59] op_sel_hi:[1,0,1]
	v_pk_fma_f32 v[60:61], v[184:185], s[50:51], v[60:61] op_sel_hi:[1,0,1]
	v_pk_fma_f32 v[62:63], v[186:187], s[50:51], v[62:63] op_sel_hi:[1,0,1]
	v_pk_fma_f32 v[64:65], v[188:189], s[60:61], v[64:65] op_sel_hi:[1,0,1]
	v_pk_fma_f32 v[66:67], v[190:191], s[60:61], v[66:67] op_sel_hi:[1,0,1]
	v_pk_fma_f32 v[68:69], v[184:185], s[52:53], v[68:69] op_sel_hi:[1,0,1]
	v_pk_fma_f32 v[70:71], v[186:187], s[52:53], v[70:71] op_sel_hi:[1,0,1]
	v_pk_fma_f32 v[72:73], v[188:189], s[62:63], v[72:73] op_sel_hi:[1,0,1]
	v_pk_fma_f32 v[74:75], v[190:191], s[62:63], v[74:75] op_sel_hi:[1,0,1]
	v_pk_fma_f32 v[76:77], v[184:185], s[54:55], v[76:77] op_sel_hi:[1,0,1]
	v_pk_fma_f32 v[78:79], v[186:187], s[54:55], v[78:79] op_sel_hi:[1,0,1]
	v_pk_fma_f32 v[80:81], v[188:189], s[64:65], v[80:81] op_sel_hi:[1,0,1]
	v_pk_fma_f32 v[82:83], v[190:191], s[64:65], v[82:83] op_sel_hi:[1,0,1]
	v_pk_fma_f32 v[84:85], v[184:185], s[56:57], v[84:85] op_sel_hi:[1,0,1]
	v_pk_fma_f32 v[86:87], v[186:187], s[56:57], v[86:87] op_sel_hi:[1,0,1]
	v_pk_fma_f32 v[88:89], v[188:189], s[66:67], v[88:89] op_sel_hi:[1,0,1]
	v_pk_fma_f32 v[90:91], v[190:191], s[66:67], v[90:91] op_sel_hi:[1,0,1]
	global_load_dwordx4 v[184:187], v232, s[2:3] offset:2048
	global_load_dwordx4 v[188:191], v232, s[40:41] offset:2048
	s_waitcnt vmcnt(14)
	v_readlane_b32 s48, v20, 19
	v_readlane_b32 s58, v25, 19
	v_readlane_b32 s50, v21, 19
	v_readlane_b32 s60, v26, 19
	v_readlane_b32 s52, v22, 19
	v_readlane_b32 s62, v27, 19
	v_readlane_b32 s54, v23, 19
	v_readlane_b32 s64, v28, 19
	v_readlane_b32 s56, v24, 19
	v_readlane_b32 s66, v29, 19
	v_pk_fma_f32 v[52:53], v[192:193], s[48:49], v[52:53] op_sel_hi:[1,0,1]
	v_pk_fma_f32 v[54:55], v[194:195], s[48:49], v[54:55] op_sel_hi:[1,0,1]
	v_pk_fma_f32 v[56:57], v[196:197], s[58:59], v[56:57] op_sel_hi:[1,0,1]
	v_pk_fma_f32 v[58:59], v[198:199], s[58:59], v[58:59] op_sel_hi:[1,0,1]
	v_pk_fma_f32 v[60:61], v[192:193], s[50:51], v[60:61] op_sel_hi:[1,0,1]
	v_pk_fma_f32 v[62:63], v[194:195], s[50:51], v[62:63] op_sel_hi:[1,0,1]
	v_pk_fma_f32 v[64:65], v[196:197], s[60:61], v[64:65] op_sel_hi:[1,0,1]
	v_pk_fma_f32 v[66:67], v[198:199], s[60:61], v[66:67] op_sel_hi:[1,0,1]
	v_pk_fma_f32 v[68:69], v[192:193], s[52:53], v[68:69] op_sel_hi:[1,0,1]
	v_pk_fma_f32 v[70:71], v[194:195], s[52:53], v[70:71] op_sel_hi:[1,0,1]
	v_pk_fma_f32 v[72:73], v[196:197], s[62:63], v[72:73] op_sel_hi:[1,0,1]
	v_pk_fma_f32 v[74:75], v[198:199], s[62:63], v[74:75] op_sel_hi:[1,0,1]
	v_pk_fma_f32 v[76:77], v[192:193], s[54:55], v[76:77] op_sel_hi:[1,0,1]
	v_pk_fma_f32 v[78:79], v[194:195], s[54:55], v[78:79] op_sel_hi:[1,0,1]
	v_pk_fma_f32 v[80:81], v[196:197], s[64:65], v[80:81] op_sel_hi:[1,0,1]
	v_pk_fma_f32 v[82:83], v[198:199], s[64:65], v[82:83] op_sel_hi:[1,0,1]
	v_pk_fma_f32 v[84:85], v[192:193], s[56:57], v[84:85] op_sel_hi:[1,0,1]
	v_pk_fma_f32 v[86:87], v[194:195], s[56:57], v[86:87] op_sel_hi:[1,0,1]
	v_pk_fma_f32 v[88:89], v[196:197], s[66:67], v[88:89] op_sel_hi:[1,0,1]
	v_pk_fma_f32 v[90:91], v[198:199], s[66:67], v[90:91] op_sel_hi:[1,0,1]
	global_load_dwordx4 v[192:195], v232, s[2:3] offset:3072
	global_load_dwordx4 v[196:199], v232, s[40:41] offset:3072
	s_add_u32 s2, s2, 0x1000
	s_addc_u32 s3, s3, 0
	s_add_u32 s40, s40, 0x1000
	s_addc_u32 s41, s41, 0
	s_waitcnt vmcnt(14)
	v_readlane_b32 s48, v20, 20
	v_readlane_b32 s58, v25, 20
	v_readlane_b32 s50, v21, 20
	v_readlane_b32 s60, v26, 20
	v_readlane_b32 s52, v22, 20
	v_readlane_b32 s62, v27, 20
	v_readlane_b32 s54, v23, 20
	v_readlane_b32 s64, v28, 20
	v_readlane_b32 s56, v24, 20
	v_readlane_b32 s66, v29, 20
	v_pk_fma_f32 v[52:53], v[200:201], s[48:49], v[52:53] op_sel_hi:[1,0,1]
	v_pk_fma_f32 v[54:55], v[202:203], s[48:49], v[54:55] op_sel_hi:[1,0,1]
	v_pk_fma_f32 v[56:57], v[204:205], s[58:59], v[56:57] op_sel_hi:[1,0,1]
	v_pk_fma_f32 v[58:59], v[206:207], s[58:59], v[58:59] op_sel_hi:[1,0,1]
	v_pk_fma_f32 v[60:61], v[200:201], s[50:51], v[60:61] op_sel_hi:[1,0,1]
	v_pk_fma_f32 v[62:63], v[202:203], s[50:51], v[62:63] op_sel_hi:[1,0,1]
	v_pk_fma_f32 v[64:65], v[204:205], s[60:61], v[64:65] op_sel_hi:[1,0,1]
	v_pk_fma_f32 v[66:67], v[206:207], s[60:61], v[66:67] op_sel_hi:[1,0,1]
	v_pk_fma_f32 v[68:69], v[200:201], s[52:53], v[68:69] op_sel_hi:[1,0,1]
	v_pk_fma_f32 v[70:71], v[202:203], s[52:53], v[70:71] op_sel_hi:[1,0,1]
	v_pk_fma_f32 v[72:73], v[204:205], s[62:63], v[72:73] op_sel_hi:[1,0,1]
	v_pk_fma_f32 v[74:75], v[206:207], s[62:63], v[74:75] op_sel_hi:[1,0,1]
	v_pk_fma_f32 v[76:77], v[200:201], s[54:55], v[76:77] op_sel_hi:[1,0,1]
	v_pk_fma_f32 v[78:79], v[202:203], s[54:55], v[78:79] op_sel_hi:[1,0,1]
	v_pk_fma_f32 v[80:81], v[204:205], s[64:65], v[80:81] op_sel_hi:[1,0,1]
	v_pk_fma_f32 v[82:83], v[206:207], s[64:65], v[82:83] op_sel_hi:[1,0,1]
	v_pk_fma_f32 v[84:85], v[200:201], s[56:57], v[84:85] op_sel_hi:[1,0,1]
	v_pk_fma_f32 v[86:87], v[202:203], s[56:57], v[86:87] op_sel_hi:[1,0,1]
	v_pk_fma_f32 v[88:89], v[204:205], s[66:67], v[88:89] op_sel_hi:[1,0,1]
	v_pk_fma_f32 v[90:91], v[206:207], s[66:67], v[90:91] op_sel_hi:[1,0,1]
	global_load_dwordx4 v[200:203], v232, s[2:3]
	global_load_dwordx4 v[204:207], v232, s[40:41]
	s_waitcnt vmcnt(14)
	v_readlane_b32 s48, v20, 21
	v_readlane_b32 s58, v25, 21
	v_readlane_b32 s50, v21, 21
	v_readlane_b32 s60, v26, 21
	v_readlane_b32 s52, v22, 21
	v_readlane_b32 s62, v27, 21
	v_readlane_b32 s54, v23, 21
	v_readlane_b32 s64, v28, 21
	v_readlane_b32 s56, v24, 21
	v_readlane_b32 s66, v29, 21
	v_pk_fma_f32 v[52:53], v[208:209], s[48:49], v[52:53] op_sel_hi:[1,0,1]
	v_pk_fma_f32 v[54:55], v[210:211], s[48:49], v[54:55] op_sel_hi:[1,0,1]
	v_pk_fma_f32 v[56:57], v[212:213], s[58:59], v[56:57] op_sel_hi:[1,0,1]
	v_pk_fma_f32 v[58:59], v[214:215], s[58:59], v[58:59] op_sel_hi:[1,0,1]
	v_pk_fma_f32 v[60:61], v[208:209], s[50:51], v[60:61] op_sel_hi:[1,0,1]
	v_pk_fma_f32 v[62:63], v[210:211], s[50:51], v[62:63] op_sel_hi:[1,0,1]
	v_pk_fma_f32 v[64:65], v[212:213], s[60:61], v[64:65] op_sel_hi:[1,0,1]
	v_pk_fma_f32 v[66:67], v[214:215], s[60:61], v[66:67] op_sel_hi:[1,0,1]
	v_pk_fma_f32 v[68:69], v[208:209], s[52:53], v[68:69] op_sel_hi:[1,0,1]
	v_pk_fma_f32 v[70:71], v[210:211], s[52:53], v[70:71] op_sel_hi:[1,0,1]
	v_pk_fma_f32 v[72:73], v[212:213], s[62:63], v[72:73] op_sel_hi:[1,0,1]
	v_pk_fma_f32 v[74:75], v[214:215], s[62:63], v[74:75] op_sel_hi:[1,0,1]
	v_pk_fma_f32 v[76:77], v[208:209], s[54:55], v[76:77] op_sel_hi:[1,0,1]
	v_pk_fma_f32 v[78:79], v[210:211], s[54:55], v[78:79] op_sel_hi:[1,0,1]
	v_pk_fma_f32 v[80:81], v[212:213], s[64:65], v[80:81] op_sel_hi:[1,0,1]
	v_pk_fma_f32 v[82:83], v[214:215], s[64:65], v[82:83] op_sel_hi:[1,0,1]
	v_pk_fma_f32 v[84:85], v[208:209], s[56:57], v[84:85] op_sel_hi:[1,0,1]
	v_pk_fma_f32 v[86:87], v[210:211], s[56:57], v[86:87] op_sel_hi:[1,0,1]
	v_pk_fma_f32 v[88:89], v[212:213], s[66:67], v[88:89] op_sel_hi:[1,0,1]
	v_pk_fma_f32 v[90:91], v[214:215], s[66:67], v[90:91] op_sel_hi:[1,0,1]
	global_load_dwordx4 v[208:211], v232, s[2:3] offset:1024
	global_load_dwordx4 v[212:215], v232, s[40:41] offset:1024
	s_waitcnt vmcnt(14)
	v_readlane_b32 s48, v20, 22
	v_readlane_b32 s58, v25, 22
	v_readlane_b32 s50, v21, 22
	v_readlane_b32 s60, v26, 22
	v_readlane_b32 s52, v22, 22
	v_readlane_b32 s62, v27, 22
	v_readlane_b32 s54, v23, 22
	v_readlane_b32 s64, v28, 22
	v_readlane_b32 s56, v24, 22
	v_readlane_b32 s66, v29, 22
	v_pk_fma_f32 v[52:53], v[216:217], s[48:49], v[52:53] op_sel_hi:[1,0,1]
	v_pk_fma_f32 v[54:55], v[218:219], s[48:49], v[54:55] op_sel_hi:[1,0,1]
	v_pk_fma_f32 v[56:57], v[220:221], s[58:59], v[56:57] op_sel_hi:[1,0,1]
	v_pk_fma_f32 v[58:59], v[222:223], s[58:59], v[58:59] op_sel_hi:[1,0,1]
	v_pk_fma_f32 v[60:61], v[216:217], s[50:51], v[60:61] op_sel_hi:[1,0,1]
	v_pk_fma_f32 v[62:63], v[218:219], s[50:51], v[62:63] op_sel_hi:[1,0,1]
	v_pk_fma_f32 v[64:65], v[220:221], s[60:61], v[64:65] op_sel_hi:[1,0,1]
	v_pk_fma_f32 v[66:67], v[222:223], s[60:61], v[66:67] op_sel_hi:[1,0,1]
	v_pk_fma_f32 v[68:69], v[216:217], s[52:53], v[68:69] op_sel_hi:[1,0,1]
	v_pk_fma_f32 v[70:71], v[218:219], s[52:53], v[70:71] op_sel_hi:[1,0,1]
	v_pk_fma_f32 v[72:73], v[220:221], s[62:63], v[72:73] op_sel_hi:[1,0,1]
	v_pk_fma_f32 v[74:75], v[222:223], s[62:63], v[74:75] op_sel_hi:[1,0,1]
	v_pk_fma_f32 v[76:77], v[216:217], s[54:55], v[76:77] op_sel_hi:[1,0,1]
	v_pk_fma_f32 v[78:79], v[218:219], s[54:55], v[78:79] op_sel_hi:[1,0,1]
	v_pk_fma_f32 v[80:81], v[220:221], s[64:65], v[80:81] op_sel_hi:[1,0,1]
	v_pk_fma_f32 v[82:83], v[222:223], s[64:65], v[82:83] op_sel_hi:[1,0,1]
	v_pk_fma_f32 v[84:85], v[216:217], s[56:57], v[84:85] op_sel_hi:[1,0,1]
	v_pk_fma_f32 v[86:87], v[218:219], s[56:57], v[86:87] op_sel_hi:[1,0,1]
	v_pk_fma_f32 v[88:89], v[220:221], s[66:67], v[88:89] op_sel_hi:[1,0,1]
	v_pk_fma_f32 v[90:91], v[222:223], s[66:67], v[90:91] op_sel_hi:[1,0,1]
	global_load_dwordx4 v[216:219], v232, s[2:3] offset:2048
	global_load_dwordx4 v[220:223], v232, s[40:41] offset:2048
	s_waitcnt vmcnt(14)
	v_readlane_b32 s48, v20, 23
	v_readlane_b32 s58, v25, 23
	v_readlane_b32 s50, v21, 23
	v_readlane_b32 s60, v26, 23
	v_readlane_b32 s52, v22, 23
	v_readlane_b32 s62, v27, 23
	v_readlane_b32 s54, v23, 23
	v_readlane_b32 s64, v28, 23
	v_readlane_b32 s56, v24, 23
	v_readlane_b32 s66, v29, 23
	v_pk_fma_f32 v[52:53], v[224:225], s[48:49], v[52:53] op_sel_hi:[1,0,1]
	v_pk_fma_f32 v[54:55], v[226:227], s[48:49], v[54:55] op_sel_hi:[1,0,1]
	v_pk_fma_f32 v[56:57], v[228:229], s[58:59], v[56:57] op_sel_hi:[1,0,1]
	v_pk_fma_f32 v[58:59], v[230:231], s[58:59], v[58:59] op_sel_hi:[1,0,1]
	v_pk_fma_f32 v[60:61], v[224:225], s[50:51], v[60:61] op_sel_hi:[1,0,1]
	v_pk_fma_f32 v[62:63], v[226:227], s[50:51], v[62:63] op_sel_hi:[1,0,1]
	v_pk_fma_f32 v[64:65], v[228:229], s[60:61], v[64:65] op_sel_hi:[1,0,1]
	v_pk_fma_f32 v[66:67], v[230:231], s[60:61], v[66:67] op_sel_hi:[1,0,1]
	v_pk_fma_f32 v[68:69], v[224:225], s[52:53], v[68:69] op_sel_hi:[1,0,1]
	v_pk_fma_f32 v[70:71], v[226:227], s[52:53], v[70:71] op_sel_hi:[1,0,1]
	v_pk_fma_f32 v[72:73], v[228:229], s[62:63], v[72:73] op_sel_hi:[1,0,1]
	v_pk_fma_f32 v[74:75], v[230:231], s[62:63], v[74:75] op_sel_hi:[1,0,1]
	v_pk_fma_f32 v[76:77], v[224:225], s[54:55], v[76:77] op_sel_hi:[1,0,1]
	v_pk_fma_f32 v[78:79], v[226:227], s[54:55], v[78:79] op_sel_hi:[1,0,1]
	v_pk_fma_f32 v[80:81], v[228:229], s[64:65], v[80:81] op_sel_hi:[1,0,1]
	v_pk_fma_f32 v[82:83], v[230:231], s[64:65], v[82:83] op_sel_hi:[1,0,1]
	v_pk_fma_f32 v[84:85], v[224:225], s[56:57], v[84:85] op_sel_hi:[1,0,1]
	v_pk_fma_f32 v[86:87], v[226:227], s[56:57], v[86:87] op_sel_hi:[1,0,1]
	v_pk_fma_f32 v[88:89], v[228:229], s[66:67], v[88:89] op_sel_hi:[1,0,1]
	v_pk_fma_f32 v[90:91], v[230:231], s[66:67], v[90:91] op_sel_hi:[1,0,1]
	global_load_dwordx4 v[224:227], v232, s[2:3] offset:3072
	global_load_dwordx4 v[228:231], v232, s[40:41] offset:3072
	s_add_u32 s2, s2, 0x1000
	s_addc_u32 s3, s3, 0
	s_add_u32 s40, s40, 0x1000
	s_addc_u32 s41, s41, 0
	s_waitcnt vmcnt(14)
	v_readlane_b32 s48, v20, 24
	v_readlane_b32 s58, v25, 24
	v_readlane_b32 s50, v21, 24
	v_readlane_b32 s60, v26, 24
	v_readlane_b32 s52, v22, 24
	v_readlane_b32 s62, v27, 24
	v_readlane_b32 s54, v23, 24
	v_readlane_b32 s64, v28, 24
	v_readlane_b32 s56, v24, 24
	v_readlane_b32 s66, v29, 24
	v_pk_fma_f32 v[52:53], v[168:169], s[48:49], v[52:53] op_sel_hi:[1,0,1]
	v_pk_fma_f32 v[54:55], v[170:171], s[48:49], v[54:55] op_sel_hi:[1,0,1]
	v_pk_fma_f32 v[56:57], v[172:173], s[58:59], v[56:57] op_sel_hi:[1,0,1]
	v_pk_fma_f32 v[58:59], v[174:175], s[58:59], v[58:59] op_sel_hi:[1,0,1]
	v_pk_fma_f32 v[60:61], v[168:169], s[50:51], v[60:61] op_sel_hi:[1,0,1]
	v_pk_fma_f32 v[62:63], v[170:171], s[50:51], v[62:63] op_sel_hi:[1,0,1]
	v_pk_fma_f32 v[64:65], v[172:173], s[60:61], v[64:65] op_sel_hi:[1,0,1]
	v_pk_fma_f32 v[66:67], v[174:175], s[60:61], v[66:67] op_sel_hi:[1,0,1]
	v_pk_fma_f32 v[68:69], v[168:169], s[52:53], v[68:69] op_sel_hi:[1,0,1]
	v_pk_fma_f32 v[70:71], v[170:171], s[52:53], v[70:71] op_sel_hi:[1,0,1]
	v_pk_fma_f32 v[72:73], v[172:173], s[62:63], v[72:73] op_sel_hi:[1,0,1]
	v_pk_fma_f32 v[74:75], v[174:175], s[62:63], v[74:75] op_sel_hi:[1,0,1]
	v_pk_fma_f32 v[76:77], v[168:169], s[54:55], v[76:77] op_sel_hi:[1,0,1]
	v_pk_fma_f32 v[78:79], v[170:171], s[54:55], v[78:79] op_sel_hi:[1,0,1]
	v_pk_fma_f32 v[80:81], v[172:173], s[64:65], v[80:81] op_sel_hi:[1,0,1]
	v_pk_fma_f32 v[82:83], v[174:175], s[64:65], v[82:83] op_sel_hi:[1,0,1]
	v_pk_fma_f32 v[84:85], v[168:169], s[56:57], v[84:85] op_sel_hi:[1,0,1]
	v_pk_fma_f32 v[86:87], v[170:171], s[56:57], v[86:87] op_sel_hi:[1,0,1]
	v_pk_fma_f32 v[88:89], v[172:173], s[66:67], v[88:89] op_sel_hi:[1,0,1]
	v_pk_fma_f32 v[90:91], v[174:175], s[66:67], v[90:91] op_sel_hi:[1,0,1]
	s_waitcnt vmcnt(12)
	v_readlane_b32 s48, v20, 25
	v_readlane_b32 s58, v25, 25
	v_readlane_b32 s50, v21, 25
	v_readlane_b32 s60, v26, 25
	v_readlane_b32 s52, v22, 25
	v_readlane_b32 s62, v27, 25
	v_readlane_b32 s54, v23, 25
	v_readlane_b32 s64, v28, 25
	v_readlane_b32 s56, v24, 25
	v_readlane_b32 s66, v29, 25
	v_pk_fma_f32 v[52:53], v[176:177], s[48:49], v[52:53] op_sel_hi:[1,0,1]
	v_pk_fma_f32 v[54:55], v[178:179], s[48:49], v[54:55] op_sel_hi:[1,0,1]
	v_pk_fma_f32 v[56:57], v[180:181], s[58:59], v[56:57] op_sel_hi:[1,0,1]
	v_pk_fma_f32 v[58:59], v[182:183], s[58:59], v[58:59] op_sel_hi:[1,0,1]
	v_pk_fma_f32 v[60:61], v[176:177], s[50:51], v[60:61] op_sel_hi:[1,0,1]
	v_pk_fma_f32 v[62:63], v[178:179], s[50:51], v[62:63] op_sel_hi:[1,0,1]
	v_pk_fma_f32 v[64:65], v[180:181], s[60:61], v[64:65] op_sel_hi:[1,0,1]
	v_pk_fma_f32 v[66:67], v[182:183], s[60:61], v[66:67] op_sel_hi:[1,0,1]
	v_pk_fma_f32 v[68:69], v[176:177], s[52:53], v[68:69] op_sel_hi:[1,0,1]
	v_pk_fma_f32 v[70:71], v[178:179], s[52:53], v[70:71] op_sel_hi:[1,0,1]
	v_pk_fma_f32 v[72:73], v[180:181], s[62:63], v[72:73] op_sel_hi:[1,0,1]
	v_pk_fma_f32 v[74:75], v[182:183], s[62:63], v[74:75] op_sel_hi:[1,0,1]
	v_pk_fma_f32 v[76:77], v[176:177], s[54:55], v[76:77] op_sel_hi:[1,0,1]
	v_pk_fma_f32 v[78:79], v[178:179], s[54:55], v[78:79] op_sel_hi:[1,0,1]
	v_pk_fma_f32 v[80:81], v[180:181], s[64:65], v[80:81] op_sel_hi:[1,0,1]
	v_pk_fma_f32 v[82:83], v[182:183], s[64:65], v[82:83] op_sel_hi:[1,0,1]
	v_pk_fma_f32 v[84:85], v[176:177], s[56:57], v[84:85] op_sel_hi:[1,0,1]
	v_pk_fma_f32 v[86:87], v[178:179], s[56:57], v[86:87] op_sel_hi:[1,0,1]
	v_pk_fma_f32 v[88:89], v[180:181], s[66:67], v[88:89] op_sel_hi:[1,0,1]
	v_pk_fma_f32 v[90:91], v[182:183], s[66:67], v[90:91] op_sel_hi:[1,0,1]
	s_waitcnt vmcnt(10)
	v_readlane_b32 s48, v20, 26
	v_readlane_b32 s58, v25, 26
	v_readlane_b32 s50, v21, 26
	v_readlane_b32 s60, v26, 26
	v_readlane_b32 s52, v22, 26
	v_readlane_b32 s62, v27, 26
	v_readlane_b32 s54, v23, 26
	v_readlane_b32 s64, v28, 26
	v_readlane_b32 s56, v24, 26
	v_readlane_b32 s66, v29, 26
	v_pk_fma_f32 v[52:53], v[184:185], s[48:49], v[52:53] op_sel_hi:[1,0,1]
	v_pk_fma_f32 v[54:55], v[186:187], s[48:49], v[54:55] op_sel_hi:[1,0,1]
	v_pk_fma_f32 v[56:57], v[188:189], s[58:59], v[56:57] op_sel_hi:[1,0,1]
	v_pk_fma_f32 v[58:59], v[190:191], s[58:59], v[58:59] op_sel_hi:[1,0,1]
	v_pk_fma_f32 v[60:61], v[184:185], s[50:51], v[60:61] op_sel_hi:[1,0,1]
	v_pk_fma_f32 v[62:63], v[186:187], s[50:51], v[62:63] op_sel_hi:[1,0,1]
	v_pk_fma_f32 v[64:65], v[188:189], s[60:61], v[64:65] op_sel_hi:[1,0,1]
	v_pk_fma_f32 v[66:67], v[190:191], s[60:61], v[66:67] op_sel_hi:[1,0,1]
	v_pk_fma_f32 v[68:69], v[184:185], s[52:53], v[68:69] op_sel_hi:[1,0,1]
	v_pk_fma_f32 v[70:71], v[186:187], s[52:53], v[70:71] op_sel_hi:[1,0,1]
	v_pk_fma_f32 v[72:73], v[188:189], s[62:63], v[72:73] op_sel_hi:[1,0,1]
	v_pk_fma_f32 v[74:75], v[190:191], s[62:63], v[74:75] op_sel_hi:[1,0,1]
	v_pk_fma_f32 v[76:77], v[184:185], s[54:55], v[76:77] op_sel_hi:[1,0,1]
	v_pk_fma_f32 v[78:79], v[186:187], s[54:55], v[78:79] op_sel_hi:[1,0,1]
	v_pk_fma_f32 v[80:81], v[188:189], s[64:65], v[80:81] op_sel_hi:[1,0,1]
	v_pk_fma_f32 v[82:83], v[190:191], s[64:65], v[82:83] op_sel_hi:[1,0,1]
	v_pk_fma_f32 v[84:85], v[184:185], s[56:57], v[84:85] op_sel_hi:[1,0,1]
	v_pk_fma_f32 v[86:87], v[186:187], s[56:57], v[86:87] op_sel_hi:[1,0,1]
	v_pk_fma_f32 v[88:89], v[188:189], s[66:67], v[88:89] op_sel_hi:[1,0,1]
	v_pk_fma_f32 v[90:91], v[190:191], s[66:67], v[90:91] op_sel_hi:[1,0,1]
	s_waitcnt vmcnt(8)
	v_readlane_b32 s48, v20, 27
	v_readlane_b32 s58, v25, 27
	v_readlane_b32 s50, v21, 27
	v_readlane_b32 s60, v26, 27
	v_readlane_b32 s52, v22, 27
	v_readlane_b32 s62, v27, 27
	v_readlane_b32 s54, v23, 27
	v_readlane_b32 s64, v28, 27
	v_readlane_b32 s56, v24, 27
	v_readlane_b32 s66, v29, 27
	v_pk_fma_f32 v[52:53], v[192:193], s[48:49], v[52:53] op_sel_hi:[1,0,1]
	v_pk_fma_f32 v[54:55], v[194:195], s[48:49], v[54:55] op_sel_hi:[1,0,1]
	v_pk_fma_f32 v[56:57], v[196:197], s[58:59], v[56:57] op_sel_hi:[1,0,1]
	v_pk_fma_f32 v[58:59], v[198:199], s[58:59], v[58:59] op_sel_hi:[1,0,1]
	v_pk_fma_f32 v[60:61], v[192:193], s[50:51], v[60:61] op_sel_hi:[1,0,1]
	v_pk_fma_f32 v[62:63], v[194:195], s[50:51], v[62:63] op_sel_hi:[1,0,1]
	v_pk_fma_f32 v[64:65], v[196:197], s[60:61], v[64:65] op_sel_hi:[1,0,1]
	v_pk_fma_f32 v[66:67], v[198:199], s[60:61], v[66:67] op_sel_hi:[1,0,1]
	v_pk_fma_f32 v[68:69], v[192:193], s[52:53], v[68:69] op_sel_hi:[1,0,1]
	v_pk_fma_f32 v[70:71], v[194:195], s[52:53], v[70:71] op_sel_hi:[1,0,1]
	v_pk_fma_f32 v[72:73], v[196:197], s[62:63], v[72:73] op_sel_hi:[1,0,1]
	v_pk_fma_f32 v[74:75], v[198:199], s[62:63], v[74:75] op_sel_hi:[1,0,1]
	v_pk_fma_f32 v[76:77], v[192:193], s[54:55], v[76:77] op_sel_hi:[1,0,1]
	v_pk_fma_f32 v[78:79], v[194:195], s[54:55], v[78:79] op_sel_hi:[1,0,1]
	v_pk_fma_f32 v[80:81], v[196:197], s[64:65], v[80:81] op_sel_hi:[1,0,1]
	v_pk_fma_f32 v[82:83], v[198:199], s[64:65], v[82:83] op_sel_hi:[1,0,1]
	v_pk_fma_f32 v[84:85], v[192:193], s[56:57], v[84:85] op_sel_hi:[1,0,1]
	v_pk_fma_f32 v[86:87], v[194:195], s[56:57], v[86:87] op_sel_hi:[1,0,1]
	v_pk_fma_f32 v[88:89], v[196:197], s[66:67], v[88:89] op_sel_hi:[1,0,1]
	v_pk_fma_f32 v[90:91], v[198:199], s[66:67], v[90:91] op_sel_hi:[1,0,1]
	s_waitcnt vmcnt(6)
	v_readlane_b32 s48, v20, 28
	v_readlane_b32 s58, v25, 28
	v_readlane_b32 s50, v21, 28
	v_readlane_b32 s60, v26, 28
	v_readlane_b32 s52, v22, 28
	v_readlane_b32 s62, v27, 28
	v_readlane_b32 s54, v23, 28
	v_readlane_b32 s64, v28, 28
	v_readlane_b32 s56, v24, 28
	v_readlane_b32 s66, v29, 28
	v_pk_fma_f32 v[52:53], v[200:201], s[48:49], v[52:53] op_sel_hi:[1,0,1]
	v_pk_fma_f32 v[54:55], v[202:203], s[48:49], v[54:55] op_sel_hi:[1,0,1]
	v_pk_fma_f32 v[56:57], v[204:205], s[58:59], v[56:57] op_sel_hi:[1,0,1]
	v_pk_fma_f32 v[58:59], v[206:207], s[58:59], v[58:59] op_sel_hi:[1,0,1]
	v_pk_fma_f32 v[60:61], v[200:201], s[50:51], v[60:61] op_sel_hi:[1,0,1]
	v_pk_fma_f32 v[62:63], v[202:203], s[50:51], v[62:63] op_sel_hi:[1,0,1]
	v_pk_fma_f32 v[64:65], v[204:205], s[60:61], v[64:65] op_sel_hi:[1,0,1]
	v_pk_fma_f32 v[66:67], v[206:207], s[60:61], v[66:67] op_sel_hi:[1,0,1]
	v_pk_fma_f32 v[68:69], v[200:201], s[52:53], v[68:69] op_sel_hi:[1,0,1]
	v_pk_fma_f32 v[70:71], v[202:203], s[52:53], v[70:71] op_sel_hi:[1,0,1]
	v_pk_fma_f32 v[72:73], v[204:205], s[62:63], v[72:73] op_sel_hi:[1,0,1]
	v_pk_fma_f32 v[74:75], v[206:207], s[62:63], v[74:75] op_sel_hi:[1,0,1]
	v_pk_fma_f32 v[76:77], v[200:201], s[54:55], v[76:77] op_sel_hi:[1,0,1]
	v_pk_fma_f32 v[78:79], v[202:203], s[54:55], v[78:79] op_sel_hi:[1,0,1]
	v_pk_fma_f32 v[80:81], v[204:205], s[64:65], v[80:81] op_sel_hi:[1,0,1]
	v_pk_fma_f32 v[82:83], v[206:207], s[64:65], v[82:83] op_sel_hi:[1,0,1]
	v_pk_fma_f32 v[84:85], v[200:201], s[56:57], v[84:85] op_sel_hi:[1,0,1]
	v_pk_fma_f32 v[86:87], v[202:203], s[56:57], v[86:87] op_sel_hi:[1,0,1]
	v_pk_fma_f32 v[88:89], v[204:205], s[66:67], v[88:89] op_sel_hi:[1,0,1]
	v_pk_fma_f32 v[90:91], v[206:207], s[66:67], v[90:91] op_sel_hi:[1,0,1]
	s_waitcnt vmcnt(4)
	v_readlane_b32 s48, v20, 29
	v_readlane_b32 s58, v25, 29
	v_readlane_b32 s50, v21, 29
	v_readlane_b32 s60, v26, 29
	v_readlane_b32 s52, v22, 29
	v_readlane_b32 s62, v27, 29
	v_readlane_b32 s54, v23, 29
	v_readlane_b32 s64, v28, 29
	v_readlane_b32 s56, v24, 29
	v_readlane_b32 s66, v29, 29
	v_pk_fma_f32 v[52:53], v[208:209], s[48:49], v[52:53] op_sel_hi:[1,0,1]
	v_pk_fma_f32 v[54:55], v[210:211], s[48:49], v[54:55] op_sel_hi:[1,0,1]
	v_pk_fma_f32 v[56:57], v[212:213], s[58:59], v[56:57] op_sel_hi:[1,0,1]
	v_pk_fma_f32 v[58:59], v[214:215], s[58:59], v[58:59] op_sel_hi:[1,0,1]
	v_pk_fma_f32 v[60:61], v[208:209], s[50:51], v[60:61] op_sel_hi:[1,0,1]
	v_pk_fma_f32 v[62:63], v[210:211], s[50:51], v[62:63] op_sel_hi:[1,0,1]
	v_pk_fma_f32 v[64:65], v[212:213], s[60:61], v[64:65] op_sel_hi:[1,0,1]
	v_pk_fma_f32 v[66:67], v[214:215], s[60:61], v[66:67] op_sel_hi:[1,0,1]
	v_pk_fma_f32 v[68:69], v[208:209], s[52:53], v[68:69] op_sel_hi:[1,0,1]
	v_pk_fma_f32 v[70:71], v[210:211], s[52:53], v[70:71] op_sel_hi:[1,0,1]
	v_pk_fma_f32 v[72:73], v[212:213], s[62:63], v[72:73] op_sel_hi:[1,0,1]
	v_pk_fma_f32 v[74:75], v[214:215], s[62:63], v[74:75] op_sel_hi:[1,0,1]
	v_pk_fma_f32 v[76:77], v[208:209], s[54:55], v[76:77] op_sel_hi:[1,0,1]
	v_pk_fma_f32 v[78:79], v[210:211], s[54:55], v[78:79] op_sel_hi:[1,0,1]
	v_pk_fma_f32 v[80:81], v[212:213], s[64:65], v[80:81] op_sel_hi:[1,0,1]
	v_pk_fma_f32 v[82:83], v[214:215], s[64:65], v[82:83] op_sel_hi:[1,0,1]
	v_pk_fma_f32 v[84:85], v[208:209], s[56:57], v[84:85] op_sel_hi:[1,0,1]
	v_pk_fma_f32 v[86:87], v[210:211], s[56:57], v[86:87] op_sel_hi:[1,0,1]
	v_pk_fma_f32 v[88:89], v[212:213], s[66:67], v[88:89] op_sel_hi:[1,0,1]
	v_pk_fma_f32 v[90:91], v[214:215], s[66:67], v[90:91] op_sel_hi:[1,0,1]
	s_waitcnt vmcnt(2)
	v_readlane_b32 s48, v20, 30
	v_readlane_b32 s58, v25, 30
	v_readlane_b32 s50, v21, 30
	v_readlane_b32 s60, v26, 30
	v_readlane_b32 s52, v22, 30
	v_readlane_b32 s62, v27, 30
	v_readlane_b32 s54, v23, 30
	v_readlane_b32 s64, v28, 30
	v_readlane_b32 s56, v24, 30
	v_readlane_b32 s66, v29, 30
	v_pk_fma_f32 v[52:53], v[216:217], s[48:49], v[52:53] op_sel_hi:[1,0,1]
	v_pk_fma_f32 v[54:55], v[218:219], s[48:49], v[54:55] op_sel_hi:[1,0,1]
	v_pk_fma_f32 v[56:57], v[220:221], s[58:59], v[56:57] op_sel_hi:[1,0,1]
	v_pk_fma_f32 v[58:59], v[222:223], s[58:59], v[58:59] op_sel_hi:[1,0,1]
	v_pk_fma_f32 v[60:61], v[216:217], s[50:51], v[60:61] op_sel_hi:[1,0,1]
	v_pk_fma_f32 v[62:63], v[218:219], s[50:51], v[62:63] op_sel_hi:[1,0,1]
	v_pk_fma_f32 v[64:65], v[220:221], s[60:61], v[64:65] op_sel_hi:[1,0,1]
	v_pk_fma_f32 v[66:67], v[222:223], s[60:61], v[66:67] op_sel_hi:[1,0,1]
	v_pk_fma_f32 v[68:69], v[216:217], s[52:53], v[68:69] op_sel_hi:[1,0,1]
	v_pk_fma_f32 v[70:71], v[218:219], s[52:53], v[70:71] op_sel_hi:[1,0,1]
	v_pk_fma_f32 v[72:73], v[220:221], s[62:63], v[72:73] op_sel_hi:[1,0,1]
	v_pk_fma_f32 v[74:75], v[222:223], s[62:63], v[74:75] op_sel_hi:[1,0,1]
	v_pk_fma_f32 v[76:77], v[216:217], s[54:55], v[76:77] op_sel_hi:[1,0,1]
	v_pk_fma_f32 v[78:79], v[218:219], s[54:55], v[78:79] op_sel_hi:[1,0,1]
	v_pk_fma_f32 v[80:81], v[220:221], s[64:65], v[80:81] op_sel_hi:[1,0,1]
	v_pk_fma_f32 v[82:83], v[222:223], s[64:65], v[82:83] op_sel_hi:[1,0,1]
	v_pk_fma_f32 v[84:85], v[216:217], s[56:57], v[84:85] op_sel_hi:[1,0,1]
	v_pk_fma_f32 v[86:87], v[218:219], s[56:57], v[86:87] op_sel_hi:[1,0,1]
	v_pk_fma_f32 v[88:89], v[220:221], s[66:67], v[88:89] op_sel_hi:[1,0,1]
	v_pk_fma_f32 v[90:91], v[222:223], s[66:67], v[90:91] op_sel_hi:[1,0,1]
	s_waitcnt vmcnt(0)
	v_readlane_b32 s48, v20, 31
	v_readlane_b32 s58, v25, 31
	v_readlane_b32 s50, v21, 31
	v_readlane_b32 s60, v26, 31
	v_readlane_b32 s52, v22, 31
	v_readlane_b32 s62, v27, 31
	v_readlane_b32 s54, v23, 31
	v_readlane_b32 s64, v28, 31
	v_readlane_b32 s56, v24, 31
	v_readlane_b32 s66, v29, 31
	v_pk_fma_f32 v[52:53], v[224:225], s[48:49], v[52:53] op_sel_hi:[1,0,1]
	v_pk_fma_f32 v[54:55], v[226:227], s[48:49], v[54:55] op_sel_hi:[1,0,1]
	v_pk_fma_f32 v[56:57], v[228:229], s[58:59], v[56:57] op_sel_hi:[1,0,1]
	v_pk_fma_f32 v[58:59], v[230:231], s[58:59], v[58:59] op_sel_hi:[1,0,1]
	v_pk_fma_f32 v[60:61], v[224:225], s[50:51], v[60:61] op_sel_hi:[1,0,1]
	v_pk_fma_f32 v[62:63], v[226:227], s[50:51], v[62:63] op_sel_hi:[1,0,1]
	v_pk_fma_f32 v[64:65], v[228:229], s[60:61], v[64:65] op_sel_hi:[1,0,1]
	v_pk_fma_f32 v[66:67], v[230:231], s[60:61], v[66:67] op_sel_hi:[1,0,1]
	v_pk_fma_f32 v[68:69], v[224:225], s[52:53], v[68:69] op_sel_hi:[1,0,1]
	v_pk_fma_f32 v[70:71], v[226:227], s[52:53], v[70:71] op_sel_hi:[1,0,1]
	v_pk_fma_f32 v[72:73], v[228:229], s[62:63], v[72:73] op_sel_hi:[1,0,1]
	v_pk_fma_f32 v[74:75], v[230:231], s[62:63], v[74:75] op_sel_hi:[1,0,1]
	v_pk_fma_f32 v[76:77], v[224:225], s[54:55], v[76:77] op_sel_hi:[1,0,1]
	v_pk_fma_f32 v[78:79], v[226:227], s[54:55], v[78:79] op_sel_hi:[1,0,1]
	v_pk_fma_f32 v[80:81], v[228:229], s[64:65], v[80:81] op_sel_hi:[1,0,1]
	v_pk_fma_f32 v[82:83], v[230:231], s[64:65], v[82:83] op_sel_hi:[1,0,1]
	v_pk_fma_f32 v[84:85], v[224:225], s[56:57], v[84:85] op_sel_hi:[1,0,1]
	v_pk_fma_f32 v[86:87], v[226:227], s[56:57], v[86:87] op_sel_hi:[1,0,1]
	v_pk_fma_f32 v[88:89], v[228:229], s[66:67], v[88:89] op_sel_hi:[1,0,1]
	v_pk_fma_f32 v[90:91], v[230:231], s[66:67], v[90:91] op_sel_hi:[1,0,1]
	s_add_u32 s2, s16, 0x8000
	s_addc_u32 s3, s17, 0
	s_add_u32 s40, s18, 0x8000
	s_addc_u32 s41, s19, 0
	global_load_dwordx4 v[168:171], v232, s[2:3]
	global_load_dwordx4 v[172:175], v232, s[40:41]
	global_load_dwordx4 v[176:179], v232, s[2:3] offset:1024
	global_load_dwordx4 v[180:183], v232, s[40:41] offset:1024
	global_load_dwordx4 v[184:187], v232, s[2:3] offset:2048
	global_load_dwordx4 v[188:191], v232, s[40:41] offset:2048
	global_load_dwordx4 v[192:195], v232, s[2:3] offset:3072
	global_load_dwordx4 v[196:199], v232, s[40:41] offset:3072
	s_add_u32 s2, s2, 0x1000
	s_addc_u32 s3, s3, 0
	s_add_u32 s40, s40, 0x1000
	s_addc_u32 s41, s41, 0
	global_load_dwordx4 v[200:203], v232, s[2:3]
	global_load_dwordx4 v[204:207], v232, s[40:41]
	global_load_dwordx4 v[208:211], v232, s[2:3] offset:1024
	global_load_dwordx4 v[212:215], v232, s[40:41] offset:1024
	global_load_dwordx4 v[216:219], v232, s[2:3] offset:2048
	global_load_dwordx4 v[220:223], v232, s[40:41] offset:2048
	s_mov_b32 s6, s13
	s_cmp_ge_u32 s6, 0x2800
	s_cbranch_scc1 .Lgprep_sk0
	v_mul_f32_e32 v92, 0xbfb8aa3b, v52
	v_exp_f32_e32 v92, v92
	s_nop 0
	v_add_f32_e32 v92, 1.0, v92
	v_div_scale_f32 v93, s[24:25], v92, v92, 1.0
	v_rcp_f32_e32 v94, v93
	s_nop 0
	v_fma_f32 v95, -v93, v94, 1.0
	v_fmac_f32_e32 v94, v95, v94
	v_div_scale_f32 v95, vcc, 1.0, v92, 1.0
	v_mul_f32_e32 v96, v95, v94
	v_fma_f32 v97, -v93, v96, v95
	v_fmac_f32_e32 v96, v97, v94
	v_fma_f32 v93, -v93, v96, v95
	v_div_fmas_f32 v93, v93, v94, v96
	v_div_fixup_f32 v52, v93, v92, 1.0
	v_mul_f32_e32 v52, 0xbf1b4598, v52
	v_mul_f32_e32 v52, 0x3fb8aa3b, v52
	v_exp_f32_e32 v52, v52
	v_mul_f32_e32 v92, 0xbfb8aa3b, v56
	v_exp_f32_e32 v92, v92
	s_nop 0
	v_add_f32_e32 v92, 1.0, v92
	v_div_scale_f32 v93, s[24:25], v92, v92, 1.0
	v_rcp_f32_e32 v94, v93
	s_nop 0
	v_fma_f32 v95, -v93, v94, 1.0
	v_fmac_f32_e32 v94, v95, v94
	v_div_scale_f32 v95, vcc, 1.0, v92, 1.0
	v_mul_f32_e32 v96, v95, v94
	v_fma_f32 v97, -v93, v96, v95
	v_fmac_f32_e32 v96, v97, v94
	v_fma_f32 v93, -v93, v96, v95
	v_div_fmas_f32 v93, v93, v94, v96
	v_div_fixup_f32 v56, v93, v92, 1.0
	v_mul_f32_e32 v92, 0xbfb8aa3b, v53
	v_exp_f32_e32 v92, v92
	s_nop 0
	v_add_f32_e32 v92, 1.0, v92
	v_div_scale_f32 v93, s[24:25], v92, v92, 1.0
	v_rcp_f32_e32 v94, v93
	s_nop 0
	v_fma_f32 v95, -v93, v94, 1.0
	v_fmac_f32_e32 v94, v95, v94
	v_div_scale_f32 v95, vcc, 1.0, v92, 1.0
	v_mul_f32_e32 v96, v95, v94
	v_fma_f32 v97, -v93, v96, v95
	v_fmac_f32_e32 v96, v97, v94
	v_fma_f32 v93, -v93, v96, v95
	v_div_fmas_f32 v93, v93, v94, v96
	v_div_fixup_f32 v53, v93, v92, 1.0
	v_mul_f32_e32 v53, 0xbf1b4598, v53
	v_mul_f32_e32 v53, 0x3fb8aa3b, v53
	v_exp_f32_e32 v53, v53
	v_mul_f32_e32 v92, 0xbfb8aa3b, v57
	v_exp_f32_e32 v92, v92
	s_nop 0
	v_add_f32_e32 v92, 1.0, v92
	v_div_scale_f32 v93, s[24:25], v92, v92, 1.0
	v_rcp_f32_e32 v94, v93
	s_nop 0
	v_fma_f32 v95, -v93, v94, 1.0
	v_fmac_f32_e32 v94, v95, v94
	v_div_scale_f32 v95, vcc, 1.0, v92, 1.0
	v_mul_f32_e32 v96, v95, v94
	v_fma_f32 v97, -v93, v96, v95
	v_fmac_f32_e32 v96, v97, v94
	v_fma_f32 v93, -v93, v96, v95
	v_div_fmas_f32 v93, v93, v94, v96
	v_div_fixup_f32 v57, v93, v92, 1.0
	v_mul_f32_e32 v92, 0xbfb8aa3b, v54
	v_exp_f32_e32 v92, v92
	s_nop 0
	v_add_f32_e32 v92, 1.0, v92
	v_div_scale_f32 v93, s[24:25], v92, v92, 1.0
	v_rcp_f32_e32 v94, v93
	s_nop 0
	v_fma_f32 v95, -v93, v94, 1.0
	v_fmac_f32_e32 v94, v95, v94
	v_div_scale_f32 v95, vcc, 1.0, v92, 1.0
	v_mul_f32_e32 v96, v95, v94
	v_fma_f32 v97, -v93, v96, v95
	v_fmac_f32_e32 v96, v97, v94
	v_fma_f32 v93, -v93, v96, v95
	v_div_fmas_f32 v93, v93, v94, v96
	v_div_fixup_f32 v54, v93, v92, 1.0
	v_mul_f32_e32 v54, 0xbf1b4598, v54
	v_mul_f32_e32 v54, 0x3fb8aa3b, v54
	v_exp_f32_e32 v54, v54
	v_mul_f32_e32 v92, 0xbfb8aa3b, v58
	v_exp_f32_e32 v92, v92
	s_nop 0
	v_add_f32_e32 v92, 1.0, v92
	v_div_scale_f32 v93, s[24:25], v92, v92, 1.0
	v_rcp_f32_e32 v94, v93
	s_nop 0
	v_fma_f32 v95, -v93, v94, 1.0
	v_fmac_f32_e32 v94, v95, v94
	v_div_scale_f32 v95, vcc, 1.0, v92, 1.0
	v_mul_f32_e32 v96, v95, v94
	v_fma_f32 v97, -v93, v96, v95
	v_fmac_f32_e32 v96, v97, v94
	v_fma_f32 v93, -v93, v96, v95
	v_div_fmas_f32 v93, v93, v94, v96
	v_div_fixup_f32 v58, v93, v92, 1.0
	v_mul_f32_e32 v92, 0xbfb8aa3b, v55
	v_exp_f32_e32 v92, v92
	s_nop 0
	v_add_f32_e32 v92, 1.0, v92
	v_div_scale_f32 v93, s[24:25], v92, v92, 1.0
	v_rcp_f32_e32 v94, v93
	s_nop 0
	v_fma_f32 v95, -v93, v94, 1.0
	v_fmac_f32_e32 v94, v95, v94
	v_div_scale_f32 v95, vcc, 1.0, v92, 1.0
	v_mul_f32_e32 v96, v95, v94
	v_fma_f32 v97, -v93, v96, v95
	v_fmac_f32_e32 v96, v97, v94
	v_fma_f32 v93, -v93, v96, v95
	v_div_fmas_f32 v93, v93, v94, v96
	v_div_fixup_f32 v55, v93, v92, 1.0
	v_mul_f32_e32 v55, 0xbf1b4598, v55
	v_mul_f32_e32 v55, 0x3fb8aa3b, v55
	v_exp_f32_e32 v55, v55
	v_mul_f32_e32 v92, 0xbfb8aa3b, v59
	v_exp_f32_e32 v92, v92
	s_nop 0
	v_add_f32_e32 v92, 1.0, v92
	v_div_scale_f32 v93, s[24:25], v92, v92, 1.0
	v_rcp_f32_e32 v94, v93
	s_nop 0
	v_fma_f32 v95, -v93, v94, 1.0
	v_fmac_f32_e32 v94, v95, v94
	v_div_scale_f32 v95, vcc, 1.0, v92, 1.0
	v_mul_f32_e32 v96, v95, v94
	v_fma_f32 v97, -v93, v96, v95
	v_fmac_f32_e32 v96, v97, v94
	v_fma_f32 v93, -v93, v96, v95
	v_div_fmas_f32 v93, v93, v94, v96
	v_div_fixup_f32 v59, v93, v92, 1.0
	s_mul_i32 s7, s6, 0x1400
	s_add_u32 s8, s82, s7
	s_addc_u32 s9, s83, 0
	global_store_dwordx4 v232, v[52:55], s[8:9] offset:1024
	global_store_dwordx4 v232, v[56:59], s[8:9] offset:2048
	global_store_dwordx4 v232, v[0:3], s[8:9]
	s_add_u32 s6, s13, 1
	s_cmp_ge_u32 s6, 0x2800
	s_cbranch_scc1 .Lgprep_sk0
	v_mul_f32_e32 v92, 0xbfb8aa3b, v60
	v_exp_f32_e32 v92, v92
	s_nop 0
	v_add_f32_e32 v92, 1.0, v92
	v_div_scale_f32 v93, s[24:25], v92, v92, 1.0
	v_rcp_f32_e32 v94, v93
	s_nop 0
	v_fma_f32 v95, -v93, v94, 1.0
	v_fmac_f32_e32 v94, v95, v94
	v_div_scale_f32 v95, vcc, 1.0, v92, 1.0
	v_mul_f32_e32 v96, v95, v94
	v_fma_f32 v97, -v93, v96, v95
	v_fmac_f32_e32 v96, v97, v94
	v_fma_f32 v93, -v93, v96, v95
	v_div_fmas_f32 v93, v93, v94, v96
	v_div_fixup_f32 v60, v93, v92, 1.0
	v_mul_f32_e32 v60, 0xbf1b4598, v60
	v_mul_f32_e32 v60, 0x3fb8aa3b, v60
	v_exp_f32_e32 v60, v60
	v_mul_f32_e32 v92, 0xbfb8aa3b, v64
	v_exp_f32_e32 v92, v92
	s_nop 0
	v_add_f32_e32 v92, 1.0, v92
	v_div_scale_f32 v93, s[24:25], v92, v92, 1.0
	v_rcp_f32_e32 v94, v93
	s_nop 0
	v_fma_f32 v95, -v93, v94, 1.0
	v_fmac_f32_e32 v94, v95, v94
	v_div_scale_f32 v95, vcc, 1.0, v92, 1.0
	v_mul_f32_e32 v96, v95, v94
	v_fma_f32 v97, -v93, v96, v95
	v_fmac_f32_e32 v96, v97, v94
	v_fma_f32 v93, -v93, v96, v95
	v_div_fmas_f32 v93, v93, v94, v96
	v_div_fixup_f32 v64, v93, v92, 1.0
	v_mul_f32_e32 v92, 0xbfb8aa3b, v61
	v_exp_f32_e32 v92, v92
	s_nop 0
	v_add_f32_e32 v92, 1.0, v92
	v_div_scale_f32 v93, s[24:25], v92, v92, 1.0
	v_rcp_f32_e32 v94, v93
	s_nop 0
	v_fma_f32 v95, -v93, v94, 1.0
	v_fmac_f32_e32 v94, v95, v94
	v_div_scale_f32 v95, vcc, 1.0, v92, 1.0
	v_mul_f32_e32 v96, v95, v94
	v_fma_f32 v97, -v93, v96, v95
	v_fmac_f32_e32 v96, v97, v94
	v_fma_f32 v93, -v93, v96, v95
	v_div_fmas_f32 v93, v93, v94, v96
	v_div_fixup_f32 v61, v93, v92, 1.0
	v_mul_f32_e32 v61, 0xbf1b4598, v61
	v_mul_f32_e32 v61, 0x3fb8aa3b, v61
	v_exp_f32_e32 v61, v61
	v_mul_f32_e32 v92, 0xbfb8aa3b, v65
	v_exp_f32_e32 v92, v92
	s_nop 0
	v_add_f32_e32 v92, 1.0, v92
	v_div_scale_f32 v93, s[24:25], v92, v92, 1.0
	v_rcp_f32_e32 v94, v93
	s_nop 0
	v_fma_f32 v95, -v93, v94, 1.0
	v_fmac_f32_e32 v94, v95, v94
	v_div_scale_f32 v95, vcc, 1.0, v92, 1.0
	v_mul_f32_e32 v96, v95, v94
	v_fma_f32 v97, -v93, v96, v95
	v_fmac_f32_e32 v96, v97, v94
	v_fma_f32 v93, -v93, v96, v95
	v_div_fmas_f32 v93, v93, v94, v96
	v_div_fixup_f32 v65, v93, v92, 1.0
	v_mul_f32_e32 v92, 0xbfb8aa3b, v62
	v_exp_f32_e32 v92, v92
	s_nop 0
	v_add_f32_e32 v92, 1.0, v92
	v_div_scale_f32 v93, s[24:25], v92, v92, 1.0
	v_rcp_f32_e32 v94, v93
	s_nop 0
	v_fma_f32 v95, -v93, v94, 1.0
	v_fmac_f32_e32 v94, v95, v94
	v_div_scale_f32 v95, vcc, 1.0, v92, 1.0
	v_mul_f32_e32 v96, v95, v94
	v_fma_f32 v97, -v93, v96, v95
	v_fmac_f32_e32 v96, v97, v94
	v_fma_f32 v93, -v93, v96, v95
	v_div_fmas_f32 v93, v93, v94, v96
	v_div_fixup_f32 v62, v93, v92, 1.0
	v_mul_f32_e32 v62, 0xbf1b4598, v62
	v_mul_f32_e32 v62, 0x3fb8aa3b, v62
	v_exp_f32_e32 v62, v62
	v_mul_f32_e32 v92, 0xbfb8aa3b, v66
	v_exp_f32_e32 v92, v92
	s_nop 0
	v_add_f32_e32 v92, 1.0, v92
	v_div_scale_f32 v93, s[24:25], v92, v92, 1.0
	v_rcp_f32_e32 v94, v93
	s_nop 0
	v_fma_f32 v95, -v93, v94, 1.0
	v_fmac_f32_e32 v94, v95, v94
	v_div_scale_f32 v95, vcc, 1.0, v92, 1.0
	v_mul_f32_e32 v96, v95, v94
	v_fma_f32 v97, -v93, v96, v95
	v_fmac_f32_e32 v96, v97, v94
	v_fma_f32 v93, -v93, v96, v95
	v_div_fmas_f32 v93, v93, v94, v96
	v_div_fixup_f32 v66, v93, v92, 1.0
	v_mul_f32_e32 v92, 0xbfb8aa3b, v63
	v_exp_f32_e32 v92, v92
	s_nop 0
	v_add_f32_e32 v92, 1.0, v92
	v_div_scale_f32 v93, s[24:25], v92, v92, 1.0
	v_rcp_f32_e32 v94, v93
	s_nop 0
	v_fma_f32 v95, -v93, v94, 1.0
	v_fmac_f32_e32 v94, v95, v94
	v_div_scale_f32 v95, vcc, 1.0, v92, 1.0
	v_mul_f32_e32 v96, v95, v94
	v_fma_f32 v97, -v93, v96, v95
	v_fmac_f32_e32 v96, v97, v94
	v_fma_f32 v93, -v93, v96, v95
	v_div_fmas_f32 v93, v93, v94, v96
	v_div_fixup_f32 v63, v93, v92, 1.0
	v_mul_f32_e32 v63, 0xbf1b4598, v63
	v_mul_f32_e32 v63, 0x3fb8aa3b, v63
	v_exp_f32_e32 v63, v63
	v_mul_f32_e32 v92, 0xbfb8aa3b, v67
	v_exp_f32_e32 v92, v92
	s_nop 0
	v_add_f32_e32 v92, 1.0, v92
	v_div_scale_f32 v93, s[24:25], v92, v92, 1.0
	v_rcp_f32_e32 v94, v93
	s_nop 0
	v_fma_f32 v95, -v93, v94, 1.0
	v_fmac_f32_e32 v94, v95, v94
	v_div_scale_f32 v95, vcc, 1.0, v92, 1.0
	v_mul_f32_e32 v96, v95, v94
	v_fma_f32 v97, -v93, v96, v95
	v_fmac_f32_e32 v96, v97, v94
	v_fma_f32 v93, -v93, v96, v95
	v_div_fmas_f32 v93, v93, v94, v96
	v_div_fixup_f32 v67, v93, v92, 1.0
	s_mul_i32 s7, s6, 0x1400
	s_add_u32 s8, s82, s7
	s_addc_u32 s9, s83, 0
	global_store_dwordx4 v232, v[60:63], s[8:9] offset:1024
	global_store_dwordx4 v232, v[64:67], s[8:9] offset:2048
	global_store_dwordx4 v232, v[4:7], s[8:9]
	s_add_u32 s6, s13, 2
	s_cmp_ge_u32 s6, 0x2800
	s_cbranch_scc1 .Lgprep_sk0
	v_mul_f32_e32 v92, 0xbfb8aa3b, v68
	v_exp_f32_e32 v92, v92
	s_nop 0
	v_add_f32_e32 v92, 1.0, v92
	v_div_scale_f32 v93, s[24:25], v92, v92, 1.0
	v_rcp_f32_e32 v94, v93
	s_nop 0
	v_fma_f32 v95, -v93, v94, 1.0
	v_fmac_f32_e32 v94, v95, v94
	v_div_scale_f32 v95, vcc, 1.0, v92, 1.0
	v_mul_f32_e32 v96, v95, v94
	v_fma_f32 v97, -v93, v96, v95
	v_fmac_f32_e32 v96, v97, v94
	v_fma_f32 v93, -v93, v96, v95
	v_div_fmas_f32 v93, v93, v94, v96
	v_div_fixup_f32 v68, v93, v92, 1.0
	v_mul_f32_e32 v68, 0xbf1b4598, v68
	v_mul_f32_e32 v68, 0x3fb8aa3b, v68
	v_exp_f32_e32 v68, v68
	v_mul_f32_e32 v92, 0xbfb8aa3b, v72
	v_exp_f32_e32 v92, v92
	s_nop 0
	v_add_f32_e32 v92, 1.0, v92
	v_div_scale_f32 v93, s[24:25], v92, v92, 1.0
	v_rcp_f32_e32 v94, v93
	s_nop 0
	v_fma_f32 v95, -v93, v94, 1.0
	v_fmac_f32_e32 v94, v95, v94
	v_div_scale_f32 v95, vcc, 1.0, v92, 1.0
	v_mul_f32_e32 v96, v95, v94
	v_fma_f32 v97, -v93, v96, v95
	v_fmac_f32_e32 v96, v97, v94
	v_fma_f32 v93, -v93, v96, v95
	v_div_fmas_f32 v93, v93, v94, v96
	v_div_fixup_f32 v72, v93, v92, 1.0
	v_mul_f32_e32 v92, 0xbfb8aa3b, v69
	v_exp_f32_e32 v92, v92
	s_nop 0
	v_add_f32_e32 v92, 1.0, v92
	v_div_scale_f32 v93, s[24:25], v92, v92, 1.0
	v_rcp_f32_e32 v94, v93
	s_nop 0
	v_fma_f32 v95, -v93, v94, 1.0
	v_fmac_f32_e32 v94, v95, v94
	v_div_scale_f32 v95, vcc, 1.0, v92, 1.0
	v_mul_f32_e32 v96, v95, v94
	v_fma_f32 v97, -v93, v96, v95
	v_fmac_f32_e32 v96, v97, v94
	v_fma_f32 v93, -v93, v96, v95
	v_div_fmas_f32 v93, v93, v94, v96
	v_div_fixup_f32 v69, v93, v92, 1.0
	v_mul_f32_e32 v69, 0xbf1b4598, v69
	v_mul_f32_e32 v69, 0x3fb8aa3b, v69
	v_exp_f32_e32 v69, v69
	v_mul_f32_e32 v92, 0xbfb8aa3b, v73
	v_exp_f32_e32 v92, v92
	s_nop 0
	v_add_f32_e32 v92, 1.0, v92
	v_div_scale_f32 v93, s[24:25], v92, v92, 1.0
	v_rcp_f32_e32 v94, v93
	s_nop 0
	v_fma_f32 v95, -v93, v94, 1.0
	v_fmac_f32_e32 v94, v95, v94
	v_div_scale_f32 v95, vcc, 1.0, v92, 1.0
	v_mul_f32_e32 v96, v95, v94
	v_fma_f32 v97, -v93, v96, v95
	v_fmac_f32_e32 v96, v97, v94
	v_fma_f32 v93, -v93, v96, v95
	v_div_fmas_f32 v93, v93, v94, v96
	v_div_fixup_f32 v73, v93, v92, 1.0
	v_mul_f32_e32 v92, 0xbfb8aa3b, v70
	v_exp_f32_e32 v92, v92
	s_nop 0
	v_add_f32_e32 v92, 1.0, v92
	v_div_scale_f32 v93, s[24:25], v92, v92, 1.0
	v_rcp_f32_e32 v94, v93
	s_nop 0
	v_fma_f32 v95, -v93, v94, 1.0
	v_fmac_f32_e32 v94, v95, v94
	v_div_scale_f32 v95, vcc, 1.0, v92, 1.0
	v_mul_f32_e32 v96, v95, v94
	v_fma_f32 v97, -v93, v96, v95
	v_fmac_f32_e32 v96, v97, v94
	v_fma_f32 v93, -v93, v96, v95
	v_div_fmas_f32 v93, v93, v94, v96
	v_div_fixup_f32 v70, v93, v92, 1.0
	v_mul_f32_e32 v70, 0xbf1b4598, v70
	v_mul_f32_e32 v70, 0x3fb8aa3b, v70
	v_exp_f32_e32 v70, v70
	v_mul_f32_e32 v92, 0xbfb8aa3b, v74
	v_exp_f32_e32 v92, v92
	s_nop 0
	v_add_f32_e32 v92, 1.0, v92
	v_div_scale_f32 v93, s[24:25], v92, v92, 1.0
	v_rcp_f32_e32 v94, v93
	s_nop 0
	v_fma_f32 v95, -v93, v94, 1.0
	v_fmac_f32_e32 v94, v95, v94
	v_div_scale_f32 v95, vcc, 1.0, v92, 1.0
	v_mul_f32_e32 v96, v95, v94
	v_fma_f32 v97, -v93, v96, v95
	v_fmac_f32_e32 v96, v97, v94
	v_fma_f32 v93, -v93, v96, v95
	v_div_fmas_f32 v93, v93, v94, v96
	v_div_fixup_f32 v74, v93, v92, 1.0
	v_mul_f32_e32 v92, 0xbfb8aa3b, v71
	v_exp_f32_e32 v92, v92
	s_nop 0
	v_add_f32_e32 v92, 1.0, v92
	v_div_scale_f32 v93, s[24:25], v92, v92, 1.0
	v_rcp_f32_e32 v94, v93
	s_nop 0
	v_fma_f32 v95, -v93, v94, 1.0
	v_fmac_f32_e32 v94, v95, v94
	v_div_scale_f32 v95, vcc, 1.0, v92, 1.0
	v_mul_f32_e32 v96, v95, v94
	v_fma_f32 v97, -v93, v96, v95
	v_fmac_f32_e32 v96, v97, v94
	v_fma_f32 v93, -v93, v96, v95
	v_div_fmas_f32 v93, v93, v94, v96
	v_div_fixup_f32 v71, v93, v92, 1.0
	v_mul_f32_e32 v71, 0xbf1b4598, v71
	v_mul_f32_e32 v71, 0x3fb8aa3b, v71
	v_exp_f32_e32 v71, v71
	v_mul_f32_e32 v92, 0xbfb8aa3b, v75
	v_exp_f32_e32 v92, v92
	s_nop 0
	v_add_f32_e32 v92, 1.0, v92
	v_div_scale_f32 v93, s[24:25], v92, v92, 1.0
	v_rcp_f32_e32 v94, v93
	s_nop 0
	v_fma_f32 v95, -v93, v94, 1.0
	v_fmac_f32_e32 v94, v95, v94
	v_div_scale_f32 v95, vcc, 1.0, v92, 1.0
	v_mul_f32_e32 v96, v95, v94
	v_fma_f32 v97, -v93, v96, v95
	v_fmac_f32_e32 v96, v97, v94
	v_fma_f32 v93, -v93, v96, v95
	v_div_fmas_f32 v93, v93, v94, v96
	v_div_fixup_f32 v75, v93, v92, 1.0
	s_mul_i32 s7, s6, 0x1400
	s_add_u32 s8, s82, s7
	s_addc_u32 s9, s83, 0
	global_store_dwordx4 v232, v[68:71], s[8:9] offset:1024
	global_store_dwordx4 v232, v[72:75], s[8:9] offset:2048
	global_store_dwordx4 v232, v[8:11], s[8:9]
	s_add_u32 s6, s13, 3
	s_cmp_ge_u32 s6, 0x2800
	s_cbranch_scc1 .Lgprep_sk0
	v_mul_f32_e32 v92, 0xbfb8aa3b, v76
	v_exp_f32_e32 v92, v92
	s_nop 0
	v_add_f32_e32 v92, 1.0, v92
	v_div_scale_f32 v93, s[24:25], v92, v92, 1.0
	v_rcp_f32_e32 v94, v93
	s_nop 0
	v_fma_f32 v95, -v93, v94, 1.0
	v_fmac_f32_e32 v94, v95, v94
	v_div_scale_f32 v95, vcc, 1.0, v92, 1.0
	v_mul_f32_e32 v96, v95, v94
	v_fma_f32 v97, -v93, v96, v95
	v_fmac_f32_e32 v96, v97, v94
	v_fma_f32 v93, -v93, v96, v95
	v_div_fmas_f32 v93, v93, v94, v96
	v_div_fixup_f32 v76, v93, v92, 1.0
	v_mul_f32_e32 v76, 0xbf1b4598, v76
	v_mul_f32_e32 v76, 0x3fb8aa3b, v76
	v_exp_f32_e32 v76, v76
	v_mul_f32_e32 v92, 0xbfb8aa3b, v80
	v_exp_f32_e32 v92, v92
	s_nop 0
	v_add_f32_e32 v92, 1.0, v92
	v_div_scale_f32 v93, s[24:25], v92, v92, 1.0
	v_rcp_f32_e32 v94, v93
	s_nop 0
	v_fma_f32 v95, -v93, v94, 1.0
	v_fmac_f32_e32 v94, v95, v94
	v_div_scale_f32 v95, vcc, 1.0, v92, 1.0
	v_mul_f32_e32 v96, v95, v94
	v_fma_f32 v97, -v93, v96, v95
	v_fmac_f32_e32 v96, v97, v94
	v_fma_f32 v93, -v93, v96, v95
	v_div_fmas_f32 v93, v93, v94, v96
	v_div_fixup_f32 v80, v93, v92, 1.0
	v_mul_f32_e32 v92, 0xbfb8aa3b, v77
	v_exp_f32_e32 v92, v92
	s_nop 0
	v_add_f32_e32 v92, 1.0, v92
	v_div_scale_f32 v93, s[24:25], v92, v92, 1.0
	v_rcp_f32_e32 v94, v93
	s_nop 0
	v_fma_f32 v95, -v93, v94, 1.0
	v_fmac_f32_e32 v94, v95, v94
	v_div_scale_f32 v95, vcc, 1.0, v92, 1.0
	v_mul_f32_e32 v96, v95, v94
	v_fma_f32 v97, -v93, v96, v95
	v_fmac_f32_e32 v96, v97, v94
	v_fma_f32 v93, -v93, v96, v95
	v_div_fmas_f32 v93, v93, v94, v96
	v_div_fixup_f32 v77, v93, v92, 1.0
	v_mul_f32_e32 v77, 0xbf1b4598, v77
	v_mul_f32_e32 v77, 0x3fb8aa3b, v77
	v_exp_f32_e32 v77, v77
	v_mul_f32_e32 v92, 0xbfb8aa3b, v81
	v_exp_f32_e32 v92, v92
	s_nop 0
	v_add_f32_e32 v92, 1.0, v92
	v_div_scale_f32 v93, s[24:25], v92, v92, 1.0
	v_rcp_f32_e32 v94, v93
	s_nop 0
	v_fma_f32 v95, -v93, v94, 1.0
	v_fmac_f32_e32 v94, v95, v94
	v_div_scale_f32 v95, vcc, 1.0, v92, 1.0
	v_mul_f32_e32 v96, v95, v94
	v_fma_f32 v97, -v93, v96, v95
	v_fmac_f32_e32 v96, v97, v94
	v_fma_f32 v93, -v93, v96, v95
	v_div_fmas_f32 v93, v93, v94, v96
	v_div_fixup_f32 v81, v93, v92, 1.0
	v_mul_f32_e32 v92, 0xbfb8aa3b, v78
	v_exp_f32_e32 v92, v92
	s_nop 0
	v_add_f32_e32 v92, 1.0, v92
	v_div_scale_f32 v93, s[24:25], v92, v92, 1.0
	v_rcp_f32_e32 v94, v93
	s_nop 0
	v_fma_f32 v95, -v93, v94, 1.0
	v_fmac_f32_e32 v94, v95, v94
	v_div_scale_f32 v95, vcc, 1.0, v92, 1.0
	v_mul_f32_e32 v96, v95, v94
	v_fma_f32 v97, -v93, v96, v95
	v_fmac_f32_e32 v96, v97, v94
	v_fma_f32 v93, -v93, v96, v95
	v_div_fmas_f32 v93, v93, v94, v96
	v_div_fixup_f32 v78, v93, v92, 1.0
	v_mul_f32_e32 v78, 0xbf1b4598, v78
	v_mul_f32_e32 v78, 0x3fb8aa3b, v78
	v_exp_f32_e32 v78, v78
	v_mul_f32_e32 v92, 0xbfb8aa3b, v82
	v_exp_f32_e32 v92, v92
	s_nop 0
	v_add_f32_e32 v92, 1.0, v92
	v_div_scale_f32 v93, s[24:25], v92, v92, 1.0
	v_rcp_f32_e32 v94, v93
	s_nop 0
	v_fma_f32 v95, -v93, v94, 1.0
	v_fmac_f32_e32 v94, v95, v94
	v_div_scale_f32 v95, vcc, 1.0, v92, 1.0
	v_mul_f32_e32 v96, v95, v94
	v_fma_f32 v97, -v93, v96, v95
	v_fmac_f32_e32 v96, v97, v94
	v_fma_f32 v93, -v93, v96, v95
	v_div_fmas_f32 v93, v93, v94, v96
	v_div_fixup_f32 v82, v93, v92, 1.0
	v_mul_f32_e32 v92, 0xbfb8aa3b, v79
	v_exp_f32_e32 v92, v92
	s_nop 0
	v_add_f32_e32 v92, 1.0, v92
	v_div_scale_f32 v93, s[24:25], v92, v92, 1.0
	v_rcp_f32_e32 v94, v93
	s_nop 0
	v_fma_f32 v95, -v93, v94, 1.0
	v_fmac_f32_e32 v94, v95, v94
	v_div_scale_f32 v95, vcc, 1.0, v92, 1.0
	v_mul_f32_e32 v96, v95, v94
	v_fma_f32 v97, -v93, v96, v95
	v_fmac_f32_e32 v96, v97, v94
	v_fma_f32 v93, -v93, v96, v95
	v_div_fmas_f32 v93, v93, v94, v96
	v_div_fixup_f32 v79, v93, v92, 1.0
	v_mul_f32_e32 v79, 0xbf1b4598, v79
	v_mul_f32_e32 v79, 0x3fb8aa3b, v79
	v_exp_f32_e32 v79, v79
	v_mul_f32_e32 v92, 0xbfb8aa3b, v83
	v_exp_f32_e32 v92, v92
	s_nop 0
	v_add_f32_e32 v92, 1.0, v92
	v_div_scale_f32 v93, s[24:25], v92, v92, 1.0
	v_rcp_f32_e32 v94, v93
	s_nop 0
	v_fma_f32 v95, -v93, v94, 1.0
	v_fmac_f32_e32 v94, v95, v94
	v_div_scale_f32 v95, vcc, 1.0, v92, 1.0
	v_mul_f32_e32 v96, v95, v94
	v_fma_f32 v97, -v93, v96, v95
	v_fmac_f32_e32 v96, v97, v94
	v_fma_f32 v93, -v93, v96, v95
	v_div_fmas_f32 v93, v93, v94, v96
	v_div_fixup_f32 v83, v93, v92, 1.0
	s_mul_i32 s7, s6, 0x1400
	s_add_u32 s8, s82, s7
	s_addc_u32 s9, s83, 0
	global_store_dwordx4 v232, v[76:79], s[8:9] offset:1024
	global_store_dwordx4 v232, v[80:83], s[8:9] offset:2048
	global_store_dwordx4 v232, v[12:15], s[8:9]
	s_add_u32 s6, s13, 4
	s_cmp_ge_u32 s6, 0x2800
	s_cbranch_scc1 .Lgprep_sk0
	v_mul_f32_e32 v92, 0xbfb8aa3b, v84
	v_exp_f32_e32 v92, v92
	s_nop 0
	v_add_f32_e32 v92, 1.0, v92
	v_div_scale_f32 v93, s[24:25], v92, v92, 1.0
	v_rcp_f32_e32 v94, v93
	s_nop 0
	v_fma_f32 v95, -v93, v94, 1.0
	v_fmac_f32_e32 v94, v95, v94
	v_div_scale_f32 v95, vcc, 1.0, v92, 1.0
	v_mul_f32_e32 v96, v95, v94
	v_fma_f32 v97, -v93, v96, v95
	v_fmac_f32_e32 v96, v97, v94
	v_fma_f32 v93, -v93, v96, v95
	v_div_fmas_f32 v93, v93, v94, v96
	v_div_fixup_f32 v84, v93, v92, 1.0
	v_mul_f32_e32 v84, 0xbf1b4598, v84
	v_mul_f32_e32 v84, 0x3fb8aa3b, v84
	v_exp_f32_e32 v84, v84
	v_mul_f32_e32 v92, 0xbfb8aa3b, v88
	v_exp_f32_e32 v92, v92
	s_nop 0
	v_add_f32_e32 v92, 1.0, v92
	v_div_scale_f32 v93, s[24:25], v92, v92, 1.0
	v_rcp_f32_e32 v94, v93
	s_nop 0
	v_fma_f32 v95, -v93, v94, 1.0
	v_fmac_f32_e32 v94, v95, v94
	v_div_scale_f32 v95, vcc, 1.0, v92, 1.0
	v_mul_f32_e32 v96, v95, v94
	v_fma_f32 v97, -v93, v96, v95
	v_fmac_f32_e32 v96, v97, v94
	v_fma_f32 v93, -v93, v96, v95
	v_div_fmas_f32 v93, v93, v94, v96
	v_div_fixup_f32 v88, v93, v92, 1.0
	v_mul_f32_e32 v92, 0xbfb8aa3b, v85
	v_exp_f32_e32 v92, v92
	s_nop 0
	v_add_f32_e32 v92, 1.0, v92
	v_div_scale_f32 v93, s[24:25], v92, v92, 1.0
	v_rcp_f32_e32 v94, v93
	s_nop 0
	v_fma_f32 v95, -v93, v94, 1.0
	v_fmac_f32_e32 v94, v95, v94
	v_div_scale_f32 v95, vcc, 1.0, v92, 1.0
	v_mul_f32_e32 v96, v95, v94
	v_fma_f32 v97, -v93, v96, v95
	v_fmac_f32_e32 v96, v97, v94
	v_fma_f32 v93, -v93, v96, v95
	v_div_fmas_f32 v93, v93, v94, v96
	v_div_fixup_f32 v85, v93, v92, 1.0
	v_mul_f32_e32 v85, 0xbf1b4598, v85
	v_mul_f32_e32 v85, 0x3fb8aa3b, v85
	v_exp_f32_e32 v85, v85
	v_mul_f32_e32 v92, 0xbfb8aa3b, v89
	v_exp_f32_e32 v92, v92
	s_nop 0
	v_add_f32_e32 v92, 1.0, v92
	v_div_scale_f32 v93, s[24:25], v92, v92, 1.0
	v_rcp_f32_e32 v94, v93
	s_nop 0
	v_fma_f32 v95, -v93, v94, 1.0
	v_fmac_f32_e32 v94, v95, v94
	v_div_scale_f32 v95, vcc, 1.0, v92, 1.0
	v_mul_f32_e32 v96, v95, v94
	v_fma_f32 v97, -v93, v96, v95
	v_fmac_f32_e32 v96, v97, v94
	v_fma_f32 v93, -v93, v96, v95
	v_div_fmas_f32 v93, v93, v94, v96
	v_div_fixup_f32 v89, v93, v92, 1.0
	v_mul_f32_e32 v92, 0xbfb8aa3b, v86
	v_exp_f32_e32 v92, v92
	s_nop 0
	v_add_f32_e32 v92, 1.0, v92
	v_div_scale_f32 v93, s[24:25], v92, v92, 1.0
	v_rcp_f32_e32 v94, v93
	s_nop 0
	v_fma_f32 v95, -v93, v94, 1.0
	v_fmac_f32_e32 v94, v95, v94
	v_div_scale_f32 v95, vcc, 1.0, v92, 1.0
	v_mul_f32_e32 v96, v95, v94
	v_fma_f32 v97, -v93, v96, v95
	v_fmac_f32_e32 v96, v97, v94
	v_fma_f32 v93, -v93, v96, v95
	v_div_fmas_f32 v93, v93, v94, v96
	v_div_fixup_f32 v86, v93, v92, 1.0
	v_mul_f32_e32 v86, 0xbf1b4598, v86
	v_mul_f32_e32 v86, 0x3fb8aa3b, v86
	v_exp_f32_e32 v86, v86
	v_mul_f32_e32 v92, 0xbfb8aa3b, v90
	v_exp_f32_e32 v92, v92
	s_nop 0
	v_add_f32_e32 v92, 1.0, v92
	v_div_scale_f32 v93, s[24:25], v92, v92, 1.0
	v_rcp_f32_e32 v94, v93
	s_nop 0
	v_fma_f32 v95, -v93, v94, 1.0
	v_fmac_f32_e32 v94, v95, v94
	v_div_scale_f32 v95, vcc, 1.0, v92, 1.0
	v_mul_f32_e32 v96, v95, v94
	v_fma_f32 v97, -v93, v96, v95
	v_fmac_f32_e32 v96, v97, v94
	v_fma_f32 v93, -v93, v96, v95
	v_div_fmas_f32 v93, v93, v94, v96
	v_div_fixup_f32 v90, v93, v92, 1.0
	v_mul_f32_e32 v92, 0xbfb8aa3b, v87
	v_exp_f32_e32 v92, v92
	s_nop 0
	v_add_f32_e32 v92, 1.0, v92
	v_div_scale_f32 v93, s[24:25], v92, v92, 1.0
	v_rcp_f32_e32 v94, v93
	s_nop 0
	v_fma_f32 v95, -v93, v94, 1.0
	v_fmac_f32_e32 v94, v95, v94
	v_div_scale_f32 v95, vcc, 1.0, v92, 1.0
	v_mul_f32_e32 v96, v95, v94
	v_fma_f32 v97, -v93, v96, v95
	v_fmac_f32_e32 v96, v97, v94
	v_fma_f32 v93, -v93, v96, v95
	v_div_fmas_f32 v93, v93, v94, v96
	v_div_fixup_f32 v87, v93, v92, 1.0
	v_mul_f32_e32 v87, 0xbf1b4598, v87
	v_mul_f32_e32 v87, 0x3fb8aa3b, v87
	v_exp_f32_e32 v87, v87
	v_mul_f32_e32 v92, 0xbfb8aa3b, v91
	v_exp_f32_e32 v92, v92
	s_nop 0
	v_add_f32_e32 v92, 1.0, v92
	v_div_scale_f32 v93, s[24:25], v92, v92, 1.0
	v_rcp_f32_e32 v94, v93
	s_nop 0
	v_fma_f32 v95, -v93, v94, 1.0
	v_fmac_f32_e32 v94, v95, v94
	v_div_scale_f32 v95, vcc, 1.0, v92, 1.0
	v_mul_f32_e32 v96, v95, v94
	v_fma_f32 v97, -v93, v96, v95
	v_fmac_f32_e32 v96, v97, v94
	v_fma_f32 v93, -v93, v96, v95
	v_div_fmas_f32 v93, v93, v94, v96
	v_div_fixup_f32 v91, v93, v92, 1.0
	s_mul_i32 s7, s6, 0x1400
	s_add_u32 s8, s82, s7
	s_addc_u32 s9, s83, 0
	global_store_dwordx4 v232, v[84:87], s[8:9] offset:1024
	global_store_dwordx4 v232, v[88:91], s[8:9] offset:2048
	global_store_dwordx4 v232, v[16:19], s[8:9]
	s_branch .Lgprep_e0

.Lgprep_e0:
	v_mov_b32_e32 v52, v38
	v_mov_b32_e32 v56, v46
	v_mov_b32_e32 v53, v39
	v_mov_b32_e32 v57, v47
	v_mov_b32_e32 v54, v40
	v_mov_b32_e32 v58, v48
	v_mov_b32_e32 v55, v41
	v_mov_b32_e32 v59, v49
	v_mov_b32_e32 v60, v38
	v_mov_b32_e32 v64, v46
	v_mov_b32_e32 v61, v39
	v_mov_b32_e32 v65, v47
	v_mov_b32_e32 v62, v40
	v_mov_b32_e32 v66, v48
	v_mov_b32_e32 v63, v41
	v_mov_b32_e32 v67, v49
	v_mov_b32_e32 v68, v38
	v_mov_b32_e32 v72, v46
	v_mov_b32_e32 v69, v39
	v_mov_b32_e32 v73, v47
	v_mov_b32_e32 v70, v40
	v_mov_b32_e32 v74, v48
	v_mov_b32_e32 v71, v41
	v_mov_b32_e32 v75, v49
	v_mov_b32_e32 v76, v38
	v_mov_b32_e32 v80, v46
	v_mov_b32_e32 v77, v39
	v_mov_b32_e32 v81, v47
	v_mov_b32_e32 v78, v40
	v_mov_b32_e32 v82, v48
	v_mov_b32_e32 v79, v41
	v_mov_b32_e32 v83, v49
	v_mov_b32_e32 v84, v38
	v_mov_b32_e32 v88, v46
	v_mov_b32_e32 v85, v39
	v_mov_b32_e32 v89, v47
	v_mov_b32_e32 v86, v40
	v_mov_b32_e32 v90, v48
	v_mov_b32_e32 v87, v41
	v_mov_b32_e32 v91, v49
	global_load_dwordx4 v[224:227], v232, s[2:3] offset:3072
	global_load_dwordx4 v[228:231], v232, s[40:41] offset:3072
	s_add_u32 s2, s2, 0x1000
	s_addc_u32 s3, s3, 0
	s_add_u32 s40, s40, 0x1000
	s_addc_u32 s41, s41, 0
	s_waitcnt vmcnt(29)
	v_readlane_b32 s48, v20, 32
	v_readlane_b32 s58, v25, 32
	v_readlane_b32 s50, v21, 32
	v_readlane_b32 s60, v26, 32
	v_readlane_b32 s52, v22, 32
	v_readlane_b32 s62, v27, 32
	v_readlane_b32 s54, v23, 32
	v_readlane_b32 s64, v28, 32
	v_readlane_b32 s56, v24, 32
	v_readlane_b32 s66, v29, 32
	v_pk_fma_f32 v[52:53], v[168:169], s[48:49], v[52:53] op_sel_hi:[1,0,1]
	v_pk_fma_f32 v[54:55], v[170:171], s[48:49], v[54:55] op_sel_hi:[1,0,1]
	v_pk_fma_f32 v[56:57], v[172:173], s[58:59], v[56:57] op_sel_hi:[1,0,1]
	v_pk_fma_f32 v[58:59], v[174:175], s[58:59], v[58:59] op_sel_hi:[1,0,1]
	v_pk_fma_f32 v[60:61], v[168:169], s[50:51], v[60:61] op_sel_hi:[1,0,1]
	v_pk_fma_f32 v[62:63], v[170:171], s[50:51], v[62:63] op_sel_hi:[1,0,1]
	v_pk_fma_f32 v[64:65], v[172:173], s[60:61], v[64:65] op_sel_hi:[1,0,1]
	v_pk_fma_f32 v[66:67], v[174:175], s[60:61], v[66:67] op_sel_hi:[1,0,1]
	v_pk_fma_f32 v[68:69], v[168:169], s[52:53], v[68:69] op_sel_hi:[1,0,1]
	v_pk_fma_f32 v[70:71], v[170:171], s[52:53], v[70:71] op_sel_hi:[1,0,1]
	v_pk_fma_f32 v[72:73], v[172:173], s[62:63], v[72:73] op_sel_hi:[1,0,1]
	v_pk_fma_f32 v[74:75], v[174:175], s[62:63], v[74:75] op_sel_hi:[1,0,1]
	v_pk_fma_f32 v[76:77], v[168:169], s[54:55], v[76:77] op_sel_hi:[1,0,1]
	v_pk_fma_f32 v[78:79], v[170:171], s[54:55], v[78:79] op_sel_hi:[1,0,1]
	v_pk_fma_f32 v[80:81], v[172:173], s[64:65], v[80:81] op_sel_hi:[1,0,1]
	v_pk_fma_f32 v[82:83], v[174:175], s[64:65], v[82:83] op_sel_hi:[1,0,1]
	v_pk_fma_f32 v[84:85], v[168:169], s[56:57], v[84:85] op_sel_hi:[1,0,1]
	v_pk_fma_f32 v[86:87], v[170:171], s[56:57], v[86:87] op_sel_hi:[1,0,1]
	v_pk_fma_f32 v[88:89], v[172:173], s[66:67], v[88:89] op_sel_hi:[1,0,1]
	v_pk_fma_f32 v[90:91], v[174:175], s[66:67], v[90:91] op_sel_hi:[1,0,1]
	global_load_dwordx4 v[168:171], v232, s[2:3]
	global_load_dwordx4 v[172:175], v232, s[40:41]
	s_waitcnt vmcnt(29)
	v_readlane_b32 s48, v20, 33
	v_readlane_b32 s58, v25, 33
	v_readlane_b32 s50, v21, 33
	v_readlane_b32 s60, v26, 33
	v_readlane_b32 s52, v22, 33
	v_readlane_b32 s62, v27, 33
	v_readlane_b32 s54, v23, 33
	v_readlane_b32 s64, v28, 33
	v_readlane_b32 s56, v24, 33
	v_readlane_b32 s66, v29, 33
	v_pk_fma_f32 v[52:53], v[176:177], s[48:49], v[52:53] op_sel_hi:[1,0,1]
	v_pk_fma_f32 v[54:55], v[178:179], s[48:49], v[54:55] op_sel_hi:[1,0,1]
	v_pk_fma_f32 v[56:57], v[180:181], s[58:59], v[56:57] op_sel_hi:[1,0,1]
	v_pk_fma_f32 v[58:59], v[182:183], s[58:59], v[58:59] op_sel_hi:[1,0,1]
	v_pk_fma_f32 v[60:61], v[176:177], s[50:51], v[60:61] op_sel_hi:[1,0,1]
	v_pk_fma_f32 v[62:63], v[178:179], s[50:51], v[62:63] op_sel_hi:[1,0,1]
	v_pk_fma_f32 v[64:65], v[180:181], s[60:61], v[64:65] op_sel_hi:[1,0,1]
	v_pk_fma_f32 v[66:67], v[182:183], s[60:61], v[66:67] op_sel_hi:[1,0,1]
	v_pk_fma_f32 v[68:69], v[176:177], s[52:53], v[68:69] op_sel_hi:[1,0,1]
	v_pk_fma_f32 v[70:71], v[178:179], s[52:53], v[70:71] op_sel_hi:[1,0,1]
	v_pk_fma_f32 v[72:73], v[180:181], s[62:63], v[72:73] op_sel_hi:[1,0,1]
	v_pk_fma_f32 v[74:75], v[182:183], s[62:63], v[74:75] op_sel_hi:[1,0,1]
	v_pk_fma_f32 v[76:77], v[176:177], s[54:55], v[76:77] op_sel_hi:[1,0,1]
	v_pk_fma_f32 v[78:79], v[178:179], s[54:55], v[78:79] op_sel_hi:[1,0,1]
	v_pk_fma_f32 v[80:81], v[180:181], s[64:65], v[80:81] op_sel_hi:[1,0,1]
	v_pk_fma_f32 v[82:83], v[182:183], s[64:65], v[82:83] op_sel_hi:[1,0,1]
	v_pk_fma_f32 v[84:85], v[176:177], s[56:57], v[84:85] op_sel_hi:[1,0,1]
	v_pk_fma_f32 v[86:87], v[178:179], s[56:57], v[86:87] op_sel_hi:[1,0,1]
	v_pk_fma_f32 v[88:89], v[180:181], s[66:67], v[88:89] op_sel_hi:[1,0,1]
	v_pk_fma_f32 v[90:91], v[182:183], s[66:67], v[90:91] op_sel_hi:[1,0,1]
	global_load_dwordx4 v[176:179], v232, s[2:3] offset:1024
	global_load_dwordx4 v[180:183], v232, s[40:41] offset:1024
	s_waitcnt vmcnt(29)
	v_readlane_b32 s48, v20, 34
	v_readlane_b32 s58, v25, 34
	v_readlane_b32 s50, v21, 34
	v_readlane_b32 s60, v26, 34
	v_readlane_b32 s52, v22, 34
	v_readlane_b32 s62, v27, 34
	v_readlane_b32 s54, v23, 34
	v_readlane_b32 s64, v28, 34
	v_readlane_b32 s56, v24, 34
	v_readlane_b32 s66, v29, 34
	v_pk_fma_f32 v[52:53], v[184:185], s[48:49], v[52:53] op_sel_hi:[1,0,1]
	v_pk_fma_f32 v[54:55], v[186:187], s[48:49], v[54:55] op_sel_hi:[1,0,1]
	v_pk_fma_f32 v[56:57], v[188:189], s[58:59], v[56:57] op_sel_hi:[1,0,1]
	v_pk_fma_f32 v[58:59], v[190:191], s[58:59], v[58:59] op_sel_hi:[1,0,1]
	v_pk_fma_f32 v[60:61], v[184:185], s[50:51], v[60:61] op_sel_hi:[1,0,1]
	v_pk_fma_f32 v[62:63], v[186:187], s[50:51], v[62:63] op_sel_hi:[1,0,1]
	v_pk_fma_f32 v[64:65], v[188:189], s[60:61], v[64:65] op_sel_hi:[1,0,1]
	v_pk_fma_f32 v[66:67], v[190:191], s[60:61], v[66:67] op_sel_hi:[1,0,1]
	v_pk_fma_f32 v[68:69], v[184:185], s[52:53], v[68:69] op_sel_hi:[1,0,1]
	v_pk_fma_f32 v[70:71], v[186:187], s[52:53], v[70:71] op_sel_hi:[1,0,1]
	v_pk_fma_f32 v[72:73], v[188:189], s[62:63], v[72:73] op_sel_hi:[1,0,1]
	v_pk_fma_f32 v[74:75], v[190:191], s[62:63], v[74:75] op_sel_hi:[1,0,1]
	v_pk_fma_f32 v[76:77], v[184:185], s[54:55], v[76:77] op_sel_hi:[1,0,1]
	v_pk_fma_f32 v[78:79], v[186:187], s[54:55], v[78:79] op_sel_hi:[1,0,1]
	v_pk_fma_f32 v[80:81], v[188:189], s[64:65], v[80:81] op_sel_hi:[1,0,1]
	v_pk_fma_f32 v[82:83], v[190:191], s[64:65], v[82:83] op_sel_hi:[1,0,1]
	v_pk_fma_f32 v[84:85], v[184:185], s[56:57], v[84:85] op_sel_hi:[1,0,1]
	v_pk_fma_f32 v[86:87], v[186:187], s[56:57], v[86:87] op_sel_hi:[1,0,1]
	v_pk_fma_f32 v[88:89], v[188:189], s[66:67], v[88:89] op_sel_hi:[1,0,1]
	v_pk_fma_f32 v[90:91], v[190:191], s[66:67], v[90:91] op_sel_hi:[1,0,1]
	global_load_dwordx4 v[184:187], v232, s[2:3] offset:2048
	global_load_dwordx4 v[188:191], v232, s[40:41] offset:2048
	s_waitcnt vmcnt(29)
	v_readlane_b32 s48, v20, 35
	v_readlane_b32 s58, v25, 35
	v_readlane_b32 s50, v21, 35
	v_readlane_b32 s60, v26, 35
	v_readlane_b32 s52, v22, 35
	v_readlane_b32 s62, v27, 35
	v_readlane_b32 s54, v23, 35
	v_readlane_b32 s64, v28, 35
	v_readlane_b32 s56, v24, 35
	v_readlane_b32 s66, v29, 35
	v_pk_fma_f32 v[52:53], v[192:193], s[48:49], v[52:53] op_sel_hi:[1,0,1]
	v_pk_fma_f32 v[54:55], v[194:195], s[48:49], v[54:55] op_sel_hi:[1,0,1]
	v_pk_fma_f32 v[56:57], v[196:197], s[58:59], v[56:57] op_sel_hi:[1,0,1]
	v_pk_fma_f32 v[58:59], v[198:199], s[58:59], v[58:59] op_sel_hi:[1,0,1]
	v_pk_fma_f32 v[60:61], v[192:193], s[50:51], v[60:61] op_sel_hi:[1,0,1]
	v_pk_fma_f32 v[62:63], v[194:195], s[50:51], v[62:63] op_sel_hi:[1,0,1]
	v_pk_fma_f32 v[64:65], v[196:197], s[60:61], v[64:65] op_sel_hi:[1,0,1]
	v_pk_fma_f32 v[66:67], v[198:199], s[60:61], v[66:67] op_sel_hi:[1,0,1]
	v_pk_fma_f32 v[68:69], v[192:193], s[52:53], v[68:69] op_sel_hi:[1,0,1]
	v_pk_fma_f32 v[70:71], v[194:195], s[52:53], v[70:71] op_sel_hi:[1,0,1]
	v_pk_fma_f32 v[72:73], v[196:197], s[62:63], v[72:73] op_sel_hi:[1,0,1]
	v_pk_fma_f32 v[74:75], v[198:199], s[62:63], v[74:75] op_sel_hi:[1,0,1]
	v_pk_fma_f32 v[76:77], v[192:193], s[54:55], v[76:77] op_sel_hi:[1,0,1]
	v_pk_fma_f32 v[78:79], v[194:195], s[54:55], v[78:79] op_sel_hi:[1,0,1]
	v_pk_fma_f32 v[80:81], v[196:197], s[64:65], v[80:81] op_sel_hi:[1,0,1]
	v_pk_fma_f32 v[82:83], v[198:199], s[64:65], v[82:83] op_sel_hi:[1,0,1]
	v_pk_fma_f32 v[84:85], v[192:193], s[56:57], v[84:85] op_sel_hi:[1,0,1]
	v_pk_fma_f32 v[86:87], v[194:195], s[56:57], v[86:87] op_sel_hi:[1,0,1]
	v_pk_fma_f32 v[88:89], v[196:197], s[66:67], v[88:89] op_sel_hi:[1,0,1]
	v_pk_fma_f32 v[90:91], v[198:199], s[66:67], v[90:91] op_sel_hi:[1,0,1]
	global_load_dwordx4 v[192:195], v232, s[2:3] offset:3072
	global_load_dwordx4 v[196:199], v232, s[40:41] offset:3072
	s_add_u32 s2, s2, 0x1000
	s_addc_u32 s3, s3, 0
	s_add_u32 s40, s40, 0x1000
	s_addc_u32 s41, s41, 0
	s_waitcnt vmcnt(29)
	v_readlane_b32 s48, v20, 36
	v_readlane_b32 s58, v25, 36
	v_readlane_b32 s50, v21, 36
	v_readlane_b32 s60, v26, 36
	v_readlane_b32 s52, v22, 36
	v_readlane_b32 s62, v27, 36
	v_readlane_b32 s54, v23, 36
	v_readlane_b32 s64, v28, 36
	v_readlane_b32 s56, v24, 36
	v_readlane_b32 s66, v29, 36
	v_pk_fma_f32 v[52:53], v[200:201], s[48:49], v[52:53] op_sel_hi:[1,0,1]
	v_pk_fma_f32 v[54:55], v[202:203], s[48:49], v[54:55] op_sel_hi:[1,0,1]
	v_pk_fma_f32 v[56:57], v[204:205], s[58:59], v[56:57] op_sel_hi:[1,0,1]
	v_pk_fma_f32 v[58:59], v[206:207], s[58:59], v[58:59] op_sel_hi:[1,0,1]
	v_pk_fma_f32 v[60:61], v[200:201], s[50:51], v[60:61] op_sel_hi:[1,0,1]
	v_pk_fma_f32 v[62:63], v[202:203], s[50:51], v[62:63] op_sel_hi:[1,0,1]
	v_pk_fma_f32 v[64:65], v[204:205], s[60:61], v[64:65] op_sel_hi:[1,0,1]
	v_pk_fma_f32 v[66:67], v[206:207], s[60:61], v[66:67] op_sel_hi:[1,0,1]
	v_pk_fma_f32 v[68:69], v[200:201], s[52:53], v[68:69] op_sel_hi:[1,0,1]
	v_pk_fma_f32 v[70:71], v[202:203], s[52:53], v[70:71] op_sel_hi:[1,0,1]
	v_pk_fma_f32 v[72:73], v[204:205], s[62:63], v[72:73] op_sel_hi:[1,0,1]
	v_pk_fma_f32 v[74:75], v[206:207], s[62:63], v[74:75] op_sel_hi:[1,0,1]
	v_pk_fma_f32 v[76:77], v[200:201], s[54:55], v[76:77] op_sel_hi:[1,0,1]
	v_pk_fma_f32 v[78:79], v[202:203], s[54:55], v[78:79] op_sel_hi:[1,0,1]
	v_pk_fma_f32 v[80:81], v[204:205], s[64:65], v[80:81] op_sel_hi:[1,0,1]
	v_pk_fma_f32 v[82:83], v[206:207], s[64:65], v[82:83] op_sel_hi:[1,0,1]
	v_pk_fma_f32 v[84:85], v[200:201], s[56:57], v[84:85] op_sel_hi:[1,0,1]
	v_pk_fma_f32 v[86:87], v[202:203], s[56:57], v[86:87] op_sel_hi:[1,0,1]
	v_pk_fma_f32 v[88:89], v[204:205], s[66:67], v[88:89] op_sel_hi:[1,0,1]
	v_pk_fma_f32 v[90:91], v[206:207], s[66:67], v[90:91] op_sel_hi:[1,0,1]
	global_load_dwordx4 v[200:203], v232, s[2:3]
	global_load_dwordx4 v[204:207], v232, s[40:41]
	s_waitcnt vmcnt(29)
	v_readlane_b32 s48, v20, 37
	v_readlane_b32 s58, v25, 37
	v_readlane_b32 s50, v21, 37
	v_readlane_b32 s60, v26, 37
	v_readlane_b32 s52, v22, 37
	v_readlane_b32 s62, v27, 37
	v_readlane_b32 s54, v23, 37
	v_readlane_b32 s64, v28, 37
	v_readlane_b32 s56, v24, 37
	v_readlane_b32 s66, v29, 37
	v_pk_fma_f32 v[52:53], v[208:209], s[48:49], v[52:53] op_sel_hi:[1,0,1]
	v_pk_fma_f32 v[54:55], v[210:211], s[48:49], v[54:55] op_sel_hi:[1,0,1]
	v_pk_fma_f32 v[56:57], v[212:213], s[58:59], v[56:57] op_sel_hi:[1,0,1]
	v_pk_fma_f32 v[58:59], v[214:215], s[58:59], v[58:59] op_sel_hi:[1,0,1]
	v_pk_fma_f32 v[60:61], v[208:209], s[50:51], v[60:61] op_sel_hi:[1,0,1]
	v_pk_fma_f32 v[62:63], v[210:211], s[50:51], v[62:63] op_sel_hi:[1,0,1]
	v_pk_fma_f32 v[64:65], v[212:213], s[60:61], v[64:65] op_sel_hi:[1,0,1]
	v_pk_fma_f32 v[66:67], v[214:215], s[60:61], v[66:67] op_sel_hi:[1,0,1]
	v_pk_fma_f32 v[68:69], v[208:209], s[52:53], v[68:69] op_sel_hi:[1,0,1]
	v_pk_fma_f32 v[70:71], v[210:211], s[52:53], v[70:71] op_sel_hi:[1,0,1]
	v_pk_fma_f32 v[72:73], v[212:213], s[62:63], v[72:73] op_sel_hi:[1,0,1]
	v_pk_fma_f32 v[74:75], v[214:215], s[62:63], v[74:75] op_sel_hi:[1,0,1]
	v_pk_fma_f32 v[76:77], v[208:209], s[54:55], v[76:77] op_sel_hi:[1,0,1]
	v_pk_fma_f32 v[78:79], v[210:211], s[54:55], v[78:79] op_sel_hi:[1,0,1]
	v_pk_fma_f32 v[80:81], v[212:213], s[64:65], v[80:81] op_sel_hi:[1,0,1]
	v_pk_fma_f32 v[82:83], v[214:215], s[64:65], v[82:83] op_sel_hi:[1,0,1]
	v_pk_fma_f32 v[84:85], v[208:209], s[56:57], v[84:85] op_sel_hi:[1,0,1]
	v_pk_fma_f32 v[86:87], v[210:211], s[56:57], v[86:87] op_sel_hi:[1,0,1]
	v_pk_fma_f32 v[88:89], v[212:213], s[66:67], v[88:89] op_sel_hi:[1,0,1]
	v_pk_fma_f32 v[90:91], v[214:215], s[66:67], v[90:91] op_sel_hi:[1,0,1]
	global_load_dwordx4 v[208:211], v232, s[2:3] offset:1024
	global_load_dwordx4 v[212:215], v232, s[40:41] offset:1024
	s_waitcnt vmcnt(29)
	v_readlane_b32 s48, v20, 38
	v_readlane_b32 s58, v25, 38
	v_readlane_b32 s50, v21, 38
	v_readlane_b32 s60, v26, 38
	v_readlane_b32 s52, v22, 38
	v_readlane_b32 s62, v27, 38
	v_readlane_b32 s54, v23, 38
	v_readlane_b32 s64, v28, 38
	v_readlane_b32 s56, v24, 38
	v_readlane_b32 s66, v29, 38
	v_pk_fma_f32 v[52:53], v[216:217], s[48:49], v[52:53] op_sel_hi:[1,0,1]
	v_pk_fma_f32 v[54:55], v[218:219], s[48:49], v[54:55] op_sel_hi:[1,0,1]
	v_pk_fma_f32 v[56:57], v[220:221], s[58:59], v[56:57] op_sel_hi:[1,0,1]
	v_pk_fma_f32 v[58:59], v[222:223], s[58:59], v[58:59] op_sel_hi:[1,0,1]
	v_pk_fma_f32 v[60:61], v[216:217], s[50:51], v[60:61] op_sel_hi:[1,0,1]
	v_pk_fma_f32 v[62:63], v[218:219], s[50:51], v[62:63] op_sel_hi:[1,0,1]
	v_pk_fma_f32 v[64:65], v[220:221], s[60:61], v[64:65] op_sel_hi:[1,0,1]
	v_pk_fma_f32 v[66:67], v[222:223], s[60:61], v[66:67] op_sel_hi:[1,0,1]
	v_pk_fma_f32 v[68:69], v[216:217], s[52:53], v[68:69] op_sel_hi:[1,0,1]
	v_pk_fma_f32 v[70:71], v[218:219], s[52:53], v[70:71] op_sel_hi:[1,0,1]
	v_pk_fma_f32 v[72:73], v[220:221], s[62:63], v[72:73] op_sel_hi:[1,0,1]
	v_pk_fma_f32 v[74:75], v[222:223], s[62:63], v[74:75] op_sel_hi:[1,0,1]
	v_pk_fma_f32 v[76:77], v[216:217], s[54:55], v[76:77] op_sel_hi:[1,0,1]
	v_pk_fma_f32 v[78:79], v[218:219], s[54:55], v[78:79] op_sel_hi:[1,0,1]
	v_pk_fma_f32 v[80:81], v[220:221], s[64:65], v[80:81] op_sel_hi:[1,0,1]
	v_pk_fma_f32 v[82:83], v[222:223], s[64:65], v[82:83] op_sel_hi:[1,0,1]
	v_pk_fma_f32 v[84:85], v[216:217], s[56:57], v[84:85] op_sel_hi:[1,0,1]
	v_pk_fma_f32 v[86:87], v[218:219], s[56:57], v[86:87] op_sel_hi:[1,0,1]
	v_pk_fma_f32 v[88:89], v[220:221], s[66:67], v[88:89] op_sel_hi:[1,0,1]
	v_pk_fma_f32 v[90:91], v[222:223], s[66:67], v[90:91] op_sel_hi:[1,0,1]
	global_load_dwordx4 v[216:219], v232, s[2:3] offset:2048
	global_load_dwordx4 v[220:223], v232, s[40:41] offset:2048
	s_waitcnt vmcnt(14)
	v_readlane_b32 s48, v20, 39
	v_readlane_b32 s58, v25, 39
	v_readlane_b32 s50, v21, 39
	v_readlane_b32 s60, v26, 39
	v_readlane_b32 s52, v22, 39
	v_readlane_b32 s62, v27, 39
	v_readlane_b32 s54, v23, 39
	v_readlane_b32 s64, v28, 39
	v_readlane_b32 s56, v24, 39
	v_readlane_b32 s66, v29, 39
	v_pk_fma_f32 v[52:53], v[224:225], s[48:49], v[52:53] op_sel_hi:[1,0,1]
	v_pk_fma_f32 v[54:55], v[226:227], s[48:49], v[54:55] op_sel_hi:[1,0,1]
	v_pk_fma_f32 v[56:57], v[228:229], s[58:59], v[56:57] op_sel_hi:[1,0,1]
	v_pk_fma_f32 v[58:59], v[230:231], s[58:59], v[58:59] op_sel_hi:[1,0,1]
	v_pk_fma_f32 v[60:61], v[224:225], s[50:51], v[60:61] op_sel_hi:[1,0,1]
	v_pk_fma_f32 v[62:63], v[226:227], s[50:51], v[62:63] op_sel_hi:[1,0,1]
	v_pk_fma_f32 v[64:65], v[228:229], s[60:61], v[64:65] op_sel_hi:[1,0,1]
	v_pk_fma_f32 v[66:67], v[230:231], s[60:61], v[66:67] op_sel_hi:[1,0,1]
	v_pk_fma_f32 v[68:69], v[224:225], s[52:53], v[68:69] op_sel_hi:[1,0,1]
	v_pk_fma_f32 v[70:71], v[226:227], s[52:53], v[70:71] op_sel_hi:[1,0,1]
	v_pk_fma_f32 v[72:73], v[228:229], s[62:63], v[72:73] op_sel_hi:[1,0,1]
	v_pk_fma_f32 v[74:75], v[230:231], s[62:63], v[74:75] op_sel_hi:[1,0,1]
	v_pk_fma_f32 v[76:77], v[224:225], s[54:55], v[76:77] op_sel_hi:[1,0,1]
	v_pk_fma_f32 v[78:79], v[226:227], s[54:55], v[78:79] op_sel_hi:[1,0,1]
	v_pk_fma_f32 v[80:81], v[228:229], s[64:65], v[80:81] op_sel_hi:[1,0,1]
	v_pk_fma_f32 v[82:83], v[230:231], s[64:65], v[82:83] op_sel_hi:[1,0,1]
	v_pk_fma_f32 v[84:85], v[224:225], s[56:57], v[84:85] op_sel_hi:[1,0,1]
	v_pk_fma_f32 v[86:87], v[226:227], s[56:57], v[86:87] op_sel_hi:[1,0,1]
	v_pk_fma_f32 v[88:89], v[228:229], s[66:67], v[88:89] op_sel_hi:[1,0,1]
	v_pk_fma_f32 v[90:91], v[230:231], s[66:67], v[90:91] op_sel_hi:[1,0,1]
	global_load_dwordx4 v[224:227], v232, s[2:3] offset:3072
	global_load_dwordx4 v[228:231], v232, s[40:41] offset:3072
	s_add_u32 s2, s2, 0x1000
	s_addc_u32 s3, s3, 0
	s_add_u32 s40, s40, 0x1000
	s_addc_u32 s41, s41, 0
	s_waitcnt vmcnt(14)
	v_readlane_b32 s48, v20, 40
	v_readlane_b32 s58, v25, 40
	v_readlane_b32 s50, v21, 40
	v_readlane_b32 s60, v26, 40
	v_readlane_b32 s52, v22, 40
	v_readlane_b32 s62, v27, 40
	v_readlane_b32 s54, v23, 40
	v_readlane_b32 s64, v28, 40
	v_readlane_b32 s56, v24, 40
	v_readlane_b32 s66, v29, 40
	v_pk_fma_f32 v[52:53], v[168:169], s[48:49], v[52:53] op_sel_hi:[1,0,1]
	v_pk_fma_f32 v[54:55], v[170:171], s[48:49], v[54:55] op_sel_hi:[1,0,1]
	v_pk_fma_f32 v[56:57], v[172:173], s[58:59], v[56:57] op_sel_hi:[1,0,1]
	v_pk_fma_f32 v[58:59], v[174:175], s[58:59], v[58:59] op_sel_hi:[1,0,1]
	v_pk_fma_f32 v[60:61], v[168:169], s[50:51], v[60:61] op_sel_hi:[1,0,1]
	v_pk_fma_f32 v[62:63], v[170:171], s[50:51], v[62:63] op_sel_hi:[1,0,1]
	v_pk_fma_f32 v[64:65], v[172:173], s[60:61], v[64:65] op_sel_hi:[1,0,1]
	v_pk_fma_f32 v[66:67], v[174:175], s[60:61], v[66:67] op_sel_hi:[1,0,1]
	v_pk_fma_f32 v[68:69], v[168:169], s[52:53], v[68:69] op_sel_hi:[1,0,1]
	v_pk_fma_f32 v[70:71], v[170:171], s[52:53], v[70:71] op_sel_hi:[1,0,1]
	v_pk_fma_f32 v[72:73], v[172:173], s[62:63], v[72:73] op_sel_hi:[1,0,1]
	v_pk_fma_f32 v[74:75], v[174:175], s[62:63], v[74:75] op_sel_hi:[1,0,1]
	v_pk_fma_f32 v[76:77], v[168:169], s[54:55], v[76:77] op_sel_hi:[1,0,1]
	v_pk_fma_f32 v[78:79], v[170:171], s[54:55], v[78:79] op_sel_hi:[1,0,1]
	v_pk_fma_f32 v[80:81], v[172:173], s[64:65], v[80:81] op_sel_hi:[1,0,1]
	v_pk_fma_f32 v[82:83], v[174:175], s[64:65], v[82:83] op_sel_hi:[1,0,1]
	v_pk_fma_f32 v[84:85], v[168:169], s[56:57], v[84:85] op_sel_hi:[1,0,1]
	v_pk_fma_f32 v[86:87], v[170:171], s[56:57], v[86:87] op_sel_hi:[1,0,1]
	v_pk_fma_f32 v[88:89], v[172:173], s[66:67], v[88:89] op_sel_hi:[1,0,1]
	v_pk_fma_f32 v[90:91], v[174:175], s[66:67], v[90:91] op_sel_hi:[1,0,1]
	global_load_dwordx4 v[168:171], v232, s[2:3]
	global_load_dwordx4 v[172:175], v232, s[40:41]
	s_waitcnt vmcnt(14)
	v_readlane_b32 s48, v20, 41
	v_readlane_b32 s58, v25, 41
	v_readlane_b32 s50, v21, 41
	v_readlane_b32 s60, v26, 41
	v_readlane_b32 s52, v22, 41
	v_readlane_b32 s62, v27, 41
	v_readlane_b32 s54, v23, 41
	v_readlane_b32 s64, v28, 41
	v_readlane_b32 s56, v24, 41
	v_readlane_b32 s66, v29, 41
	v_pk_fma_f32 v[52:53], v[176:177], s[48:49], v[52:53] op_sel_hi:[1,0,1]
	v_pk_fma_f32 v[54:55], v[178:179], s[48:49], v[54:55] op_sel_hi:[1,0,1]
	v_pk_fma_f32 v[56:57], v[180:181], s[58:59], v[56:57] op_sel_hi:[1,0,1]
	v_pk_fma_f32 v[58:59], v[182:183], s[58:59], v[58:59] op_sel_hi:[1,0,1]
	v_pk_fma_f32 v[60:61], v[176:177], s[50:51], v[60:61] op_sel_hi:[1,0,1]
	v_pk_fma_f32 v[62:63], v[178:179], s[50:51], v[62:63] op_sel_hi:[1,0,1]
	v_pk_fma_f32 v[64:65], v[180:181], s[60:61], v[64:65] op_sel_hi:[1,0,1]
	v_pk_fma_f32 v[66:67], v[182:183], s[60:61], v[66:67] op_sel_hi:[1,0,1]
	v_pk_fma_f32 v[68:69], v[176:177], s[52:53], v[68:69] op_sel_hi:[1,0,1]
	v_pk_fma_f32 v[70:71], v[178:179], s[52:53], v[70:71] op_sel_hi:[1,0,1]
	v_pk_fma_f32 v[72:73], v[180:181], s[62:63], v[72:73] op_sel_hi:[1,0,1]
	v_pk_fma_f32 v[74:75], v[182:183], s[62:63], v[74:75] op_sel_hi:[1,0,1]
	v_pk_fma_f32 v[76:77], v[176:177], s[54:55], v[76:77] op_sel_hi:[1,0,1]
	v_pk_fma_f32 v[78:79], v[178:179], s[54:55], v[78:79] op_sel_hi:[1,0,1]
	v_pk_fma_f32 v[80:81], v[180:181], s[64:65], v[80:81] op_sel_hi:[1,0,1]
	v_pk_fma_f32 v[82:83], v[182:183], s[64:65], v[82:83] op_sel_hi:[1,0,1]
	v_pk_fma_f32 v[84:85], v[176:177], s[56:57], v[84:85] op_sel_hi:[1,0,1]
	v_pk_fma_f32 v[86:87], v[178:179], s[56:57], v[86:87] op_sel_hi:[1,0,1]
	v_pk_fma_f32 v[88:89], v[180:181], s[66:67], v[88:89] op_sel_hi:[1,0,1]
	v_pk_fma_f32 v[90:91], v[182:183], s[66:67], v[90:91] op_sel_hi:[1,0,1]
	global_load_dwordx4 v[176:179], v232, s[2:3] offset:1024
	global_load_dwordx4 v[180:183], v232, s[40:41] offset:1024
	s_waitcnt vmcnt(14)
	v_readlane_b32 s48, v20, 42
	v_readlane_b32 s58, v25, 42
	v_readlane_b32 s50, v21, 42
	v_readlane_b32 s60, v26, 42
	v_readlane_b32 s52, v22, 42
	v_readlane_b32 s62, v27, 42
	v_readlane_b32 s54, v23, 42
	v_readlane_b32 s64, v28, 42
	v_readlane_b32 s56, v24, 42
	v_readlane_b32 s66, v29, 42
	v_pk_fma_f32 v[52:53], v[184:185], s[48:49], v[52:53] op_sel_hi:[1,0,1]
	v_pk_fma_f32 v[54:55], v[186:187], s[48:49], v[54:55] op_sel_hi:[1,0,1]
	v_pk_fma_f32 v[56:57], v[188:189], s[58:59], v[56:57] op_sel_hi:[1,0,1]
	v_pk_fma_f32 v[58:59], v[190:191], s[58:59], v[58:59] op_sel_hi:[1,0,1]
	v_pk_fma_f32 v[60:61], v[184:185], s[50:51], v[60:61] op_sel_hi:[1,0,1]
	v_pk_fma_f32 v[62:63], v[186:187], s[50:51], v[62:63] op_sel_hi:[1,0,1]
	v_pk_fma_f32 v[64:65], v[188:189], s[60:61], v[64:65] op_sel_hi:[1,0,1]
	v_pk_fma_f32 v[66:67], v[190:191], s[60:61], v[66:67] op_sel_hi:[1,0,1]
	v_pk_fma_f32 v[68:69], v[184:185], s[52:53], v[68:69] op_sel_hi:[1,0,1]
	v_pk_fma_f32 v[70:71], v[186:187], s[52:53], v[70:71] op_sel_hi:[1,0,1]
	v_pk_fma_f32 v[72:73], v[188:189], s[62:63], v[72:73] op_sel_hi:[1,0,1]
	v_pk_fma_f32 v[74:75], v[190:191], s[62:63], v[74:75] op_sel_hi:[1,0,1]
	v_pk_fma_f32 v[76:77], v[184:185], s[54:55], v[76:77] op_sel_hi:[1,0,1]
	v_pk_fma_f32 v[78:79], v[186:187], s[54:55], v[78:79] op_sel_hi:[1,0,1]
	v_pk_fma_f32 v[80:81], v[188:189], s[64:65], v[80:81] op_sel_hi:[1,0,1]
	v_pk_fma_f32 v[82:83], v[190:191], s[64:65], v[82:83] op_sel_hi:[1,0,1]
	v_pk_fma_f32 v[84:85], v[184:185], s[56:57], v[84:85] op_sel_hi:[1,0,1]
	v_pk_fma_f32 v[86:87], v[186:187], s[56:57], v[86:87] op_sel_hi:[1,0,1]
	v_pk_fma_f32 v[88:89], v[188:189], s[66:67], v[88:89] op_sel_hi:[1,0,1]
	v_pk_fma_f32 v[90:91], v[190:191], s[66:67], v[90:91] op_sel_hi:[1,0,1]
	global_load_dwordx4 v[184:187], v232, s[2:3] offset:2048
	global_load_dwordx4 v[188:191], v232, s[40:41] offset:2048
	s_waitcnt vmcnt(14)
	v_readlane_b32 s48, v20, 43
	v_readlane_b32 s58, v25, 43
	v_readlane_b32 s50, v21, 43
	v_readlane_b32 s60, v26, 43
	v_readlane_b32 s52, v22, 43
	v_readlane_b32 s62, v27, 43
	v_readlane_b32 s54, v23, 43
	v_readlane_b32 s64, v28, 43
	v_readlane_b32 s56, v24, 43
	v_readlane_b32 s66, v29, 43
	v_pk_fma_f32 v[52:53], v[192:193], s[48:49], v[52:53] op_sel_hi:[1,0,1]
	v_pk_fma_f32 v[54:55], v[194:195], s[48:49], v[54:55] op_sel_hi:[1,0,1]
	v_pk_fma_f32 v[56:57], v[196:197], s[58:59], v[56:57] op_sel_hi:[1,0,1]
	v_pk_fma_f32 v[58:59], v[198:199], s[58:59], v[58:59] op_sel_hi:[1,0,1]
	v_pk_fma_f32 v[60:61], v[192:193], s[50:51], v[60:61] op_sel_hi:[1,0,1]
	v_pk_fma_f32 v[62:63], v[194:195], s[50:51], v[62:63] op_sel_hi:[1,0,1]
	v_pk_fma_f32 v[64:65], v[196:197], s[60:61], v[64:65] op_sel_hi:[1,0,1]
	v_pk_fma_f32 v[66:67], v[198:199], s[60:61], v[66:67] op_sel_hi:[1,0,1]
	v_pk_fma_f32 v[68:69], v[192:193], s[52:53], v[68:69] op_sel_hi:[1,0,1]
	v_pk_fma_f32 v[70:71], v[194:195], s[52:53], v[70:71] op_sel_hi:[1,0,1]
	v_pk_fma_f32 v[72:73], v[196:197], s[62:63], v[72:73] op_sel_hi:[1,0,1]
	v_pk_fma_f32 v[74:75], v[198:199], s[62:63], v[74:75] op_sel_hi:[1,0,1]
	v_pk_fma_f32 v[76:77], v[192:193], s[54:55], v[76:77] op_sel_hi:[1,0,1]
	v_pk_fma_f32 v[78:79], v[194:195], s[54:55], v[78:79] op_sel_hi:[1,0,1]
	v_pk_fma_f32 v[80:81], v[196:197], s[64:65], v[80:81] op_sel_hi:[1,0,1]
	v_pk_fma_f32 v[82:83], v[198:199], s[64:65], v[82:83] op_sel_hi:[1,0,1]
	v_pk_fma_f32 v[84:85], v[192:193], s[56:57], v[84:85] op_sel_hi:[1,0,1]
	v_pk_fma_f32 v[86:87], v[194:195], s[56:57], v[86:87] op_sel_hi:[1,0,1]
	v_pk_fma_f32 v[88:89], v[196:197], s[66:67], v[88:89] op_sel_hi:[1,0,1]
	v_pk_fma_f32 v[90:91], v[198:199], s[66:67], v[90:91] op_sel_hi:[1,0,1]
	global_load_dwordx4 v[192:195], v232, s[2:3] offset:3072
	global_load_dwordx4 v[196:199], v232, s[40:41] offset:3072
	s_add_u32 s2, s2, 0x1000
	s_addc_u32 s3, s3, 0
	s_add_u32 s40, s40, 0x1000
	s_addc_u32 s41, s41, 0
	s_waitcnt vmcnt(14)
	v_readlane_b32 s48, v20, 44
	v_readlane_b32 s58, v25, 44
	v_readlane_b32 s50, v21, 44
	v_readlane_b32 s60, v26, 44
	v_readlane_b32 s52, v22, 44
	v_readlane_b32 s62, v27, 44
	v_readlane_b32 s54, v23, 44
	v_readlane_b32 s64, v28, 44
	v_readlane_b32 s56, v24, 44
	v_readlane_b32 s66, v29, 44
	v_pk_fma_f32 v[52:53], v[200:201], s[48:49], v[52:53] op_sel_hi:[1,0,1]
	v_pk_fma_f32 v[54:55], v[202:203], s[48:49], v[54:55] op_sel_hi:[1,0,1]
	v_pk_fma_f32 v[56:57], v[204:205], s[58:59], v[56:57] op_sel_hi:[1,0,1]
	v_pk_fma_f32 v[58:59], v[206:207], s[58:59], v[58:59] op_sel_hi:[1,0,1]
	v_pk_fma_f32 v[60:61], v[200:201], s[50:51], v[60:61] op_sel_hi:[1,0,1]
	v_pk_fma_f32 v[62:63], v[202:203], s[50:51], v[62:63] op_sel_hi:[1,0,1]
	v_pk_fma_f32 v[64:65], v[204:205], s[60:61], v[64:65] op_sel_hi:[1,0,1]
	v_pk_fma_f32 v[66:67], v[206:207], s[60:61], v[66:67] op_sel_hi:[1,0,1]
	v_pk_fma_f32 v[68:69], v[200:201], s[52:53], v[68:69] op_sel_hi:[1,0,1]
	v_pk_fma_f32 v[70:71], v[202:203], s[52:53], v[70:71] op_sel_hi:[1,0,1]
	v_pk_fma_f32 v[72:73], v[204:205], s[62:63], v[72:73] op_sel_hi:[1,0,1]
	v_pk_fma_f32 v[74:75], v[206:207], s[62:63], v[74:75] op_sel_hi:[1,0,1]
	v_pk_fma_f32 v[76:77], v[200:201], s[54:55], v[76:77] op_sel_hi:[1,0,1]
	v_pk_fma_f32 v[78:79], v[202:203], s[54:55], v[78:79] op_sel_hi:[1,0,1]
	v_pk_fma_f32 v[80:81], v[204:205], s[64:65], v[80:81] op_sel_hi:[1,0,1]
	v_pk_fma_f32 v[82:83], v[206:207], s[64:65], v[82:83] op_sel_hi:[1,0,1]
	v_pk_fma_f32 v[84:85], v[200:201], s[56:57], v[84:85] op_sel_hi:[1,0,1]
	v_pk_fma_f32 v[86:87], v[202:203], s[56:57], v[86:87] op_sel_hi:[1,0,1]
	v_pk_fma_f32 v[88:89], v[204:205], s[66:67], v[88:89] op_sel_hi:[1,0,1]
	v_pk_fma_f32 v[90:91], v[206:207], s[66:67], v[90:91] op_sel_hi:[1,0,1]
	global_load_dwordx4 v[200:203], v232, s[2:3]
	global_load_dwordx4 v[204:207], v232, s[40:41]
	s_waitcnt vmcnt(14)
	v_readlane_b32 s48, v20, 45
	v_readlane_b32 s58, v25, 45
	v_readlane_b32 s50, v21, 45
	v_readlane_b32 s60, v26, 45
	v_readlane_b32 s52, v22, 45
	v_readlane_b32 s62, v27, 45
	v_readlane_b32 s54, v23, 45
	v_readlane_b32 s64, v28, 45
	v_readlane_b32 s56, v24, 45
	v_readlane_b32 s66, v29, 45
	v_pk_fma_f32 v[52:53], v[208:209], s[48:49], v[52:53] op_sel_hi:[1,0,1]
	v_pk_fma_f32 v[54:55], v[210:211], s[48:49], v[54:55] op_sel_hi:[1,0,1]
	v_pk_fma_f32 v[56:57], v[212:213], s[58:59], v[56:57] op_sel_hi:[1,0,1]
	v_pk_fma_f32 v[58:59], v[214:215], s[58:59], v[58:59] op_sel_hi:[1,0,1]
	v_pk_fma_f32 v[60:61], v[208:209], s[50:51], v[60:61] op_sel_hi:[1,0,1]
	v_pk_fma_f32 v[62:63], v[210:211], s[50:51], v[62:63] op_sel_hi:[1,0,1]
	v_pk_fma_f32 v[64:65], v[212:213], s[60:61], v[64:65] op_sel_hi:[1,0,1]
	v_pk_fma_f32 v[66:67], v[214:215], s[60:61], v[66:67] op_sel_hi:[1,0,1]
	v_pk_fma_f32 v[68:69], v[208:209], s[52:53], v[68:69] op_sel_hi:[1,0,1]
	v_pk_fma_f32 v[70:71], v[210:211], s[52:53], v[70:71] op_sel_hi:[1,0,1]
	v_pk_fma_f32 v[72:73], v[212:213], s[62:63], v[72:73] op_sel_hi:[1,0,1]
	v_pk_fma_f32 v[74:75], v[214:215], s[62:63], v[74:75] op_sel_hi:[1,0,1]
	v_pk_fma_f32 v[76:77], v[208:209], s[54:55], v[76:77] op_sel_hi:[1,0,1]
	v_pk_fma_f32 v[78:79], v[210:211], s[54:55], v[78:79] op_sel_hi:[1,0,1]
	v_pk_fma_f32 v[80:81], v[212:213], s[64:65], v[80:81] op_sel_hi:[1,0,1]
	v_pk_fma_f32 v[82:83], v[214:215], s[64:65], v[82:83] op_sel_hi:[1,0,1]
	v_pk_fma_f32 v[84:85], v[208:209], s[56:57], v[84:85] op_sel_hi:[1,0,1]
	v_pk_fma_f32 v[86:87], v[210:211], s[56:57], v[86:87] op_sel_hi:[1,0,1]
	v_pk_fma_f32 v[88:89], v[212:213], s[66:67], v[88:89] op_sel_hi:[1,0,1]
	v_pk_fma_f32 v[90:91], v[214:215], s[66:67], v[90:91] op_sel_hi:[1,0,1]
	global_load_dwordx4 v[208:211], v232, s[2:3] offset:1024
	global_load_dwordx4 v[212:215], v232, s[40:41] offset:1024
	s_waitcnt vmcnt(14)
	v_readlane_b32 s48, v20, 46
	v_readlane_b32 s58, v25, 46
	v_readlane_b32 s50, v21, 46
	v_readlane_b32 s60, v26, 46
	v_readlane_b32 s52, v22, 46
	v_readlane_b32 s62, v27, 46
	v_readlane_b32 s54, v23, 46
	v_readlane_b32 s64, v28, 46
	v_readlane_b32 s56, v24, 46
	v_readlane_b32 s66, v29, 46
	v_pk_fma_f32 v[52:53], v[216:217], s[48:49], v[52:53] op_sel_hi:[1,0,1]
	v_pk_fma_f32 v[54:55], v[218:219], s[48:49], v[54:55] op_sel_hi:[1,0,1]
	v_pk_fma_f32 v[56:57], v[220:221], s[58:59], v[56:57] op_sel_hi:[1,0,1]
	v_pk_fma_f32 v[58:59], v[222:223], s[58:59], v[58:59] op_sel_hi:[1,0,1]
	v_pk_fma_f32 v[60:61], v[216:217], s[50:51], v[60:61] op_sel_hi:[1,0,1]
	v_pk_fma_f32 v[62:63], v[218:219], s[50:51], v[62:63] op_sel_hi:[1,0,1]
	v_pk_fma_f32 v[64:65], v[220:221], s[60:61], v[64:65] op_sel_hi:[1,0,1]
	v_pk_fma_f32 v[66:67], v[222:223], s[60:61], v[66:67] op_sel_hi:[1,0,1]
	v_pk_fma_f32 v[68:69], v[216:217], s[52:53], v[68:69] op_sel_hi:[1,0,1]
	v_pk_fma_f32 v[70:71], v[218:219], s[52:53], v[70:71] op_sel_hi:[1,0,1]
	v_pk_fma_f32 v[72:73], v[220:221], s[62:63], v[72:73] op_sel_hi:[1,0,1]
	v_pk_fma_f32 v[74:75], v[222:223], s[62:63], v[74:75] op_sel_hi:[1,0,1]
	v_pk_fma_f32 v[76:77], v[216:217], s[54:55], v[76:77] op_sel_hi:[1,0,1]
	v_pk_fma_f32 v[78:79], v[218:219], s[54:55], v[78:79] op_sel_hi:[1,0,1]
	v_pk_fma_f32 v[80:81], v[220:221], s[64:65], v[80:81] op_sel_hi:[1,0,1]
	v_pk_fma_f32 v[82:83], v[222:223], s[64:65], v[82:83] op_sel_hi:[1,0,1]
	v_pk_fma_f32 v[84:85], v[216:217], s[56:57], v[84:85] op_sel_hi:[1,0,1]
	v_pk_fma_f32 v[86:87], v[218:219], s[56:57], v[86:87] op_sel_hi:[1,0,1]
	v_pk_fma_f32 v[88:89], v[220:221], s[66:67], v[88:89] op_sel_hi:[1,0,1]
	v_pk_fma_f32 v[90:91], v[222:223], s[66:67], v[90:91] op_sel_hi:[1,0,1]
	global_load_dwordx4 v[216:219], v232, s[2:3] offset:2048
	global_load_dwordx4 v[220:223], v232, s[40:41] offset:2048
	s_waitcnt vmcnt(14)
	v_readlane_b32 s48, v20, 47
	v_readlane_b32 s58, v25, 47
	v_readlane_b32 s50, v21, 47
	v_readlane_b32 s60, v26, 47
	v_readlane_b32 s52, v22, 47
	v_readlane_b32 s62, v27, 47
	v_readlane_b32 s54, v23, 47
	v_readlane_b32 s64, v28, 47
	v_readlane_b32 s56, v24, 47
	v_readlane_b32 s66, v29, 47
	v_pk_fma_f32 v[52:53], v[224:225], s[48:49], v[52:53] op_sel_hi:[1,0,1]
	v_pk_fma_f32 v[54:55], v[226:227], s[48:49], v[54:55] op_sel_hi:[1,0,1]
	v_pk_fma_f32 v[56:57], v[228:229], s[58:59], v[56:57] op_sel_hi:[1,0,1]
	v_pk_fma_f32 v[58:59], v[230:231], s[58:59], v[58:59] op_sel_hi:[1,0,1]
	v_pk_fma_f32 v[60:61], v[224:225], s[50:51], v[60:61] op_sel_hi:[1,0,1]
	v_pk_fma_f32 v[62:63], v[226:227], s[50:51], v[62:63] op_sel_hi:[1,0,1]
	v_pk_fma_f32 v[64:65], v[228:229], s[60:61], v[64:65] op_sel_hi:[1,0,1]
	v_pk_fma_f32 v[66:67], v[230:231], s[60:61], v[66:67] op_sel_hi:[1,0,1]
	v_pk_fma_f32 v[68:69], v[224:225], s[52:53], v[68:69] op_sel_hi:[1,0,1]
	v_pk_fma_f32 v[70:71], v[226:227], s[52:53], v[70:71] op_sel_hi:[1,0,1]
	v_pk_fma_f32 v[72:73], v[228:229], s[62:63], v[72:73] op_sel_hi:[1,0,1]
	v_pk_fma_f32 v[74:75], v[230:231], s[62:63], v[74:75] op_sel_hi:[1,0,1]
	v_pk_fma_f32 v[76:77], v[224:225], s[54:55], v[76:77] op_sel_hi:[1,0,1]
	v_pk_fma_f32 v[78:79], v[226:227], s[54:55], v[78:79] op_sel_hi:[1,0,1]
	v_pk_fma_f32 v[80:81], v[228:229], s[64:65], v[80:81] op_sel_hi:[1,0,1]
	v_pk_fma_f32 v[82:83], v[230:231], s[64:65], v[82:83] op_sel_hi:[1,0,1]
	v_pk_fma_f32 v[84:85], v[224:225], s[56:57], v[84:85] op_sel_hi:[1,0,1]
	v_pk_fma_f32 v[86:87], v[226:227], s[56:57], v[86:87] op_sel_hi:[1,0,1]
	v_pk_fma_f32 v[88:89], v[228:229], s[66:67], v[88:89] op_sel_hi:[1,0,1]
	v_pk_fma_f32 v[90:91], v[230:231], s[66:67], v[90:91] op_sel_hi:[1,0,1]
	global_load_dwordx4 v[224:227], v232, s[2:3] offset:3072
	global_load_dwordx4 v[228:231], v232, s[40:41] offset:3072
	s_add_u32 s2, s2, 0x1000
	s_addc_u32 s3, s3, 0
	s_add_u32 s40, s40, 0x1000
	s_addc_u32 s41, s41, 0
	s_waitcnt vmcnt(14)
	v_readlane_b32 s48, v20, 48
	v_readlane_b32 s58, v25, 48
	v_readlane_b32 s50, v21, 48
	v_readlane_b32 s60, v26, 48
	v_readlane_b32 s52, v22, 48
	v_readlane_b32 s62, v27, 48
	v_readlane_b32 s54, v23, 48
	v_readlane_b32 s64, v28, 48
	v_readlane_b32 s56, v24, 48
	v_readlane_b32 s66, v29, 48
	v_pk_fma_f32 v[52:53], v[168:169], s[48:49], v[52:53] op_sel_hi:[1,0,1]
	v_pk_fma_f32 v[54:55], v[170:171], s[48:49], v[54:55] op_sel_hi:[1,0,1]
	v_pk_fma_f32 v[56:57], v[172:173], s[58:59], v[56:57] op_sel_hi:[1,0,1]
	v_pk_fma_f32 v[58:59], v[174:175], s[58:59], v[58:59] op_sel_hi:[1,0,1]
	v_pk_fma_f32 v[60:61], v[168:169], s[50:51], v[60:61] op_sel_hi:[1,0,1]
	v_pk_fma_f32 v[62:63], v[170:171], s[50:51], v[62:63] op_sel_hi:[1,0,1]
	v_pk_fma_f32 v[64:65], v[172:173], s[60:61], v[64:65] op_sel_hi:[1,0,1]
	v_pk_fma_f32 v[66:67], v[174:175], s[60:61], v[66:67] op_sel_hi:[1,0,1]
	v_pk_fma_f32 v[68:69], v[168:169], s[52:53], v[68:69] op_sel_hi:[1,0,1]
	v_pk_fma_f32 v[70:71], v[170:171], s[52:53], v[70:71] op_sel_hi:[1,0,1]
	v_pk_fma_f32 v[72:73], v[172:173], s[62:63], v[72:73] op_sel_hi:[1,0,1]
	v_pk_fma_f32 v[74:75], v[174:175], s[62:63], v[74:75] op_sel_hi:[1,0,1]
	v_pk_fma_f32 v[76:77], v[168:169], s[54:55], v[76:77] op_sel_hi:[1,0,1]
	v_pk_fma_f32 v[78:79], v[170:171], s[54:55], v[78:79] op_sel_hi:[1,0,1]
	v_pk_fma_f32 v[80:81], v[172:173], s[64:65], v[80:81] op_sel_hi:[1,0,1]
	v_pk_fma_f32 v[82:83], v[174:175], s[64:65], v[82:83] op_sel_hi:[1,0,1]
	v_pk_fma_f32 v[84:85], v[168:169], s[56:57], v[84:85] op_sel_hi:[1,0,1]
	v_pk_fma_f32 v[86:87], v[170:171], s[56:57], v[86:87] op_sel_hi:[1,0,1]
	v_pk_fma_f32 v[88:89], v[172:173], s[66:67], v[88:89] op_sel_hi:[1,0,1]
	v_pk_fma_f32 v[90:91], v[174:175], s[66:67], v[90:91] op_sel_hi:[1,0,1]
	global_load_dwordx4 v[168:171], v232, s[2:3]
	global_load_dwordx4 v[172:175], v232, s[40:41]
	s_waitcnt vmcnt(14)
	v_readlane_b32 s48, v20, 49
	v_readlane_b32 s58, v25, 49
	v_readlane_b32 s50, v21, 49
	v_readlane_b32 s60, v26, 49
	v_readlane_b32 s52, v22, 49
	v_readlane_b32 s62, v27, 49
	v_readlane_b32 s54, v23, 49
	v_readlane_b32 s64, v28, 49
	v_readlane_b32 s56, v24, 49
	v_readlane_b32 s66, v29, 49
	v_pk_fma_f32 v[52:53], v[176:177], s[48:49], v[52:53] op_sel_hi:[1,0,1]
	v_pk_fma_f32 v[54:55], v[178:179], s[48:49], v[54:55] op_sel_hi:[1,0,1]
	v_pk_fma_f32 v[56:57], v[180:181], s[58:59], v[56:57] op_sel_hi:[1,0,1]
	v_pk_fma_f32 v[58:59], v[182:183], s[58:59], v[58:59] op_sel_hi:[1,0,1]
	v_pk_fma_f32 v[60:61], v[176:177], s[50:51], v[60:61] op_sel_hi:[1,0,1]
	v_pk_fma_f32 v[62:63], v[178:179], s[50:51], v[62:63] op_sel_hi:[1,0,1]
	v_pk_fma_f32 v[64:65], v[180:181], s[60:61], v[64:65] op_sel_hi:[1,0,1]
	v_pk_fma_f32 v[66:67], v[182:183], s[60:61], v[66:67] op_sel_hi:[1,0,1]
	v_pk_fma_f32 v[68:69], v[176:177], s[52:53], v[68:69] op_sel_hi:[1,0,1]
	v_pk_fma_f32 v[70:71], v[178:179], s[52:53], v[70:71] op_sel_hi:[1,0,1]
	v_pk_fma_f32 v[72:73], v[180:181], s[62:63], v[72:73] op_sel_hi:[1,0,1]
	v_pk_fma_f32 v[74:75], v[182:183], s[62:63], v[74:75] op_sel_hi:[1,0,1]
	v_pk_fma_f32 v[76:77], v[176:177], s[54:55], v[76:77] op_sel_hi:[1,0,1]
	v_pk_fma_f32 v[78:79], v[178:179], s[54:55], v[78:79] op_sel_hi:[1,0,1]
	v_pk_fma_f32 v[80:81], v[180:181], s[64:65], v[80:81] op_sel_hi:[1,0,1]
	v_pk_fma_f32 v[82:83], v[182:183], s[64:65], v[82:83] op_sel_hi:[1,0,1]
	v_pk_fma_f32 v[84:85], v[176:177], s[56:57], v[84:85] op_sel_hi:[1,0,1]
	v_pk_fma_f32 v[86:87], v[178:179], s[56:57], v[86:87] op_sel_hi:[1,0,1]
	v_pk_fma_f32 v[88:89], v[180:181], s[66:67], v[88:89] op_sel_hi:[1,0,1]
	v_pk_fma_f32 v[90:91], v[182:183], s[66:67], v[90:91] op_sel_hi:[1,0,1]
	global_load_dwordx4 v[176:179], v232, s[2:3] offset:1024
	global_load_dwordx4 v[180:183], v232, s[40:41] offset:1024
	s_waitcnt vmcnt(14)
	v_readlane_b32 s48, v20, 50
	v_readlane_b32 s58, v25, 50
	v_readlane_b32 s50, v21, 50
	v_readlane_b32 s60, v26, 50
	v_readlane_b32 s52, v22, 50
	v_readlane_b32 s62, v27, 50
	v_readlane_b32 s54, v23, 50
	v_readlane_b32 s64, v28, 50
	v_readlane_b32 s56, v24, 50
	v_readlane_b32 s66, v29, 50
	v_pk_fma_f32 v[52:53], v[184:185], s[48:49], v[52:53] op_sel_hi:[1,0,1]
	v_pk_fma_f32 v[54:55], v[186:187], s[48:49], v[54:55] op_sel_hi:[1,0,1]
	v_pk_fma_f32 v[56:57], v[188:189], s[58:59], v[56:57] op_sel_hi:[1,0,1]
	v_pk_fma_f32 v[58:59], v[190:191], s[58:59], v[58:59] op_sel_hi:[1,0,1]
	v_pk_fma_f32 v[60:61], v[184:185], s[50:51], v[60:61] op_sel_hi:[1,0,1]
	v_pk_fma_f32 v[62:63], v[186:187], s[50:51], v[62:63] op_sel_hi:[1,0,1]
	v_pk_fma_f32 v[64:65], v[188:189], s[60:61], v[64:65] op_sel_hi:[1,0,1]
	v_pk_fma_f32 v[66:67], v[190:191], s[60:61], v[66:67] op_sel_hi:[1,0,1]
	v_pk_fma_f32 v[68:69], v[184:185], s[52:53], v[68:69] op_sel_hi:[1,0,1]
	v_pk_fma_f32 v[70:71], v[186:187], s[52:53], v[70:71] op_sel_hi:[1,0,1]
	v_pk_fma_f32 v[72:73], v[188:189], s[62:63], v[72:73] op_sel_hi:[1,0,1]
	v_pk_fma_f32 v[74:75], v[190:191], s[62:63], v[74:75] op_sel_hi:[1,0,1]
	v_pk_fma_f32 v[76:77], v[184:185], s[54:55], v[76:77] op_sel_hi:[1,0,1]
	v_pk_fma_f32 v[78:79], v[186:187], s[54:55], v[78:79] op_sel_hi:[1,0,1]
	v_pk_fma_f32 v[80:81], v[188:189], s[64:65], v[80:81] op_sel_hi:[1,0,1]
	v_pk_fma_f32 v[82:83], v[190:191], s[64:65], v[82:83] op_sel_hi:[1,0,1]
	v_pk_fma_f32 v[84:85], v[184:185], s[56:57], v[84:85] op_sel_hi:[1,0,1]
	v_pk_fma_f32 v[86:87], v[186:187], s[56:57], v[86:87] op_sel_hi:[1,0,1]
	v_pk_fma_f32 v[88:89], v[188:189], s[66:67], v[88:89] op_sel_hi:[1,0,1]
	v_pk_fma_f32 v[90:91], v[190:191], s[66:67], v[90:91] op_sel_hi:[1,0,1]
	global_load_dwordx4 v[184:187], v232, s[2:3] offset:2048
	global_load_dwordx4 v[188:191], v232, s[40:41] offset:2048
	s_waitcnt vmcnt(14)
	v_readlane_b32 s48, v20, 51
	v_readlane_b32 s58, v25, 51
	v_readlane_b32 s50, v21, 51
	v_readlane_b32 s60, v26, 51
	v_readlane_b32 s52, v22, 51
	v_readlane_b32 s62, v27, 51
	v_readlane_b32 s54, v23, 51
	v_readlane_b32 s64, v28, 51
	v_readlane_b32 s56, v24, 51
	v_readlane_b32 s66, v29, 51
	v_pk_fma_f32 v[52:53], v[192:193], s[48:49], v[52:53] op_sel_hi:[1,0,1]
	v_pk_fma_f32 v[54:55], v[194:195], s[48:49], v[54:55] op_sel_hi:[1,0,1]
	v_pk_fma_f32 v[56:57], v[196:197], s[58:59], v[56:57] op_sel_hi:[1,0,1]
	v_pk_fma_f32 v[58:59], v[198:199], s[58:59], v[58:59] op_sel_hi:[1,0,1]
	v_pk_fma_f32 v[60:61], v[192:193], s[50:51], v[60:61] op_sel_hi:[1,0,1]
	v_pk_fma_f32 v[62:63], v[194:195], s[50:51], v[62:63] op_sel_hi:[1,0,1]
	v_pk_fma_f32 v[64:65], v[196:197], s[60:61], v[64:65] op_sel_hi:[1,0,1]
	v_pk_fma_f32 v[66:67], v[198:199], s[60:61], v[66:67] op_sel_hi:[1,0,1]
	v_pk_fma_f32 v[68:69], v[192:193], s[52:53], v[68:69] op_sel_hi:[1,0,1]
	v_pk_fma_f32 v[70:71], v[194:195], s[52:53], v[70:71] op_sel_hi:[1,0,1]
	v_pk_fma_f32 v[72:73], v[196:197], s[62:63], v[72:73] op_sel_hi:[1,0,1]
	v_pk_fma_f32 v[74:75], v[198:199], s[62:63], v[74:75] op_sel_hi:[1,0,1]
	v_pk_fma_f32 v[76:77], v[192:193], s[54:55], v[76:77] op_sel_hi:[1,0,1]
	v_pk_fma_f32 v[78:79], v[194:195], s[54:55], v[78:79] op_sel_hi:[1,0,1]
	v_pk_fma_f32 v[80:81], v[196:197], s[64:65], v[80:81] op_sel_hi:[1,0,1]
	v_pk_fma_f32 v[82:83], v[198:199], s[64:65], v[82:83] op_sel_hi:[1,0,1]
	v_pk_fma_f32 v[84:85], v[192:193], s[56:57], v[84:85] op_sel_hi:[1,0,1]
	v_pk_fma_f32 v[86:87], v[194:195], s[56:57], v[86:87] op_sel_hi:[1,0,1]
	v_pk_fma_f32 v[88:89], v[196:197], s[66:67], v[88:89] op_sel_hi:[1,0,1]
	v_pk_fma_f32 v[90:91], v[198:199], s[66:67], v[90:91] op_sel_hi:[1,0,1]
	global_load_dwordx4 v[192:195], v232, s[2:3] offset:3072
	global_load_dwordx4 v[196:199], v232, s[40:41] offset:3072
	s_add_u32 s2, s2, 0x1000
	s_addc_u32 s3, s3, 0
	s_add_u32 s40, s40, 0x1000
	s_addc_u32 s41, s41, 0
	s_waitcnt vmcnt(14)
	v_readlane_b32 s48, v20, 52
	v_readlane_b32 s58, v25, 52
	v_readlane_b32 s50, v21, 52
	v_readlane_b32 s60, v26, 52
	v_readlane_b32 s52, v22, 52
	v_readlane_b32 s62, v27, 52
	v_readlane_b32 s54, v23, 52
	v_readlane_b32 s64, v28, 52
	v_readlane_b32 s56, v24, 52
	v_readlane_b32 s66, v29, 52
	v_pk_fma_f32 v[52:53], v[200:201], s[48:49], v[52:53] op_sel_hi:[1,0,1]
	v_pk_fma_f32 v[54:55], v[202:203], s[48:49], v[54:55] op_sel_hi:[1,0,1]
	v_pk_fma_f32 v[56:57], v[204:205], s[58:59], v[56:57] op_sel_hi:[1,0,1]
	v_pk_fma_f32 v[58:59], v[206:207], s[58:59], v[58:59] op_sel_hi:[1,0,1]
	v_pk_fma_f32 v[60:61], v[200:201], s[50:51], v[60:61] op_sel_hi:[1,0,1]
	v_pk_fma_f32 v[62:63], v[202:203], s[50:51], v[62:63] op_sel_hi:[1,0,1]
	v_pk_fma_f32 v[64:65], v[204:205], s[60:61], v[64:65] op_sel_hi:[1,0,1]
	v_pk_fma_f32 v[66:67], v[206:207], s[60:61], v[66:67] op_sel_hi:[1,0,1]
	v_pk_fma_f32 v[68:69], v[200:201], s[52:53], v[68:69] op_sel_hi:[1,0,1]
	v_pk_fma_f32 v[70:71], v[202:203], s[52:53], v[70:71] op_sel_hi:[1,0,1]
	v_pk_fma_f32 v[72:73], v[204:205], s[62:63], v[72:73] op_sel_hi:[1,0,1]
	v_pk_fma_f32 v[74:75], v[206:207], s[62:63], v[74:75] op_sel_hi:[1,0,1]
	v_pk_fma_f32 v[76:77], v[200:201], s[54:55], v[76:77] op_sel_hi:[1,0,1]
	v_pk_fma_f32 v[78:79], v[202:203], s[54:55], v[78:79] op_sel_hi:[1,0,1]
	v_pk_fma_f32 v[80:81], v[204:205], s[64:65], v[80:81] op_sel_hi:[1,0,1]
	v_pk_fma_f32 v[82:83], v[206:207], s[64:65], v[82:83] op_sel_hi:[1,0,1]
	v_pk_fma_f32 v[84:85], v[200:201], s[56:57], v[84:85] op_sel_hi:[1,0,1]
	v_pk_fma_f32 v[86:87], v[202:203], s[56:57], v[86:87] op_sel_hi:[1,0,1]
	v_pk_fma_f32 v[88:89], v[204:205], s[66:67], v[88:89] op_sel_hi:[1,0,1]
	v_pk_fma_f32 v[90:91], v[206:207], s[66:67], v[90:91] op_sel_hi:[1,0,1]
	global_load_dwordx4 v[200:203], v232, s[2:3]
	global_load_dwordx4 v[204:207], v232, s[40:41]
	s_waitcnt vmcnt(14)
	v_readlane_b32 s48, v20, 53
	v_readlane_b32 s58, v25, 53
	v_readlane_b32 s50, v21, 53
	v_readlane_b32 s60, v26, 53
	v_readlane_b32 s52, v22, 53
	v_readlane_b32 s62, v27, 53
	v_readlane_b32 s54, v23, 53
	v_readlane_b32 s64, v28, 53
	v_readlane_b32 s56, v24, 53
	v_readlane_b32 s66, v29, 53
	v_pk_fma_f32 v[52:53], v[208:209], s[48:49], v[52:53] op_sel_hi:[1,0,1]
	v_pk_fma_f32 v[54:55], v[210:211], s[48:49], v[54:55] op_sel_hi:[1,0,1]
	v_pk_fma_f32 v[56:57], v[212:213], s[58:59], v[56:57] op_sel_hi:[1,0,1]
	v_pk_fma_f32 v[58:59], v[214:215], s[58:59], v[58:59] op_sel_hi:[1,0,1]
	v_pk_fma_f32 v[60:61], v[208:209], s[50:51], v[60:61] op_sel_hi:[1,0,1]
	v_pk_fma_f32 v[62:63], v[210:211], s[50:51], v[62:63] op_sel_hi:[1,0,1]
	v_pk_fma_f32 v[64:65], v[212:213], s[60:61], v[64:65] op_sel_hi:[1,0,1]
	v_pk_fma_f32 v[66:67], v[214:215], s[60:61], v[66:67] op_sel_hi:[1,0,1]
	v_pk_fma_f32 v[68:69], v[208:209], s[52:53], v[68:69] op_sel_hi:[1,0,1]
	v_pk_fma_f32 v[70:71], v[210:211], s[52:53], v[70:71] op_sel_hi:[1,0,1]
	v_pk_fma_f32 v[72:73], v[212:213], s[62:63], v[72:73] op_sel_hi:[1,0,1]
	v_pk_fma_f32 v[74:75], v[214:215], s[62:63], v[74:75] op_sel_hi:[1,0,1]
	v_pk_fma_f32 v[76:77], v[208:209], s[54:55], v[76:77] op_sel_hi:[1,0,1]
	v_pk_fma_f32 v[78:79], v[210:211], s[54:55], v[78:79] op_sel_hi:[1,0,1]
	v_pk_fma_f32 v[80:81], v[212:213], s[64:65], v[80:81] op_sel_hi:[1,0,1]
	v_pk_fma_f32 v[82:83], v[214:215], s[64:65], v[82:83] op_sel_hi:[1,0,1]
	v_pk_fma_f32 v[84:85], v[208:209], s[56:57], v[84:85] op_sel_hi:[1,0,1]
	v_pk_fma_f32 v[86:87], v[210:211], s[56:57], v[86:87] op_sel_hi:[1,0,1]
	v_pk_fma_f32 v[88:89], v[212:213], s[66:67], v[88:89] op_sel_hi:[1,0,1]
	v_pk_fma_f32 v[90:91], v[214:215], s[66:67], v[90:91] op_sel_hi:[1,0,1]
	global_load_dwordx4 v[208:211], v232, s[2:3] offset:1024
	global_load_dwordx4 v[212:215], v232, s[40:41] offset:1024
	s_waitcnt vmcnt(14)
	v_readlane_b32 s48, v20, 54
	v_readlane_b32 s58, v25, 54
	v_readlane_b32 s50, v21, 54
	v_readlane_b32 s60, v26, 54
	v_readlane_b32 s52, v22, 54
	v_readlane_b32 s62, v27, 54
	v_readlane_b32 s54, v23, 54
	v_readlane_b32 s64, v28, 54
	v_readlane_b32 s56, v24, 54
	v_readlane_b32 s66, v29, 54
	v_pk_fma_f32 v[52:53], v[216:217], s[48:49], v[52:53] op_sel_hi:[1,0,1]
	v_pk_fma_f32 v[54:55], v[218:219], s[48:49], v[54:55] op_sel_hi:[1,0,1]
	v_pk_fma_f32 v[56:57], v[220:221], s[58:59], v[56:57] op_sel_hi:[1,0,1]
	v_pk_fma_f32 v[58:59], v[222:223], s[58:59], v[58:59] op_sel_hi:[1,0,1]
	v_pk_fma_f32 v[60:61], v[216:217], s[50:51], v[60:61] op_sel_hi:[1,0,1]
	v_pk_fma_f32 v[62:63], v[218:219], s[50:51], v[62:63] op_sel_hi:[1,0,1]
	v_pk_fma_f32 v[64:65], v[220:221], s[60:61], v[64:65] op_sel_hi:[1,0,1]
	v_pk_fma_f32 v[66:67], v[222:223], s[60:61], v[66:67] op_sel_hi:[1,0,1]
	v_pk_fma_f32 v[68:69], v[216:217], s[52:53], v[68:69] op_sel_hi:[1,0,1]
	v_pk_fma_f32 v[70:71], v[218:219], s[52:53], v[70:71] op_sel_hi:[1,0,1]
	v_pk_fma_f32 v[72:73], v[220:221], s[62:63], v[72:73] op_sel_hi:[1,0,1]
	v_pk_fma_f32 v[74:75], v[222:223], s[62:63], v[74:75] op_sel_hi:[1,0,1]
	v_pk_fma_f32 v[76:77], v[216:217], s[54:55], v[76:77] op_sel_hi:[1,0,1]
	v_pk_fma_f32 v[78:79], v[218:219], s[54:55], v[78:79] op_sel_hi:[1,0,1]
	v_pk_fma_f32 v[80:81], v[220:221], s[64:65], v[80:81] op_sel_hi:[1,0,1]
	v_pk_fma_f32 v[82:83], v[222:223], s[64:65], v[82:83] op_sel_hi:[1,0,1]
	v_pk_fma_f32 v[84:85], v[216:217], s[56:57], v[84:85] op_sel_hi:[1,0,1]
	v_pk_fma_f32 v[86:87], v[218:219], s[56:57], v[86:87] op_sel_hi:[1,0,1]
	v_pk_fma_f32 v[88:89], v[220:221], s[66:67], v[88:89] op_sel_hi:[1,0,1]
	v_pk_fma_f32 v[90:91], v[222:223], s[66:67], v[90:91] op_sel_hi:[1,0,1]
	global_load_dwordx4 v[216:219], v232, s[2:3] offset:2048
	global_load_dwordx4 v[220:223], v232, s[40:41] offset:2048
	s_waitcnt vmcnt(14)
	v_readlane_b32 s48, v20, 55
	v_readlane_b32 s58, v25, 55
	v_readlane_b32 s50, v21, 55
	v_readlane_b32 s60, v26, 55
	v_readlane_b32 s52, v22, 55
	v_readlane_b32 s62, v27, 55
	v_readlane_b32 s54, v23, 55
	v_readlane_b32 s64, v28, 55
	v_readlane_b32 s56, v24, 55
	v_readlane_b32 s66, v29, 55
	v_pk_fma_f32 v[52:53], v[224:225], s[48:49], v[52:53] op_sel_hi:[1,0,1]
	v_pk_fma_f32 v[54:55], v[226:227], s[48:49], v[54:55] op_sel_hi:[1,0,1]
	v_pk_fma_f32 v[56:57], v[228:229], s[58:59], v[56:57] op_sel_hi:[1,0,1]
	v_pk_fma_f32 v[58:59], v[230:231], s[58:59], v[58:59] op_sel_hi:[1,0,1]
	v_pk_fma_f32 v[60:61], v[224:225], s[50:51], v[60:61] op_sel_hi:[1,0,1]
	v_pk_fma_f32 v[62:63], v[226:227], s[50:51], v[62:63] op_sel_hi:[1,0,1]
	v_pk_fma_f32 v[64:65], v[228:229], s[60:61], v[64:65] op_sel_hi:[1,0,1]
	v_pk_fma_f32 v[66:67], v[230:231], s[60:61], v[66:67] op_sel_hi:[1,0,1]
	v_pk_fma_f32 v[68:69], v[224:225], s[52:53], v[68:69] op_sel_hi:[1,0,1]
	v_pk_fma_f32 v[70:71], v[226:227], s[52:53], v[70:71] op_sel_hi:[1,0,1]
	v_pk_fma_f32 v[72:73], v[228:229], s[62:63], v[72:73] op_sel_hi:[1,0,1]
	v_pk_fma_f32 v[74:75], v[230:231], s[62:63], v[74:75] op_sel_hi:[1,0,1]
	v_pk_fma_f32 v[76:77], v[224:225], s[54:55], v[76:77] op_sel_hi:[1,0,1]
	v_pk_fma_f32 v[78:79], v[226:227], s[54:55], v[78:79] op_sel_hi:[1,0,1]
	v_pk_fma_f32 v[80:81], v[228:229], s[64:65], v[80:81] op_sel_hi:[1,0,1]
	v_pk_fma_f32 v[82:83], v[230:231], s[64:65], v[82:83] op_sel_hi:[1,0,1]
	v_pk_fma_f32 v[84:85], v[224:225], s[56:57], v[84:85] op_sel_hi:[1,0,1]
	v_pk_fma_f32 v[86:87], v[226:227], s[56:57], v[86:87] op_sel_hi:[1,0,1]
	v_pk_fma_f32 v[88:89], v[228:229], s[66:67], v[88:89] op_sel_hi:[1,0,1]
	v_pk_fma_f32 v[90:91], v[230:231], s[66:67], v[90:91] op_sel_hi:[1,0,1]
	global_load_dwordx4 v[224:227], v232, s[2:3] offset:3072
	global_load_dwordx4 v[228:231], v232, s[40:41] offset:3072
	s_add_u32 s2, s2, 0x1000
	s_addc_u32 s3, s3, 0
	s_add_u32 s40, s40, 0x1000
	s_addc_u32 s41, s41, 0
	s_waitcnt vmcnt(14)
	v_readlane_b32 s48, v20, 56
	v_readlane_b32 s58, v25, 56
	v_readlane_b32 s50, v21, 56
	v_readlane_b32 s60, v26, 56
	v_readlane_b32 s52, v22, 56
	v_readlane_b32 s62, v27, 56
	v_readlane_b32 s54, v23, 56
	v_readlane_b32 s64, v28, 56
	v_readlane_b32 s56, v24, 56
	v_readlane_b32 s66, v29, 56
	v_pk_fma_f32 v[52:53], v[168:169], s[48:49], v[52:53] op_sel_hi:[1,0,1]
	v_pk_fma_f32 v[54:55], v[170:171], s[48:49], v[54:55] op_sel_hi:[1,0,1]
	v_pk_fma_f32 v[56:57], v[172:173], s[58:59], v[56:57] op_sel_hi:[1,0,1]
	v_pk_fma_f32 v[58:59], v[174:175], s[58:59], v[58:59] op_sel_hi:[1,0,1]
	v_pk_fma_f32 v[60:61], v[168:169], s[50:51], v[60:61] op_sel_hi:[1,0,1]
	v_pk_fma_f32 v[62:63], v[170:171], s[50:51], v[62:63] op_sel_hi:[1,0,1]
	v_pk_fma_f32 v[64:65], v[172:173], s[60:61], v[64:65] op_sel_hi:[1,0,1]
	v_pk_fma_f32 v[66:67], v[174:175], s[60:61], v[66:67] op_sel_hi:[1,0,1]
	v_pk_fma_f32 v[68:69], v[168:169], s[52:53], v[68:69] op_sel_hi:[1,0,1]
	v_pk_fma_f32 v[70:71], v[170:171], s[52:53], v[70:71] op_sel_hi:[1,0,1]
	v_pk_fma_f32 v[72:73], v[172:173], s[62:63], v[72:73] op_sel_hi:[1,0,1]
	v_pk_fma_f32 v[74:75], v[174:175], s[62:63], v[74:75] op_sel_hi:[1,0,1]
	v_pk_fma_f32 v[76:77], v[168:169], s[54:55], v[76:77] op_sel_hi:[1,0,1]
	v_pk_fma_f32 v[78:79], v[170:171], s[54:55], v[78:79] op_sel_hi:[1,0,1]
	v_pk_fma_f32 v[80:81], v[172:173], s[64:65], v[80:81] op_sel_hi:[1,0,1]
	v_pk_fma_f32 v[82:83], v[174:175], s[64:65], v[82:83] op_sel_hi:[1,0,1]
	v_pk_fma_f32 v[84:85], v[168:169], s[56:57], v[84:85] op_sel_hi:[1,0,1]
	v_pk_fma_f32 v[86:87], v[170:171], s[56:57], v[86:87] op_sel_hi:[1,0,1]
	v_pk_fma_f32 v[88:89], v[172:173], s[66:67], v[88:89] op_sel_hi:[1,0,1]
	v_pk_fma_f32 v[90:91], v[174:175], s[66:67], v[90:91] op_sel_hi:[1,0,1]
	s_waitcnt vmcnt(12)
	v_readlane_b32 s48, v20, 57
	v_readlane_b32 s58, v25, 57
	v_readlane_b32 s50, v21, 57
	v_readlane_b32 s60, v26, 57
	v_readlane_b32 s52, v22, 57
	v_readlane_b32 s62, v27, 57
	v_readlane_b32 s54, v23, 57
	v_readlane_b32 s64, v28, 57
	v_readlane_b32 s56, v24, 57
	v_readlane_b32 s66, v29, 57
	v_pk_fma_f32 v[52:53], v[176:177], s[48:49], v[52:53] op_sel_hi:[1,0,1]
	v_pk_fma_f32 v[54:55], v[178:179], s[48:49], v[54:55] op_sel_hi:[1,0,1]
	v_pk_fma_f32 v[56:57], v[180:181], s[58:59], v[56:57] op_sel_hi:[1,0,1]
	v_pk_fma_f32 v[58:59], v[182:183], s[58:59], v[58:59] op_sel_hi:[1,0,1]
	v_pk_fma_f32 v[60:61], v[176:177], s[50:51], v[60:61] op_sel_hi:[1,0,1]
	v_pk_fma_f32 v[62:63], v[178:179], s[50:51], v[62:63] op_sel_hi:[1,0,1]
	v_pk_fma_f32 v[64:65], v[180:181], s[60:61], v[64:65] op_sel_hi:[1,0,1]
	v_pk_fma_f32 v[66:67], v[182:183], s[60:61], v[66:67] op_sel_hi:[1,0,1]
	v_pk_fma_f32 v[68:69], v[176:177], s[52:53], v[68:69] op_sel_hi:[1,0,1]
	v_pk_fma_f32 v[70:71], v[178:179], s[52:53], v[70:71] op_sel_hi:[1,0,1]
	v_pk_fma_f32 v[72:73], v[180:181], s[62:63], v[72:73] op_sel_hi:[1,0,1]
	v_pk_fma_f32 v[74:75], v[182:183], s[62:63], v[74:75] op_sel_hi:[1,0,1]
	v_pk_fma_f32 v[76:77], v[176:177], s[54:55], v[76:77] op_sel_hi:[1,0,1]
	v_pk_fma_f32 v[78:79], v[178:179], s[54:55], v[78:79] op_sel_hi:[1,0,1]
	v_pk_fma_f32 v[80:81], v[180:181], s[64:65], v[80:81] op_sel_hi:[1,0,1]
	v_pk_fma_f32 v[82:83], v[182:183], s[64:65], v[82:83] op_sel_hi:[1,0,1]
	v_pk_fma_f32 v[84:85], v[176:177], s[56:57], v[84:85] op_sel_hi:[1,0,1]
	v_pk_fma_f32 v[86:87], v[178:179], s[56:57], v[86:87] op_sel_hi:[1,0,1]
	v_pk_fma_f32 v[88:89], v[180:181], s[66:67], v[88:89] op_sel_hi:[1,0,1]
	v_pk_fma_f32 v[90:91], v[182:183], s[66:67], v[90:91] op_sel_hi:[1,0,1]
	s_waitcnt vmcnt(10)
	v_readlane_b32 s48, v20, 58
	v_readlane_b32 s58, v25, 58
	v_readlane_b32 s50, v21, 58
	v_readlane_b32 s60, v26, 58
	v_readlane_b32 s52, v22, 58
	v_readlane_b32 s62, v27, 58
	v_readlane_b32 s54, v23, 58
	v_readlane_b32 s64, v28, 58
	v_readlane_b32 s56, v24, 58
	v_readlane_b32 s66, v29, 58
	v_pk_fma_f32 v[52:53], v[184:185], s[48:49], v[52:53] op_sel_hi:[1,0,1]
	v_pk_fma_f32 v[54:55], v[186:187], s[48:49], v[54:55] op_sel_hi:[1,0,1]
	v_pk_fma_f32 v[56:57], v[188:189], s[58:59], v[56:57] op_sel_hi:[1,0,1]
	v_pk_fma_f32 v[58:59], v[190:191], s[58:59], v[58:59] op_sel_hi:[1,0,1]
	v_pk_fma_f32 v[60:61], v[184:185], s[50:51], v[60:61] op_sel_hi:[1,0,1]
	v_pk_fma_f32 v[62:63], v[186:187], s[50:51], v[62:63] op_sel_hi:[1,0,1]
	v_pk_fma_f32 v[64:65], v[188:189], s[60:61], v[64:65] op_sel_hi:[1,0,1]
	v_pk_fma_f32 v[66:67], v[190:191], s[60:61], v[66:67] op_sel_hi:[1,0,1]
	v_pk_fma_f32 v[68:69], v[184:185], s[52:53], v[68:69] op_sel_hi:[1,0,1]
	v_pk_fma_f32 v[70:71], v[186:187], s[52:53], v[70:71] op_sel_hi:[1,0,1]
	v_pk_fma_f32 v[72:73], v[188:189], s[62:63], v[72:73] op_sel_hi:[1,0,1]
	v_pk_fma_f32 v[74:75], v[190:191], s[62:63], v[74:75] op_sel_hi:[1,0,1]
	v_pk_fma_f32 v[76:77], v[184:185], s[54:55], v[76:77] op_sel_hi:[1,0,1]
	v_pk_fma_f32 v[78:79], v[186:187], s[54:55], v[78:79] op_sel_hi:[1,0,1]
	v_pk_fma_f32 v[80:81], v[188:189], s[64:65], v[80:81] op_sel_hi:[1,0,1]
	v_pk_fma_f32 v[82:83], v[190:191], s[64:65], v[82:83] op_sel_hi:[1,0,1]
	v_pk_fma_f32 v[84:85], v[184:185], s[56:57], v[84:85] op_sel_hi:[1,0,1]
	v_pk_fma_f32 v[86:87], v[186:187], s[56:57], v[86:87] op_sel_hi:[1,0,1]
	v_pk_fma_f32 v[88:89], v[188:189], s[66:67], v[88:89] op_sel_hi:[1,0,1]
	v_pk_fma_f32 v[90:91], v[190:191], s[66:67], v[90:91] op_sel_hi:[1,0,1]
	s_waitcnt vmcnt(8)
	v_readlane_b32 s48, v20, 59
	v_readlane_b32 s58, v25, 59
	v_readlane_b32 s50, v21, 59
	v_readlane_b32 s60, v26, 59
	v_readlane_b32 s52, v22, 59
	v_readlane_b32 s62, v27, 59
	v_readlane_b32 s54, v23, 59
	v_readlane_b32 s64, v28, 59
	v_readlane_b32 s56, v24, 59
	v_readlane_b32 s66, v29, 59
	v_pk_fma_f32 v[52:53], v[192:193], s[48:49], v[52:53] op_sel_hi:[1,0,1]
	v_pk_fma_f32 v[54:55], v[194:195], s[48:49], v[54:55] op_sel_hi:[1,0,1]
	v_pk_fma_f32 v[56:57], v[196:197], s[58:59], v[56:57] op_sel_hi:[1,0,1]
	v_pk_fma_f32 v[58:59], v[198:199], s[58:59], v[58:59] op_sel_hi:[1,0,1]
	v_pk_fma_f32 v[60:61], v[192:193], s[50:51], v[60:61] op_sel_hi:[1,0,1]
	v_pk_fma_f32 v[62:63], v[194:195], s[50:51], v[62:63] op_sel_hi:[1,0,1]
	v_pk_fma_f32 v[64:65], v[196:197], s[60:61], v[64:65] op_sel_hi:[1,0,1]
	v_pk_fma_f32 v[66:67], v[198:199], s[60:61], v[66:67] op_sel_hi:[1,0,1]
	v_pk_fma_f32 v[68:69], v[192:193], s[52:53], v[68:69] op_sel_hi:[1,0,1]
	v_pk_fma_f32 v[70:71], v[194:195], s[52:53], v[70:71] op_sel_hi:[1,0,1]
	v_pk_fma_f32 v[72:73], v[196:197], s[62:63], v[72:73] op_sel_hi:[1,0,1]
	v_pk_fma_f32 v[74:75], v[198:199], s[62:63], v[74:75] op_sel_hi:[1,0,1]
	v_pk_fma_f32 v[76:77], v[192:193], s[54:55], v[76:77] op_sel_hi:[1,0,1]
	v_pk_fma_f32 v[78:79], v[194:195], s[54:55], v[78:79] op_sel_hi:[1,0,1]
	v_pk_fma_f32 v[80:81], v[196:197], s[64:65], v[80:81] op_sel_hi:[1,0,1]
	v_pk_fma_f32 v[82:83], v[198:199], s[64:65], v[82:83] op_sel_hi:[1,0,1]
	v_pk_fma_f32 v[84:85], v[192:193], s[56:57], v[84:85] op_sel_hi:[1,0,1]
	v_pk_fma_f32 v[86:87], v[194:195], s[56:57], v[86:87] op_sel_hi:[1,0,1]
	v_pk_fma_f32 v[88:89], v[196:197], s[66:67], v[88:89] op_sel_hi:[1,0,1]
	v_pk_fma_f32 v[90:91], v[198:199], s[66:67], v[90:91] op_sel_hi:[1,0,1]
	s_waitcnt vmcnt(6)
	v_readlane_b32 s48, v20, 60
	v_readlane_b32 s58, v25, 60
	v_readlane_b32 s50, v21, 60
	v_readlane_b32 s60, v26, 60
	v_readlane_b32 s52, v22, 60
	v_readlane_b32 s62, v27, 60
	v_readlane_b32 s54, v23, 60
	v_readlane_b32 s64, v28, 60
	v_readlane_b32 s56, v24, 60
	v_readlane_b32 s66, v29, 60
	v_pk_fma_f32 v[52:53], v[200:201], s[48:49], v[52:53] op_sel_hi:[1,0,1]
	v_pk_fma_f32 v[54:55], v[202:203], s[48:49], v[54:55] op_sel_hi:[1,0,1]
	v_pk_fma_f32 v[56:57], v[204:205], s[58:59], v[56:57] op_sel_hi:[1,0,1]
	v_pk_fma_f32 v[58:59], v[206:207], s[58:59], v[58:59] op_sel_hi:[1,0,1]
	v_pk_fma_f32 v[60:61], v[200:201], s[50:51], v[60:61] op_sel_hi:[1,0,1]
	v_pk_fma_f32 v[62:63], v[202:203], s[50:51], v[62:63] op_sel_hi:[1,0,1]
	v_pk_fma_f32 v[64:65], v[204:205], s[60:61], v[64:65] op_sel_hi:[1,0,1]
	v_pk_fma_f32 v[66:67], v[206:207], s[60:61], v[66:67] op_sel_hi:[1,0,1]
	v_pk_fma_f32 v[68:69], v[200:201], s[52:53], v[68:69] op_sel_hi:[1,0,1]
	v_pk_fma_f32 v[70:71], v[202:203], s[52:53], v[70:71] op_sel_hi:[1,0,1]
	v_pk_fma_f32 v[72:73], v[204:205], s[62:63], v[72:73] op_sel_hi:[1,0,1]
	v_pk_fma_f32 v[74:75], v[206:207], s[62:63], v[74:75] op_sel_hi:[1,0,1]
	v_pk_fma_f32 v[76:77], v[200:201], s[54:55], v[76:77] op_sel_hi:[1,0,1]
	v_pk_fma_f32 v[78:79], v[202:203], s[54:55], v[78:79] op_sel_hi:[1,0,1]
	v_pk_fma_f32 v[80:81], v[204:205], s[64:65], v[80:81] op_sel_hi:[1,0,1]
	v_pk_fma_f32 v[82:83], v[206:207], s[64:65], v[82:83] op_sel_hi:[1,0,1]
	v_pk_fma_f32 v[84:85], v[200:201], s[56:57], v[84:85] op_sel_hi:[1,0,1]
	v_pk_fma_f32 v[86:87], v[202:203], s[56:57], v[86:87] op_sel_hi:[1,0,1]
	v_pk_fma_f32 v[88:89], v[204:205], s[66:67], v[88:89] op_sel_hi:[1,0,1]
	v_pk_fma_f32 v[90:91], v[206:207], s[66:67], v[90:91] op_sel_hi:[1,0,1]
	s_waitcnt vmcnt(4)
	v_readlane_b32 s48, v20, 61
	v_readlane_b32 s58, v25, 61
	v_readlane_b32 s50, v21, 61
	v_readlane_b32 s60, v26, 61
	v_readlane_b32 s52, v22, 61
	v_readlane_b32 s62, v27, 61
	v_readlane_b32 s54, v23, 61
	v_readlane_b32 s64, v28, 61
	v_readlane_b32 s56, v24, 61
	v_readlane_b32 s66, v29, 61
	v_pk_fma_f32 v[52:53], v[208:209], s[48:49], v[52:53] op_sel_hi:[1,0,1]
	v_pk_fma_f32 v[54:55], v[210:211], s[48:49], v[54:55] op_sel_hi:[1,0,1]
	v_pk_fma_f32 v[56:57], v[212:213], s[58:59], v[56:57] op_sel_hi:[1,0,1]
	v_pk_fma_f32 v[58:59], v[214:215], s[58:59], v[58:59] op_sel_hi:[1,0,1]
	v_pk_fma_f32 v[60:61], v[208:209], s[50:51], v[60:61] op_sel_hi:[1,0,1]
	v_pk_fma_f32 v[62:63], v[210:211], s[50:51], v[62:63] op_sel_hi:[1,0,1]
	v_pk_fma_f32 v[64:65], v[212:213], s[60:61], v[64:65] op_sel_hi:[1,0,1]
	v_pk_fma_f32 v[66:67], v[214:215], s[60:61], v[66:67] op_sel_hi:[1,0,1]
	v_pk_fma_f32 v[68:69], v[208:209], s[52:53], v[68:69] op_sel_hi:[1,0,1]
	v_pk_fma_f32 v[70:71], v[210:211], s[52:53], v[70:71] op_sel_hi:[1,0,1]
	v_pk_fma_f32 v[72:73], v[212:213], s[62:63], v[72:73] op_sel_hi:[1,0,1]
	v_pk_fma_f32 v[74:75], v[214:215], s[62:63], v[74:75] op_sel_hi:[1,0,1]
	v_pk_fma_f32 v[76:77], v[208:209], s[54:55], v[76:77] op_sel_hi:[1,0,1]
	v_pk_fma_f32 v[78:79], v[210:211], s[54:55], v[78:79] op_sel_hi:[1,0,1]
	v_pk_fma_f32 v[80:81], v[212:213], s[64:65], v[80:81] op_sel_hi:[1,0,1]
	v_pk_fma_f32 v[82:83], v[214:215], s[64:65], v[82:83] op_sel_hi:[1,0,1]
	v_pk_fma_f32 v[84:85], v[208:209], s[56:57], v[84:85] op_sel_hi:[1,0,1]
	v_pk_fma_f32 v[86:87], v[210:211], s[56:57], v[86:87] op_sel_hi:[1,0,1]
	v_pk_fma_f32 v[88:89], v[212:213], s[66:67], v[88:89] op_sel_hi:[1,0,1]
	v_pk_fma_f32 v[90:91], v[214:215], s[66:67], v[90:91] op_sel_hi:[1,0,1]
	s_waitcnt vmcnt(2)
	v_readlane_b32 s48, v20, 62
	v_readlane_b32 s58, v25, 62
	v_readlane_b32 s50, v21, 62
	v_readlane_b32 s60, v26, 62
	v_readlane_b32 s52, v22, 62
	v_readlane_b32 s62, v27, 62
	v_readlane_b32 s54, v23, 62
	v_readlane_b32 s64, v28, 62
	v_readlane_b32 s56, v24, 62
	v_readlane_b32 s66, v29, 62
	v_pk_fma_f32 v[52:53], v[216:217], s[48:49], v[52:53] op_sel_hi:[1,0,1]
	v_pk_fma_f32 v[54:55], v[218:219], s[48:49], v[54:55] op_sel_hi:[1,0,1]
	v_pk_fma_f32 v[56:57], v[220:221], s[58:59], v[56:57] op_sel_hi:[1,0,1]
	v_pk_fma_f32 v[58:59], v[222:223], s[58:59], v[58:59] op_sel_hi:[1,0,1]
	v_pk_fma_f32 v[60:61], v[216:217], s[50:51], v[60:61] op_sel_hi:[1,0,1]
	v_pk_fma_f32 v[62:63], v[218:219], s[50:51], v[62:63] op_sel_hi:[1,0,1]
	v_pk_fma_f32 v[64:65], v[220:221], s[60:61], v[64:65] op_sel_hi:[1,0,1]
	v_pk_fma_f32 v[66:67], v[222:223], s[60:61], v[66:67] op_sel_hi:[1,0,1]
	v_pk_fma_f32 v[68:69], v[216:217], s[52:53], v[68:69] op_sel_hi:[1,0,1]
	v_pk_fma_f32 v[70:71], v[218:219], s[52:53], v[70:71] op_sel_hi:[1,0,1]
	v_pk_fma_f32 v[72:73], v[220:221], s[62:63], v[72:73] op_sel_hi:[1,0,1]
	v_pk_fma_f32 v[74:75], v[222:223], s[62:63], v[74:75] op_sel_hi:[1,0,1]
	v_pk_fma_f32 v[76:77], v[216:217], s[54:55], v[76:77] op_sel_hi:[1,0,1]
	v_pk_fma_f32 v[78:79], v[218:219], s[54:55], v[78:79] op_sel_hi:[1,0,1]
	v_pk_fma_f32 v[80:81], v[220:221], s[64:65], v[80:81] op_sel_hi:[1,0,1]
	v_pk_fma_f32 v[82:83], v[222:223], s[64:65], v[82:83] op_sel_hi:[1,0,1]
	v_pk_fma_f32 v[84:85], v[216:217], s[56:57], v[84:85] op_sel_hi:[1,0,1]
	v_pk_fma_f32 v[86:87], v[218:219], s[56:57], v[86:87] op_sel_hi:[1,0,1]
	v_pk_fma_f32 v[88:89], v[220:221], s[66:67], v[88:89] op_sel_hi:[1,0,1]
	v_pk_fma_f32 v[90:91], v[222:223], s[66:67], v[90:91] op_sel_hi:[1,0,1]
	s_waitcnt vmcnt(0)
	v_readlane_b32 s48, v20, 63
	v_readlane_b32 s58, v25, 63
	v_readlane_b32 s50, v21, 63
	v_readlane_b32 s60, v26, 63
	v_readlane_b32 s52, v22, 63
	v_readlane_b32 s62, v27, 63
	v_readlane_b32 s54, v23, 63
	v_readlane_b32 s64, v28, 63
	v_readlane_b32 s56, v24, 63
	v_readlane_b32 s66, v29, 63
	v_pk_fma_f32 v[52:53], v[224:225], s[48:49], v[52:53] op_sel_hi:[1,0,1]
	v_pk_fma_f32 v[54:55], v[226:227], s[48:49], v[54:55] op_sel_hi:[1,0,1]
	v_pk_fma_f32 v[56:57], v[228:229], s[58:59], v[56:57] op_sel_hi:[1,0,1]
	v_pk_fma_f32 v[58:59], v[230:231], s[58:59], v[58:59] op_sel_hi:[1,0,1]
	v_pk_fma_f32 v[60:61], v[224:225], s[50:51], v[60:61] op_sel_hi:[1,0,1]
	v_pk_fma_f32 v[62:63], v[226:227], s[50:51], v[62:63] op_sel_hi:[1,0,1]
	v_pk_fma_f32 v[64:65], v[228:229], s[60:61], v[64:65] op_sel_hi:[1,0,1]
	v_pk_fma_f32 v[66:67], v[230:231], s[60:61], v[66:67] op_sel_hi:[1,0,1]
	v_pk_fma_f32 v[68:69], v[224:225], s[52:53], v[68:69] op_sel_hi:[1,0,1]
	v_pk_fma_f32 v[70:71], v[226:227], s[52:53], v[70:71] op_sel_hi:[1,0,1]
	v_pk_fma_f32 v[72:73], v[228:229], s[62:63], v[72:73] op_sel_hi:[1,0,1]
	v_pk_fma_f32 v[74:75], v[230:231], s[62:63], v[74:75] op_sel_hi:[1,0,1]
	v_pk_fma_f32 v[76:77], v[224:225], s[54:55], v[76:77] op_sel_hi:[1,0,1]
	v_pk_fma_f32 v[78:79], v[226:227], s[54:55], v[78:79] op_sel_hi:[1,0,1]
	v_pk_fma_f32 v[80:81], v[228:229], s[64:65], v[80:81] op_sel_hi:[1,0,1]
	v_pk_fma_f32 v[82:83], v[230:231], s[64:65], v[82:83] op_sel_hi:[1,0,1]
	v_pk_fma_f32 v[84:85], v[224:225], s[56:57], v[84:85] op_sel_hi:[1,0,1]
	v_pk_fma_f32 v[86:87], v[226:227], s[56:57], v[86:87] op_sel_hi:[1,0,1]
	v_pk_fma_f32 v[88:89], v[228:229], s[66:67], v[88:89] op_sel_hi:[1,0,1]
	v_pk_fma_f32 v[90:91], v[230:231], s[66:67], v[90:91] op_sel_hi:[1,0,1]
	s_mov_b32 s6, s13
	s_cmp_ge_u32 s6, 0x2800
	s_cbranch_scc1 .Lgprep_sk1
	v_mul_f32_e32 v92, 0xbfb8aa3b, v52
	v_exp_f32_e32 v92, v92
	s_nop 0
	v_add_f32_e32 v92, 1.0, v92
	v_div_scale_f32 v93, s[24:25], v92, v92, 1.0
	v_rcp_f32_e32 v94, v93
	s_nop 0
	v_fma_f32 v95, -v93, v94, 1.0
	v_fmac_f32_e32 v94, v95, v94
	v_div_scale_f32 v95, vcc, 1.0, v92, 1.0
	v_mul_f32_e32 v96, v95, v94
	v_fma_f32 v97, -v93, v96, v95
	v_fmac_f32_e32 v96, v97, v94
	v_fma_f32 v93, -v93, v96, v95
	v_div_fmas_f32 v93, v93, v94, v96
	v_div_fixup_f32 v52, v93, v92, 1.0
	v_mul_f32_e32 v52, 0xbf1b4598, v52
	v_mul_f32_e32 v52, 0x3fb8aa3b, v52
	v_exp_f32_e32 v52, v52
	v_mul_f32_e32 v92, 0xbfb8aa3b, v56
	v_exp_f32_e32 v92, v92
	s_nop 0
	v_add_f32_e32 v92, 1.0, v92
	v_div_scale_f32 v93, s[24:25], v92, v92, 1.0
	v_rcp_f32_e32 v94, v93
	s_nop 0
	v_fma_f32 v95, -v93, v94, 1.0
	v_fmac_f32_e32 v94, v95, v94
	v_div_scale_f32 v95, vcc, 1.0, v92, 1.0
	v_mul_f32_e32 v96, v95, v94
	v_fma_f32 v97, -v93, v96, v95
	v_fmac_f32_e32 v96, v97, v94
	v_fma_f32 v93, -v93, v96, v95
	v_div_fmas_f32 v93, v93, v94, v96
	v_div_fixup_f32 v56, v93, v92, 1.0
	v_mul_f32_e32 v92, 0xbfb8aa3b, v53
	v_exp_f32_e32 v92, v92
	s_nop 0
	v_add_f32_e32 v92, 1.0, v92
	v_div_scale_f32 v93, s[24:25], v92, v92, 1.0
	v_rcp_f32_e32 v94, v93
	s_nop 0
	v_fma_f32 v95, -v93, v94, 1.0
	v_fmac_f32_e32 v94, v95, v94
	v_div_scale_f32 v95, vcc, 1.0, v92, 1.0
	v_mul_f32_e32 v96, v95, v94
	v_fma_f32 v97, -v93, v96, v95
	v_fmac_f32_e32 v96, v97, v94
	v_fma_f32 v93, -v93, v96, v95
	v_div_fmas_f32 v93, v93, v94, v96
	v_div_fixup_f32 v53, v93, v92, 1.0
	v_mul_f32_e32 v53, 0xbf1b4598, v53
	v_mul_f32_e32 v53, 0x3fb8aa3b, v53
	v_exp_f32_e32 v53, v53
	v_mul_f32_e32 v92, 0xbfb8aa3b, v57
	v_exp_f32_e32 v92, v92
	s_nop 0
	v_add_f32_e32 v92, 1.0, v92
	v_div_scale_f32 v93, s[24:25], v92, v92, 1.0
	v_rcp_f32_e32 v94, v93
	s_nop 0
	v_fma_f32 v95, -v93, v94, 1.0
	v_fmac_f32_e32 v94, v95, v94
	v_div_scale_f32 v95, vcc, 1.0, v92, 1.0
	v_mul_f32_e32 v96, v95, v94
	v_fma_f32 v97, -v93, v96, v95
	v_fmac_f32_e32 v96, v97, v94
	v_fma_f32 v93, -v93, v96, v95
	v_div_fmas_f32 v93, v93, v94, v96
	v_div_fixup_f32 v57, v93, v92, 1.0
	v_mul_f32_e32 v92, 0xbfb8aa3b, v54
	v_exp_f32_e32 v92, v92
	s_nop 0
	v_add_f32_e32 v92, 1.0, v92
	v_div_scale_f32 v93, s[24:25], v92, v92, 1.0
	v_rcp_f32_e32 v94, v93
	s_nop 0
	v_fma_f32 v95, -v93, v94, 1.0
	v_fmac_f32_e32 v94, v95, v94
	v_div_scale_f32 v95, vcc, 1.0, v92, 1.0
	v_mul_f32_e32 v96, v95, v94
	v_fma_f32 v97, -v93, v96, v95
	v_fmac_f32_e32 v96, v97, v94
	v_fma_f32 v93, -v93, v96, v95
	v_div_fmas_f32 v93, v93, v94, v96
	v_div_fixup_f32 v54, v93, v92, 1.0
	v_mul_f32_e32 v54, 0xbf1b4598, v54
	v_mul_f32_e32 v54, 0x3fb8aa3b, v54
	v_exp_f32_e32 v54, v54
	v_mul_f32_e32 v92, 0xbfb8aa3b, v58
	v_exp_f32_e32 v92, v92
	s_nop 0
	v_add_f32_e32 v92, 1.0, v92
	v_div_scale_f32 v93, s[24:25], v92, v92, 1.0
	v_rcp_f32_e32 v94, v93
	s_nop 0
	v_fma_f32 v95, -v93, v94, 1.0
	v_fmac_f32_e32 v94, v95, v94
	v_div_scale_f32 v95, vcc, 1.0, v92, 1.0
	v_mul_f32_e32 v96, v95, v94
	v_fma_f32 v97, -v93, v96, v95
	v_fmac_f32_e32 v96, v97, v94
	v_fma_f32 v93, -v93, v96, v95
	v_div_fmas_f32 v93, v93, v94, v96
	v_div_fixup_f32 v58, v93, v92, 1.0
	v_mul_f32_e32 v92, 0xbfb8aa3b, v55
	v_exp_f32_e32 v92, v92
	s_nop 0
	v_add_f32_e32 v92, 1.0, v92
	v_div_scale_f32 v93, s[24:25], v92, v92, 1.0
	v_rcp_f32_e32 v94, v93
	s_nop 0
	v_fma_f32 v95, -v93, v94, 1.0
	v_fmac_f32_e32 v94, v95, v94
	v_div_scale_f32 v95, vcc, 1.0, v92, 1.0
	v_mul_f32_e32 v96, v95, v94
	v_fma_f32 v97, -v93, v96, v95
	v_fmac_f32_e32 v96, v97, v94
	v_fma_f32 v93, -v93, v96, v95
	v_div_fmas_f32 v93, v93, v94, v96
	v_div_fixup_f32 v55, v93, v92, 1.0
	v_mul_f32_e32 v55, 0xbf1b4598, v55
	v_mul_f32_e32 v55, 0x3fb8aa3b, v55
	v_exp_f32_e32 v55, v55
	v_mul_f32_e32 v92, 0xbfb8aa3b, v59
	v_exp_f32_e32 v92, v92
	s_nop 0
	v_add_f32_e32 v92, 1.0, v92
	v_div_scale_f32 v93, s[24:25], v92, v92, 1.0
	v_rcp_f32_e32 v94, v93
	s_nop 0
	v_fma_f32 v95, -v93, v94, 1.0
	v_fmac_f32_e32 v94, v95, v94
	v_div_scale_f32 v95, vcc, 1.0, v92, 1.0
	v_mul_f32_e32 v96, v95, v94
	v_fma_f32 v97, -v93, v96, v95
	v_fmac_f32_e32 v96, v97, v94
	v_fma_f32 v93, -v93, v96, v95
	v_div_fmas_f32 v93, v93, v94, v96
	v_div_fixup_f32 v59, v93, v92, 1.0
	s_mul_i32 s7, s6, 0x1400
	s_add_u32 s7, s7, 0x800
	s_add_u32 s8, s82, s7
	s_addc_u32 s9, s83, 0
	global_store_dwordx4 v232, v[52:55], s[8:9] offset:1024
	global_store_dwordx4 v232, v[56:59], s[8:9] offset:2048
	s_add_u32 s6, s13, 1
	s_cmp_ge_u32 s6, 0x2800
	s_cbranch_scc1 .Lgprep_sk1
	v_mul_f32_e32 v92, 0xbfb8aa3b, v60
	v_exp_f32_e32 v92, v92
	s_nop 0
	v_add_f32_e32 v92, 1.0, v92
	v_div_scale_f32 v93, s[24:25], v92, v92, 1.0
	v_rcp_f32_e32 v94, v93
	s_nop 0
	v_fma_f32 v95, -v93, v94, 1.0
	v_fmac_f32_e32 v94, v95, v94
	v_div_scale_f32 v95, vcc, 1.0, v92, 1.0
	v_mul_f32_e32 v96, v95, v94
	v_fma_f32 v97, -v93, v96, v95
	v_fmac_f32_e32 v96, v97, v94
	v_fma_f32 v93, -v93, v96, v95
	v_div_fmas_f32 v93, v93, v94, v96
	v_div_fixup_f32 v60, v93, v92, 1.0
	v_mul_f32_e32 v60, 0xbf1b4598, v60
	v_mul_f32_e32 v60, 0x3fb8aa3b, v60
	v_exp_f32_e32 v60, v60
	v_mul_f32_e32 v92, 0xbfb8aa3b, v64
	v_exp_f32_e32 v92, v92
	s_nop 0
	v_add_f32_e32 v92, 1.0, v92
	v_div_scale_f32 v93, s[24:25], v92, v92, 1.0
	v_rcp_f32_e32 v94, v93
	s_nop 0
	v_fma_f32 v95, -v93, v94, 1.0
	v_fmac_f32_e32 v94, v95, v94
	v_div_scale_f32 v95, vcc, 1.0, v92, 1.0
	v_mul_f32_e32 v96, v95, v94
	v_fma_f32 v97, -v93, v96, v95
	v_fmac_f32_e32 v96, v97, v94
	v_fma_f32 v93, -v93, v96, v95
	v_div_fmas_f32 v93, v93, v94, v96
	v_div_fixup_f32 v64, v93, v92, 1.0
	v_mul_f32_e32 v92, 0xbfb8aa3b, v61
	v_exp_f32_e32 v92, v92
	s_nop 0
	v_add_f32_e32 v92, 1.0, v92
	v_div_scale_f32 v93, s[24:25], v92, v92, 1.0
	v_rcp_f32_e32 v94, v93
	s_nop 0
	v_fma_f32 v95, -v93, v94, 1.0
	v_fmac_f32_e32 v94, v95, v94
	v_div_scale_f32 v95, vcc, 1.0, v92, 1.0
	v_mul_f32_e32 v96, v95, v94
	v_fma_f32 v97, -v93, v96, v95
	v_fmac_f32_e32 v96, v97, v94
	v_fma_f32 v93, -v93, v96, v95
	v_div_fmas_f32 v93, v93, v94, v96
	v_div_fixup_f32 v61, v93, v92, 1.0
	v_mul_f32_e32 v61, 0xbf1b4598, v61
	v_mul_f32_e32 v61, 0x3fb8aa3b, v61
	v_exp_f32_e32 v61, v61
	v_mul_f32_e32 v92, 0xbfb8aa3b, v65
	v_exp_f32_e32 v92, v92
	s_nop 0
	v_add_f32_e32 v92, 1.0, v92
	v_div_scale_f32 v93, s[24:25], v92, v92, 1.0
	v_rcp_f32_e32 v94, v93
	s_nop 0
	v_fma_f32 v95, -v93, v94, 1.0
	v_fmac_f32_e32 v94, v95, v94
	v_div_scale_f32 v95, vcc, 1.0, v92, 1.0
	v_mul_f32_e32 v96, v95, v94
	v_fma_f32 v97, -v93, v96, v95
	v_fmac_f32_e32 v96, v97, v94
	v_fma_f32 v93, -v93, v96, v95
	v_div_fmas_f32 v93, v93, v94, v96
	v_div_fixup_f32 v65, v93, v92, 1.0
	v_mul_f32_e32 v92, 0xbfb8aa3b, v62
	v_exp_f32_e32 v92, v92
	s_nop 0
	v_add_f32_e32 v92, 1.0, v92
	v_div_scale_f32 v93, s[24:25], v92, v92, 1.0
	v_rcp_f32_e32 v94, v93
	s_nop 0
	v_fma_f32 v95, -v93, v94, 1.0
	v_fmac_f32_e32 v94, v95, v94
	v_div_scale_f32 v95, vcc, 1.0, v92, 1.0
	v_mul_f32_e32 v96, v95, v94
	v_fma_f32 v97, -v93, v96, v95
	v_fmac_f32_e32 v96, v97, v94
	v_fma_f32 v93, -v93, v96, v95
	v_div_fmas_f32 v93, v93, v94, v96
	v_div_fixup_f32 v62, v93, v92, 1.0
	v_mul_f32_e32 v62, 0xbf1b4598, v62
	v_mul_f32_e32 v62, 0x3fb8aa3b, v62
	v_exp_f32_e32 v62, v62
	v_mul_f32_e32 v92, 0xbfb8aa3b, v66
	v_exp_f32_e32 v92, v92
	s_nop 0
	v_add_f32_e32 v92, 1.0, v92
	v_div_scale_f32 v93, s[24:25], v92, v92, 1.0
	v_rcp_f32_e32 v94, v93
	s_nop 0
	v_fma_f32 v95, -v93, v94, 1.0
	v_fmac_f32_e32 v94, v95, v94
	v_div_scale_f32 v95, vcc, 1.0, v92, 1.0
	v_mul_f32_e32 v96, v95, v94
	v_fma_f32 v97, -v93, v96, v95
	v_fmac_f32_e32 v96, v97, v94
	v_fma_f32 v93, -v93, v96, v95
	v_div_fmas_f32 v93, v93, v94, v96
	v_div_fixup_f32 v66, v93, v92, 1.0
	v_mul_f32_e32 v92, 0xbfb8aa3b, v63
	v_exp_f32_e32 v92, v92
	s_nop 0
	v_add_f32_e32 v92, 1.0, v92
	v_div_scale_f32 v93, s[24:25], v92, v92, 1.0
	v_rcp_f32_e32 v94, v93
	s_nop 0
	v_fma_f32 v95, -v93, v94, 1.0
	v_fmac_f32_e32 v94, v95, v94
	v_div_scale_f32 v95, vcc, 1.0, v92, 1.0
	v_mul_f32_e32 v96, v95, v94
	v_fma_f32 v97, -v93, v96, v95
	v_fmac_f32_e32 v96, v97, v94
	v_fma_f32 v93, -v93, v96, v95
	v_div_fmas_f32 v93, v93, v94, v96
	v_div_fixup_f32 v63, v93, v92, 1.0
	v_mul_f32_e32 v63, 0xbf1b4598, v63
	v_mul_f32_e32 v63, 0x3fb8aa3b, v63
	v_exp_f32_e32 v63, v63
	v_mul_f32_e32 v92, 0xbfb8aa3b, v67
	v_exp_f32_e32 v92, v92
	s_nop 0
	v_add_f32_e32 v92, 1.0, v92
	v_div_scale_f32 v93, s[24:25], v92, v92, 1.0
	v_rcp_f32_e32 v94, v93
	s_nop 0
	v_fma_f32 v95, -v93, v94, 1.0
	v_fmac_f32_e32 v94, v95, v94
	v_div_scale_f32 v95, vcc, 1.0, v92, 1.0
	v_mul_f32_e32 v96, v95, v94
	v_fma_f32 v97, -v93, v96, v95
	v_fmac_f32_e32 v96, v97, v94
	v_fma_f32 v93, -v93, v96, v95
	v_div_fmas_f32 v93, v93, v94, v96
	v_div_fixup_f32 v67, v93, v92, 1.0
	s_mul_i32 s7, s6, 0x1400
	s_add_u32 s7, s7, 0x800
	s_add_u32 s8, s82, s7
	s_addc_u32 s9, s83, 0
	global_store_dwordx4 v232, v[60:63], s[8:9] offset:1024
	global_store_dwordx4 v232, v[64:67], s[8:9] offset:2048
	s_add_u32 s6, s13, 2
	s_cmp_ge_u32 s6, 0x2800
	s_cbranch_scc1 .Lgprep_sk1
	v_mul_f32_e32 v92, 0xbfb8aa3b, v68
	v_exp_f32_e32 v92, v92
	s_nop 0
	v_add_f32_e32 v92, 1.0, v92
	v_div_scale_f32 v93, s[24:25], v92, v92, 1.0
	v_rcp_f32_e32 v94, v93
	s_nop 0
	v_fma_f32 v95, -v93, v94, 1.0
	v_fmac_f32_e32 v94, v95, v94
	v_div_scale_f32 v95, vcc, 1.0, v92, 1.0
	v_mul_f32_e32 v96, v95, v94
	v_fma_f32 v97, -v93, v96, v95
	v_fmac_f32_e32 v96, v97, v94
	v_fma_f32 v93, -v93, v96, v95
	v_div_fmas_f32 v93, v93, v94, v96
	v_div_fixup_f32 v68, v93, v92, 1.0
	v_mul_f32_e32 v68, 0xbf1b4598, v68
	v_mul_f32_e32 v68, 0x3fb8aa3b, v68
	v_exp_f32_e32 v68, v68
	v_mul_f32_e32 v92, 0xbfb8aa3b, v72
	v_exp_f32_e32 v92, v92
	s_nop 0
	v_add_f32_e32 v92, 1.0, v92
	v_div_scale_f32 v93, s[24:25], v92, v92, 1.0
	v_rcp_f32_e32 v94, v93
	s_nop 0
	v_fma_f32 v95, -v93, v94, 1.0
	v_fmac_f32_e32 v94, v95, v94
	v_div_scale_f32 v95, vcc, 1.0, v92, 1.0
	v_mul_f32_e32 v96, v95, v94
	v_fma_f32 v97, -v93, v96, v95
	v_fmac_f32_e32 v96, v97, v94
	v_fma_f32 v93, -v93, v96, v95
	v_div_fmas_f32 v93, v93, v94, v96
	v_div_fixup_f32 v72, v93, v92, 1.0
	v_mul_f32_e32 v92, 0xbfb8aa3b, v69
	v_exp_f32_e32 v92, v92
	s_nop 0
	v_add_f32_e32 v92, 1.0, v92
	v_div_scale_f32 v93, s[24:25], v92, v92, 1.0
	v_rcp_f32_e32 v94, v93
	s_nop 0
	v_fma_f32 v95, -v93, v94, 1.0
	v_fmac_f32_e32 v94, v95, v94
	v_div_scale_f32 v95, vcc, 1.0, v92, 1.0
	v_mul_f32_e32 v96, v95, v94
	v_fma_f32 v97, -v93, v96, v95
	v_fmac_f32_e32 v96, v97, v94
	v_fma_f32 v93, -v93, v96, v95
	v_div_fmas_f32 v93, v93, v94, v96
	v_div_fixup_f32 v69, v93, v92, 1.0
	v_mul_f32_e32 v69, 0xbf1b4598, v69
	v_mul_f32_e32 v69, 0x3fb8aa3b, v69
	v_exp_f32_e32 v69, v69
	v_mul_f32_e32 v92, 0xbfb8aa3b, v73
	v_exp_f32_e32 v92, v92
	s_nop 0
	v_add_f32_e32 v92, 1.0, v92
	v_div_scale_f32 v93, s[24:25], v92, v92, 1.0
	v_rcp_f32_e32 v94, v93
	s_nop 0
	v_fma_f32 v95, -v93, v94, 1.0
	v_fmac_f32_e32 v94, v95, v94
	v_div_scale_f32 v95, vcc, 1.0, v92, 1.0
	v_mul_f32_e32 v96, v95, v94
	v_fma_f32 v97, -v93, v96, v95
	v_fmac_f32_e32 v96, v97, v94
	v_fma_f32 v93, -v93, v96, v95
	v_div_fmas_f32 v93, v93, v94, v96
	v_div_fixup_f32 v73, v93, v92, 1.0
	v_mul_f32_e32 v92, 0xbfb8aa3b, v70
	v_exp_f32_e32 v92, v92
	s_nop 0
	v_add_f32_e32 v92, 1.0, v92
	v_div_scale_f32 v93, s[24:25], v92, v92, 1.0
	v_rcp_f32_e32 v94, v93
	s_nop 0
	v_fma_f32 v95, -v93, v94, 1.0
	v_fmac_f32_e32 v94, v95, v94
	v_div_scale_f32 v95, vcc, 1.0, v92, 1.0
	v_mul_f32_e32 v96, v95, v94
	v_fma_f32 v97, -v93, v96, v95
	v_fmac_f32_e32 v96, v97, v94
	v_fma_f32 v93, -v93, v96, v95
	v_div_fmas_f32 v93, v93, v94, v96
	v_div_fixup_f32 v70, v93, v92, 1.0
	v_mul_f32_e32 v70, 0xbf1b4598, v70
	v_mul_f32_e32 v70, 0x3fb8aa3b, v70
	v_exp_f32_e32 v70, v70
	v_mul_f32_e32 v92, 0xbfb8aa3b, v74
	v_exp_f32_e32 v92, v92
	s_nop 0
	v_add_f32_e32 v92, 1.0, v92
	v_div_scale_f32 v93, s[24:25], v92, v92, 1.0
	v_rcp_f32_e32 v94, v93
	s_nop 0
	v_fma_f32 v95, -v93, v94, 1.0
	v_fmac_f32_e32 v94, v95, v94
	v_div_scale_f32 v95, vcc, 1.0, v92, 1.0
	v_mul_f32_e32 v96, v95, v94
	v_fma_f32 v97, -v93, v96, v95
	v_fmac_f32_e32 v96, v97, v94
	v_fma_f32 v93, -v93, v96, v95
	v_div_fmas_f32 v93, v93, v94, v96
	v_div_fixup_f32 v74, v93, v92, 1.0
	v_mul_f32_e32 v92, 0xbfb8aa3b, v71
	v_exp_f32_e32 v92, v92
	s_nop 0
	v_add_f32_e32 v92, 1.0, v92
	v_div_scale_f32 v93, s[24:25], v92, v92, 1.0
	v_rcp_f32_e32 v94, v93
	s_nop 0
	v_fma_f32 v95, -v93, v94, 1.0
	v_fmac_f32_e32 v94, v95, v94
	v_div_scale_f32 v95, vcc, 1.0, v92, 1.0
	v_mul_f32_e32 v96, v95, v94
	v_fma_f32 v97, -v93, v96, v95
	v_fmac_f32_e32 v96, v97, v94
	v_fma_f32 v93, -v93, v96, v95
	v_div_fmas_f32 v93, v93, v94, v96
	v_div_fixup_f32 v71, v93, v92, 1.0
	v_mul_f32_e32 v71, 0xbf1b4598, v71
	v_mul_f32_e32 v71, 0x3fb8aa3b, v71
	v_exp_f32_e32 v71, v71
	v_mul_f32_e32 v92, 0xbfb8aa3b, v75
	v_exp_f32_e32 v92, v92
	s_nop 0
	v_add_f32_e32 v92, 1.0, v92
	v_div_scale_f32 v93, s[24:25], v92, v92, 1.0
	v_rcp_f32_e32 v94, v93
	s_nop 0
	v_fma_f32 v95, -v93, v94, 1.0
	v_fmac_f32_e32 v94, v95, v94
	v_div_scale_f32 v95, vcc, 1.0, v92, 1.0
	v_mul_f32_e32 v96, v95, v94
	v_fma_f32 v97, -v93, v96, v95
	v_fmac_f32_e32 v96, v97, v94
	v_fma_f32 v93, -v93, v96, v95
	v_div_fmas_f32 v93, v93, v94, v96
	v_div_fixup_f32 v75, v93, v92, 1.0
	s_mul_i32 s7, s6, 0x1400
	s_add_u32 s7, s7, 0x800
	s_add_u32 s8, s82, s7
	s_addc_u32 s9, s83, 0
	global_store_dwordx4 v232, v[68:71], s[8:9] offset:1024
	global_store_dwordx4 v232, v[72:75], s[8:9] offset:2048
	s_add_u32 s6, s13, 3
	s_cmp_ge_u32 s6, 0x2800
	s_cbranch_scc1 .Lgprep_sk1
	v_mul_f32_e32 v92, 0xbfb8aa3b, v76
	v_exp_f32_e32 v92, v92
	s_nop 0
	v_add_f32_e32 v92, 1.0, v92
	v_div_scale_f32 v93, s[24:25], v92, v92, 1.0
	v_rcp_f32_e32 v94, v93
	s_nop 0
	v_fma_f32 v95, -v93, v94, 1.0
	v_fmac_f32_e32 v94, v95, v94
	v_div_scale_f32 v95, vcc, 1.0, v92, 1.0
	v_mul_f32_e32 v96, v95, v94
	v_fma_f32 v97, -v93, v96, v95
	v_fmac_f32_e32 v96, v97, v94
	v_fma_f32 v93, -v93, v96, v95
	v_div_fmas_f32 v93, v93, v94, v96
	v_div_fixup_f32 v76, v93, v92, 1.0
	v_mul_f32_e32 v76, 0xbf1b4598, v76
	v_mul_f32_e32 v76, 0x3fb8aa3b, v76
	v_exp_f32_e32 v76, v76
	v_mul_f32_e32 v92, 0xbfb8aa3b, v80
	v_exp_f32_e32 v92, v92
	s_nop 0
	v_add_f32_e32 v92, 1.0, v92
	v_div_scale_f32 v93, s[24:25], v92, v92, 1.0
	v_rcp_f32_e32 v94, v93
	s_nop 0
	v_fma_f32 v95, -v93, v94, 1.0
	v_fmac_f32_e32 v94, v95, v94
	v_div_scale_f32 v95, vcc, 1.0, v92, 1.0
	v_mul_f32_e32 v96, v95, v94
	v_fma_f32 v97, -v93, v96, v95
	v_fmac_f32_e32 v96, v97, v94
	v_fma_f32 v93, -v93, v96, v95
	v_div_fmas_f32 v93, v93, v94, v96
	v_div_fixup_f32 v80, v93, v92, 1.0
	v_mul_f32_e32 v92, 0xbfb8aa3b, v77
	v_exp_f32_e32 v92, v92
	s_nop 0
	v_add_f32_e32 v92, 1.0, v92
	v_div_scale_f32 v93, s[24:25], v92, v92, 1.0
	v_rcp_f32_e32 v94, v93
	s_nop 0
	v_fma_f32 v95, -v93, v94, 1.0
	v_fmac_f32_e32 v94, v95, v94
	v_div_scale_f32 v95, vcc, 1.0, v92, 1.0
	v_mul_f32_e32 v96, v95, v94
	v_fma_f32 v97, -v93, v96, v95
	v_fmac_f32_e32 v96, v97, v94
	v_fma_f32 v93, -v93, v96, v95
	v_div_fmas_f32 v93, v93, v94, v96
	v_div_fixup_f32 v77, v93, v92, 1.0
	v_mul_f32_e32 v77, 0xbf1b4598, v77
	v_mul_f32_e32 v77, 0x3fb8aa3b, v77
	v_exp_f32_e32 v77, v77
	v_mul_f32_e32 v92, 0xbfb8aa3b, v81
	v_exp_f32_e32 v92, v92
	s_nop 0
	v_add_f32_e32 v92, 1.0, v92
	v_div_scale_f32 v93, s[24:25], v92, v92, 1.0
	v_rcp_f32_e32 v94, v93
	s_nop 0
	v_fma_f32 v95, -v93, v94, 1.0
	v_fmac_f32_e32 v94, v95, v94
	v_div_scale_f32 v95, vcc, 1.0, v92, 1.0
	v_mul_f32_e32 v96, v95, v94
	v_fma_f32 v97, -v93, v96, v95
	v_fmac_f32_e32 v96, v97, v94
	v_fma_f32 v93, -v93, v96, v95
	v_div_fmas_f32 v93, v93, v94, v96
	v_div_fixup_f32 v81, v93, v92, 1.0
	v_mul_f32_e32 v92, 0xbfb8aa3b, v78
	v_exp_f32_e32 v92, v92
	s_nop 0
	v_add_f32_e32 v92, 1.0, v92
	v_div_scale_f32 v93, s[24:25], v92, v92, 1.0
	v_rcp_f32_e32 v94, v93
	s_nop 0
	v_fma_f32 v95, -v93, v94, 1.0
	v_fmac_f32_e32 v94, v95, v94
	v_div_scale_f32 v95, vcc, 1.0, v92, 1.0
	v_mul_f32_e32 v96, v95, v94
	v_fma_f32 v97, -v93, v96, v95
	v_fmac_f32_e32 v96, v97, v94
	v_fma_f32 v93, -v93, v96, v95
	v_div_fmas_f32 v93, v93, v94, v96
	v_div_fixup_f32 v78, v93, v92, 1.0
	v_mul_f32_e32 v78, 0xbf1b4598, v78
	v_mul_f32_e32 v78, 0x3fb8aa3b, v78
	v_exp_f32_e32 v78, v78
	v_mul_f32_e32 v92, 0xbfb8aa3b, v82
	v_exp_f32_e32 v92, v92
	s_nop 0
	v_add_f32_e32 v92, 1.0, v92
	v_div_scale_f32 v93, s[24:25], v92, v92, 1.0
	v_rcp_f32_e32 v94, v93
	s_nop 0
	v_fma_f32 v95, -v93, v94, 1.0
	v_fmac_f32_e32 v94, v95, v94
	v_div_scale_f32 v95, vcc, 1.0, v92, 1.0
	v_mul_f32_e32 v96, v95, v94
	v_fma_f32 v97, -v93, v96, v95
	v_fmac_f32_e32 v96, v97, v94
	v_fma_f32 v93, -v93, v96, v95
	v_div_fmas_f32 v93, v93, v94, v96
	v_div_fixup_f32 v82, v93, v92, 1.0
	v_mul_f32_e32 v92, 0xbfb8aa3b, v79
	v_exp_f32_e32 v92, v92
	s_nop 0
	v_add_f32_e32 v92, 1.0, v92
	v_div_scale_f32 v93, s[24:25], v92, v92, 1.0
	v_rcp_f32_e32 v94, v93
	s_nop 0
	v_fma_f32 v95, -v93, v94, 1.0
	v_fmac_f32_e32 v94, v95, v94
	v_div_scale_f32 v95, vcc, 1.0, v92, 1.0
	v_mul_f32_e32 v96, v95, v94
	v_fma_f32 v97, -v93, v96, v95
	v_fmac_f32_e32 v96, v97, v94
	v_fma_f32 v93, -v93, v96, v95
	v_div_fmas_f32 v93, v93, v94, v96
	v_div_fixup_f32 v79, v93, v92, 1.0
	v_mul_f32_e32 v79, 0xbf1b4598, v79
	v_mul_f32_e32 v79, 0x3fb8aa3b, v79
	v_exp_f32_e32 v79, v79
	v_mul_f32_e32 v92, 0xbfb8aa3b, v83
	v_exp_f32_e32 v92, v92
	s_nop 0
	v_add_f32_e32 v92, 1.0, v92
	v_div_scale_f32 v93, s[24:25], v92, v92, 1.0
	v_rcp_f32_e32 v94, v93
	s_nop 0
	v_fma_f32 v95, -v93, v94, 1.0
	v_fmac_f32_e32 v94, v95, v94
	v_div_scale_f32 v95, vcc, 1.0, v92, 1.0
	v_mul_f32_e32 v96, v95, v94
	v_fma_f32 v97, -v93, v96, v95
	v_fmac_f32_e32 v96, v97, v94
	v_fma_f32 v93, -v93, v96, v95
	v_div_fmas_f32 v93, v93, v94, v96
	v_div_fixup_f32 v83, v93, v92, 1.0
	s_mul_i32 s7, s6, 0x1400
	s_add_u32 s7, s7, 0x800
	s_add_u32 s8, s82, s7
	s_addc_u32 s9, s83, 0
	global_store_dwordx4 v232, v[76:79], s[8:9] offset:1024
	global_store_dwordx4 v232, v[80:83], s[8:9] offset:2048
	s_add_u32 s6, s13, 4
	s_cmp_ge_u32 s6, 0x2800
	s_cbranch_scc1 .Lgprep_sk1
	v_mul_f32_e32 v92, 0xbfb8aa3b, v84
	v_exp_f32_e32 v92, v92
	s_nop 0
	v_add_f32_e32 v92, 1.0, v92
	v_div_scale_f32 v93, s[24:25], v92, v92, 1.0
	v_rcp_f32_e32 v94, v93
	s_nop 0
	v_fma_f32 v95, -v93, v94, 1.0
	v_fmac_f32_e32 v94, v95, v94
	v_div_scale_f32 v95, vcc, 1.0, v92, 1.0
	v_mul_f32_e32 v96, v95, v94
	v_fma_f32 v97, -v93, v96, v95
	v_fmac_f32_e32 v96, v97, v94
	v_fma_f32 v93, -v93, v96, v95
	v_div_fmas_f32 v93, v93, v94, v96
	v_div_fixup_f32 v84, v93, v92, 1.0
	v_mul_f32_e32 v84, 0xbf1b4598, v84
	v_mul_f32_e32 v84, 0x3fb8aa3b, v84
	v_exp_f32_e32 v84, v84
	v_mul_f32_e32 v92, 0xbfb8aa3b, v88
	v_exp_f32_e32 v92, v92
	s_nop 0
	v_add_f32_e32 v92, 1.0, v92
	v_div_scale_f32 v93, s[24:25], v92, v92, 1.0
	v_rcp_f32_e32 v94, v93
	s_nop 0
	v_fma_f32 v95, -v93, v94, 1.0
	v_fmac_f32_e32 v94, v95, v94
	v_div_scale_f32 v95, vcc, 1.0, v92, 1.0
	v_mul_f32_e32 v96, v95, v94
	v_fma_f32 v97, -v93, v96, v95
	v_fmac_f32_e32 v96, v97, v94
	v_fma_f32 v93, -v93, v96, v95
	v_div_fmas_f32 v93, v93, v94, v96
	v_div_fixup_f32 v88, v93, v92, 1.0
	v_mul_f32_e32 v92, 0xbfb8aa3b, v85
	v_exp_f32_e32 v92, v92
	s_nop 0
	v_add_f32_e32 v92, 1.0, v92
	v_div_scale_f32 v93, s[24:25], v92, v92, 1.0
	v_rcp_f32_e32 v94, v93
	s_nop 0
	v_fma_f32 v95, -v93, v94, 1.0
	v_fmac_f32_e32 v94, v95, v94
	v_div_scale_f32 v95, vcc, 1.0, v92, 1.0
	v_mul_f32_e32 v96, v95, v94
	v_fma_f32 v97, -v93, v96, v95
	v_fmac_f32_e32 v96, v97, v94
	v_fma_f32 v93, -v93, v96, v95
	v_div_fmas_f32 v93, v93, v94, v96
	v_div_fixup_f32 v85, v93, v92, 1.0
	v_mul_f32_e32 v85, 0xbf1b4598, v85
	v_mul_f32_e32 v85, 0x3fb8aa3b, v85
	v_exp_f32_e32 v85, v85
	v_mul_f32_e32 v92, 0xbfb8aa3b, v89
	v_exp_f32_e32 v92, v92
	s_nop 0
	v_add_f32_e32 v92, 1.0, v92
	v_div_scale_f32 v93, s[24:25], v92, v92, 1.0
	v_rcp_f32_e32 v94, v93
	s_nop 0
	v_fma_f32 v95, -v93, v94, 1.0
	v_fmac_f32_e32 v94, v95, v94
	v_div_scale_f32 v95, vcc, 1.0, v92, 1.0
	v_mul_f32_e32 v96, v95, v94
	v_fma_f32 v97, -v93, v96, v95
	v_fmac_f32_e32 v96, v97, v94
	v_fma_f32 v93, -v93, v96, v95
	v_div_fmas_f32 v93, v93, v94, v96
	v_div_fixup_f32 v89, v93, v92, 1.0
	v_mul_f32_e32 v92, 0xbfb8aa3b, v86
	v_exp_f32_e32 v92, v92
	s_nop 0
	v_add_f32_e32 v92, 1.0, v92
	v_div_scale_f32 v93, s[24:25], v92, v92, 1.0
	v_rcp_f32_e32 v94, v93
	s_nop 0
	v_fma_f32 v95, -v93, v94, 1.0
	v_fmac_f32_e32 v94, v95, v94
	v_div_scale_f32 v95, vcc, 1.0, v92, 1.0
	v_mul_f32_e32 v96, v95, v94
	v_fma_f32 v97, -v93, v96, v95
	v_fmac_f32_e32 v96, v97, v94
	v_fma_f32 v93, -v93, v96, v95
	v_div_fmas_f32 v93, v93, v94, v96
	v_div_fixup_f32 v86, v93, v92, 1.0
	v_mul_f32_e32 v86, 0xbf1b4598, v86
	v_mul_f32_e32 v86, 0x3fb8aa3b, v86
	v_exp_f32_e32 v86, v86
	v_mul_f32_e32 v92, 0xbfb8aa3b, v90
	v_exp_f32_e32 v92, v92
	s_nop 0
	v_add_f32_e32 v92, 1.0, v92
	v_div_scale_f32 v93, s[24:25], v92, v92, 1.0
	v_rcp_f32_e32 v94, v93
	s_nop 0
	v_fma_f32 v95, -v93, v94, 1.0
	v_fmac_f32_e32 v94, v95, v94
	v_div_scale_f32 v95, vcc, 1.0, v92, 1.0
	v_mul_f32_e32 v96, v95, v94
	v_fma_f32 v97, -v93, v96, v95
	v_fmac_f32_e32 v96, v97, v94
	v_fma_f32 v93, -v93, v96, v95
	v_div_fmas_f32 v93, v93, v94, v96
	v_div_fixup_f32 v90, v93, v92, 1.0
	v_mul_f32_e32 v92, 0xbfb8aa3b, v87
	v_exp_f32_e32 v92, v92
	s_nop 0
	v_add_f32_e32 v92, 1.0, v92
	v_div_scale_f32 v93, s[24:25], v92, v92, 1.0
	v_rcp_f32_e32 v94, v93
	s_nop 0
	v_fma_f32 v95, -v93, v94, 1.0
	v_fmac_f32_e32 v94, v95, v94
	v_div_scale_f32 v95, vcc, 1.0, v92, 1.0
	v_mul_f32_e32 v96, v95, v94
	v_fma_f32 v97, -v93, v96, v95
	v_fmac_f32_e32 v96, v97, v94
	v_fma_f32 v93, -v93, v96, v95
	v_div_fmas_f32 v93, v93, v94, v96
	v_div_fixup_f32 v87, v93, v92, 1.0
	v_mul_f32_e32 v87, 0xbf1b4598, v87
	v_mul_f32_e32 v87, 0x3fb8aa3b, v87
	v_exp_f32_e32 v87, v87
	v_mul_f32_e32 v92, 0xbfb8aa3b, v91
	v_exp_f32_e32 v92, v92
	s_nop 0
	v_add_f32_e32 v92, 1.0, v92
	v_div_scale_f32 v93, s[24:25], v92, v92, 1.0
	v_rcp_f32_e32 v94, v93
	s_nop 0
	v_fma_f32 v95, -v93, v94, 1.0
	v_fmac_f32_e32 v94, v95, v94
	v_div_scale_f32 v95, vcc, 1.0, v92, 1.0
	v_mul_f32_e32 v96, v95, v94
	v_fma_f32 v97, -v93, v96, v95
	v_fmac_f32_e32 v96, v97, v94
	v_fma_f32 v93, -v93, v96, v95
	v_div_fmas_f32 v93, v93, v94, v96
	v_div_fixup_f32 v91, v93, v92, 1.0
	s_mul_i32 s7, s6, 0x1400
	s_add_u32 s7, s7, 0x800
	s_add_u32 s8, s82, s7
	s_addc_u32 s9, s83, 0
	global_store_dwordx4 v232, v[84:87], s[8:9] offset:1024
	global_store_dwordx4 v232, v[88:91], s[8:9] offset:2048
	s_branch .Lgprep_e1

.Lgpost_batch:
	s_mov_b32 s6, s13
	s_min_u32 s6, s6, 0x27ff
	s_mul_i32 s7, s6, 0x2f00
	s_add_u32 s7, s7, 0x2000
	s_add_u32 s8, s74, s7
	s_addc_u32 s9, s75, 0
	global_load_dword v0, v249, s[8:9] offset:3584
	s_add_u32 s6, s13, 1
	s_min_u32 s6, s6, 0x27ff
	s_mul_i32 s7, s6, 0x2f00
	s_add_u32 s7, s7, 0x2000
	s_add_u32 s8, s74, s7
	s_addc_u32 s9, s75, 0
	global_load_dword v22, v249, s[8:9] offset:3584
	s_add_u32 s6, s13, 2
	s_min_u32 s6, s6, 0x27ff
	s_mul_i32 s7, s6, 0x2f00
	s_add_u32 s7, s7, 0x2000
	s_add_u32 s8, s74, s7
	s_addc_u32 s9, s75, 0
	global_load_dword v44, v249, s[8:9] offset:3584
	s_add_u32 s6, s13, 3
	s_min_u32 s6, s6, 0x27ff
	s_mul_i32 s7, s6, 0x2f00
	s_add_u32 s7, s7, 0x2000
	s_add_u32 s8, s74, s7
	s_addc_u32 s9, s75, 0
	global_load_dword v66, v249, s[8:9] offset:3584
	s_add_u32 s6, s13, 4
	s_min_u32 s6, s6, 0x27ff
	s_mul_i32 s7, s6, 0x2f00
	s_add_u32 s7, s7, 0x2000
	s_add_u32 s8, s74, s7
	s_addc_u32 s9, s75, 0
	global_load_dword v88, v249, s[8:9] offset:3584
	s_mov_b32 s6, s13
	s_min_u32 s6, s6, 0x27ff
	s_mul_i32 s7, s6, 0x2f00
	s_add_u32 s7, s7, 0x2000
	s_add_u32 s8, s74, s7
	s_addc_u32 s9, s75, 0
	global_load_dwordx4 v[10:13], v248, s[8:9]
	global_load_dwordx4 v[14:17], v248, s[8:9] offset:1024
	global_load_dwordx4 v[18:21], v248, s[8:9] offset:2048
	s_lshl_b32 s7, s6, 10
	s_add_u32 s8, s72, s7
	s_addc_u32 s9, s73, 0
	global_load_dwordx4 v[2:5], v248, s[8:9]
	s_add_u32 s8, s8, 0xa00000
	s_addc_u32 s9, s9, 0
	global_load_dwordx4 v[6:9], v248, s[8:9]
	s_add_u32 s6, s13, 1
	s_min_u32 s6, s6, 0x27ff
	s_mul_i32 s7, s6, 0x2f00
	s_add_u32 s7, s7, 0x2000
	s_add_u32 s8, s74, s7
	s_addc_u32 s9, s75, 0
	global_load_dwordx4 v[32:35], v248, s[8:9]
	global_load_dwordx4 v[36:39], v248, s[8:9] offset:1024
	global_load_dwordx4 v[40:43], v248, s[8:9] offset:2048
	s_lshl_b32 s7, s6, 10
	s_add_u32 s8, s72, s7
	s_addc_u32 s9, s73, 0
	global_load_dwordx4 v[24:27], v248, s[8:9]
	s_add_u32 s8, s8, 0xa00000
	s_addc_u32 s9, s9, 0
	global_load_dwordx4 v[28:31], v248, s[8:9]
	s_add_u32 s6, s13, 2
	s_min_u32 s6, s6, 0x27ff
	s_mul_i32 s7, s6, 0x2f00
	s_add_u32 s7, s7, 0x2000
	s_add_u32 s8, s74, s7
	s_addc_u32 s9, s75, 0
	global_load_dwordx4 v[54:57], v248, s[8:9]
	global_load_dwordx4 v[58:61], v248, s[8:9] offset:1024
	global_load_dwordx4 v[62:65], v248, s[8:9] offset:2048
	s_lshl_b32 s7, s6, 10
	s_add_u32 s8, s72, s7
	s_addc_u32 s9, s73, 0
	global_load_dwordx4 v[46:49], v248, s[8:9]
	s_add_u32 s8, s8, 0xa00000
	s_addc_u32 s9, s9, 0
	global_load_dwordx4 v[50:53], v248, s[8:9]
	s_add_u32 s6, s13, 3
	s_min_u32 s6, s6, 0x27ff
	s_mul_i32 s7, s6, 0x2f00
	s_add_u32 s7, s7, 0x2000
	s_add_u32 s8, s74, s7
	s_addc_u32 s9, s75, 0
	global_load_dwordx4 v[76:79], v248, s[8:9]
	global_load_dwordx4 v[80:83], v248, s[8:9] offset:1024
	global_load_dwordx4 v[84:87], v248, s[8:9] offset:2048
	s_lshl_b32 s7, s6, 10
	s_add_u32 s8, s72, s7
	s_addc_u32 s9, s73, 0
	global_load_dwordx4 v[68:71], v248, s[8:9]
	s_add_u32 s8, s8, 0xa00000
	s_addc_u32 s9, s9, 0
	global_load_dwordx4 v[72:75], v248, s[8:9]
	s_add_u32 s6, s13, 4
	s_min_u32 s6, s6, 0x27ff
	s_mul_i32 s7, s6, 0x2f00
	s_add_u32 s7, s7, 0x2000
	s_add_u32 s8, s74, s7
	s_addc_u32 s9, s75, 0
	global_load_dwordx4 v[98:101], v248, s[8:9]
	global_load_dwordx4 v[102:105], v248, s[8:9] offset:1024
	global_load_dwordx4 v[106:109], v248, s[8:9] offset:2048
	s_lshl_b32 s7, s6, 10
	s_add_u32 s8, s72, s7
	s_addc_u32 s9, s73, 0
	global_load_dwordx4 v[90:93], v248, s[8:9]
	s_add_u32 s8, s8, 0xa00000
	s_addc_u32 s9, s9, 0
	global_load_dwordx4 v[94:97], v248, s[8:9]
	s_mov_b32 s8, s16
	s_mov_b32 s9, s17
	global_load_dwordx4 v[188:191], v248, s[8:9]
	global_load_dwordx4 v[192:195], v248, s[8:9] offset:1024
	global_load_dwordx4 v[196:199], v248, s[8:9] offset:2048
	global_load_dwordx4 v[200:203], v248, s[8:9] offset:3072
	s_add_u32 s8, s8, 0x1000
	s_addc_u32 s9, s9, 0
	global_load_dwordx4 v[204:207], v248, s[8:9]
	global_load_dwordx4 v[208:211], v248, s[8:9] offset:1024
	global_load_dwordx4 v[212:215], v248, s[8:9] offset:2048
	global_load_dwordx4 v[216:219], v248, s[8:9] offset:3072
	s_add_u32 s8, s8, 0x1000
	s_addc_u32 s9, s9, 0
	global_load_dwordx4 v[220:223], v248, s[8:9]
	global_load_dwordx4 v[224:227], v248, s[8:9] offset:1024
	global_load_dwordx4 v[228:231], v248, s[8:9] offset:2048
	s_waitcnt vmcnt(36)
	v_mul_f32_e32 v241, 0xbfb8aa3b, v0
	v_exp_f32_e32 v241, v241
	s_nop 0
	v_add_f32_e32 v241, 1.0, v241
	v_div_scale_f32 v242, s[24:25], v241, v241, 1.0
	v_rcp_f32_e32 v243, v242
	s_nop 0
	v_fma_f32 v244, -v242, v243, 1.0
	v_fmac_f32_e32 v243, v244, v243
	v_div_scale_f32 v244, vcc, 1.0, v241, 1.0
	v_mul_f32_e32 v245, v244, v243
	v_fma_f32 v246, -v242, v245, v244
	v_fmac_f32_e32 v245, v246, v243
	v_fma_f32 v242, -v242, v245, v244
	v_div_fmas_f32 v242, v242, v243, v245
	v_div_fixup_f32 v236, v242, v241, 1.0
	v_mul_f32_e32 v241, 0xbfb8aa3b, v22
	v_exp_f32_e32 v241, v241
	s_nop 0
	v_add_f32_e32 v241, 1.0, v241
	v_div_scale_f32 v242, s[24:25], v241, v241, 1.0
	v_rcp_f32_e32 v243, v242
	s_nop 0
	v_fma_f32 v244, -v242, v243, 1.0
	v_fmac_f32_e32 v243, v244, v243
	v_div_scale_f32 v244, vcc, 1.0, v241, 1.0
	v_mul_f32_e32 v245, v244, v243
	v_fma_f32 v246, -v242, v245, v244
	v_fmac_f32_e32 v245, v246, v243
	v_fma_f32 v242, -v242, v245, v244
	v_div_fmas_f32 v242, v242, v243, v245
	v_div_fixup_f32 v237, v242, v241, 1.0
	v_mul_f32_e32 v241, 0xbfb8aa3b, v44
	v_exp_f32_e32 v241, v241
	s_nop 0
	v_add_f32_e32 v241, 1.0, v241
	v_div_scale_f32 v242, s[24:25], v241, v241, 1.0
	v_rcp_f32_e32 v243, v242
	s_nop 0
	v_fma_f32 v244, -v242, v243, 1.0
	v_fmac_f32_e32 v243, v244, v243
	v_div_scale_f32 v244, vcc, 1.0, v241, 1.0
	v_mul_f32_e32 v245, v244, v243
	v_fma_f32 v246, -v242, v245, v244
	v_fmac_f32_e32 v245, v246, v243
	v_fma_f32 v242, -v242, v245, v244
	v_div_fmas_f32 v242, v242, v243, v245
	v_div_fixup_f32 v238, v242, v241, 1.0
	v_mul_f32_e32 v241, 0xbfb8aa3b, v66
	v_exp_f32_e32 v241, v241
	s_nop 0
	v_add_f32_e32 v241, 1.0, v241
	v_div_scale_f32 v242, s[24:25], v241, v241, 1.0
	v_rcp_f32_e32 v243, v242
	s_nop 0
	v_fma_f32 v244, -v242, v243, 1.0
	v_fmac_f32_e32 v243, v244, v243
	v_div_scale_f32 v244, vcc, 1.0, v241, 1.0
	v_mul_f32_e32 v245, v244, v243
	v_fma_f32 v246, -v242, v245, v244
	v_fmac_f32_e32 v245, v246, v243
	v_fma_f32 v242, -v242, v245, v244
	v_div_fmas_f32 v242, v242, v243, v245
	v_div_fixup_f32 v239, v242, v241, 1.0
	v_mul_f32_e32 v241, 0xbfb8aa3b, v88
	v_exp_f32_e32 v241, v241
	s_nop 0
	v_add_f32_e32 v241, 1.0, v241
	v_div_scale_f32 v242, s[24:25], v241, v241, 1.0
	v_rcp_f32_e32 v243, v242
	s_nop 0
	v_fma_f32 v244, -v242, v243, 1.0
	v_fmac_f32_e32 v243, v244, v243
	v_div_scale_f32 v244, vcc, 1.0, v241, 1.0
	v_mul_f32_e32 v245, v244, v243
	v_fma_f32 v246, -v242, v245, v244
	v_fmac_f32_e32 v245, v246, v243
	v_fma_f32 v242, -v242, v245, v244
	v_div_fmas_f32 v242, v242, v243, v245
	v_div_fixup_f32 v240, v242, v241, 1.0
	v_mov_b32_e32 v168, 0
	v_mov_b32_e32 v169, 0
	v_mov_b32_e32 v170, 0
	v_mov_b32_e32 v171, 0
	v_mov_b32_e32 v172, 0
	v_mov_b32_e32 v173, 0
	v_mov_b32_e32 v174, 0
	v_mov_b32_e32 v175, 0
	v_mov_b32_e32 v176, 0
	v_mov_b32_e32 v177, 0
	v_mov_b32_e32 v178, 0
	v_mov_b32_e32 v179, 0
	v_mov_b32_e32 v180, 0
	v_mov_b32_e32 v181, 0
	v_mov_b32_e32 v182, 0
	v_mov_b32_e32 v183, 0
	v_mov_b32_e32 v184, 0
	v_mov_b32_e32 v185, 0
	v_mov_b32_e32 v186, 0
	v_mov_b32_e32 v187, 0
	global_load_dwordx4 v[232:235], v248, s[8:9] offset:3072
	s_add_u32 s8, s8, 0x1000
	s_addc_u32 s9, s9, 0
	s_waitcnt vmcnt(11)
	v_readlane_b32 s50, v236, 0
	v_readlane_b32 s52, v237, 0
	v_readlane_b32 s54, v238, 0
	v_readlane_b32 s56, v239, 0
	v_readlane_b32 s58, v240, 0
	v_pk_fma_f32 v[168:169], v[188:189], s[50:51], v[168:169] op_sel_hi:[1,0,1]
	v_pk_fma_f32 v[170:171], v[190:191], s[50:51], v[170:171] op_sel_hi:[1,0,1]
	v_pk_fma_f32 v[172:173], v[188:189], s[52:53], v[172:173] op_sel_hi:[1,0,1]
	v_pk_fma_f32 v[174:175], v[190:191], s[52:53], v[174:175] op_sel_hi:[1,0,1]
	v_pk_fma_f32 v[176:177], v[188:189], s[54:55], v[176:177] op_sel_hi:[1,0,1]
	v_pk_fma_f32 v[178:179], v[190:191], s[54:55], v[178:179] op_sel_hi:[1,0,1]
	v_pk_fma_f32 v[180:181], v[188:189], s[56:57], v[180:181] op_sel_hi:[1,0,1]
	v_pk_fma_f32 v[182:183], v[190:191], s[56:57], v[182:183] op_sel_hi:[1,0,1]
	v_pk_fma_f32 v[184:185], v[188:189], s[58:59], v[184:185] op_sel_hi:[1,0,1]
	v_pk_fma_f32 v[186:187], v[190:191], s[58:59], v[186:187] op_sel_hi:[1,0,1]
	global_load_dwordx4 v[188:191], v248, s[8:9]
	s_waitcnt vmcnt(11)
	v_readlane_b32 s50, v236, 1
	v_readlane_b32 s52, v237, 1
	v_readlane_b32 s54, v238, 1
	v_readlane_b32 s56, v239, 1
	v_readlane_b32 s58, v240, 1
	v_pk_fma_f32 v[168:169], v[192:193], s[50:51], v[168:169] op_sel_hi:[1,0,1]
	v_pk_fma_f32 v[170:171], v[194:195], s[50:51], v[170:171] op_sel_hi:[1,0,1]
	v_pk_fma_f32 v[172:173], v[192:193], s[52:53], v[172:173] op_sel_hi:[1,0,1]
	v_pk_fma_f32 v[174:175], v[194:195], s[52:53], v[174:175] op_sel_hi:[1,0,1]
	v_pk_fma_f32 v[176:177], v[192:193], s[54:55], v[176:177] op_sel_hi:[1,0,1]
	v_pk_fma_f32 v[178:179], v[194:195], s[54:55], v[178:179] op_sel_hi:[1,0,1]
	v_pk_fma_f32 v[180:181], v[192:193], s[56:57], v[180:181] op_sel_hi:[1,0,1]
	v_pk_fma_f32 v[182:183], v[194:195], s[56:57], v[182:183] op_sel_hi:[1,0,1]
	v_pk_fma_f32 v[184:185], v[192:193], s[58:59], v[184:185] op_sel_hi:[1,0,1]
	v_pk_fma_f32 v[186:187], v[194:195], s[58:59], v[186:187] op_sel_hi:[1,0,1]
	global_load_dwordx4 v[192:195], v248, s[8:9] offset:1024
	s_waitcnt vmcnt(11)
	v_readlane_b32 s50, v236, 2
	v_readlane_b32 s52, v237, 2
	v_readlane_b32 s54, v238, 2
	v_readlane_b32 s56, v239, 2
	v_readlane_b32 s58, v240, 2
	v_pk_fma_f32 v[168:169], v[196:197], s[50:51], v[168:169] op_sel_hi:[1,0,1]
	v_pk_fma_f32 v[170:171], v[198:199], s[50:51], v[170:171] op_sel_hi:[1,0,1]
	v_pk_fma_f32 v[172:173], v[196:197], s[52:53], v[172:173] op_sel_hi:[1,0,1]
	v_pk_fma_f32 v[174:175], v[198:199], s[52:53], v[174:175] op_sel_hi:[1,0,1]
	v_pk_fma_f32 v[176:177], v[196:197], s[54:55], v[176:177] op_sel_hi:[1,0,1]
	v_pk_fma_f32 v[178:179], v[198:199], s[54:55], v[178:179] op_sel_hi:[1,0,1]
	v_pk_fma_f32 v[180:181], v[196:197], s[56:57], v[180:181] op_sel_hi:[1,0,1]
	v_pk_fma_f32 v[182:183], v[198:199], s[56:57], v[182:183] op_sel_hi:[1,0,1]
	v_pk_fma_f32 v[184:185], v[196:197], s[58:59], v[184:185] op_sel_hi:[1,0,1]
	v_pk_fma_f32 v[186:187], v[198:199], s[58:59], v[186:187] op_sel_hi:[1,0,1]
	global_load_dwordx4 v[196:199], v248, s[8:9] offset:2048
	s_waitcnt vmcnt(11)
	v_readlane_b32 s50, v236, 3
	v_readlane_b32 s52, v237, 3
	v_readlane_b32 s54, v238, 3
	v_readlane_b32 s56, v239, 3
	v_readlane_b32 s58, v240, 3
	v_pk_fma_f32 v[168:169], v[200:201], s[50:51], v[168:169] op_sel_hi:[1,0,1]
	v_pk_fma_f32 v[170:171], v[202:203], s[50:51], v[170:171] op_sel_hi:[1,0,1]
	v_pk_fma_f32 v[172:173], v[200:201], s[52:53], v[172:173] op_sel_hi:[1,0,1]
	v_pk_fma_f32 v[174:175], v[202:203], s[52:53], v[174:175] op_sel_hi:[1,0,1]
	v_pk_fma_f32 v[176:177], v[200:201], s[54:55], v[176:177] op_sel_hi:[1,0,1]
	v_pk_fma_f32 v[178:179], v[202:203], s[54:55], v[178:179] op_sel_hi:[1,0,1]
	v_pk_fma_f32 v[180:181], v[200:201], s[56:57], v[180:181] op_sel_hi:[1,0,1]
	v_pk_fma_f32 v[182:183], v[202:203], s[56:57], v[182:183] op_sel_hi:[1,0,1]
	v_pk_fma_f32 v[184:185], v[200:201], s[58:59], v[184:185] op_sel_hi:[1,0,1]
	v_pk_fma_f32 v[186:187], v[202:203], s[58:59], v[186:187] op_sel_hi:[1,0,1]
	global_load_dwordx4 v[200:203], v248, s[8:9] offset:3072
	s_add_u32 s8, s8, 0x1000
	s_addc_u32 s9, s9, 0
	s_waitcnt vmcnt(11)
	v_readlane_b32 s50, v236, 4
	v_readlane_b32 s52, v237, 4
	v_readlane_b32 s54, v238, 4
	v_readlane_b32 s56, v239, 4
	v_readlane_b32 s58, v240, 4
	v_pk_fma_f32 v[168:169], v[204:205], s[50:51], v[168:169] op_sel_hi:[1,0,1]
	v_pk_fma_f32 v[170:171], v[206:207], s[50:51], v[170:171] op_sel_hi:[1,0,1]
	v_pk_fma_f32 v[172:173], v[204:205], s[52:53], v[172:173] op_sel_hi:[1,0,1]
	v_pk_fma_f32 v[174:175], v[206:207], s[52:53], v[174:175] op_sel_hi:[1,0,1]
	v_pk_fma_f32 v[176:177], v[204:205], s[54:55], v[176:177] op_sel_hi:[1,0,1]
	v_pk_fma_f32 v[178:179], v[206:207], s[54:55], v[178:179] op_sel_hi:[1,0,1]
	v_pk_fma_f32 v[180:181], v[204:205], s[56:57], v[180:181] op_sel_hi:[1,0,1]
	v_pk_fma_f32 v[182:183], v[206:207], s[56:57], v[182:183] op_sel_hi:[1,0,1]
	v_pk_fma_f32 v[184:185], v[204:205], s[58:59], v[184:185] op_sel_hi:[1,0,1]
	v_pk_fma_f32 v[186:187], v[206:207], s[58:59], v[186:187] op_sel_hi:[1,0,1]
	global_load_dwordx4 v[204:207], v248, s[8:9]
	s_waitcnt vmcnt(11)
	v_readlane_b32 s50, v236, 5
	v_readlane_b32 s52, v237, 5
	v_readlane_b32 s54, v238, 5
	v_readlane_b32 s56, v239, 5
	v_readlane_b32 s58, v240, 5
	v_pk_fma_f32 v[168:169], v[208:209], s[50:51], v[168:169] op_sel_hi:[1,0,1]
	v_pk_fma_f32 v[170:171], v[210:211], s[50:51], v[170:171] op_sel_hi:[1,0,1]
	v_pk_fma_f32 v[172:173], v[208:209], s[52:53], v[172:173] op_sel_hi:[1,0,1]
	v_pk_fma_f32 v[174:175], v[210:211], s[52:53], v[174:175] op_sel_hi:[1,0,1]
	v_pk_fma_f32 v[176:177], v[208:209], s[54:55], v[176:177] op_sel_hi:[1,0,1]
	v_pk_fma_f32 v[178:179], v[210:211], s[54:55], v[178:179] op_sel_hi:[1,0,1]
	v_pk_fma_f32 v[180:181], v[208:209], s[56:57], v[180:181] op_sel_hi:[1,0,1]
	v_pk_fma_f32 v[182:183], v[210:211], s[56:57], v[182:183] op_sel_hi:[1,0,1]
	v_pk_fma_f32 v[184:185], v[208:209], s[58:59], v[184:185] op_sel_hi:[1,0,1]
	v_pk_fma_f32 v[186:187], v[210:211], s[58:59], v[186:187] op_sel_hi:[1,0,1]
	global_load_dwordx4 v[208:211], v248, s[8:9] offset:1024
	s_waitcnt vmcnt(11)
	v_readlane_b32 s50, v236, 6
	v_readlane_b32 s52, v237, 6
	v_readlane_b32 s54, v238, 6
	v_readlane_b32 s56, v239, 6
	v_readlane_b32 s58, v240, 6
	v_pk_fma_f32 v[168:169], v[212:213], s[50:51], v[168:169] op_sel_hi:[1,0,1]
	v_pk_fma_f32 v[170:171], v[214:215], s[50:51], v[170:171] op_sel_hi:[1,0,1]
	v_pk_fma_f32 v[172:173], v[212:213], s[52:53], v[172:173] op_sel_hi:[1,0,1]
	v_pk_fma_f32 v[174:175], v[214:215], s[52:53], v[174:175] op_sel_hi:[1,0,1]
	v_pk_fma_f32 v[176:177], v[212:213], s[54:55], v[176:177] op_sel_hi:[1,0,1]
	v_pk_fma_f32 v[178:179], v[214:215], s[54:55], v[178:179] op_sel_hi:[1,0,1]
	v_pk_fma_f32 v[180:181], v[212:213], s[56:57], v[180:181] op_sel_hi:[1,0,1]
	v_pk_fma_f32 v[182:183], v[214:215], s[56:57], v[182:183] op_sel_hi:[1,0,1]
	v_pk_fma_f32 v[184:185], v[212:213], s[58:59], v[184:185] op_sel_hi:[1,0,1]
	v_pk_fma_f32 v[186:187], v[214:215], s[58:59], v[186:187] op_sel_hi:[1,0,1]
	global_load_dwordx4 v[212:215], v248, s[8:9] offset:2048
	s_waitcnt vmcnt(11)
	v_readlane_b32 s50, v236, 7
	v_readlane_b32 s52, v237, 7
	v_readlane_b32 s54, v238, 7
	v_readlane_b32 s56, v239, 7
	v_readlane_b32 s58, v240, 7
	v_pk_fma_f32 v[168:169], v[216:217], s[50:51], v[168:169] op_sel_hi:[1,0,1]
	v_pk_fma_f32 v[170:171], v[218:219], s[50:51], v[170:171] op_sel_hi:[1,0,1]
	v_pk_fma_f32 v[172:173], v[216:217], s[52:53], v[172:173] op_sel_hi:[1,0,1]
	v_pk_fma_f32 v[174:175], v[218:219], s[52:53], v[174:175] op_sel_hi:[1,0,1]
	v_pk_fma_f32 v[176:177], v[216:217], s[54:55], v[176:177] op_sel_hi:[1,0,1]
	v_pk_fma_f32 v[178:179], v[218:219], s[54:55], v[178:179] op_sel_hi:[1,0,1]
	v_pk_fma_f32 v[180:181], v[216:217], s[56:57], v[180:181] op_sel_hi:[1,0,1]
	v_pk_fma_f32 v[182:183], v[218:219], s[56:57], v[182:183] op_sel_hi:[1,0,1]
	v_pk_fma_f32 v[184:185], v[216:217], s[58:59], v[184:185] op_sel_hi:[1,0,1]
	v_pk_fma_f32 v[186:187], v[218:219], s[58:59], v[186:187] op_sel_hi:[1,0,1]
	global_load_dwordx4 v[216:219], v248, s[8:9] offset:3072
	s_add_u32 s8, s8, 0x1000
	s_addc_u32 s9, s9, 0
	s_waitcnt vmcnt(11)
	v_readlane_b32 s50, v236, 8
	v_readlane_b32 s52, v237, 8
	v_readlane_b32 s54, v238, 8
	v_readlane_b32 s56, v239, 8
	v_readlane_b32 s58, v240, 8
	v_pk_fma_f32 v[168:169], v[220:221], s[50:51], v[168:169] op_sel_hi:[1,0,1]
	v_pk_fma_f32 v[170:171], v[222:223], s[50:51], v[170:171] op_sel_hi:[1,0,1]
	v_pk_fma_f32 v[172:173], v[220:221], s[52:53], v[172:173] op_sel_hi:[1,0,1]
	v_pk_fma_f32 v[174:175], v[222:223], s[52:53], v[174:175] op_sel_hi:[1,0,1]
	v_pk_fma_f32 v[176:177], v[220:221], s[54:55], v[176:177] op_sel_hi:[1,0,1]
	v_pk_fma_f32 v[178:179], v[222:223], s[54:55], v[178:179] op_sel_hi:[1,0,1]
	v_pk_fma_f32 v[180:181], v[220:221], s[56:57], v[180:181] op_sel_hi:[1,0,1]
	v_pk_fma_f32 v[182:183], v[222:223], s[56:57], v[182:183] op_sel_hi:[1,0,1]
	v_pk_fma_f32 v[184:185], v[220:221], s[58:59], v[184:185] op_sel_hi:[1,0,1]
	v_pk_fma_f32 v[186:187], v[222:223], s[58:59], v[186:187] op_sel_hi:[1,0,1]
	global_load_dwordx4 v[220:223], v248, s[8:9]
	s_waitcnt vmcnt(11)
	v_readlane_b32 s50, v236, 9
	v_readlane_b32 s52, v237, 9
	v_readlane_b32 s54, v238, 9
	v_readlane_b32 s56, v239, 9
	v_readlane_b32 s58, v240, 9
	v_pk_fma_f32 v[168:169], v[224:225], s[50:51], v[168:169] op_sel_hi:[1,0,1]
	v_pk_fma_f32 v[170:171], v[226:227], s[50:51], v[170:171] op_sel_hi:[1,0,1]
	v_pk_fma_f32 v[172:173], v[224:225], s[52:53], v[172:173] op_sel_hi:[1,0,1]
	v_pk_fma_f32 v[174:175], v[226:227], s[52:53], v[174:175] op_sel_hi:[1,0,1]
	v_pk_fma_f32 v[176:177], v[224:225], s[54:55], v[176:177] op_sel_hi:[1,0,1]
	v_pk_fma_f32 v[178:179], v[226:227], s[54:55], v[178:179] op_sel_hi:[1,0,1]
	v_pk_fma_f32 v[180:181], v[224:225], s[56:57], v[180:181] op_sel_hi:[1,0,1]
	v_pk_fma_f32 v[182:183], v[226:227], s[56:57], v[182:183] op_sel_hi:[1,0,1]
	v_pk_fma_f32 v[184:185], v[224:225], s[58:59], v[184:185] op_sel_hi:[1,0,1]
	v_pk_fma_f32 v[186:187], v[226:227], s[58:59], v[186:187] op_sel_hi:[1,0,1]
	global_load_dwordx4 v[224:227], v248, s[8:9] offset:1024
	s_waitcnt vmcnt(11)
	v_readlane_b32 s50, v236, 10
	v_readlane_b32 s52, v237, 10
	v_readlane_b32 s54, v238, 10
	v_readlane_b32 s56, v239, 10
	v_readlane_b32 s58, v240, 10
	v_pk_fma_f32 v[168:169], v[228:229], s[50:51], v[168:169] op_sel_hi:[1,0,1]
	v_pk_fma_f32 v[170:171], v[230:231], s[50:51], v[170:171] op_sel_hi:[1,0,1]
	v_pk_fma_f32 v[172:173], v[228:229], s[52:53], v[172:173] op_sel_hi:[1,0,1]
	v_pk_fma_f32 v[174:175], v[230:231], s[52:53], v[174:175] op_sel_hi:[1,0,1]
	v_pk_fma_f32 v[176:177], v[228:229], s[54:55], v[176:177] op_sel_hi:[1,0,1]
	v_pk_fma_f32 v[178:179], v[230:231], s[54:55], v[178:179] op_sel_hi:[1,0,1]
	v_pk_fma_f32 v[180:181], v[228:229], s[56:57], v[180:181] op_sel_hi:[1,0,1]
	v_pk_fma_f32 v[182:183], v[230:231], s[56:57], v[182:183] op_sel_hi:[1,0,1]
	v_pk_fma_f32 v[184:185], v[228:229], s[58:59], v[184:185] op_sel_hi:[1,0,1]
	v_pk_fma_f32 v[186:187], v[230:231], s[58:59], v[186:187] op_sel_hi:[1,0,1]
	global_load_dwordx4 v[228:231], v248, s[8:9] offset:2048
	s_waitcnt vmcnt(11)
	v_readlane_b32 s50, v236, 11
	v_readlane_b32 s52, v237, 11
	v_readlane_b32 s54, v238, 11
	v_readlane_b32 s56, v239, 11
	v_readlane_b32 s58, v240, 11
	v_pk_fma_f32 v[168:169], v[232:233], s[50:51], v[168:169] op_sel_hi:[1,0,1]
	v_pk_fma_f32 v[170:171], v[234:235], s[50:51], v[170:171] op_sel_hi:[1,0,1]
	v_pk_fma_f32 v[172:173], v[232:233], s[52:53], v[172:173] op_sel_hi:[1,0,1]
	v_pk_fma_f32 v[174:175], v[234:235], s[52:53], v[174:175] op_sel_hi:[1,0,1]
	v_pk_fma_f32 v[176:177], v[232:233], s[54:55], v[176:177] op_sel_hi:[1,0,1]
	v_pk_fma_f32 v[178:179], v[234:235], s[54:55], v[178:179] op_sel_hi:[1,0,1]
	v_pk_fma_f32 v[180:181], v[232:233], s[56:57], v[180:181] op_sel_hi:[1,0,1]
	v_pk_fma_f32 v[182:183], v[234:235], s[56:57], v[182:183] op_sel_hi:[1,0,1]
	v_pk_fma_f32 v[184:185], v[232:233], s[58:59], v[184:185] op_sel_hi:[1,0,1]
	v_pk_fma_f32 v[186:187], v[234:235], s[58:59], v[186:187] op_sel_hi:[1,0,1]
	global_load_dwordx4 v[232:235], v248, s[8:9] offset:3072
	s_add_u32 s8, s8, 0x1000
	s_addc_u32 s9, s9, 0
	s_waitcnt vmcnt(11)
	v_readlane_b32 s50, v236, 12
	v_readlane_b32 s52, v237, 12
	v_readlane_b32 s54, v238, 12
	v_readlane_b32 s56, v239, 12
	v_readlane_b32 s58, v240, 12
	v_pk_fma_f32 v[168:169], v[188:189], s[50:51], v[168:169] op_sel_hi:[1,0,1]
	v_pk_fma_f32 v[170:171], v[190:191], s[50:51], v[170:171] op_sel_hi:[1,0,1]
	v_pk_fma_f32 v[172:173], v[188:189], s[52:53], v[172:173] op_sel_hi:[1,0,1]
	v_pk_fma_f32 v[174:175], v[190:191], s[52:53], v[174:175] op_sel_hi:[1,0,1]
	v_pk_fma_f32 v[176:177], v[188:189], s[54:55], v[176:177] op_sel_hi:[1,0,1]
	v_pk_fma_f32 v[178:179], v[190:191], s[54:55], v[178:179] op_sel_hi:[1,0,1]
	v_pk_fma_f32 v[180:181], v[188:189], s[56:57], v[180:181] op_sel_hi:[1,0,1]
	v_pk_fma_f32 v[182:183], v[190:191], s[56:57], v[182:183] op_sel_hi:[1,0,1]
	v_pk_fma_f32 v[184:185], v[188:189], s[58:59], v[184:185] op_sel_hi:[1,0,1]
	v_pk_fma_f32 v[186:187], v[190:191], s[58:59], v[186:187] op_sel_hi:[1,0,1]
	global_load_dwordx4 v[188:191], v248, s[8:9]
	s_waitcnt vmcnt(11)
	v_readlane_b32 s50, v236, 13
	v_readlane_b32 s52, v237, 13
	v_readlane_b32 s54, v238, 13
	v_readlane_b32 s56, v239, 13
	v_readlane_b32 s58, v240, 13
	v_pk_fma_f32 v[168:169], v[192:193], s[50:51], v[168:169] op_sel_hi:[1,0,1]
	v_pk_fma_f32 v[170:171], v[194:195], s[50:51], v[170:171] op_sel_hi:[1,0,1]
	v_pk_fma_f32 v[172:173], v[192:193], s[52:53], v[172:173] op_sel_hi:[1,0,1]
	v_pk_fma_f32 v[174:175], v[194:195], s[52:53], v[174:175] op_sel_hi:[1,0,1]
	v_pk_fma_f32 v[176:177], v[192:193], s[54:55], v[176:177] op_sel_hi:[1,0,1]
	v_pk_fma_f32 v[178:179], v[194:195], s[54:55], v[178:179] op_sel_hi:[1,0,1]
	v_pk_fma_f32 v[180:181], v[192:193], s[56:57], v[180:181] op_sel_hi:[1,0,1]
	v_pk_fma_f32 v[182:183], v[194:195], s[56:57], v[182:183] op_sel_hi:[1,0,1]
	v_pk_fma_f32 v[184:185], v[192:193], s[58:59], v[184:185] op_sel_hi:[1,0,1]
	v_pk_fma_f32 v[186:187], v[194:195], s[58:59], v[186:187] op_sel_hi:[1,0,1]
	global_load_dwordx4 v[192:195], v248, s[8:9] offset:1024
	s_waitcnt vmcnt(11)
	v_readlane_b32 s50, v236, 14
	v_readlane_b32 s52, v237, 14
	v_readlane_b32 s54, v238, 14
	v_readlane_b32 s56, v239, 14
	v_readlane_b32 s58, v240, 14
	v_pk_fma_f32 v[168:169], v[196:197], s[50:51], v[168:169] op_sel_hi:[1,0,1]
	v_pk_fma_f32 v[170:171], v[198:199], s[50:51], v[170:171] op_sel_hi:[1,0,1]
	v_pk_fma_f32 v[172:173], v[196:197], s[52:53], v[172:173] op_sel_hi:[1,0,1]
	v_pk_fma_f32 v[174:175], v[198:199], s[52:53], v[174:175] op_sel_hi:[1,0,1]
	v_pk_fma_f32 v[176:177], v[196:197], s[54:55], v[176:177] op_sel_hi:[1,0,1]
	v_pk_fma_f32 v[178:179], v[198:199], s[54:55], v[178:179] op_sel_hi:[1,0,1]
	v_pk_fma_f32 v[180:181], v[196:197], s[56:57], v[180:181] op_sel_hi:[1,0,1]
	v_pk_fma_f32 v[182:183], v[198:199], s[56:57], v[182:183] op_sel_hi:[1,0,1]
	v_pk_fma_f32 v[184:185], v[196:197], s[58:59], v[184:185] op_sel_hi:[1,0,1]
	v_pk_fma_f32 v[186:187], v[198:199], s[58:59], v[186:187] op_sel_hi:[1,0,1]
	global_load_dwordx4 v[196:199], v248, s[8:9] offset:2048
	s_waitcnt vmcnt(11)
	v_readlane_b32 s50, v236, 15
	v_readlane_b32 s52, v237, 15
	v_readlane_b32 s54, v238, 15
	v_readlane_b32 s56, v239, 15
	v_readlane_b32 s58, v240, 15
	v_pk_fma_f32 v[168:169], v[200:201], s[50:51], v[168:169] op_sel_hi:[1,0,1]
	v_pk_fma_f32 v[170:171], v[202:203], s[50:51], v[170:171] op_sel_hi:[1,0,1]
	v_pk_fma_f32 v[172:173], v[200:201], s[52:53], v[172:173] op_sel_hi:[1,0,1]
	v_pk_fma_f32 v[174:175], v[202:203], s[52:53], v[174:175] op_sel_hi:[1,0,1]
	v_pk_fma_f32 v[176:177], v[200:201], s[54:55], v[176:177] op_sel_hi:[1,0,1]
	v_pk_fma_f32 v[178:179], v[202:203], s[54:55], v[178:179] op_sel_hi:[1,0,1]
	v_pk_fma_f32 v[180:181], v[200:201], s[56:57], v[180:181] op_sel_hi:[1,0,1]
	v_pk_fma_f32 v[182:183], v[202:203], s[56:57], v[182:183] op_sel_hi:[1,0,1]
	v_pk_fma_f32 v[184:185], v[200:201], s[58:59], v[184:185] op_sel_hi:[1,0,1]
	v_pk_fma_f32 v[186:187], v[202:203], s[58:59], v[186:187] op_sel_hi:[1,0,1]
	global_load_dwordx4 v[200:203], v248, s[8:9] offset:3072
	s_add_u32 s8, s8, 0x1000
	s_addc_u32 s9, s9, 0
	s_waitcnt vmcnt(11)
	v_readlane_b32 s50, v236, 16
	v_readlane_b32 s52, v237, 16
	v_readlane_b32 s54, v238, 16
	v_readlane_b32 s56, v239, 16
	v_readlane_b32 s58, v240, 16
	v_pk_fma_f32 v[168:169], v[204:205], s[50:51], v[168:169] op_sel_hi:[1,0,1]
	v_pk_fma_f32 v[170:171], v[206:207], s[50:51], v[170:171] op_sel_hi:[1,0,1]
	v_pk_fma_f32 v[172:173], v[204:205], s[52:53], v[172:173] op_sel_hi:[1,0,1]
	v_pk_fma_f32 v[174:175], v[206:207], s[52:53], v[174:175] op_sel_hi:[1,0,1]
	v_pk_fma_f32 v[176:177], v[204:205], s[54:55], v[176:177] op_sel_hi:[1,0,1]
	v_pk_fma_f32 v[178:179], v[206:207], s[54:55], v[178:179] op_sel_hi:[1,0,1]
	v_pk_fma_f32 v[180:181], v[204:205], s[56:57], v[180:181] op_sel_hi:[1,0,1]
	v_pk_fma_f32 v[182:183], v[206:207], s[56:57], v[182:183] op_sel_hi:[1,0,1]
	v_pk_fma_f32 v[184:185], v[204:205], s[58:59], v[184:185] op_sel_hi:[1,0,1]
	v_pk_fma_f32 v[186:187], v[206:207], s[58:59], v[186:187] op_sel_hi:[1,0,1]
	global_load_dwordx4 v[204:207], v248, s[8:9]
	s_waitcnt vmcnt(11)
	v_readlane_b32 s50, v236, 17
	v_readlane_b32 s52, v237, 17
	v_readlane_b32 s54, v238, 17
	v_readlane_b32 s56, v239, 17
	v_readlane_b32 s58, v240, 17
	v_pk_fma_f32 v[168:169], v[208:209], s[50:51], v[168:169] op_sel_hi:[1,0,1]
	v_pk_fma_f32 v[170:171], v[210:211], s[50:51], v[170:171] op_sel_hi:[1,0,1]
	v_pk_fma_f32 v[172:173], v[208:209], s[52:53], v[172:173] op_sel_hi:[1,0,1]
	v_pk_fma_f32 v[174:175], v[210:211], s[52:53], v[174:175] op_sel_hi:[1,0,1]
	v_pk_fma_f32 v[176:177], v[208:209], s[54:55], v[176:177] op_sel_hi:[1,0,1]
	v_pk_fma_f32 v[178:179], v[210:211], s[54:55], v[178:179] op_sel_hi:[1,0,1]
	v_pk_fma_f32 v[180:181], v[208:209], s[56:57], v[180:181] op_sel_hi:[1,0,1]
	v_pk_fma_f32 v[182:183], v[210:211], s[56:57], v[182:183] op_sel_hi:[1,0,1]
	v_pk_fma_f32 v[184:185], v[208:209], s[58:59], v[184:185] op_sel_hi:[1,0,1]
	v_pk_fma_f32 v[186:187], v[210:211], s[58:59], v[186:187] op_sel_hi:[1,0,1]
	global_load_dwordx4 v[208:211], v248, s[8:9] offset:1024
	s_waitcnt vmcnt(11)
	v_readlane_b32 s50, v236, 18
	v_readlane_b32 s52, v237, 18
	v_readlane_b32 s54, v238, 18
	v_readlane_b32 s56, v239, 18
	v_readlane_b32 s58, v240, 18
	v_pk_fma_f32 v[168:169], v[212:213], s[50:51], v[168:169] op_sel_hi:[1,0,1]
	v_pk_fma_f32 v[170:171], v[214:215], s[50:51], v[170:171] op_sel_hi:[1,0,1]
	v_pk_fma_f32 v[172:173], v[212:213], s[52:53], v[172:173] op_sel_hi:[1,0,1]
	v_pk_fma_f32 v[174:175], v[214:215], s[52:53], v[174:175] op_sel_hi:[1,0,1]
	v_pk_fma_f32 v[176:177], v[212:213], s[54:55], v[176:177] op_sel_hi:[1,0,1]
	v_pk_fma_f32 v[178:179], v[214:215], s[54:55], v[178:179] op_sel_hi:[1,0,1]
	v_pk_fma_f32 v[180:181], v[212:213], s[56:57], v[180:181] op_sel_hi:[1,0,1]
	v_pk_fma_f32 v[182:183], v[214:215], s[56:57], v[182:183] op_sel_hi:[1,0,1]
	v_pk_fma_f32 v[184:185], v[212:213], s[58:59], v[184:185] op_sel_hi:[1,0,1]
	v_pk_fma_f32 v[186:187], v[214:215], s[58:59], v[186:187] op_sel_hi:[1,0,1]
	global_load_dwordx4 v[212:215], v248, s[8:9] offset:2048
	s_waitcnt vmcnt(11)
	v_readlane_b32 s50, v236, 19
	v_readlane_b32 s52, v237, 19
	v_readlane_b32 s54, v238, 19
	v_readlane_b32 s56, v239, 19
	v_readlane_b32 s58, v240, 19
	v_pk_fma_f32 v[168:169], v[216:217], s[50:51], v[168:169] op_sel_hi:[1,0,1]
	v_pk_fma_f32 v[170:171], v[218:219], s[50:51], v[170:171] op_sel_hi:[1,0,1]
	v_pk_fma_f32 v[172:173], v[216:217], s[52:53], v[172:173] op_sel_hi:[1,0,1]
	v_pk_fma_f32 v[174:175], v[218:219], s[52:53], v[174:175] op_sel_hi:[1,0,1]
	v_pk_fma_f32 v[176:177], v[216:217], s[54:55], v[176:177] op_sel_hi:[1,0,1]
	v_pk_fma_f32 v[178:179], v[218:219], s[54:55], v[178:179] op_sel_hi:[1,0,1]
	v_pk_fma_f32 v[180:181], v[216:217], s[56:57], v[180:181] op_sel_hi:[1,0,1]
	v_pk_fma_f32 v[182:183], v[218:219], s[56:57], v[182:183] op_sel_hi:[1,0,1]
	v_pk_fma_f32 v[184:185], v[216:217], s[58:59], v[184:185] op_sel_hi:[1,0,1]
	v_pk_fma_f32 v[186:187], v[218:219], s[58:59], v[186:187] op_sel_hi:[1,0,1]
	global_load_dwordx4 v[216:219], v248, s[8:9] offset:3072
	s_add_u32 s8, s8, 0x1000
	s_addc_u32 s9, s9, 0
	s_waitcnt vmcnt(11)
	v_readlane_b32 s50, v236, 20
	v_readlane_b32 s52, v237, 20
	v_readlane_b32 s54, v238, 20
	v_readlane_b32 s56, v239, 20
	v_readlane_b32 s58, v240, 20
	v_pk_fma_f32 v[168:169], v[220:221], s[50:51], v[168:169] op_sel_hi:[1,0,1]
	v_pk_fma_f32 v[170:171], v[222:223], s[50:51], v[170:171] op_sel_hi:[1,0,1]
	v_pk_fma_f32 v[172:173], v[220:221], s[52:53], v[172:173] op_sel_hi:[1,0,1]
	v_pk_fma_f32 v[174:175], v[222:223], s[52:53], v[174:175] op_sel_hi:[1,0,1]
	v_pk_fma_f32 v[176:177], v[220:221], s[54:55], v[176:177] op_sel_hi:[1,0,1]
	v_pk_fma_f32 v[178:179], v[222:223], s[54:55], v[178:179] op_sel_hi:[1,0,1]
	v_pk_fma_f32 v[180:181], v[220:221], s[56:57], v[180:181] op_sel_hi:[1,0,1]
	v_pk_fma_f32 v[182:183], v[222:223], s[56:57], v[182:183] op_sel_hi:[1,0,1]
	v_pk_fma_f32 v[184:185], v[220:221], s[58:59], v[184:185] op_sel_hi:[1,0,1]
	v_pk_fma_f32 v[186:187], v[222:223], s[58:59], v[186:187] op_sel_hi:[1,0,1]
	global_load_dwordx4 v[220:223], v248, s[8:9]
	s_waitcnt vmcnt(11)
	v_readlane_b32 s50, v236, 21
	v_readlane_b32 s52, v237, 21
	v_readlane_b32 s54, v238, 21
	v_readlane_b32 s56, v239, 21
	v_readlane_b32 s58, v240, 21
	v_pk_fma_f32 v[168:169], v[224:225], s[50:51], v[168:169] op_sel_hi:[1,0,1]
	v_pk_fma_f32 v[170:171], v[226:227], s[50:51], v[170:171] op_sel_hi:[1,0,1]
	v_pk_fma_f32 v[172:173], v[224:225], s[52:53], v[172:173] op_sel_hi:[1,0,1]
	v_pk_fma_f32 v[174:175], v[226:227], s[52:53], v[174:175] op_sel_hi:[1,0,1]
	v_pk_fma_f32 v[176:177], v[224:225], s[54:55], v[176:177] op_sel_hi:[1,0,1]
	v_pk_fma_f32 v[178:179], v[226:227], s[54:55], v[178:179] op_sel_hi:[1,0,1]
	v_pk_fma_f32 v[180:181], v[224:225], s[56:57], v[180:181] op_sel_hi:[1,0,1]
	v_pk_fma_f32 v[182:183], v[226:227], s[56:57], v[182:183] op_sel_hi:[1,0,1]
	v_pk_fma_f32 v[184:185], v[224:225], s[58:59], v[184:185] op_sel_hi:[1,0,1]
	v_pk_fma_f32 v[186:187], v[226:227], s[58:59], v[186:187] op_sel_hi:[1,0,1]
	global_load_dwordx4 v[224:227], v248, s[8:9] offset:1024
	s_waitcnt vmcnt(11)
	v_readlane_b32 s50, v236, 22
	v_readlane_b32 s52, v237, 22
	v_readlane_b32 s54, v238, 22
	v_readlane_b32 s56, v239, 22
	v_readlane_b32 s58, v240, 22
	v_pk_fma_f32 v[168:169], v[228:229], s[50:51], v[168:169] op_sel_hi:[1,0,1]
	v_pk_fma_f32 v[170:171], v[230:231], s[50:51], v[170:171] op_sel_hi:[1,0,1]
	v_pk_fma_f32 v[172:173], v[228:229], s[52:53], v[172:173] op_sel_hi:[1,0,1]
	v_pk_fma_f32 v[174:175], v[230:231], s[52:53], v[174:175] op_sel_hi:[1,0,1]
	v_pk_fma_f32 v[176:177], v[228:229], s[54:55], v[176:177] op_sel_hi:[1,0,1]
	v_pk_fma_f32 v[178:179], v[230:231], s[54:55], v[178:179] op_sel_hi:[1,0,1]
	v_pk_fma_f32 v[180:181], v[228:229], s[56:57], v[180:181] op_sel_hi:[1,0,1]
	v_pk_fma_f32 v[182:183], v[230:231], s[56:57], v[182:183] op_sel_hi:[1,0,1]
	v_pk_fma_f32 v[184:185], v[228:229], s[58:59], v[184:185] op_sel_hi:[1,0,1]
	v_pk_fma_f32 v[186:187], v[230:231], s[58:59], v[186:187] op_sel_hi:[1,0,1]
	global_load_dwordx4 v[228:231], v248, s[8:9] offset:2048
	s_waitcnt vmcnt(11)
	v_readlane_b32 s50, v236, 23
	v_readlane_b32 s52, v237, 23
	v_readlane_b32 s54, v238, 23
	v_readlane_b32 s56, v239, 23
	v_readlane_b32 s58, v240, 23
	v_pk_fma_f32 v[168:169], v[232:233], s[50:51], v[168:169] op_sel_hi:[1,0,1]
	v_pk_fma_f32 v[170:171], v[234:235], s[50:51], v[170:171] op_sel_hi:[1,0,1]
	v_pk_fma_f32 v[172:173], v[232:233], s[52:53], v[172:173] op_sel_hi:[1,0,1]
	v_pk_fma_f32 v[174:175], v[234:235], s[52:53], v[174:175] op_sel_hi:[1,0,1]
	v_pk_fma_f32 v[176:177], v[232:233], s[54:55], v[176:177] op_sel_hi:[1,0,1]
	v_pk_fma_f32 v[178:179], v[234:235], s[54:55], v[178:179] op_sel_hi:[1,0,1]
	v_pk_fma_f32 v[180:181], v[232:233], s[56:57], v[180:181] op_sel_hi:[1,0,1]
	v_pk_fma_f32 v[182:183], v[234:235], s[56:57], v[182:183] op_sel_hi:[1,0,1]
	v_pk_fma_f32 v[184:185], v[232:233], s[58:59], v[184:185] op_sel_hi:[1,0,1]
	v_pk_fma_f32 v[186:187], v[234:235], s[58:59], v[186:187] op_sel_hi:[1,0,1]
	global_load_dwordx4 v[232:235], v248, s[8:9] offset:3072
	s_add_u32 s8, s8, 0x1000
	s_addc_u32 s9, s9, 0
	s_waitcnt vmcnt(11)
	v_readlane_b32 s50, v236, 24
	v_readlane_b32 s52, v237, 24
	v_readlane_b32 s54, v238, 24
	v_readlane_b32 s56, v239, 24
	v_readlane_b32 s58, v240, 24
	v_pk_fma_f32 v[168:169], v[188:189], s[50:51], v[168:169] op_sel_hi:[1,0,1]
	v_pk_fma_f32 v[170:171], v[190:191], s[50:51], v[170:171] op_sel_hi:[1,0,1]
	v_pk_fma_f32 v[172:173], v[188:189], s[52:53], v[172:173] op_sel_hi:[1,0,1]
	v_pk_fma_f32 v[174:175], v[190:191], s[52:53], v[174:175] op_sel_hi:[1,0,1]
	v_pk_fma_f32 v[176:177], v[188:189], s[54:55], v[176:177] op_sel_hi:[1,0,1]
	v_pk_fma_f32 v[178:179], v[190:191], s[54:55], v[178:179] op_sel_hi:[1,0,1]
	v_pk_fma_f32 v[180:181], v[188:189], s[56:57], v[180:181] op_sel_hi:[1,0,1]
	v_pk_fma_f32 v[182:183], v[190:191], s[56:57], v[182:183] op_sel_hi:[1,0,1]
	v_pk_fma_f32 v[184:185], v[188:189], s[58:59], v[184:185] op_sel_hi:[1,0,1]
	v_pk_fma_f32 v[186:187], v[190:191], s[58:59], v[186:187] op_sel_hi:[1,0,1]
	global_load_dwordx4 v[188:191], v248, s[8:9]
	s_waitcnt vmcnt(11)
	v_readlane_b32 s50, v236, 25
	v_readlane_b32 s52, v237, 25
	v_readlane_b32 s54, v238, 25
	v_readlane_b32 s56, v239, 25
	v_readlane_b32 s58, v240, 25
	v_pk_fma_f32 v[168:169], v[192:193], s[50:51], v[168:169] op_sel_hi:[1,0,1]
	v_pk_fma_f32 v[170:171], v[194:195], s[50:51], v[170:171] op_sel_hi:[1,0,1]
	v_pk_fma_f32 v[172:173], v[192:193], s[52:53], v[172:173] op_sel_hi:[1,0,1]
	v_pk_fma_f32 v[174:175], v[194:195], s[52:53], v[174:175] op_sel_hi:[1,0,1]
	v_pk_fma_f32 v[176:177], v[192:193], s[54:55], v[176:177] op_sel_hi:[1,0,1]
	v_pk_fma_f32 v[178:179], v[194:195], s[54:55], v[178:179] op_sel_hi:[1,0,1]
	v_pk_fma_f32 v[180:181], v[192:193], s[56:57], v[180:181] op_sel_hi:[1,0,1]
	v_pk_fma_f32 v[182:183], v[194:195], s[56:57], v[182:183] op_sel_hi:[1,0,1]
	v_pk_fma_f32 v[184:185], v[192:193], s[58:59], v[184:185] op_sel_hi:[1,0,1]
	v_pk_fma_f32 v[186:187], v[194:195], s[58:59], v[186:187] op_sel_hi:[1,0,1]
	global_load_dwordx4 v[192:195], v248, s[8:9] offset:1024
	s_waitcnt vmcnt(11)
	v_readlane_b32 s50, v236, 26
	v_readlane_b32 s52, v237, 26
	v_readlane_b32 s54, v238, 26
	v_readlane_b32 s56, v239, 26
	v_readlane_b32 s58, v240, 26
	v_pk_fma_f32 v[168:169], v[196:197], s[50:51], v[168:169] op_sel_hi:[1,0,1]
	v_pk_fma_f32 v[170:171], v[198:199], s[50:51], v[170:171] op_sel_hi:[1,0,1]
	v_pk_fma_f32 v[172:173], v[196:197], s[52:53], v[172:173] op_sel_hi:[1,0,1]
	v_pk_fma_f32 v[174:175], v[198:199], s[52:53], v[174:175] op_sel_hi:[1,0,1]
	v_pk_fma_f32 v[176:177], v[196:197], s[54:55], v[176:177] op_sel_hi:[1,0,1]
	v_pk_fma_f32 v[178:179], v[198:199], s[54:55], v[178:179] op_sel_hi:[1,0,1]
	v_pk_fma_f32 v[180:181], v[196:197], s[56:57], v[180:181] op_sel_hi:[1,0,1]
	v_pk_fma_f32 v[182:183], v[198:199], s[56:57], v[182:183] op_sel_hi:[1,0,1]
	v_pk_fma_f32 v[184:185], v[196:197], s[58:59], v[184:185] op_sel_hi:[1,0,1]
	v_pk_fma_f32 v[186:187], v[198:199], s[58:59], v[186:187] op_sel_hi:[1,0,1]
	global_load_dwordx4 v[196:199], v248, s[8:9] offset:2048
	s_waitcnt vmcnt(11)
	v_readlane_b32 s50, v236, 27
	v_readlane_b32 s52, v237, 27
	v_readlane_b32 s54, v238, 27
	v_readlane_b32 s56, v239, 27
	v_readlane_b32 s58, v240, 27
	v_pk_fma_f32 v[168:169], v[200:201], s[50:51], v[168:169] op_sel_hi:[1,0,1]
	v_pk_fma_f32 v[170:171], v[202:203], s[50:51], v[170:171] op_sel_hi:[1,0,1]
	v_pk_fma_f32 v[172:173], v[200:201], s[52:53], v[172:173] op_sel_hi:[1,0,1]
	v_pk_fma_f32 v[174:175], v[202:203], s[52:53], v[174:175] op_sel_hi:[1,0,1]
	v_pk_fma_f32 v[176:177], v[200:201], s[54:55], v[176:177] op_sel_hi:[1,0,1]
	v_pk_fma_f32 v[178:179], v[202:203], s[54:55], v[178:179] op_sel_hi:[1,0,1]
	v_pk_fma_f32 v[180:181], v[200:201], s[56:57], v[180:181] op_sel_hi:[1,0,1]
	v_pk_fma_f32 v[182:183], v[202:203], s[56:57], v[182:183] op_sel_hi:[1,0,1]
	v_pk_fma_f32 v[184:185], v[200:201], s[58:59], v[184:185] op_sel_hi:[1,0,1]
	v_pk_fma_f32 v[186:187], v[202:203], s[58:59], v[186:187] op_sel_hi:[1,0,1]
	global_load_dwordx4 v[200:203], v248, s[8:9] offset:3072
	s_add_u32 s8, s8, 0x1000
	s_addc_u32 s9, s9, 0
	s_waitcnt vmcnt(11)
	v_readlane_b32 s50, v236, 28
	v_readlane_b32 s52, v237, 28
	v_readlane_b32 s54, v238, 28
	v_readlane_b32 s56, v239, 28
	v_readlane_b32 s58, v240, 28
	v_pk_fma_f32 v[168:169], v[204:205], s[50:51], v[168:169] op_sel_hi:[1,0,1]
	v_pk_fma_f32 v[170:171], v[206:207], s[50:51], v[170:171] op_sel_hi:[1,0,1]
	v_pk_fma_f32 v[172:173], v[204:205], s[52:53], v[172:173] op_sel_hi:[1,0,1]
	v_pk_fma_f32 v[174:175], v[206:207], s[52:53], v[174:175] op_sel_hi:[1,0,1]
	v_pk_fma_f32 v[176:177], v[204:205], s[54:55], v[176:177] op_sel_hi:[1,0,1]
	v_pk_fma_f32 v[178:179], v[206:207], s[54:55], v[178:179] op_sel_hi:[1,0,1]
	v_pk_fma_f32 v[180:181], v[204:205], s[56:57], v[180:181] op_sel_hi:[1,0,1]
	v_pk_fma_f32 v[182:183], v[206:207], s[56:57], v[182:183] op_sel_hi:[1,0,1]
	v_pk_fma_f32 v[184:185], v[204:205], s[58:59], v[184:185] op_sel_hi:[1,0,1]
	v_pk_fma_f32 v[186:187], v[206:207], s[58:59], v[186:187] op_sel_hi:[1,0,1]
	global_load_dwordx4 v[204:207], v248, s[8:9]
	s_waitcnt vmcnt(11)
	v_readlane_b32 s50, v236, 29
	v_readlane_b32 s52, v237, 29
	v_readlane_b32 s54, v238, 29
	v_readlane_b32 s56, v239, 29
	v_readlane_b32 s58, v240, 29
	v_pk_fma_f32 v[168:169], v[208:209], s[50:51], v[168:169] op_sel_hi:[1,0,1]
	v_pk_fma_f32 v[170:171], v[210:211], s[50:51], v[170:171] op_sel_hi:[1,0,1]
	v_pk_fma_f32 v[172:173], v[208:209], s[52:53], v[172:173] op_sel_hi:[1,0,1]
	v_pk_fma_f32 v[174:175], v[210:211], s[52:53], v[174:175] op_sel_hi:[1,0,1]
	v_pk_fma_f32 v[176:177], v[208:209], s[54:55], v[176:177] op_sel_hi:[1,0,1]
	v_pk_fma_f32 v[178:179], v[210:211], s[54:55], v[178:179] op_sel_hi:[1,0,1]
	v_pk_fma_f32 v[180:181], v[208:209], s[56:57], v[180:181] op_sel_hi:[1,0,1]
	v_pk_fma_f32 v[182:183], v[210:211], s[56:57], v[182:183] op_sel_hi:[1,0,1]
	v_pk_fma_f32 v[184:185], v[208:209], s[58:59], v[184:185] op_sel_hi:[1,0,1]
	v_pk_fma_f32 v[186:187], v[210:211], s[58:59], v[186:187] op_sel_hi:[1,0,1]
	global_load_dwordx4 v[208:211], v248, s[8:9] offset:1024
	s_waitcnt vmcnt(11)
	v_readlane_b32 s50, v236, 30
	v_readlane_b32 s52, v237, 30
	v_readlane_b32 s54, v238, 30
	v_readlane_b32 s56, v239, 30
	v_readlane_b32 s58, v240, 30
	v_pk_fma_f32 v[168:169], v[212:213], s[50:51], v[168:169] op_sel_hi:[1,0,1]
	v_pk_fma_f32 v[170:171], v[214:215], s[50:51], v[170:171] op_sel_hi:[1,0,1]
	v_pk_fma_f32 v[172:173], v[212:213], s[52:53], v[172:173] op_sel_hi:[1,0,1]
	v_pk_fma_f32 v[174:175], v[214:215], s[52:53], v[174:175] op_sel_hi:[1,0,1]
	v_pk_fma_f32 v[176:177], v[212:213], s[54:55], v[176:177] op_sel_hi:[1,0,1]
	v_pk_fma_f32 v[178:179], v[214:215], s[54:55], v[178:179] op_sel_hi:[1,0,1]
	v_pk_fma_f32 v[180:181], v[212:213], s[56:57], v[180:181] op_sel_hi:[1,0,1]
	v_pk_fma_f32 v[182:183], v[214:215], s[56:57], v[182:183] op_sel_hi:[1,0,1]
	v_pk_fma_f32 v[184:185], v[212:213], s[58:59], v[184:185] op_sel_hi:[1,0,1]
	v_pk_fma_f32 v[186:187], v[214:215], s[58:59], v[186:187] op_sel_hi:[1,0,1]
	global_load_dwordx4 v[212:215], v248, s[8:9] offset:2048
	s_waitcnt vmcnt(11)
	v_readlane_b32 s50, v236, 31
	v_readlane_b32 s52, v237, 31
	v_readlane_b32 s54, v238, 31
	v_readlane_b32 s56, v239, 31
	v_readlane_b32 s58, v240, 31
	v_pk_fma_f32 v[168:169], v[216:217], s[50:51], v[168:169] op_sel_hi:[1,0,1]
	v_pk_fma_f32 v[170:171], v[218:219], s[50:51], v[170:171] op_sel_hi:[1,0,1]
	v_pk_fma_f32 v[172:173], v[216:217], s[52:53], v[172:173] op_sel_hi:[1,0,1]
	v_pk_fma_f32 v[174:175], v[218:219], s[52:53], v[174:175] op_sel_hi:[1,0,1]
	v_pk_fma_f32 v[176:177], v[216:217], s[54:55], v[176:177] op_sel_hi:[1,0,1]
	v_pk_fma_f32 v[178:179], v[218:219], s[54:55], v[178:179] op_sel_hi:[1,0,1]
	v_pk_fma_f32 v[180:181], v[216:217], s[56:57], v[180:181] op_sel_hi:[1,0,1]
	v_pk_fma_f32 v[182:183], v[218:219], s[56:57], v[182:183] op_sel_hi:[1,0,1]
	v_pk_fma_f32 v[184:185], v[216:217], s[58:59], v[184:185] op_sel_hi:[1,0,1]
	v_pk_fma_f32 v[186:187], v[218:219], s[58:59], v[186:187] op_sel_hi:[1,0,1]
	global_load_dwordx4 v[216:219], v248, s[8:9] offset:3072
	s_add_u32 s8, s8, 0x1000
	s_addc_u32 s9, s9, 0
	s_waitcnt vmcnt(11)
	v_readlane_b32 s50, v236, 32
	v_readlane_b32 s52, v237, 32
	v_readlane_b32 s54, v238, 32
	v_readlane_b32 s56, v239, 32
	v_readlane_b32 s58, v240, 32
	v_pk_fma_f32 v[168:169], v[220:221], s[50:51], v[168:169] op_sel_hi:[1,0,1]
	v_pk_fma_f32 v[170:171], v[222:223], s[50:51], v[170:171] op_sel_hi:[1,0,1]
	v_pk_fma_f32 v[172:173], v[220:221], s[52:53], v[172:173] op_sel_hi:[1,0,1]
	v_pk_fma_f32 v[174:175], v[222:223], s[52:53], v[174:175] op_sel_hi:[1,0,1]
	v_pk_fma_f32 v[176:177], v[220:221], s[54:55], v[176:177] op_sel_hi:[1,0,1]
	v_pk_fma_f32 v[178:179], v[222:223], s[54:55], v[178:179] op_sel_hi:[1,0,1]
	v_pk_fma_f32 v[180:181], v[220:221], s[56:57], v[180:181] op_sel_hi:[1,0,1]
	v_pk_fma_f32 v[182:183], v[222:223], s[56:57], v[182:183] op_sel_hi:[1,0,1]
	v_pk_fma_f32 v[184:185], v[220:221], s[58:59], v[184:185] op_sel_hi:[1,0,1]
	v_pk_fma_f32 v[186:187], v[222:223], s[58:59], v[186:187] op_sel_hi:[1,0,1]
	global_load_dwordx4 v[220:223], v248, s[8:9]
	s_waitcnt vmcnt(11)
	v_readlane_b32 s50, v236, 33
	v_readlane_b32 s52, v237, 33
	v_readlane_b32 s54, v238, 33
	v_readlane_b32 s56, v239, 33
	v_readlane_b32 s58, v240, 33
	v_pk_fma_f32 v[168:169], v[224:225], s[50:51], v[168:169] op_sel_hi:[1,0,1]
	v_pk_fma_f32 v[170:171], v[226:227], s[50:51], v[170:171] op_sel_hi:[1,0,1]
	v_pk_fma_f32 v[172:173], v[224:225], s[52:53], v[172:173] op_sel_hi:[1,0,1]
	v_pk_fma_f32 v[174:175], v[226:227], s[52:53], v[174:175] op_sel_hi:[1,0,1]
	v_pk_fma_f32 v[176:177], v[224:225], s[54:55], v[176:177] op_sel_hi:[1,0,1]
	v_pk_fma_f32 v[178:179], v[226:227], s[54:55], v[178:179] op_sel_hi:[1,0,1]
	v_pk_fma_f32 v[180:181], v[224:225], s[56:57], v[180:181] op_sel_hi:[1,0,1]
	v_pk_fma_f32 v[182:183], v[226:227], s[56:57], v[182:183] op_sel_hi:[1,0,1]
	v_pk_fma_f32 v[184:185], v[224:225], s[58:59], v[184:185] op_sel_hi:[1,0,1]
	v_pk_fma_f32 v[186:187], v[226:227], s[58:59], v[186:187] op_sel_hi:[1,0,1]
	global_load_dwordx4 v[224:227], v248, s[8:9] offset:1024
	s_waitcnt vmcnt(11)
	v_readlane_b32 s50, v236, 34
	v_readlane_b32 s52, v237, 34
	v_readlane_b32 s54, v238, 34
	v_readlane_b32 s56, v239, 34
	v_readlane_b32 s58, v240, 34
	v_pk_fma_f32 v[168:169], v[228:229], s[50:51], v[168:169] op_sel_hi:[1,0,1]
	v_pk_fma_f32 v[170:171], v[230:231], s[50:51], v[170:171] op_sel_hi:[1,0,1]
	v_pk_fma_f32 v[172:173], v[228:229], s[52:53], v[172:173] op_sel_hi:[1,0,1]
	v_pk_fma_f32 v[174:175], v[230:231], s[52:53], v[174:175] op_sel_hi:[1,0,1]
	v_pk_fma_f32 v[176:177], v[228:229], s[54:55], v[176:177] op_sel_hi:[1,0,1]
	v_pk_fma_f32 v[178:179], v[230:231], s[54:55], v[178:179] op_sel_hi:[1,0,1]
	v_pk_fma_f32 v[180:181], v[228:229], s[56:57], v[180:181] op_sel_hi:[1,0,1]
	v_pk_fma_f32 v[182:183], v[230:231], s[56:57], v[182:183] op_sel_hi:[1,0,1]
	v_pk_fma_f32 v[184:185], v[228:229], s[58:59], v[184:185] op_sel_hi:[1,0,1]
	v_pk_fma_f32 v[186:187], v[230:231], s[58:59], v[186:187] op_sel_hi:[1,0,1]
	global_load_dwordx4 v[228:231], v248, s[8:9] offset:2048
	s_waitcnt vmcnt(11)
	v_readlane_b32 s50, v236, 35
	v_readlane_b32 s52, v237, 35
	v_readlane_b32 s54, v238, 35
	v_readlane_b32 s56, v239, 35
	v_readlane_b32 s58, v240, 35
	v_pk_fma_f32 v[168:169], v[232:233], s[50:51], v[168:169] op_sel_hi:[1,0,1]
	v_pk_fma_f32 v[170:171], v[234:235], s[50:51], v[170:171] op_sel_hi:[1,0,1]
	v_pk_fma_f32 v[172:173], v[232:233], s[52:53], v[172:173] op_sel_hi:[1,0,1]
	v_pk_fma_f32 v[174:175], v[234:235], s[52:53], v[174:175] op_sel_hi:[1,0,1]
	v_pk_fma_f32 v[176:177], v[232:233], s[54:55], v[176:177] op_sel_hi:[1,0,1]
	v_pk_fma_f32 v[178:179], v[234:235], s[54:55], v[178:179] op_sel_hi:[1,0,1]
	v_pk_fma_f32 v[180:181], v[232:233], s[56:57], v[180:181] op_sel_hi:[1,0,1]
	v_pk_fma_f32 v[182:183], v[234:235], s[56:57], v[182:183] op_sel_hi:[1,0,1]
	v_pk_fma_f32 v[184:185], v[232:233], s[58:59], v[184:185] op_sel_hi:[1,0,1]
	v_pk_fma_f32 v[186:187], v[234:235], s[58:59], v[186:187] op_sel_hi:[1,0,1]
	global_load_dwordx4 v[232:235], v248, s[8:9] offset:3072
	s_add_u32 s8, s8, 0x1000
	s_addc_u32 s9, s9, 0
	s_waitcnt vmcnt(11)
	v_readlane_b32 s50, v236, 36
	v_readlane_b32 s52, v237, 36
	v_readlane_b32 s54, v238, 36
	v_readlane_b32 s56, v239, 36
	v_readlane_b32 s58, v240, 36
	v_pk_fma_f32 v[168:169], v[188:189], s[50:51], v[168:169] op_sel_hi:[1,0,1]
	v_pk_fma_f32 v[170:171], v[190:191], s[50:51], v[170:171] op_sel_hi:[1,0,1]
	v_pk_fma_f32 v[172:173], v[188:189], s[52:53], v[172:173] op_sel_hi:[1,0,1]
	v_pk_fma_f32 v[174:175], v[190:191], s[52:53], v[174:175] op_sel_hi:[1,0,1]
	v_pk_fma_f32 v[176:177], v[188:189], s[54:55], v[176:177] op_sel_hi:[1,0,1]
	v_pk_fma_f32 v[178:179], v[190:191], s[54:55], v[178:179] op_sel_hi:[1,0,1]
	v_pk_fma_f32 v[180:181], v[188:189], s[56:57], v[180:181] op_sel_hi:[1,0,1]
	v_pk_fma_f32 v[182:183], v[190:191], s[56:57], v[182:183] op_sel_hi:[1,0,1]
	v_pk_fma_f32 v[184:185], v[188:189], s[58:59], v[184:185] op_sel_hi:[1,0,1]
	v_pk_fma_f32 v[186:187], v[190:191], s[58:59], v[186:187] op_sel_hi:[1,0,1]
	global_load_dwordx4 v[188:191], v248, s[8:9]
	s_waitcnt vmcnt(11)
	v_readlane_b32 s50, v236, 37
	v_readlane_b32 s52, v237, 37
	v_readlane_b32 s54, v238, 37
	v_readlane_b32 s56, v239, 37
	v_readlane_b32 s58, v240, 37
	v_pk_fma_f32 v[168:169], v[192:193], s[50:51], v[168:169] op_sel_hi:[1,0,1]
	v_pk_fma_f32 v[170:171], v[194:195], s[50:51], v[170:171] op_sel_hi:[1,0,1]
	v_pk_fma_f32 v[172:173], v[192:193], s[52:53], v[172:173] op_sel_hi:[1,0,1]
	v_pk_fma_f32 v[174:175], v[194:195], s[52:53], v[174:175] op_sel_hi:[1,0,1]
	v_pk_fma_f32 v[176:177], v[192:193], s[54:55], v[176:177] op_sel_hi:[1,0,1]
	v_pk_fma_f32 v[178:179], v[194:195], s[54:55], v[178:179] op_sel_hi:[1,0,1]
	v_pk_fma_f32 v[180:181], v[192:193], s[56:57], v[180:181] op_sel_hi:[1,0,1]
	v_pk_fma_f32 v[182:183], v[194:195], s[56:57], v[182:183] op_sel_hi:[1,0,1]
	v_pk_fma_f32 v[184:185], v[192:193], s[58:59], v[184:185] op_sel_hi:[1,0,1]
	v_pk_fma_f32 v[186:187], v[194:195], s[58:59], v[186:187] op_sel_hi:[1,0,1]
	global_load_dwordx4 v[192:195], v248, s[8:9] offset:1024
	s_waitcnt vmcnt(11)
	v_readlane_b32 s50, v236, 38
	v_readlane_b32 s52, v237, 38
	v_readlane_b32 s54, v238, 38
	v_readlane_b32 s56, v239, 38
	v_readlane_b32 s58, v240, 38
	v_pk_fma_f32 v[168:169], v[196:197], s[50:51], v[168:169] op_sel_hi:[1,0,1]
	v_pk_fma_f32 v[170:171], v[198:199], s[50:51], v[170:171] op_sel_hi:[1,0,1]
	v_pk_fma_f32 v[172:173], v[196:197], s[52:53], v[172:173] op_sel_hi:[1,0,1]
	v_pk_fma_f32 v[174:175], v[198:199], s[52:53], v[174:175] op_sel_hi:[1,0,1]
	v_pk_fma_f32 v[176:177], v[196:197], s[54:55], v[176:177] op_sel_hi:[1,0,1]
	v_pk_fma_f32 v[178:179], v[198:199], s[54:55], v[178:179] op_sel_hi:[1,0,1]
	v_pk_fma_f32 v[180:181], v[196:197], s[56:57], v[180:181] op_sel_hi:[1,0,1]
	v_pk_fma_f32 v[182:183], v[198:199], s[56:57], v[182:183] op_sel_hi:[1,0,1]
	v_pk_fma_f32 v[184:185], v[196:197], s[58:59], v[184:185] op_sel_hi:[1,0,1]
	v_pk_fma_f32 v[186:187], v[198:199], s[58:59], v[186:187] op_sel_hi:[1,0,1]
	global_load_dwordx4 v[196:199], v248, s[8:9] offset:2048
	s_waitcnt vmcnt(11)
	v_readlane_b32 s50, v236, 39
	v_readlane_b32 s52, v237, 39
	v_readlane_b32 s54, v238, 39
	v_readlane_b32 s56, v239, 39
	v_readlane_b32 s58, v240, 39
	v_pk_fma_f32 v[168:169], v[200:201], s[50:51], v[168:169] op_sel_hi:[1,0,1]
	v_pk_fma_f32 v[170:171], v[202:203], s[50:51], v[170:171] op_sel_hi:[1,0,1]
	v_pk_fma_f32 v[172:173], v[200:201], s[52:53], v[172:173] op_sel_hi:[1,0,1]
	v_pk_fma_f32 v[174:175], v[202:203], s[52:53], v[174:175] op_sel_hi:[1,0,1]
	v_pk_fma_f32 v[176:177], v[200:201], s[54:55], v[176:177] op_sel_hi:[1,0,1]
	v_pk_fma_f32 v[178:179], v[202:203], s[54:55], v[178:179] op_sel_hi:[1,0,1]
	v_pk_fma_f32 v[180:181], v[200:201], s[56:57], v[180:181] op_sel_hi:[1,0,1]
	v_pk_fma_f32 v[182:183], v[202:203], s[56:57], v[182:183] op_sel_hi:[1,0,1]
	v_pk_fma_f32 v[184:185], v[200:201], s[58:59], v[184:185] op_sel_hi:[1,0,1]
	v_pk_fma_f32 v[186:187], v[202:203], s[58:59], v[186:187] op_sel_hi:[1,0,1]
	global_load_dwordx4 v[200:203], v248, s[8:9] offset:3072
	s_add_u32 s8, s8, 0x1000
	s_addc_u32 s9, s9, 0
	s_waitcnt vmcnt(11)
	v_readlane_b32 s50, v236, 40
	v_readlane_b32 s52, v237, 40
	v_readlane_b32 s54, v238, 40
	v_readlane_b32 s56, v239, 40
	v_readlane_b32 s58, v240, 40
	v_pk_fma_f32 v[168:169], v[204:205], s[50:51], v[168:169] op_sel_hi:[1,0,1]
	v_pk_fma_f32 v[170:171], v[206:207], s[50:51], v[170:171] op_sel_hi:[1,0,1]
	v_pk_fma_f32 v[172:173], v[204:205], s[52:53], v[172:173] op_sel_hi:[1,0,1]
	v_pk_fma_f32 v[174:175], v[206:207], s[52:53], v[174:175] op_sel_hi:[1,0,1]
	v_pk_fma_f32 v[176:177], v[204:205], s[54:55], v[176:177] op_sel_hi:[1,0,1]
	v_pk_fma_f32 v[178:179], v[206:207], s[54:55], v[178:179] op_sel_hi:[1,0,1]
	v_pk_fma_f32 v[180:181], v[204:205], s[56:57], v[180:181] op_sel_hi:[1,0,1]
	v_pk_fma_f32 v[182:183], v[206:207], s[56:57], v[182:183] op_sel_hi:[1,0,1]
	v_pk_fma_f32 v[184:185], v[204:205], s[58:59], v[184:185] op_sel_hi:[1,0,1]
	v_pk_fma_f32 v[186:187], v[206:207], s[58:59], v[186:187] op_sel_hi:[1,0,1]
	global_load_dwordx4 v[204:207], v248, s[8:9]
	s_waitcnt vmcnt(11)
	v_readlane_b32 s50, v236, 41
	v_readlane_b32 s52, v237, 41
	v_readlane_b32 s54, v238, 41
	v_readlane_b32 s56, v239, 41
	v_readlane_b32 s58, v240, 41
	v_pk_fma_f32 v[168:169], v[208:209], s[50:51], v[168:169] op_sel_hi:[1,0,1]
	v_pk_fma_f32 v[170:171], v[210:211], s[50:51], v[170:171] op_sel_hi:[1,0,1]
	v_pk_fma_f32 v[172:173], v[208:209], s[52:53], v[172:173] op_sel_hi:[1,0,1]
	v_pk_fma_f32 v[174:175], v[210:211], s[52:53], v[174:175] op_sel_hi:[1,0,1]
	v_pk_fma_f32 v[176:177], v[208:209], s[54:55], v[176:177] op_sel_hi:[1,0,1]
	v_pk_fma_f32 v[178:179], v[210:211], s[54:55], v[178:179] op_sel_hi:[1,0,1]
	v_pk_fma_f32 v[180:181], v[208:209], s[56:57], v[180:181] op_sel_hi:[1,0,1]
	v_pk_fma_f32 v[182:183], v[210:211], s[56:57], v[182:183] op_sel_hi:[1,0,1]
	v_pk_fma_f32 v[184:185], v[208:209], s[58:59], v[184:185] op_sel_hi:[1,0,1]
	v_pk_fma_f32 v[186:187], v[210:211], s[58:59], v[186:187] op_sel_hi:[1,0,1]
	global_load_dwordx4 v[208:211], v248, s[8:9] offset:1024
	s_waitcnt vmcnt(11)
	v_readlane_b32 s50, v236, 42
	v_readlane_b32 s52, v237, 42
	v_readlane_b32 s54, v238, 42
	v_readlane_b32 s56, v239, 42
	v_readlane_b32 s58, v240, 42
	v_pk_fma_f32 v[168:169], v[212:213], s[50:51], v[168:169] op_sel_hi:[1,0,1]
	v_pk_fma_f32 v[170:171], v[214:215], s[50:51], v[170:171] op_sel_hi:[1,0,1]
	v_pk_fma_f32 v[172:173], v[212:213], s[52:53], v[172:173] op_sel_hi:[1,0,1]
	v_pk_fma_f32 v[174:175], v[214:215], s[52:53], v[174:175] op_sel_hi:[1,0,1]
	v_pk_fma_f32 v[176:177], v[212:213], s[54:55], v[176:177] op_sel_hi:[1,0,1]
	v_pk_fma_f32 v[178:179], v[214:215], s[54:55], v[178:179] op_sel_hi:[1,0,1]
	v_pk_fma_f32 v[180:181], v[212:213], s[56:57], v[180:181] op_sel_hi:[1,0,1]
	v_pk_fma_f32 v[182:183], v[214:215], s[56:57], v[182:183] op_sel_hi:[1,0,1]
	v_pk_fma_f32 v[184:185], v[212:213], s[58:59], v[184:185] op_sel_hi:[1,0,1]
	v_pk_fma_f32 v[186:187], v[214:215], s[58:59], v[186:187] op_sel_hi:[1,0,1]
	global_load_dwordx4 v[212:215], v248, s[8:9] offset:2048
	s_waitcnt vmcnt(11)
	v_readlane_b32 s50, v236, 43
	v_readlane_b32 s52, v237, 43
	v_readlane_b32 s54, v238, 43
	v_readlane_b32 s56, v239, 43
	v_readlane_b32 s58, v240, 43
	v_pk_fma_f32 v[168:169], v[216:217], s[50:51], v[168:169] op_sel_hi:[1,0,1]
	v_pk_fma_f32 v[170:171], v[218:219], s[50:51], v[170:171] op_sel_hi:[1,0,1]
	v_pk_fma_f32 v[172:173], v[216:217], s[52:53], v[172:173] op_sel_hi:[1,0,1]
	v_pk_fma_f32 v[174:175], v[218:219], s[52:53], v[174:175] op_sel_hi:[1,0,1]
	v_pk_fma_f32 v[176:177], v[216:217], s[54:55], v[176:177] op_sel_hi:[1,0,1]
	v_pk_fma_f32 v[178:179], v[218:219], s[54:55], v[178:179] op_sel_hi:[1,0,1]
	v_pk_fma_f32 v[180:181], v[216:217], s[56:57], v[180:181] op_sel_hi:[1,0,1]
	v_pk_fma_f32 v[182:183], v[218:219], s[56:57], v[182:183] op_sel_hi:[1,0,1]
	v_pk_fma_f32 v[184:185], v[216:217], s[58:59], v[184:185] op_sel_hi:[1,0,1]
	v_pk_fma_f32 v[186:187], v[218:219], s[58:59], v[186:187] op_sel_hi:[1,0,1]
	global_load_dwordx4 v[216:219], v248, s[8:9] offset:3072
	s_add_u32 s8, s8, 0x1000
	s_addc_u32 s9, s9, 0
	s_waitcnt vmcnt(11)
	v_readlane_b32 s50, v236, 44
	v_readlane_b32 s52, v237, 44
	v_readlane_b32 s54, v238, 44
	v_readlane_b32 s56, v239, 44
	v_readlane_b32 s58, v240, 44
	v_pk_fma_f32 v[168:169], v[220:221], s[50:51], v[168:169] op_sel_hi:[1,0,1]
	v_pk_fma_f32 v[170:171], v[222:223], s[50:51], v[170:171] op_sel_hi:[1,0,1]
	v_pk_fma_f32 v[172:173], v[220:221], s[52:53], v[172:173] op_sel_hi:[1,0,1]
	v_pk_fma_f32 v[174:175], v[222:223], s[52:53], v[174:175] op_sel_hi:[1,0,1]
	v_pk_fma_f32 v[176:177], v[220:221], s[54:55], v[176:177] op_sel_hi:[1,0,1]
	v_pk_fma_f32 v[178:179], v[222:223], s[54:55], v[178:179] op_sel_hi:[1,0,1]
	v_pk_fma_f32 v[180:181], v[220:221], s[56:57], v[180:181] op_sel_hi:[1,0,1]
	v_pk_fma_f32 v[182:183], v[222:223], s[56:57], v[182:183] op_sel_hi:[1,0,1]
	v_pk_fma_f32 v[184:185], v[220:221], s[58:59], v[184:185] op_sel_hi:[1,0,1]
	v_pk_fma_f32 v[186:187], v[222:223], s[58:59], v[186:187] op_sel_hi:[1,0,1]
	global_load_dwordx4 v[220:223], v248, s[8:9]
	s_waitcnt vmcnt(11)
	v_readlane_b32 s50, v236, 45
	v_readlane_b32 s52, v237, 45
	v_readlane_b32 s54, v238, 45
	v_readlane_b32 s56, v239, 45
	v_readlane_b32 s58, v240, 45
	v_pk_fma_f32 v[168:169], v[224:225], s[50:51], v[168:169] op_sel_hi:[1,0,1]
	v_pk_fma_f32 v[170:171], v[226:227], s[50:51], v[170:171] op_sel_hi:[1,0,1]
	v_pk_fma_f32 v[172:173], v[224:225], s[52:53], v[172:173] op_sel_hi:[1,0,1]
	v_pk_fma_f32 v[174:175], v[226:227], s[52:53], v[174:175] op_sel_hi:[1,0,1]
	v_pk_fma_f32 v[176:177], v[224:225], s[54:55], v[176:177] op_sel_hi:[1,0,1]
	v_pk_fma_f32 v[178:179], v[226:227], s[54:55], v[178:179] op_sel_hi:[1,0,1]
	v_pk_fma_f32 v[180:181], v[224:225], s[56:57], v[180:181] op_sel_hi:[1,0,1]
	v_pk_fma_f32 v[182:183], v[226:227], s[56:57], v[182:183] op_sel_hi:[1,0,1]
	v_pk_fma_f32 v[184:185], v[224:225], s[58:59], v[184:185] op_sel_hi:[1,0,1]
	v_pk_fma_f32 v[186:187], v[226:227], s[58:59], v[186:187] op_sel_hi:[1,0,1]
	global_load_dwordx4 v[224:227], v248, s[8:9] offset:1024
	s_waitcnt vmcnt(11)
	v_readlane_b32 s50, v236, 46
	v_readlane_b32 s52, v237, 46
	v_readlane_b32 s54, v238, 46
	v_readlane_b32 s56, v239, 46
	v_readlane_b32 s58, v240, 46
	v_pk_fma_f32 v[168:169], v[228:229], s[50:51], v[168:169] op_sel_hi:[1,0,1]
	v_pk_fma_f32 v[170:171], v[230:231], s[50:51], v[170:171] op_sel_hi:[1,0,1]
	v_pk_fma_f32 v[172:173], v[228:229], s[52:53], v[172:173] op_sel_hi:[1,0,1]
	v_pk_fma_f32 v[174:175], v[230:231], s[52:53], v[174:175] op_sel_hi:[1,0,1]
	v_pk_fma_f32 v[176:177], v[228:229], s[54:55], v[176:177] op_sel_hi:[1,0,1]
	v_pk_fma_f32 v[178:179], v[230:231], s[54:55], v[178:179] op_sel_hi:[1,0,1]
	v_pk_fma_f32 v[180:181], v[228:229], s[56:57], v[180:181] op_sel_hi:[1,0,1]
	v_pk_fma_f32 v[182:183], v[230:231], s[56:57], v[182:183] op_sel_hi:[1,0,1]
	v_pk_fma_f32 v[184:185], v[228:229], s[58:59], v[184:185] op_sel_hi:[1,0,1]
	v_pk_fma_f32 v[186:187], v[230:231], s[58:59], v[186:187] op_sel_hi:[1,0,1]
	global_load_dwordx4 v[228:231], v248, s[8:9] offset:2048
	s_waitcnt vmcnt(11)
	v_readlane_b32 s50, v236, 47
	v_readlane_b32 s52, v237, 47
	v_readlane_b32 s54, v238, 47
	v_readlane_b32 s56, v239, 47
	v_readlane_b32 s58, v240, 47
	v_pk_fma_f32 v[168:169], v[232:233], s[50:51], v[168:169] op_sel_hi:[1,0,1]
	v_pk_fma_f32 v[170:171], v[234:235], s[50:51], v[170:171] op_sel_hi:[1,0,1]
	v_pk_fma_f32 v[172:173], v[232:233], s[52:53], v[172:173] op_sel_hi:[1,0,1]
	v_pk_fma_f32 v[174:175], v[234:235], s[52:53], v[174:175] op_sel_hi:[1,0,1]
	v_pk_fma_f32 v[176:177], v[232:233], s[54:55], v[176:177] op_sel_hi:[1,0,1]
	v_pk_fma_f32 v[178:179], v[234:235], s[54:55], v[178:179] op_sel_hi:[1,0,1]
	v_pk_fma_f32 v[180:181], v[232:233], s[56:57], v[180:181] op_sel_hi:[1,0,1]
	v_pk_fma_f32 v[182:183], v[234:235], s[56:57], v[182:183] op_sel_hi:[1,0,1]
	v_pk_fma_f32 v[184:185], v[232:233], s[58:59], v[184:185] op_sel_hi:[1,0,1]
	v_pk_fma_f32 v[186:187], v[234:235], s[58:59], v[186:187] op_sel_hi:[1,0,1]
	global_load_dwordx4 v[232:235], v248, s[8:9] offset:3072
	s_add_u32 s8, s8, 0x1000
	s_addc_u32 s9, s9, 0
	s_waitcnt vmcnt(11)
	v_readlane_b32 s50, v236, 48
	v_readlane_b32 s52, v237, 48
	v_readlane_b32 s54, v238, 48
	v_readlane_b32 s56, v239, 48
	v_readlane_b32 s58, v240, 48
	v_pk_fma_f32 v[168:169], v[188:189], s[50:51], v[168:169] op_sel_hi:[1,0,1]
	v_pk_fma_f32 v[170:171], v[190:191], s[50:51], v[170:171] op_sel_hi:[1,0,1]
	v_pk_fma_f32 v[172:173], v[188:189], s[52:53], v[172:173] op_sel_hi:[1,0,1]
	v_pk_fma_f32 v[174:175], v[190:191], s[52:53], v[174:175] op_sel_hi:[1,0,1]
	v_pk_fma_f32 v[176:177], v[188:189], s[54:55], v[176:177] op_sel_hi:[1,0,1]
	v_pk_fma_f32 v[178:179], v[190:191], s[54:55], v[178:179] op_sel_hi:[1,0,1]
	v_pk_fma_f32 v[180:181], v[188:189], s[56:57], v[180:181] op_sel_hi:[1,0,1]
	v_pk_fma_f32 v[182:183], v[190:191], s[56:57], v[182:183] op_sel_hi:[1,0,1]
	v_pk_fma_f32 v[184:185], v[188:189], s[58:59], v[184:185] op_sel_hi:[1,0,1]
	v_pk_fma_f32 v[186:187], v[190:191], s[58:59], v[186:187] op_sel_hi:[1,0,1]
	global_load_dwordx4 v[188:191], v248, s[8:9]
	s_waitcnt vmcnt(11)
	v_readlane_b32 s50, v236, 49
	v_readlane_b32 s52, v237, 49
	v_readlane_b32 s54, v238, 49
	v_readlane_b32 s56, v239, 49
	v_readlane_b32 s58, v240, 49
	v_pk_fma_f32 v[168:169], v[192:193], s[50:51], v[168:169] op_sel_hi:[1,0,1]
	v_pk_fma_f32 v[170:171], v[194:195], s[50:51], v[170:171] op_sel_hi:[1,0,1]
	v_pk_fma_f32 v[172:173], v[192:193], s[52:53], v[172:173] op_sel_hi:[1,0,1]
	v_pk_fma_f32 v[174:175], v[194:195], s[52:53], v[174:175] op_sel_hi:[1,0,1]
	v_pk_fma_f32 v[176:177], v[192:193], s[54:55], v[176:177] op_sel_hi:[1,0,1]
	v_pk_fma_f32 v[178:179], v[194:195], s[54:55], v[178:179] op_sel_hi:[1,0,1]
	v_pk_fma_f32 v[180:181], v[192:193], s[56:57], v[180:181] op_sel_hi:[1,0,1]
	v_pk_fma_f32 v[182:183], v[194:195], s[56:57], v[182:183] op_sel_hi:[1,0,1]
	v_pk_fma_f32 v[184:185], v[192:193], s[58:59], v[184:185] op_sel_hi:[1,0,1]
	v_pk_fma_f32 v[186:187], v[194:195], s[58:59], v[186:187] op_sel_hi:[1,0,1]
	global_load_dwordx4 v[192:195], v248, s[8:9] offset:1024
	s_waitcnt vmcnt(11)
	v_readlane_b32 s50, v236, 50
	v_readlane_b32 s52, v237, 50
	v_readlane_b32 s54, v238, 50
	v_readlane_b32 s56, v239, 50
	v_readlane_b32 s58, v240, 50
	v_pk_fma_f32 v[168:169], v[196:197], s[50:51], v[168:169] op_sel_hi:[1,0,1]
	v_pk_fma_f32 v[170:171], v[198:199], s[50:51], v[170:171] op_sel_hi:[1,0,1]
	v_pk_fma_f32 v[172:173], v[196:197], s[52:53], v[172:173] op_sel_hi:[1,0,1]
	v_pk_fma_f32 v[174:175], v[198:199], s[52:53], v[174:175] op_sel_hi:[1,0,1]
	v_pk_fma_f32 v[176:177], v[196:197], s[54:55], v[176:177] op_sel_hi:[1,0,1]
	v_pk_fma_f32 v[178:179], v[198:199], s[54:55], v[178:179] op_sel_hi:[1,0,1]
	v_pk_fma_f32 v[180:181], v[196:197], s[56:57], v[180:181] op_sel_hi:[1,0,1]
	v_pk_fma_f32 v[182:183], v[198:199], s[56:57], v[182:183] op_sel_hi:[1,0,1]
	v_pk_fma_f32 v[184:185], v[196:197], s[58:59], v[184:185] op_sel_hi:[1,0,1]
	v_pk_fma_f32 v[186:187], v[198:199], s[58:59], v[186:187] op_sel_hi:[1,0,1]
	global_load_dwordx4 v[196:199], v248, s[8:9] offset:2048
	s_waitcnt vmcnt(11)
	v_readlane_b32 s50, v236, 51
	v_readlane_b32 s52, v237, 51
	v_readlane_b32 s54, v238, 51
	v_readlane_b32 s56, v239, 51
	v_readlane_b32 s58, v240, 51
	v_pk_fma_f32 v[168:169], v[200:201], s[50:51], v[168:169] op_sel_hi:[1,0,1]
	v_pk_fma_f32 v[170:171], v[202:203], s[50:51], v[170:171] op_sel_hi:[1,0,1]
	v_pk_fma_f32 v[172:173], v[200:201], s[52:53], v[172:173] op_sel_hi:[1,0,1]
	v_pk_fma_f32 v[174:175], v[202:203], s[52:53], v[174:175] op_sel_hi:[1,0,1]
	v_pk_fma_f32 v[176:177], v[200:201], s[54:55], v[176:177] op_sel_hi:[1,0,1]
	v_pk_fma_f32 v[178:179], v[202:203], s[54:55], v[178:179] op_sel_hi:[1,0,1]
	v_pk_fma_f32 v[180:181], v[200:201], s[56:57], v[180:181] op_sel_hi:[1,0,1]
	v_pk_fma_f32 v[182:183], v[202:203], s[56:57], v[182:183] op_sel_hi:[1,0,1]
	v_pk_fma_f32 v[184:185], v[200:201], s[58:59], v[184:185] op_sel_hi:[1,0,1]
	v_pk_fma_f32 v[186:187], v[202:203], s[58:59], v[186:187] op_sel_hi:[1,0,1]
	global_load_dwordx4 v[200:203], v248, s[8:9] offset:3072
	s_add_u32 s8, s8, 0x1000
	s_addc_u32 s9, s9, 0
	s_waitcnt vmcnt(11)
	v_readlane_b32 s50, v236, 52
	v_readlane_b32 s52, v237, 52
	v_readlane_b32 s54, v238, 52
	v_readlane_b32 s56, v239, 52
	v_readlane_b32 s58, v240, 52
	v_pk_fma_f32 v[168:169], v[204:205], s[50:51], v[168:169] op_sel_hi:[1,0,1]
	v_pk_fma_f32 v[170:171], v[206:207], s[50:51], v[170:171] op_sel_hi:[1,0,1]
	v_pk_fma_f32 v[172:173], v[204:205], s[52:53], v[172:173] op_sel_hi:[1,0,1]
	v_pk_fma_f32 v[174:175], v[206:207], s[52:53], v[174:175] op_sel_hi:[1,0,1]
	v_pk_fma_f32 v[176:177], v[204:205], s[54:55], v[176:177] op_sel_hi:[1,0,1]
	v_pk_fma_f32 v[178:179], v[206:207], s[54:55], v[178:179] op_sel_hi:[1,0,1]
	v_pk_fma_f32 v[180:181], v[204:205], s[56:57], v[180:181] op_sel_hi:[1,0,1]
	v_pk_fma_f32 v[182:183], v[206:207], s[56:57], v[182:183] op_sel_hi:[1,0,1]
	v_pk_fma_f32 v[184:185], v[204:205], s[58:59], v[184:185] op_sel_hi:[1,0,1]
	v_pk_fma_f32 v[186:187], v[206:207], s[58:59], v[186:187] op_sel_hi:[1,0,1]
	s_waitcnt vmcnt(10)
	v_readlane_b32 s50, v236, 53
	v_readlane_b32 s52, v237, 53
	v_readlane_b32 s54, v238, 53
	v_readlane_b32 s56, v239, 53
	v_readlane_b32 s58, v240, 53
	v_pk_fma_f32 v[168:169], v[208:209], s[50:51], v[168:169] op_sel_hi:[1,0,1]
	v_pk_fma_f32 v[170:171], v[210:211], s[50:51], v[170:171] op_sel_hi:[1,0,1]
	v_pk_fma_f32 v[172:173], v[208:209], s[52:53], v[172:173] op_sel_hi:[1,0,1]
	v_pk_fma_f32 v[174:175], v[210:211], s[52:53], v[174:175] op_sel_hi:[1,0,1]
	v_pk_fma_f32 v[176:177], v[208:209], s[54:55], v[176:177] op_sel_hi:[1,0,1]
	v_pk_fma_f32 v[178:179], v[210:211], s[54:55], v[178:179] op_sel_hi:[1,0,1]
	v_pk_fma_f32 v[180:181], v[208:209], s[56:57], v[180:181] op_sel_hi:[1,0,1]
	v_pk_fma_f32 v[182:183], v[210:211], s[56:57], v[182:183] op_sel_hi:[1,0,1]
	v_pk_fma_f32 v[184:185], v[208:209], s[58:59], v[184:185] op_sel_hi:[1,0,1]
	v_pk_fma_f32 v[186:187], v[210:211], s[58:59], v[186:187] op_sel_hi:[1,0,1]
	s_waitcnt vmcnt(9)
	v_readlane_b32 s50, v236, 54
	v_readlane_b32 s52, v237, 54
	v_readlane_b32 s54, v238, 54
	v_readlane_b32 s56, v239, 54
	v_readlane_b32 s58, v240, 54
	v_pk_fma_f32 v[168:169], v[212:213], s[50:51], v[168:169] op_sel_hi:[1,0,1]
	v_pk_fma_f32 v[170:171], v[214:215], s[50:51], v[170:171] op_sel_hi:[1,0,1]
	v_pk_fma_f32 v[172:173], v[212:213], s[52:53], v[172:173] op_sel_hi:[1,0,1]
	v_pk_fma_f32 v[174:175], v[214:215], s[52:53], v[174:175] op_sel_hi:[1,0,1]
	v_pk_fma_f32 v[176:177], v[212:213], s[54:55], v[176:177] op_sel_hi:[1,0,1]
	v_pk_fma_f32 v[178:179], v[214:215], s[54:55], v[178:179] op_sel_hi:[1,0,1]
	v_pk_fma_f32 v[180:181], v[212:213], s[56:57], v[180:181] op_sel_hi:[1,0,1]
	v_pk_fma_f32 v[182:183], v[214:215], s[56:57], v[182:183] op_sel_hi:[1,0,1]
	v_pk_fma_f32 v[184:185], v[212:213], s[58:59], v[184:185] op_sel_hi:[1,0,1]
	v_pk_fma_f32 v[186:187], v[214:215], s[58:59], v[186:187] op_sel_hi:[1,0,1]
	s_waitcnt vmcnt(8)
	v_readlane_b32 s50, v236, 55
	v_readlane_b32 s52, v237, 55
	v_readlane_b32 s54, v238, 55
	v_readlane_b32 s56, v239, 55
	v_readlane_b32 s58, v240, 55
	v_pk_fma_f32 v[168:169], v[216:217], s[50:51], v[168:169] op_sel_hi:[1,0,1]
	v_pk_fma_f32 v[170:171], v[218:219], s[50:51], v[170:171] op_sel_hi:[1,0,1]
	v_pk_fma_f32 v[172:173], v[216:217], s[52:53], v[172:173] op_sel_hi:[1,0,1]
	v_pk_fma_f32 v[174:175], v[218:219], s[52:53], v[174:175] op_sel_hi:[1,0,1]
	v_pk_fma_f32 v[176:177], v[216:217], s[54:55], v[176:177] op_sel_hi:[1,0,1]
	v_pk_fma_f32 v[178:179], v[218:219], s[54:55], v[178:179] op_sel_hi:[1,0,1]
	v_pk_fma_f32 v[180:181], v[216:217], s[56:57], v[180:181] op_sel_hi:[1,0,1]
	v_pk_fma_f32 v[182:183], v[218:219], s[56:57], v[182:183] op_sel_hi:[1,0,1]
	v_pk_fma_f32 v[184:185], v[216:217], s[58:59], v[184:185] op_sel_hi:[1,0,1]
	v_pk_fma_f32 v[186:187], v[218:219], s[58:59], v[186:187] op_sel_hi:[1,0,1]
	s_waitcnt vmcnt(7)
	v_readlane_b32 s50, v236, 56
	v_readlane_b32 s52, v237, 56
	v_readlane_b32 s54, v238, 56
	v_readlane_b32 s56, v239, 56
	v_readlane_b32 s58, v240, 56
	v_pk_fma_f32 v[168:169], v[220:221], s[50:51], v[168:169] op_sel_hi:[1,0,1]
	v_pk_fma_f32 v[170:171], v[222:223], s[50:51], v[170:171] op_sel_hi:[1,0,1]
	v_pk_fma_f32 v[172:173], v[220:221], s[52:53], v[172:173] op_sel_hi:[1,0,1]
	v_pk_fma_f32 v[174:175], v[222:223], s[52:53], v[174:175] op_sel_hi:[1,0,1]
	v_pk_fma_f32 v[176:177], v[220:221], s[54:55], v[176:177] op_sel_hi:[1,0,1]
	v_pk_fma_f32 v[178:179], v[222:223], s[54:55], v[178:179] op_sel_hi:[1,0,1]
	v_pk_fma_f32 v[180:181], v[220:221], s[56:57], v[180:181] op_sel_hi:[1,0,1]
	v_pk_fma_f32 v[182:183], v[222:223], s[56:57], v[182:183] op_sel_hi:[1,0,1]
	v_pk_fma_f32 v[184:185], v[220:221], s[58:59], v[184:185] op_sel_hi:[1,0,1]
	v_pk_fma_f32 v[186:187], v[222:223], s[58:59], v[186:187] op_sel_hi:[1,0,1]
	s_waitcnt vmcnt(6)
	v_readlane_b32 s50, v236, 57
	v_readlane_b32 s52, v237, 57
	v_readlane_b32 s54, v238, 57
	v_readlane_b32 s56, v239, 57
	v_readlane_b32 s58, v240, 57
	v_pk_fma_f32 v[168:169], v[224:225], s[50:51], v[168:169] op_sel_hi:[1,0,1]
	v_pk_fma_f32 v[170:171], v[226:227], s[50:51], v[170:171] op_sel_hi:[1,0,1]
	v_pk_fma_f32 v[172:173], v[224:225], s[52:53], v[172:173] op_sel_hi:[1,0,1]
	v_pk_fma_f32 v[174:175], v[226:227], s[52:53], v[174:175] op_sel_hi:[1,0,1]
	v_pk_fma_f32 v[176:177], v[224:225], s[54:55], v[176:177] op_sel_hi:[1,0,1]
	v_pk_fma_f32 v[178:179], v[226:227], s[54:55], v[178:179] op_sel_hi:[1,0,1]
	v_pk_fma_f32 v[180:181], v[224:225], s[56:57], v[180:181] op_sel_hi:[1,0,1]
	v_pk_fma_f32 v[182:183], v[226:227], s[56:57], v[182:183] op_sel_hi:[1,0,1]
	v_pk_fma_f32 v[184:185], v[224:225], s[58:59], v[184:185] op_sel_hi:[1,0,1]
	v_pk_fma_f32 v[186:187], v[226:227], s[58:59], v[186:187] op_sel_hi:[1,0,1]
	s_waitcnt vmcnt(5)
	v_readlane_b32 s50, v236, 58
	v_readlane_b32 s52, v237, 58
	v_readlane_b32 s54, v238, 58
	v_readlane_b32 s56, v239, 58
	v_readlane_b32 s58, v240, 58
	v_pk_fma_f32 v[168:169], v[228:229], s[50:51], v[168:169] op_sel_hi:[1,0,1]
	v_pk_fma_f32 v[170:171], v[230:231], s[50:51], v[170:171] op_sel_hi:[1,0,1]
	v_pk_fma_f32 v[172:173], v[228:229], s[52:53], v[172:173] op_sel_hi:[1,0,1]
	v_pk_fma_f32 v[174:175], v[230:231], s[52:53], v[174:175] op_sel_hi:[1,0,1]
	v_pk_fma_f32 v[176:177], v[228:229], s[54:55], v[176:177] op_sel_hi:[1,0,1]
	v_pk_fma_f32 v[178:179], v[230:231], s[54:55], v[178:179] op_sel_hi:[1,0,1]
	v_pk_fma_f32 v[180:181], v[228:229], s[56:57], v[180:181] op_sel_hi:[1,0,1]
	v_pk_fma_f32 v[182:183], v[230:231], s[56:57], v[182:183] op_sel_hi:[1,0,1]
	v_pk_fma_f32 v[184:185], v[228:229], s[58:59], v[184:185] op_sel_hi:[1,0,1]
	v_pk_fma_f32 v[186:187], v[230:231], s[58:59], v[186:187] op_sel_hi:[1,0,1]
	s_waitcnt vmcnt(4)
	v_readlane_b32 s50, v236, 59
	v_readlane_b32 s52, v237, 59
	v_readlane_b32 s54, v238, 59
	v_readlane_b32 s56, v239, 59
	v_readlane_b32 s58, v240, 59
	v_pk_fma_f32 v[168:169], v[232:233], s[50:51], v[168:169] op_sel_hi:[1,0,1]
	v_pk_fma_f32 v[170:171], v[234:235], s[50:51], v[170:171] op_sel_hi:[1,0,1]
	v_pk_fma_f32 v[172:173], v[232:233], s[52:53], v[172:173] op_sel_hi:[1,0,1]
	v_pk_fma_f32 v[174:175], v[234:235], s[52:53], v[174:175] op_sel_hi:[1,0,1]
	v_pk_fma_f32 v[176:177], v[232:233], s[54:55], v[176:177] op_sel_hi:[1,0,1]
	v_pk_fma_f32 v[178:179], v[234:235], s[54:55], v[178:179] op_sel_hi:[1,0,1]
	v_pk_fma_f32 v[180:181], v[232:233], s[56:57], v[180:181] op_sel_hi:[1,0,1]
	v_pk_fma_f32 v[182:183], v[234:235], s[56:57], v[182:183] op_sel_hi:[1,0,1]
	v_pk_fma_f32 v[184:185], v[232:233], s[58:59], v[184:185] op_sel_hi:[1,0,1]
	v_pk_fma_f32 v[186:187], v[234:235], s[58:59], v[186:187] op_sel_hi:[1,0,1]
	s_waitcnt vmcnt(3)
	v_readlane_b32 s50, v236, 60
	v_readlane_b32 s52, v237, 60
	v_readlane_b32 s54, v238, 60
	v_readlane_b32 s56, v239, 60
	v_readlane_b32 s58, v240, 60
	v_pk_fma_f32 v[168:169], v[188:189], s[50:51], v[168:169] op_sel_hi:[1,0,1]
	v_pk_fma_f32 v[170:171], v[190:191], s[50:51], v[170:171] op_sel_hi:[1,0,1]
	v_pk_fma_f32 v[172:173], v[188:189], s[52:53], v[172:173] op_sel_hi:[1,0,1]
	v_pk_fma_f32 v[174:175], v[190:191], s[52:53], v[174:175] op_sel_hi:[1,0,1]
	v_pk_fma_f32 v[176:177], v[188:189], s[54:55], v[176:177] op_sel_hi:[1,0,1]
	v_pk_fma_f32 v[178:179], v[190:191], s[54:55], v[178:179] op_sel_hi:[1,0,1]
	v_pk_fma_f32 v[180:181], v[188:189], s[56:57], v[180:181] op_sel_hi:[1,0,1]
	v_pk_fma_f32 v[182:183], v[190:191], s[56:57], v[182:183] op_sel_hi:[1,0,1]
	v_pk_fma_f32 v[184:185], v[188:189], s[58:59], v[184:185] op_sel_hi:[1,0,1]
	v_pk_fma_f32 v[186:187], v[190:191], s[58:59], v[186:187] op_sel_hi:[1,0,1]
	s_waitcnt vmcnt(2)
	v_readlane_b32 s50, v236, 61
	v_readlane_b32 s52, v237, 61
	v_readlane_b32 s54, v238, 61
	v_readlane_b32 s56, v239, 61
	v_readlane_b32 s58, v240, 61
	v_pk_fma_f32 v[168:169], v[192:193], s[50:51], v[168:169] op_sel_hi:[1,0,1]
	v_pk_fma_f32 v[170:171], v[194:195], s[50:51], v[170:171] op_sel_hi:[1,0,1]
	v_pk_fma_f32 v[172:173], v[192:193], s[52:53], v[172:173] op_sel_hi:[1,0,1]
	v_pk_fma_f32 v[174:175], v[194:195], s[52:53], v[174:175] op_sel_hi:[1,0,1]
	v_pk_fma_f32 v[176:177], v[192:193], s[54:55], v[176:177] op_sel_hi:[1,0,1]
	v_pk_fma_f32 v[178:179], v[194:195], s[54:55], v[178:179] op_sel_hi:[1,0,1]
	v_pk_fma_f32 v[180:181], v[192:193], s[56:57], v[180:181] op_sel_hi:[1,0,1]
	v_pk_fma_f32 v[182:183], v[194:195], s[56:57], v[182:183] op_sel_hi:[1,0,1]
	v_pk_fma_f32 v[184:185], v[192:193], s[58:59], v[184:185] op_sel_hi:[1,0,1]
	v_pk_fma_f32 v[186:187], v[194:195], s[58:59], v[186:187] op_sel_hi:[1,0,1]
	s_waitcnt vmcnt(1)
	v_readlane_b32 s50, v236, 62
	v_readlane_b32 s52, v237, 62
	v_readlane_b32 s54, v238, 62
	v_readlane_b32 s56, v239, 62
	v_readlane_b32 s58, v240, 62
	v_pk_fma_f32 v[168:169], v[196:197], s[50:51], v[168:169] op_sel_hi:[1,0,1]
	v_pk_fma_f32 v[170:171], v[198:199], s[50:51], v[170:171] op_sel_hi:[1,0,1]
	v_pk_fma_f32 v[172:173], v[196:197], s[52:53], v[172:173] op_sel_hi:[1,0,1]
	v_pk_fma_f32 v[174:175], v[198:199], s[52:53], v[174:175] op_sel_hi:[1,0,1]
	v_pk_fma_f32 v[176:177], v[196:197], s[54:55], v[176:177] op_sel_hi:[1,0,1]
	v_pk_fma_f32 v[178:179], v[198:199], s[54:55], v[178:179] op_sel_hi:[1,0,1]
	v_pk_fma_f32 v[180:181], v[196:197], s[56:57], v[180:181] op_sel_hi:[1,0,1]
	v_pk_fma_f32 v[182:183], v[198:199], s[56:57], v[182:183] op_sel_hi:[1,0,1]
	v_pk_fma_f32 v[184:185], v[196:197], s[58:59], v[184:185] op_sel_hi:[1,0,1]
	v_pk_fma_f32 v[186:187], v[198:199], s[58:59], v[186:187] op_sel_hi:[1,0,1]
	s_waitcnt vmcnt(0)
	v_readlane_b32 s50, v236, 63
	v_readlane_b32 s52, v237, 63
	v_readlane_b32 s54, v238, 63
	v_readlane_b32 s56, v239, 63
	v_readlane_b32 s58, v240, 63
	v_pk_fma_f32 v[168:169], v[200:201], s[50:51], v[168:169] op_sel_hi:[1,0,1]
	v_pk_fma_f32 v[170:171], v[202:203], s[50:51], v[170:171] op_sel_hi:[1,0,1]
	v_pk_fma_f32 v[172:173], v[200:201], s[52:53], v[172:173] op_sel_hi:[1,0,1]
	v_pk_fma_f32 v[174:175], v[202:203], s[52:53], v[174:175] op_sel_hi:[1,0,1]
	v_pk_fma_f32 v[176:177], v[200:201], s[54:55], v[176:177] op_sel_hi:[1,0,1]
	v_pk_fma_f32 v[178:179], v[202:203], s[54:55], v[178:179] op_sel_hi:[1,0,1]
	v_pk_fma_f32 v[180:181], v[200:201], s[56:57], v[180:181] op_sel_hi:[1,0,1]
	v_pk_fma_f32 v[182:183], v[202:203], s[56:57], v[182:183] op_sel_hi:[1,0,1]
	v_pk_fma_f32 v[184:185], v[200:201], s[58:59], v[184:185] op_sel_hi:[1,0,1]
	v_pk_fma_f32 v[186:187], v[202:203], s[58:59], v[186:187] op_sel_hi:[1,0,1]
	s_mov_b32 s6, s13
	s_cmp_ge_u32 s6, 0x2800
	s_cbranch_scc1 .Lgpost_bend
	v_add_f32_e32 v2, v2, v6
	v_add_f32_e32 v3, v3, v7
	v_add_f32_e32 v4, v4, v8
	v_add_f32_e32 v5, v5, v9
	v_add_f32_e32 v241, v2, v3
	v_add_f32_e32 v242, v4, v5
	v_add_f32_e32 v241, v241, v242
	s_nop 1
	v_add_f32_dpp v241, v241, v241 quad_perm:[1,0,3,2] row_mask:0xf bank_mask:0xf bound_ctrl:1
	s_nop 1
	v_add_f32_dpp v241, v241, v241 quad_perm:[2,3,0,1] row_mask:0xf bank_mask:0xf bound_ctrl:1
	s_nop 1
	v_add_f32_dpp v241, v241, v241 row_half_mirror row_mask:0xf bank_mask:0xf bound_ctrl:1
	s_nop 1
	v_add_f32_dpp v241, v241, v241 row_mirror row_mask:0xf bank_mask:0xf bound_ctrl:1
	v_mul_f32_e32 v241, 0x3c800000, v241
	v_sub_f32_e32 v2, v2, v241
	v_sub_f32_e32 v3, v3, v241
	v_sub_f32_e32 v4, v4, v241
	v_sub_f32_e32 v5, v5, v241
	v_mul_f32_e32 v243, v10, v14
	v_mul_f32_e32 v244, v11, v15
	v_mul_f32_e32 v245, v12, v16
	v_mul_f32_e32 v246, v13, v17
	v_mul_f32_e32 v243, v122, v243
	v_mul_f32_e32 v245, v124, v245
	v_fmac_f32_e32 v243, v123, v244
	v_fmac_f32_e32 v245, v125, v246
	v_add_f32_e32 v243, v243, v245
	s_nop 1
	v_add_f32_dpp v243, v243, v243 quad_perm:[1,0,3,2] row_mask:0xf bank_mask:0xf bound_ctrl:1
	s_nop 1
	v_add_f32_dpp v243, v243, v243 quad_perm:[2,3,0,1] row_mask:0xf bank_mask:0xf bound_ctrl:1
	s_nop 1
	v_add_f32_dpp v243, v243, v243 row_half_mirror row_mask:0xf bank_mask:0xf bound_ctrl:1
	s_nop 1
	v_add_f32_dpp v243, v243, v243 row_mirror row_mask:0xf bank_mask:0xf bound_ctrl:1
	v_mul_f32_e32 v244, v3, v3
	v_mul_f32_e32 v245, v5, v5
	v_fmac_f32_e32 v244, v2, v2
	v_fmac_f32_e32 v245, v4, v4
	v_add_f32_e32 v244, v244, v245
	s_nop 1
	v_add_f32_dpp v244, v244, v244 quad_perm:[1,0,3,2] row_mask:0xf bank_mask:0xf bound_ctrl:1
	s_nop 1
	v_add_f32_dpp v244, v244, v244 quad_perm:[2,3,0,1] row_mask:0xf bank_mask:0xf bound_ctrl:1
	s_nop 1
	v_add_f32_dpp v244, v244, v244 row_half_mirror row_mask:0xf bank_mask:0xf bound_ctrl:1
	s_nop 1
	v_add_f32_dpp v244, v244, v244 row_mirror row_mask:0xf bank_mask:0xf bound_ctrl:1
	v_fmamk_f32 v244, v244, 0x3c800000, v132
	v_rsq_f32_e32 v244, v244
	s_nop 0
	v_mul_f32_e32 v245, v2, v244
	v_fma_f32 v245, v110, v245, v118
	v_fmac_f32_e32 v245, v18, v243
	v_mul_f32_e32 v6, v168, v245
	v_mul_f32_e32 v245, v3, v244
	v_fma_f32 v245, v111, v245, v119
	v_fmac_f32_e32 v245, v19, v243
	v_mul_f32_e32 v7, v169, v245
	v_mul_f32_e32 v245, v4, v244
	v_fma_f32 v245, v112, v245, v120
	v_fmac_f32_e32 v245, v20, v243
	v_mul_f32_e32 v8, v170, v245
	v_mul_f32_e32 v245, v5, v244
	v_fma_f32 v245, v113, v245, v121
	v_fmac_f32_e32 v245, v21, v243
	v_mul_f32_e32 v9, v171, v245
	v_cvt_pk_bf16_f32 v10, v6, v7
	v_cvt_pk_bf16_f32 v11, v8, v9
	s_lshl_b32 s7, s6, 11
	s_add_u32 s7, s7, 0x600
	s_add_u32 s8, s80, s7
	s_addc_u32 s9, s81, 0
	global_store_dwordx2 v250, v[10:11], s[8:9]
	s_add_u32 s6, s13, 1
	s_cmp_ge_u32 s6, 0x2800
	s_cbranch_scc1 .Lgpost_bend
	v_add_f32_e32 v24, v24, v28
	v_add_f32_e32 v25, v25, v29
	v_add_f32_e32 v26, v26, v30
	v_add_f32_e32 v27, v27, v31
	v_add_f32_e32 v241, v24, v25
	v_add_f32_e32 v242, v26, v27
	v_add_f32_e32 v241, v241, v242
	s_nop 1
	v_add_f32_dpp v241, v241, v241 quad_perm:[1,0,3,2] row_mask:0xf bank_mask:0xf bound_ctrl:1
	s_nop 1
	v_add_f32_dpp v241, v241, v241 quad_perm:[2,3,0,1] row_mask:0xf bank_mask:0xf bound_ctrl:1
	s_nop 1
	v_add_f32_dpp v241, v241, v241 row_half_mirror row_mask:0xf bank_mask:0xf bound_ctrl:1
	s_nop 1
	v_add_f32_dpp v241, v241, v241 row_mirror row_mask:0xf bank_mask:0xf bound_ctrl:1
	v_mul_f32_e32 v241, 0x3c800000, v241
	v_sub_f32_e32 v24, v24, v241
	v_sub_f32_e32 v25, v25, v241
	v_sub_f32_e32 v26, v26, v241
	v_sub_f32_e32 v27, v27, v241
	v_mul_f32_e32 v243, v32, v36
	v_mul_f32_e32 v244, v33, v37
	v_mul_f32_e32 v245, v34, v38
	v_mul_f32_e32 v246, v35, v39
	v_mul_f32_e32 v243, v122, v243
	v_mul_f32_e32 v245, v124, v245
	v_fmac_f32_e32 v243, v123, v244
	v_fmac_f32_e32 v245, v125, v246
	v_add_f32_e32 v243, v243, v245
	s_nop 1
	v_add_f32_dpp v243, v243, v243 quad_perm:[1,0,3,2] row_mask:0xf bank_mask:0xf bound_ctrl:1
	s_nop 1
	v_add_f32_dpp v243, v243, v243 quad_perm:[2,3,0,1] row_mask:0xf bank_mask:0xf bound_ctrl:1
	s_nop 1
	v_add_f32_dpp v243, v243, v243 row_half_mirror row_mask:0xf bank_mask:0xf bound_ctrl:1
	s_nop 1
	v_add_f32_dpp v243, v243, v243 row_mirror row_mask:0xf bank_mask:0xf bound_ctrl:1
	v_mul_f32_e32 v244, v25, v25
	v_mul_f32_e32 v245, v27, v27
	v_fmac_f32_e32 v244, v24, v24
	v_fmac_f32_e32 v245, v26, v26
	v_add_f32_e32 v244, v244, v245
	s_nop 1
	v_add_f32_dpp v244, v244, v244 quad_perm:[1,0,3,2] row_mask:0xf bank_mask:0xf bound_ctrl:1
	s_nop 1
	v_add_f32_dpp v244, v244, v244 quad_perm:[2,3,0,1] row_mask:0xf bank_mask:0xf bound_ctrl:1
	s_nop 1
	v_add_f32_dpp v244, v244, v244 row_half_mirror row_mask:0xf bank_mask:0xf bound_ctrl:1
	s_nop 1
	v_add_f32_dpp v244, v244, v244 row_mirror row_mask:0xf bank_mask:0xf bound_ctrl:1
	v_fmamk_f32 v244, v244, 0x3c800000, v132
	v_rsq_f32_e32 v244, v244
	s_nop 0
	v_mul_f32_e32 v245, v24, v244
	v_fma_f32 v245, v110, v245, v118
	v_fmac_f32_e32 v245, v40, v243
	v_mul_f32_e32 v28, v172, v245
	v_mul_f32_e32 v245, v25, v244
	v_fma_f32 v245, v111, v245, v119
	v_fmac_f32_e32 v245, v41, v243
	v_mul_f32_e32 v29, v173, v245
	v_mul_f32_e32 v245, v26, v244
	v_fma_f32 v245, v112, v245, v120
	v_fmac_f32_e32 v245, v42, v243
	v_mul_f32_e32 v30, v174, v245
	v_mul_f32_e32 v245, v27, v244
	v_fma_f32 v245, v113, v245, v121
	v_fmac_f32_e32 v245, v43, v243
	v_mul_f32_e32 v31, v175, v245
	v_cvt_pk_bf16_f32 v32, v28, v29
	v_cvt_pk_bf16_f32 v33, v30, v31
	s_lshl_b32 s7, s6, 11
	s_add_u32 s7, s7, 0x600
	s_add_u32 s8, s80, s7
	s_addc_u32 s9, s81, 0
	global_store_dwordx2 v250, v[32:33], s[8:9]
	s_add_u32 s6, s13, 2
	s_cmp_ge_u32 s6, 0x2800
	s_cbranch_scc1 .Lgpost_bend
	v_add_f32_e32 v46, v46, v50
	v_add_f32_e32 v47, v47, v51
	v_add_f32_e32 v48, v48, v52
	v_add_f32_e32 v49, v49, v53
	v_add_f32_e32 v241, v46, v47
	v_add_f32_e32 v242, v48, v49
	v_add_f32_e32 v241, v241, v242
	s_nop 1
	v_add_f32_dpp v241, v241, v241 quad_perm:[1,0,3,2] row_mask:0xf bank_mask:0xf bound_ctrl:1
	s_nop 1
	v_add_f32_dpp v241, v241, v241 quad_perm:[2,3,0,1] row_mask:0xf bank_mask:0xf bound_ctrl:1
	s_nop 1
	v_add_f32_dpp v241, v241, v241 row_half_mirror row_mask:0xf bank_mask:0xf bound_ctrl:1
	s_nop 1
	v_add_f32_dpp v241, v241, v241 row_mirror row_mask:0xf bank_mask:0xf bound_ctrl:1
	v_mul_f32_e32 v241, 0x3c800000, v241
	v_sub_f32_e32 v46, v46, v241
	v_sub_f32_e32 v47, v47, v241
	v_sub_f32_e32 v48, v48, v241
	v_sub_f32_e32 v49, v49, v241
	v_mul_f32_e32 v243, v54, v58
	v_mul_f32_e32 v244, v55, v59
	v_mul_f32_e32 v245, v56, v60
	v_mul_f32_e32 v246, v57, v61
	v_mul_f32_e32 v243, v122, v243
	v_mul_f32_e32 v245, v124, v245
	v_fmac_f32_e32 v243, v123, v244
	v_fmac_f32_e32 v245, v125, v246
	v_add_f32_e32 v243, v243, v245
	s_nop 1
	v_add_f32_dpp v243, v243, v243 quad_perm:[1,0,3,2] row_mask:0xf bank_mask:0xf bound_ctrl:1
	s_nop 1
	v_add_f32_dpp v243, v243, v243 quad_perm:[2,3,0,1] row_mask:0xf bank_mask:0xf bound_ctrl:1
	s_nop 1
	v_add_f32_dpp v243, v243, v243 row_half_mirror row_mask:0xf bank_mask:0xf bound_ctrl:1
	s_nop 1
	v_add_f32_dpp v243, v243, v243 row_mirror row_mask:0xf bank_mask:0xf bound_ctrl:1
	v_mul_f32_e32 v244, v47, v47
	v_mul_f32_e32 v245, v49, v49
	v_fmac_f32_e32 v244, v46, v46
	v_fmac_f32_e32 v245, v48, v48
	v_add_f32_e32 v244, v244, v245
	s_nop 1
	v_add_f32_dpp v244, v244, v244 quad_perm:[1,0,3,2] row_mask:0xf bank_mask:0xf bound_ctrl:1
	s_nop 1
	v_add_f32_dpp v244, v244, v244 quad_perm:[2,3,0,1] row_mask:0xf bank_mask:0xf bound_ctrl:1
	s_nop 1
	v_add_f32_dpp v244, v244, v244 row_half_mirror row_mask:0xf bank_mask:0xf bound_ctrl:1
	s_nop 1
	v_add_f32_dpp v244, v244, v244 row_mirror row_mask:0xf bank_mask:0xf bound_ctrl:1
	v_fmamk_f32 v244, v244, 0x3c800000, v132
	v_rsq_f32_e32 v244, v244
	s_nop 0
	v_mul_f32_e32 v245, v46, v244
	v_fma_f32 v245, v110, v245, v118
	v_fmac_f32_e32 v245, v62, v243
	v_mul_f32_e32 v50, v176, v245
	v_mul_f32_e32 v245, v47, v244
	v_fma_f32 v245, v111, v245, v119
	v_fmac_f32_e32 v245, v63, v243
	v_mul_f32_e32 v51, v177, v245
	v_mul_f32_e32 v245, v48, v244
	v_fma_f32 v245, v112, v245, v120
	v_fmac_f32_e32 v245, v64, v243
	v_mul_f32_e32 v52, v178, v245
	v_mul_f32_e32 v245, v49, v244
	v_fma_f32 v245, v113, v245, v121
	v_fmac_f32_e32 v245, v65, v243
	v_mul_f32_e32 v53, v179, v245
	v_cvt_pk_bf16_f32 v54, v50, v51
	v_cvt_pk_bf16_f32 v55, v52, v53
	s_lshl_b32 s7, s6, 11
	s_add_u32 s7, s7, 0x600
	s_add_u32 s8, s80, s7
	s_addc_u32 s9, s81, 0
	global_store_dwordx2 v250, v[54:55], s[8:9]
	s_add_u32 s6, s13, 3
	s_cmp_ge_u32 s6, 0x2800
	s_cbranch_scc1 .Lgpost_bend
	v_add_f32_e32 v68, v68, v72
	v_add_f32_e32 v69, v69, v73
	v_add_f32_e32 v70, v70, v74
	v_add_f32_e32 v71, v71, v75
	v_add_f32_e32 v241, v68, v69
	v_add_f32_e32 v242, v70, v71
	v_add_f32_e32 v241, v241, v242
	s_nop 1
	v_add_f32_dpp v241, v241, v241 quad_perm:[1,0,3,2] row_mask:0xf bank_mask:0xf bound_ctrl:1
	s_nop 1
	v_add_f32_dpp v241, v241, v241 quad_perm:[2,3,0,1] row_mask:0xf bank_mask:0xf bound_ctrl:1
	s_nop 1
	v_add_f32_dpp v241, v241, v241 row_half_mirror row_mask:0xf bank_mask:0xf bound_ctrl:1
	s_nop 1
	v_add_f32_dpp v241, v241, v241 row_mirror row_mask:0xf bank_mask:0xf bound_ctrl:1
	v_mul_f32_e32 v241, 0x3c800000, v241
	v_sub_f32_e32 v68, v68, v241
	v_sub_f32_e32 v69, v69, v241
	v_sub_f32_e32 v70, v70, v241
	v_sub_f32_e32 v71, v71, v241
	v_mul_f32_e32 v243, v76, v80
	v_mul_f32_e32 v244, v77, v81
	v_mul_f32_e32 v245, v78, v82
	v_mul_f32_e32 v246, v79, v83
	v_mul_f32_e32 v243, v122, v243
	v_mul_f32_e32 v245, v124, v245
	v_fmac_f32_e32 v243, v123, v244
	v_fmac_f32_e32 v245, v125, v246
	v_add_f32_e32 v243, v243, v245
	s_nop 1
	v_add_f32_dpp v243, v243, v243 quad_perm:[1,0,3,2] row_mask:0xf bank_mask:0xf bound_ctrl:1
	s_nop 1
	v_add_f32_dpp v243, v243, v243 quad_perm:[2,3,0,1] row_mask:0xf bank_mask:0xf bound_ctrl:1
	s_nop 1
	v_add_f32_dpp v243, v243, v243 row_half_mirror row_mask:0xf bank_mask:0xf bound_ctrl:1
	s_nop 1
	v_add_f32_dpp v243, v243, v243 row_mirror row_mask:0xf bank_mask:0xf bound_ctrl:1
	v_mul_f32_e32 v244, v69, v69
	v_mul_f32_e32 v245, v71, v71
	v_fmac_f32_e32 v244, v68, v68
	v_fmac_f32_e32 v245, v70, v70
	v_add_f32_e32 v244, v244, v245
	s_nop 1
	v_add_f32_dpp v244, v244, v244 quad_perm:[1,0,3,2] row_mask:0xf bank_mask:0xf bound_ctrl:1
	s_nop 1
	v_add_f32_dpp v244, v244, v244 quad_perm:[2,3,0,1] row_mask:0xf bank_mask:0xf bound_ctrl:1
	s_nop 1
	v_add_f32_dpp v244, v244, v244 row_half_mirror row_mask:0xf bank_mask:0xf bound_ctrl:1
	s_nop 1
	v_add_f32_dpp v244, v244, v244 row_mirror row_mask:0xf bank_mask:0xf bound_ctrl:1
	v_fmamk_f32 v244, v244, 0x3c800000, v132
	v_rsq_f32_e32 v244, v244
	s_nop 0
	v_mul_f32_e32 v245, v68, v244
	v_fma_f32 v245, v110, v245, v118
	v_fmac_f32_e32 v245, v84, v243
	v_mul_f32_e32 v72, v180, v245
	v_mul_f32_e32 v245, v69, v244
	v_fma_f32 v245, v111, v245, v119
	v_fmac_f32_e32 v245, v85, v243
	v_mul_f32_e32 v73, v181, v245
	v_mul_f32_e32 v245, v70, v244
	v_fma_f32 v245, v112, v245, v120
	v_fmac_f32_e32 v245, v86, v243
	v_mul_f32_e32 v74, v182, v245
	v_mul_f32_e32 v245, v71, v244
	v_fma_f32 v245, v113, v245, v121
	v_fmac_f32_e32 v245, v87, v243
	v_mul_f32_e32 v75, v183, v245
	v_cvt_pk_bf16_f32 v76, v72, v73
	v_cvt_pk_bf16_f32 v77, v74, v75
	s_lshl_b32 s7, s6, 11
	s_add_u32 s7, s7, 0x600
	s_add_u32 s8, s80, s7
	s_addc_u32 s9, s81, 0
	global_store_dwordx2 v250, v[76:77], s[8:9]
	s_add_u32 s6, s13, 4
	s_cmp_ge_u32 s6, 0x2800
	s_cbranch_scc1 .Lgpost_bend
	v_add_f32_e32 v90, v90, v94
	v_add_f32_e32 v91, v91, v95
	v_add_f32_e32 v92, v92, v96
	v_add_f32_e32 v93, v93, v97
	v_add_f32_e32 v241, v90, v91
	v_add_f32_e32 v242, v92, v93
	v_add_f32_e32 v241, v241, v242
	s_nop 1
	v_add_f32_dpp v241, v241, v241 quad_perm:[1,0,3,2] row_mask:0xf bank_mask:0xf bound_ctrl:1
	s_nop 1
	v_add_f32_dpp v241, v241, v241 quad_perm:[2,3,0,1] row_mask:0xf bank_mask:0xf bound_ctrl:1
	s_nop 1
	v_add_f32_dpp v241, v241, v241 row_half_mirror row_mask:0xf bank_mask:0xf bound_ctrl:1
	s_nop 1
	v_add_f32_dpp v241, v241, v241 row_mirror row_mask:0xf bank_mask:0xf bound_ctrl:1
	v_mul_f32_e32 v241, 0x3c800000, v241
	v_sub_f32_e32 v90, v90, v241
	v_sub_f32_e32 v91, v91, v241
	v_sub_f32_e32 v92, v92, v241
	v_sub_f32_e32 v93, v93, v241
	v_mul_f32_e32 v243, v98, v102
	v_mul_f32_e32 v244, v99, v103
	v_mul_f32_e32 v245, v100, v104
	v_mul_f32_e32 v246, v101, v105
	v_mul_f32_e32 v243, v122, v243
	v_mul_f32_e32 v245, v124, v245
	v_fmac_f32_e32 v243, v123, v244
	v_fmac_f32_e32 v245, v125, v246
	v_add_f32_e32 v243, v243, v245
	s_nop 1
	v_add_f32_dpp v243, v243, v243 quad_perm:[1,0,3,2] row_mask:0xf bank_mask:0xf bound_ctrl:1
	s_nop 1
	v_add_f32_dpp v243, v243, v243 quad_perm:[2,3,0,1] row_mask:0xf bank_mask:0xf bound_ctrl:1
	s_nop 1
	v_add_f32_dpp v243, v243, v243 row_half_mirror row_mask:0xf bank_mask:0xf bound_ctrl:1
	s_nop 1
	v_add_f32_dpp v243, v243, v243 row_mirror row_mask:0xf bank_mask:0xf bound_ctrl:1
	v_mul_f32_e32 v244, v91, v91
	v_mul_f32_e32 v245, v93, v93
	v_fmac_f32_e32 v244, v90, v90
	v_fmac_f32_e32 v245, v92, v92
	v_add_f32_e32 v244, v244, v245
	s_nop 1
	v_add_f32_dpp v244, v244, v244 quad_perm:[1,0,3,2] row_mask:0xf bank_mask:0xf bound_ctrl:1
	s_nop 1
	v_add_f32_dpp v244, v244, v244 quad_perm:[2,3,0,1] row_mask:0xf bank_mask:0xf bound_ctrl:1
	s_nop 1
	v_add_f32_dpp v244, v244, v244 row_half_mirror row_mask:0xf bank_mask:0xf bound_ctrl:1
	s_nop 1
	v_add_f32_dpp v244, v244, v244 row_mirror row_mask:0xf bank_mask:0xf bound_ctrl:1
	v_fmamk_f32 v244, v244, 0x3c800000, v132
	v_rsq_f32_e32 v244, v244
	s_nop 0
	v_mul_f32_e32 v245, v90, v244
	v_fma_f32 v245, v110, v245, v118
	v_fmac_f32_e32 v245, v106, v243
	v_mul_f32_e32 v94, v184, v245
	v_mul_f32_e32 v245, v91, v244
	v_fma_f32 v245, v111, v245, v119
	v_fmac_f32_e32 v245, v107, v243
	v_mul_f32_e32 v95, v185, v245
	v_mul_f32_e32 v245, v92, v244
	v_fma_f32 v245, v112, v245, v120
	v_fmac_f32_e32 v245, v108, v243
	v_mul_f32_e32 v96, v186, v245
	v_mul_f32_e32 v245, v93, v244
	v_fma_f32 v245, v113, v245, v121
	v_fmac_f32_e32 v245, v109, v243
	v_mul_f32_e32 v97, v187, v245
	v_cvt_pk_bf16_f32 v98, v94, v95
	v_cvt_pk_bf16_f32 v99, v96, v97
	s_lshl_b32 s7, s6, 11
	s_add_u32 s7, s7, 0x600
	s_add_u32 s8, s80, s7
	s_addc_u32 s9, s81, 0
	global_store_dwordx2 v250, v[98:99], s[8:9]
